# stack: combined load-segment waits + SGPR-base DMA addressing added to nt conversion stores + peeled C=0 first K-iteration + no canonicalizing v_max + MFMA-head trim + barrier XGEN-first
# speedup vs baseline: 1.0169x; 1.0076x over previous
.LBB0_349:
	s_ashr_i32 s9, s8, 31
	s_lshl_b64 s[4:5], s[8:9], 20
	s_add_u32 s12, s36, s4
	s_addc_u32 s13, s37, s5
	s_and_b64 s[4:5], s[14:15], exec
	s_cselect_b32 s4, s13, s25
	s_cselect_b32 s5, s12, s24
	s_ashr_i32 s11, s10, 31
	s_lshl_b64 s[18:19], s[10:11], 20
	s_add_u32 s18, s0, s18
	s_addc_u32 s19, s1, s19
	s_and_b64 s[28:29], s[14:15], exec
	s_cselect_b32 s9, s19, s27
	s_cselect_b32 s11, s18, s26
	s_add_u32 s50, s5, 0x80
	s_addc_u32 s51, s4, 0
	s_add_u32 s52, s26, 0x10000
	v_mov_b32_e32 v2, 0
	s_addc_u32 s53, s27, 0
	v_lshl_add_u64 v[142:143], s[24:25], 0, v[138:139]
	v_lshl_add_u64 v[144:145], s[24:25], 0, v[140:141]
	s_mov_b32 s54, -2
	s_mov_b64 s[26:27], 0
	ds_read_b128 v[152:155], v148
	ds_read_b128 v[156:159], v148 offset:1024
	ds_read_b128 v[160:163], v148 offset:2048
	ds_read_b128 v[164:167], v148 offset:3072
	ds_read_b128 v[168:171], v149
	ds_read_b128 v[172:175], v149 offset:1024
	ds_read_b128 v[176:179], v149 offset:2048
	ds_read_b128 v[180:183], v149 offset:3072
	s_add_u32 s28, s24, s26
	s_addc_u32 s29, s25, s27
	s_add_u32 s34, s28, 0x100
	s_addc_u32 s35, s29, 0
	s_add_u32 s28, s28, 0x180
	s_addc_u32 s29, s29, 0
	s_cmpk_eq_i32 s26, 0xf00
	s_cselect_b32 s29, s51, s29
	s_cselect_b32 s28, s50, s28
	s_cselect_b32 s31, s9, s53
	s_cselect_b32 s30, s11, s52
	s_cselect_b32 s35, s4, s35
	s_cselect_b32 s34, s5, s34
	s_mov_b32 m0, s49
	v_lshl_add_u64 v[216:217], v[142:143], 0, s[26:27]
	ds_read_b128 v[184:187], v150
	ds_read_b128 v[188:191], v150 offset:1024
	ds_read_b128 v[192:195], v150 offset:2048
	ds_read_b128 v[196:199], v150 offset:3072
	ds_read_b128 v[200:203], v150 offset:4096
	ds_read_b128 v[204:207], v150 offset:5120
	ds_read_b128 v[208:211], v150 offset:6144
	ds_read_b128 v[212:215], v150 offset:7168
	global_load_lds_dwordx4 v[216:217], off
	v_lshl_add_u64 v[216:217], v[144:145], 0, s[26:27]
	s_add_i32 m0, s21, 0xe000
	s_nop 0
	global_load_lds_dwordx4 v[216:217], off
	s_waitcnt vmcnt(8) lgkmcnt(0)
	s_barrier
	v_mfma_f32_16x16x32_bf16 v[122:125], v[152:155], v[184:187], 0
	v_mfma_f32_16x16x32_bf16 v[118:121], v[160:163], v[184:187], 0
	v_mfma_f32_16x16x32_bf16 v[106:109], v[152:155], v[192:195], 0
	v_mfma_f32_16x16x32_bf16 v[102:105], v[160:163], v[192:195], 0
	v_mfma_f32_16x16x32_bf16 v[90:93], v[152:155], v[200:203], 0
	v_mfma_f32_16x16x32_bf16 v[86:89], v[160:163], v[200:203], 0
	v_mfma_f32_16x16x32_bf16 v[74:77], v[152:155], v[208:211], 0
	v_mfma_f32_16x16x32_bf16 v[70:73], v[160:163], v[208:211], 0
	v_mfma_f32_16x16x32_bf16 v[122:125], v[156:159], v[188:191], v[122:125]
	v_mfma_f32_16x16x32_bf16 v[118:121], v[164:167], v[188:191], v[118:121]
	v_mfma_f32_16x16x32_bf16 v[106:109], v[156:159], v[196:199], v[106:109]
	v_mfma_f32_16x16x32_bf16 v[102:105], v[164:167], v[196:199], v[102:105]
	v_mfma_f32_16x16x32_bf16 v[90:93], v[156:159], v[204:207], v[90:93]
	v_mfma_f32_16x16x32_bf16 v[86:89], v[164:167], v[204:207], v[86:89]
	v_mfma_f32_16x16x32_bf16 v[74:77], v[156:159], v[212:215], v[74:77]
	v_mfma_f32_16x16x32_bf16 v[70:73], v[164:167], v[212:215], v[70:73]
	v_mfma_f32_16x16x32_bf16 v[126:129], v[168:171], v[184:187], 0
	v_mfma_f32_16x16x32_bf16 v[114:117], v[176:179], v[184:187], 0
	v_mfma_f32_16x16x32_bf16 v[110:113], v[168:171], v[192:195], 0
	v_mfma_f32_16x16x32_bf16 v[98:101], v[176:179], v[192:195], 0
	v_mfma_f32_16x16x32_bf16 v[94:97], v[168:171], v[200:203], 0
	v_mfma_f32_16x16x32_bf16 v[82:85], v[176:179], v[200:203], 0
	v_mfma_f32_16x16x32_bf16 v[78:81], v[168:171], v[208:211], 0
	v_mfma_f32_16x16x32_bf16 v[66:69], v[176:179], v[208:211], 0
	v_mfma_f32_16x16x32_bf16 v[126:129], v[172:175], v[188:191], v[126:129]
	v_mfma_f32_16x16x32_bf16 v[114:117], v[180:183], v[188:191], v[114:117]
	v_mfma_f32_16x16x32_bf16 v[110:113], v[172:175], v[196:199], v[110:113]
	v_mfma_f32_16x16x32_bf16 v[98:101], v[180:183], v[196:199], v[98:101]
	v_mfma_f32_16x16x32_bf16 v[94:97], v[172:175], v[204:207], v[94:97]
	v_mfma_f32_16x16x32_bf16 v[82:85], v[180:183], v[204:207], v[82:85]
	v_mfma_f32_16x16x32_bf16 v[78:81], v[172:175], v[212:215], v[78:81]
	v_mfma_f32_16x16x32_bf16 v[66:69], v[180:183], v[212:215], v[66:69]
	s_barrier
	s_add_i32 s55, s44, s33
	s_mov_b32 m0, s55
	ds_read_b128 v[184:187], v150 offset:16384
	ds_read_b128 v[188:191], v150 offset:17408
	ds_read_b128 v[192:195], v150 offset:18432
	ds_read_b128 v[196:199], v150 offset:19456
	ds_read_b128 v[200:203], v150 offset:20480
	ds_read_b128 v[204:207], v150 offset:21504
	ds_read_b128 v[208:211], v150 offset:22528
	ds_read_b128 v[212:215], v150 offset:23552
	global_load_lds_dwordx4 v134, s[30:31]
	s_add_i32 m0, s55, 0x2000
	s_add_u32 s56, s30, 0x4000
	s_addc_u32 s57, s31, 0
	s_add_i32 s55, s45, s33
	global_load_lds_dwordx4 v130, s[30:31]
	s_mov_b32 m0, s55
	s_nop 0
	global_load_lds_dwordx4 v134, s[56:57]
	s_add_i32 m0, s55, 0x2000
	s_nop 0
	global_load_lds_dwordx4 v130, s[56:57]
	s_mov_b32 m0, s21
	s_nop 0
	global_load_lds_dwordx4 v136, s[34:35]
	s_mov_b32 m0, s23
	s_nop 0
	global_load_lds_dwordx4 v132, s[34:35]
	s_waitcnt vmcnt(8) lgkmcnt(0)
	s_barrier
	v_mfma_f32_16x16x32_bf16 v[58:61], v[152:155], v[184:187], 0
	v_mfma_f32_16x16x32_bf16 v[54:57], v[160:163], v[184:187], 0
	v_mfma_f32_16x16x32_bf16 v[42:45], v[152:155], v[192:195], 0
	v_mfma_f32_16x16x32_bf16 v[38:41], v[160:163], v[192:195], 0
	v_mfma_f32_16x16x32_bf16 v[26:29], v[152:155], v[200:203], 0
	v_mfma_f32_16x16x32_bf16 v[22:25], v[160:163], v[200:203], 0
	v_mfma_f32_16x16x32_bf16 v[10:13], v[152:155], v[208:211], 0
	v_mfma_f32_16x16x32_bf16 v[6:9], v[160:163], v[208:211], 0
	v_mfma_f32_16x16x32_bf16 v[58:61], v[156:159], v[188:191], v[58:61]
	v_mfma_f32_16x16x32_bf16 v[54:57], v[164:167], v[188:191], v[54:57]
	v_mfma_f32_16x16x32_bf16 v[42:45], v[156:159], v[196:199], v[42:45]
	v_mfma_f32_16x16x32_bf16 v[38:41], v[164:167], v[196:199], v[38:41]
	v_mfma_f32_16x16x32_bf16 v[26:29], v[156:159], v[204:207], v[26:29]
	v_mfma_f32_16x16x32_bf16 v[22:25], v[164:167], v[204:207], v[22:25]
	v_mfma_f32_16x16x32_bf16 v[10:13], v[156:159], v[212:215], v[10:13]
	v_mfma_f32_16x16x32_bf16 v[6:9], v[164:167], v[212:215], v[6:9]
	v_mfma_f32_16x16x32_bf16 v[62:65], v[168:171], v[184:187], 0
	v_mfma_f32_16x16x32_bf16 v[50:53], v[176:179], v[184:187], 0
	v_mfma_f32_16x16x32_bf16 v[46:49], v[168:171], v[192:195], 0
	v_mfma_f32_16x16x32_bf16 v[34:37], v[176:179], v[192:195], 0
	v_mfma_f32_16x16x32_bf16 v[30:33], v[168:171], v[200:203], 0
	v_mfma_f32_16x16x32_bf16 v[18:21], v[176:179], v[200:203], 0
	v_mfma_f32_16x16x32_bf16 v[14:17], v[168:171], v[208:211], 0
	v_mfma_f32_16x16x32_bf16 v[2:5], v[176:179], v[208:211], 0
	v_mfma_f32_16x16x32_bf16 v[62:65], v[172:175], v[188:191], v[62:65]
	v_mfma_f32_16x16x32_bf16 v[50:53], v[180:183], v[188:191], v[50:53]
	v_mfma_f32_16x16x32_bf16 v[46:49], v[172:175], v[196:199], v[46:49]
	v_mfma_f32_16x16x32_bf16 v[34:37], v[180:183], v[196:199], v[34:37]
	v_mfma_f32_16x16x32_bf16 v[30:33], v[172:175], v[204:207], v[30:33]
	v_mfma_f32_16x16x32_bf16 v[18:21], v[180:183], v[204:207], v[18:21]
	v_mfma_f32_16x16x32_bf16 v[14:17], v[172:175], v[212:215], v[14:17]
	v_mfma_f32_16x16x32_bf16 v[2:5], v[180:183], v[212:215], v[2:5]
	s_barrier
	s_add_i32 s55, 0, 0x18000
	v_add_u32_e32 v151, s55, v146
	s_add_i32 s56, 0, 0x1c000
	ds_read_b128 v[152:155], v151
	ds_read_b128 v[156:159], v151 offset:1024
	ds_read_b128 v[160:163], v151 offset:2048
	ds_read_b128 v[164:167], v151 offset:3072
	v_add_u32_e32 v151, s56, v146
	ds_read_b128 v[168:171], v151
	ds_read_b128 v[172:175], v151 offset:1024
	ds_read_b128 v[176:179], v151 offset:2048
	ds_read_b128 v[180:183], v151 offset:3072
	s_add_u32 s34, s34, 0x80000
	s_addc_u32 s35, s35, 0
	s_mov_b32 m0, s39
	ds_read_b128 v[184:187], v150 offset:32768
	ds_read_b128 v[188:191], v150 offset:33792
	ds_read_b128 v[192:195], v150 offset:34816
	ds_read_b128 v[196:199], v150 offset:35840
	ds_read_b128 v[200:203], v150 offset:36864
	ds_read_b128 v[204:207], v150 offset:37888
	ds_read_b128 v[208:211], v150 offset:38912
	ds_read_b128 v[212:215], v150 offset:39936
	global_load_lds_dwordx4 v136, s[34:35]
	s_mov_b32 m0, s40
	s_nop 0
	global_load_lds_dwordx4 v132, s[34:35]
	s_waitcnt vmcnt(8) lgkmcnt(0)
	s_barrier
	v_mfma_f32_16x16x32_bf16 v[122:125], v[152:155], v[184:187], v[122:125]
	v_mfma_f32_16x16x32_bf16 v[118:121], v[160:163], v[184:187], v[118:121]
	v_mfma_f32_16x16x32_bf16 v[106:109], v[152:155], v[192:195], v[106:109]
	v_mfma_f32_16x16x32_bf16 v[102:105], v[160:163], v[192:195], v[102:105]
	v_mfma_f32_16x16x32_bf16 v[90:93], v[152:155], v[200:203], v[90:93]
	v_mfma_f32_16x16x32_bf16 v[86:89], v[160:163], v[200:203], v[86:89]
	v_mfma_f32_16x16x32_bf16 v[74:77], v[152:155], v[208:211], v[74:77]
	v_mfma_f32_16x16x32_bf16 v[70:73], v[160:163], v[208:211], v[70:73]
	v_mfma_f32_16x16x32_bf16 v[122:125], v[156:159], v[188:191], v[122:125]
	v_mfma_f32_16x16x32_bf16 v[118:121], v[164:167], v[188:191], v[118:121]
	v_mfma_f32_16x16x32_bf16 v[106:109], v[156:159], v[196:199], v[106:109]
	v_mfma_f32_16x16x32_bf16 v[102:105], v[164:167], v[196:199], v[102:105]
	v_mfma_f32_16x16x32_bf16 v[90:93], v[156:159], v[204:207], v[90:93]
	v_mfma_f32_16x16x32_bf16 v[86:89], v[164:167], v[204:207], v[86:89]
	v_mfma_f32_16x16x32_bf16 v[74:77], v[156:159], v[212:215], v[74:77]
	v_mfma_f32_16x16x32_bf16 v[70:73], v[164:167], v[212:215], v[70:73]
	v_mfma_f32_16x16x32_bf16 v[126:129], v[168:171], v[184:187], v[126:129]
	v_mfma_f32_16x16x32_bf16 v[114:117], v[176:179], v[184:187], v[114:117]
	v_mfma_f32_16x16x32_bf16 v[110:113], v[168:171], v[192:195], v[110:113]
	v_mfma_f32_16x16x32_bf16 v[98:101], v[176:179], v[192:195], v[98:101]
	v_mfma_f32_16x16x32_bf16 v[94:97], v[168:171], v[200:203], v[94:97]
	v_mfma_f32_16x16x32_bf16 v[82:85], v[176:179], v[200:203], v[82:85]
	v_mfma_f32_16x16x32_bf16 v[78:81], v[168:171], v[208:211], v[78:81]
	v_mfma_f32_16x16x32_bf16 v[66:69], v[176:179], v[208:211], v[66:69]
	v_mfma_f32_16x16x32_bf16 v[126:129], v[172:175], v[188:191], v[126:129]
	v_mfma_f32_16x16x32_bf16 v[114:117], v[180:183], v[188:191], v[114:117]
	v_mfma_f32_16x16x32_bf16 v[110:113], v[172:175], v[196:199], v[110:113]
	v_mfma_f32_16x16x32_bf16 v[98:101], v[180:183], v[196:199], v[98:101]
	v_mfma_f32_16x16x32_bf16 v[94:97], v[172:175], v[204:207], v[94:97]
	v_mfma_f32_16x16x32_bf16 v[82:85], v[180:183], v[204:207], v[82:85]
	v_mfma_f32_16x16x32_bf16 v[78:81], v[172:175], v[212:215], v[78:81]
	v_mfma_f32_16x16x32_bf16 v[66:69], v[180:183], v[212:215], v[66:69]
	s_barrier
	s_add_u32 s34, s30, 0x8000
	s_addc_u32 s35, s31, 0
	s_add_i32 s55, s55, s33
	s_mov_b32 m0, s55
	ds_read_b128 v[184:187], v150 offset:49152
	ds_read_b128 v[188:191], v150 offset:50176
	ds_read_b128 v[192:195], v150 offset:51200
	ds_read_b128 v[196:199], v150 offset:52224
	ds_read_b128 v[200:203], v150 offset:53248
	ds_read_b128 v[204:207], v150 offset:54272
	ds_read_b128 v[208:211], v150 offset:55296
	ds_read_b128 v[212:215], v150 offset:56320
	global_load_lds_dwordx4 v134, s[34:35]
	s_add_i32 m0, s55, 0x2000
	s_add_u32 s30, s30, 0xc000
	v_lshl_add_u64 v[216:217], s[34:35], 0, v[130:131]
	s_addc_u32 s31, s31, 0
	s_add_i32 s34, s56, s33
	global_load_lds_dwordx4 v[216:217], off
	s_mov_b32 m0, s34
	s_nop 0
	global_load_lds_dwordx4 v134, s[30:31]
	s_add_i32 m0, s34, 0x2000
	s_nop 0
	global_load_lds_dwordx4 v130, s[30:31]
	s_mov_b32 m0, s42
	s_nop 0
	global_load_lds_dwordx4 v136, s[28:29]
	s_mov_b32 m0, s43
	s_nop 0
	global_load_lds_dwordx4 v132, s[28:29]
	s_waitcnt vmcnt(8) lgkmcnt(0)
	s_barrier
	v_mfma_f32_16x16x32_bf16 v[58:61], v[152:155], v[184:187], v[58:61]
	v_mfma_f32_16x16x32_bf16 v[54:57], v[160:163], v[184:187], v[54:57]
	v_mfma_f32_16x16x32_bf16 v[42:45], v[152:155], v[192:195], v[42:45]
	v_mfma_f32_16x16x32_bf16 v[38:41], v[160:163], v[192:195], v[38:41]
	v_mfma_f32_16x16x32_bf16 v[26:29], v[152:155], v[200:203], v[26:29]
	v_mfma_f32_16x16x32_bf16 v[22:25], v[160:163], v[200:203], v[22:25]
	v_mfma_f32_16x16x32_bf16 v[10:13], v[152:155], v[208:211], v[10:13]
	v_mfma_f32_16x16x32_bf16 v[6:9], v[160:163], v[208:211], v[6:9]
	v_mfma_f32_16x16x32_bf16 v[58:61], v[156:159], v[188:191], v[58:61]
	v_mfma_f32_16x16x32_bf16 v[54:57], v[164:167], v[188:191], v[54:57]
	v_mfma_f32_16x16x32_bf16 v[42:45], v[156:159], v[196:199], v[42:45]
	v_mfma_f32_16x16x32_bf16 v[38:41], v[164:167], v[196:199], v[38:41]
	v_mfma_f32_16x16x32_bf16 v[26:29], v[156:159], v[204:207], v[26:29]
	v_mfma_f32_16x16x32_bf16 v[22:25], v[164:167], v[204:207], v[22:25]
	v_mfma_f32_16x16x32_bf16 v[10:13], v[156:159], v[212:215], v[10:13]
	v_mfma_f32_16x16x32_bf16 v[6:9], v[164:167], v[212:215], v[6:9]
	v_mfma_f32_16x16x32_bf16 v[62:65], v[168:171], v[184:187], v[62:65]
	v_mfma_f32_16x16x32_bf16 v[50:53], v[176:179], v[184:187], v[50:53]
	v_mfma_f32_16x16x32_bf16 v[46:49], v[168:171], v[192:195], v[46:49]
	v_mfma_f32_16x16x32_bf16 v[34:37], v[176:179], v[192:195], v[34:37]
	v_mfma_f32_16x16x32_bf16 v[30:33], v[168:171], v[200:203], v[30:33]
	v_mfma_f32_16x16x32_bf16 v[18:21], v[176:179], v[200:203], v[18:21]
	v_mfma_f32_16x16x32_bf16 v[14:17], v[168:171], v[208:211], v[14:17]
	v_mfma_f32_16x16x32_bf16 v[2:5], v[176:179], v[208:211], v[2:5]
	v_mfma_f32_16x16x32_bf16 v[62:65], v[172:175], v[188:191], v[62:65]
	v_mfma_f32_16x16x32_bf16 v[50:53], v[180:183], v[188:191], v[50:53]
	v_mfma_f32_16x16x32_bf16 v[46:49], v[172:175], v[196:199], v[46:49]
	v_mfma_f32_16x16x32_bf16 v[34:37], v[180:183], v[196:199], v[34:37]
	v_mfma_f32_16x16x32_bf16 v[30:33], v[172:175], v[204:207], v[30:33]
	v_mfma_f32_16x16x32_bf16 v[18:21], v[180:183], v[204:207], v[18:21]
	v_mfma_f32_16x16x32_bf16 v[14:17], v[172:175], v[212:215], v[14:17]
	v_mfma_f32_16x16x32_bf16 v[2:5], v[180:183], v[212:215], v[2:5]
	s_barrier
	s_add_i32 s54, s54, 2
	s_add_u32 s26, s26, 0x100
	s_addc_u32 s27, s27, 0
	s_add_u32 s52, s52, 0x10000
	s_addc_u32 s53, s53, 0
	s_cmp_gt_u32 s54, 29

.LBB0_474:
	s_ashr_i32 s11, s10, 31
	s_lshl_b64 s[4:5], s[10:11], 20
	s_add_u32 s14, s41, s4
	s_addc_u32 s15, s42, s5
	s_and_b64 s[4:5], s[18:19], exec
	s_cselect_b32 s4, s15, s27
	s_cselect_b32 s5, s14, s26
	s_ashr_i32 s13, s12, 31
	s_lshl_b64 s[20:21], s[12:13], 20
	s_add_u32 s20, s0, s20
	s_addc_u32 s21, s39, s21
	s_and_b64 s[30:31], s[18:19], exec
	s_cselect_b32 s11, s21, s29
	s_cselect_b32 s13, s20, s28
	s_add_u32 s23, s5, 0x80
	s_addc_u32 s57, s4, 0
	s_add_u32 s58, s28, 0x10000
	v_mov_b32_e32 v2, 0
	s_addc_u32 s59, s29, 0
	v_lshl_add_u64 v[164:165], s[26:27], 0, v[160:161]
	v_lshl_add_u64 v[166:167], s[26:27], 0, v[162:163]
	s_mov_b32 s60, -2
	s_mov_b64 s[28:29], 0
	ds_read_b128 v[172:175], v168
	ds_read_b128 v[176:179], v168 offset:1024
	ds_read_b128 v[180:183], v168 offset:2048
	ds_read_b128 v[184:187], v168 offset:3072
	ds_read_b128 v[188:191], v169
	ds_read_b128 v[192:195], v169 offset:1024
	ds_read_b128 v[196:199], v169 offset:2048
	ds_read_b128 v[200:203], v169 offset:3072
	s_add_u32 s30, s26, s28
	s_addc_u32 s31, s27, s29
	s_add_u32 s36, s30, 0x100
	s_addc_u32 s37, s31, 0
	s_add_u32 s30, s30, 0x180
	s_addc_u32 s31, s31, 0
	s_cmpk_eq_i32 s28, 0xf00
	s_cselect_b32 s31, s57, s31
	s_cselect_b32 s30, s23, s30
	s_cselect_b32 s35, s11, s59
	s_cselect_b32 s34, s13, s58
	s_cselect_b32 s37, s4, s37
	s_cselect_b32 s36, s5, s36
	s_mov_b32 m0, s53
	v_lshl_add_u64 v[236:237], v[164:165], 0, s[28:29]
	ds_read_b128 v[204:207], v170
	ds_read_b128 v[208:211], v170 offset:1024
	ds_read_b128 v[212:215], v170 offset:2048
	ds_read_b128 v[216:219], v170 offset:3072
	ds_read_b128 v[220:223], v170 offset:4096
	ds_read_b128 v[224:227], v170 offset:5120
	ds_read_b128 v[228:231], v170 offset:6144
	ds_read_b128 v[232:235], v170 offset:7168
	global_load_lds_dwordx4 v[236:237], off
	v_lshl_add_u64 v[236:237], v[166:167], 0, s[28:29]
	s_mov_b32 m0, s54
	s_nop 0
	global_load_lds_dwordx4 v[236:237], off
	s_waitcnt vmcnt(8) lgkmcnt(0)
	s_barrier
	v_mfma_f32_16x16x32_bf16 v[126:129], v[172:175], v[204:207], 0
	v_mfma_f32_16x16x32_bf16 v[122:125], v[180:183], v[204:207], 0
	v_mfma_f32_16x16x32_bf16 v[110:113], v[172:175], v[212:215], 0
	v_mfma_f32_16x16x32_bf16 v[106:109], v[180:183], v[212:215], 0
	v_mfma_f32_16x16x32_bf16 v[94:97], v[172:175], v[220:223], 0
	v_mfma_f32_16x16x32_bf16 v[90:93], v[180:183], v[220:223], 0
	v_mfma_f32_16x16x32_bf16 v[78:81], v[172:175], v[228:231], 0
	v_mfma_f32_16x16x32_bf16 v[74:77], v[180:183], v[228:231], 0
	v_mfma_f32_16x16x32_bf16 v[126:129], v[176:179], v[208:211], v[126:129]
	v_mfma_f32_16x16x32_bf16 v[122:125], v[184:187], v[208:211], v[122:125]
	v_mfma_f32_16x16x32_bf16 v[110:113], v[176:179], v[216:219], v[110:113]
	v_mfma_f32_16x16x32_bf16 v[106:109], v[184:187], v[216:219], v[106:109]
	v_mfma_f32_16x16x32_bf16 v[94:97], v[176:179], v[224:227], v[94:97]
	v_mfma_f32_16x16x32_bf16 v[90:93], v[184:187], v[224:227], v[90:93]
	v_mfma_f32_16x16x32_bf16 v[78:81], v[176:179], v[232:235], v[78:81]
	v_mfma_f32_16x16x32_bf16 v[74:77], v[184:187], v[232:235], v[74:77]
	v_mfma_f32_16x16x32_bf16 v[118:121], v[188:191], v[204:207], 0
	v_mfma_f32_16x16x32_bf16 v[114:117], v[196:199], v[204:207], 0
	v_mfma_f32_16x16x32_bf16 v[102:105], v[188:191], v[212:215], 0
	v_mfma_f32_16x16x32_bf16 v[98:101], v[196:199], v[212:215], 0
	v_mfma_f32_16x16x32_bf16 v[86:89], v[188:191], v[220:223], 0
	v_mfma_f32_16x16x32_bf16 v[82:85], v[196:199], v[220:223], 0
	v_mfma_f32_16x16x32_bf16 v[70:73], v[188:191], v[228:231], 0
	v_mfma_f32_16x16x32_bf16 v[66:69], v[196:199], v[228:231], 0
	v_mfma_f32_16x16x32_bf16 v[118:121], v[192:195], v[208:211], v[118:121]
	v_mfma_f32_16x16x32_bf16 v[114:117], v[200:203], v[208:211], v[114:117]
	v_mfma_f32_16x16x32_bf16 v[102:105], v[192:195], v[216:219], v[102:105]
	v_mfma_f32_16x16x32_bf16 v[98:101], v[200:203], v[216:219], v[98:101]
	v_mfma_f32_16x16x32_bf16 v[86:89], v[192:195], v[224:227], v[86:89]
	v_mfma_f32_16x16x32_bf16 v[82:85], v[200:203], v[224:227], v[82:85]
	v_mfma_f32_16x16x32_bf16 v[70:73], v[192:195], v[232:235], v[70:73]
	v_mfma_f32_16x16x32_bf16 v[66:69], v[200:203], v[232:235], v[66:69]
	s_barrier
	s_mov_b32 m0, s55
	s_add_u32 s62, s34, 0x4000
	ds_read_b128 v[204:207], v170 offset:16384
	ds_read_b128 v[208:211], v170 offset:17408
	ds_read_b128 v[212:215], v170 offset:18432
	ds_read_b128 v[216:219], v170 offset:19456
	ds_read_b128 v[220:223], v170 offset:20480
	ds_read_b128 v[224:227], v170 offset:21504
	ds_read_b128 v[228:231], v170 offset:22528
	ds_read_b128 v[232:235], v170 offset:23552
	global_load_lds_dwordx4 v134, s[34:35]
	s_mov_b32 m0, s56
	s_addc_u32 s63, s35, 0
	s_add_i32 s61, s52, s40
	global_load_lds_dwordx4 v130, s[34:35]
	s_mov_b32 m0, s61
	s_nop 0
	global_load_lds_dwordx4 v134, s[62:63]
	s_add_i32 m0, s61, 0x2000
	s_nop 0
	global_load_lds_dwordx4 v130, s[62:63]
	s_mov_b32 m0, s25
	s_nop 0
	global_load_lds_dwordx4 v136, s[36:37]
	s_mov_b32 m0, s43
	s_nop 0
	global_load_lds_dwordx4 v132, s[36:37]
	s_waitcnt vmcnt(8) lgkmcnt(0)
	s_barrier
	v_mfma_f32_16x16x32_bf16 v[62:65], v[172:175], v[204:207], 0
	v_mfma_f32_16x16x32_bf16 v[58:61], v[180:183], v[204:207], 0
	v_mfma_f32_16x16x32_bf16 v[46:49], v[172:175], v[212:215], 0
	v_mfma_f32_16x16x32_bf16 v[42:45], v[180:183], v[212:215], 0
	v_mfma_f32_16x16x32_bf16 v[30:33], v[172:175], v[220:223], 0
	v_mfma_f32_16x16x32_bf16 v[26:29], v[180:183], v[220:223], 0
	v_mfma_f32_16x16x32_bf16 v[14:17], v[172:175], v[228:231], 0
	v_mfma_f32_16x16x32_bf16 v[10:13], v[180:183], v[228:231], 0
	v_mfma_f32_16x16x32_bf16 v[62:65], v[176:179], v[208:211], v[62:65]
	v_mfma_f32_16x16x32_bf16 v[58:61], v[184:187], v[208:211], v[58:61]
	v_mfma_f32_16x16x32_bf16 v[46:49], v[176:179], v[216:219], v[46:49]
	v_mfma_f32_16x16x32_bf16 v[42:45], v[184:187], v[216:219], v[42:45]
	v_mfma_f32_16x16x32_bf16 v[30:33], v[176:179], v[224:227], v[30:33]
	v_mfma_f32_16x16x32_bf16 v[26:29], v[184:187], v[224:227], v[26:29]
	v_mfma_f32_16x16x32_bf16 v[14:17], v[176:179], v[232:235], v[14:17]
	v_mfma_f32_16x16x32_bf16 v[10:13], v[184:187], v[232:235], v[10:13]
	v_mfma_f32_16x16x32_bf16 v[54:57], v[188:191], v[204:207], 0
	v_mfma_f32_16x16x32_bf16 v[50:53], v[196:199], v[204:207], 0
	v_mfma_f32_16x16x32_bf16 v[38:41], v[188:191], v[212:215], 0
	v_mfma_f32_16x16x32_bf16 v[34:37], v[196:199], v[212:215], 0
	v_mfma_f32_16x16x32_bf16 v[22:25], v[188:191], v[220:223], 0
	v_mfma_f32_16x16x32_bf16 v[18:21], v[196:199], v[220:223], 0
	v_mfma_f32_16x16x32_bf16 v[6:9], v[188:191], v[228:231], 0
	v_mfma_f32_16x16x32_bf16 v[2:5], v[196:199], v[228:231], 0
	v_mfma_f32_16x16x32_bf16 v[54:57], v[192:195], v[208:211], v[54:57]
	v_mfma_f32_16x16x32_bf16 v[50:53], v[200:203], v[208:211], v[50:53]
	v_mfma_f32_16x16x32_bf16 v[38:41], v[192:195], v[216:219], v[38:41]
	v_mfma_f32_16x16x32_bf16 v[34:37], v[200:203], v[216:219], v[34:37]
	v_mfma_f32_16x16x32_bf16 v[22:25], v[192:195], v[224:227], v[22:25]
	v_mfma_f32_16x16x32_bf16 v[18:21], v[200:203], v[224:227], v[18:21]
	v_mfma_f32_16x16x32_bf16 v[6:9], v[192:195], v[232:235], v[6:9]
	v_mfma_f32_16x16x32_bf16 v[2:5], v[200:203], v[232:235], v[2:5]
	s_barrier
	s_add_i32 s61, 0, 0x18000
	v_add_u32_e32 v171, s61, v1
	s_add_i32 s62, 0, 0x1c000
	ds_read_b128 v[172:175], v171
	ds_read_b128 v[176:179], v171 offset:1024
	ds_read_b128 v[180:183], v171 offset:2048
	ds_read_b128 v[184:187], v171 offset:3072
	v_add_u32_e32 v171, s62, v1
	ds_read_b128 v[188:191], v171
	ds_read_b128 v[192:195], v171 offset:1024
	ds_read_b128 v[196:199], v171 offset:2048
	ds_read_b128 v[200:203], v171 offset:3072
	s_add_u32 s36, s36, 0x80000
	s_addc_u32 s37, s37, 0
	s_mov_b32 m0, s46
	ds_read_b128 v[204:207], v170 offset:32768
	ds_read_b128 v[208:211], v170 offset:33792
	ds_read_b128 v[212:215], v170 offset:34816
	ds_read_b128 v[216:219], v170 offset:35840
	ds_read_b128 v[220:223], v170 offset:36864
	ds_read_b128 v[224:227], v170 offset:37888
	ds_read_b128 v[228:231], v170 offset:38912
	ds_read_b128 v[232:235], v170 offset:39936
	global_load_lds_dwordx4 v136, s[36:37]
	s_mov_b32 m0, s47
	s_nop 0
	global_load_lds_dwordx4 v132, s[36:37]
	s_waitcnt vmcnt(8) lgkmcnt(0)
	s_barrier
	v_mfma_f32_16x16x32_bf16 v[126:129], v[172:175], v[204:207], v[126:129]
	v_mfma_f32_16x16x32_bf16 v[122:125], v[180:183], v[204:207], v[122:125]
	v_mfma_f32_16x16x32_bf16 v[110:113], v[172:175], v[212:215], v[110:113]
	v_mfma_f32_16x16x32_bf16 v[106:109], v[180:183], v[212:215], v[106:109]
	v_mfma_f32_16x16x32_bf16 v[94:97], v[172:175], v[220:223], v[94:97]
	v_mfma_f32_16x16x32_bf16 v[90:93], v[180:183], v[220:223], v[90:93]
	v_mfma_f32_16x16x32_bf16 v[78:81], v[172:175], v[228:231], v[78:81]
	v_mfma_f32_16x16x32_bf16 v[74:77], v[180:183], v[228:231], v[74:77]
	v_mfma_f32_16x16x32_bf16 v[126:129], v[176:179], v[208:211], v[126:129]
	v_mfma_f32_16x16x32_bf16 v[122:125], v[184:187], v[208:211], v[122:125]
	v_mfma_f32_16x16x32_bf16 v[110:113], v[176:179], v[216:219], v[110:113]
	v_mfma_f32_16x16x32_bf16 v[106:109], v[184:187], v[216:219], v[106:109]
	v_mfma_f32_16x16x32_bf16 v[94:97], v[176:179], v[224:227], v[94:97]
	v_mfma_f32_16x16x32_bf16 v[90:93], v[184:187], v[224:227], v[90:93]
	v_mfma_f32_16x16x32_bf16 v[78:81], v[176:179], v[232:235], v[78:81]
	v_mfma_f32_16x16x32_bf16 v[74:77], v[184:187], v[232:235], v[74:77]
	v_mfma_f32_16x16x32_bf16 v[118:121], v[188:191], v[204:207], v[118:121]
	v_mfma_f32_16x16x32_bf16 v[114:117], v[196:199], v[204:207], v[114:117]
	v_mfma_f32_16x16x32_bf16 v[102:105], v[188:191], v[212:215], v[102:105]
	v_mfma_f32_16x16x32_bf16 v[98:101], v[196:199], v[212:215], v[98:101]
	v_mfma_f32_16x16x32_bf16 v[86:89], v[188:191], v[220:223], v[86:89]
	v_mfma_f32_16x16x32_bf16 v[82:85], v[196:199], v[220:223], v[82:85]
	v_mfma_f32_16x16x32_bf16 v[70:73], v[188:191], v[228:231], v[70:73]
	v_mfma_f32_16x16x32_bf16 v[66:69], v[196:199], v[228:231], v[66:69]
	v_mfma_f32_16x16x32_bf16 v[118:121], v[192:195], v[208:211], v[118:121]
	v_mfma_f32_16x16x32_bf16 v[114:117], v[200:203], v[208:211], v[114:117]
	v_mfma_f32_16x16x32_bf16 v[102:105], v[192:195], v[216:219], v[102:105]
	v_mfma_f32_16x16x32_bf16 v[98:101], v[200:203], v[216:219], v[98:101]
	v_mfma_f32_16x16x32_bf16 v[86:89], v[192:195], v[224:227], v[86:89]
	v_mfma_f32_16x16x32_bf16 v[82:85], v[200:203], v[224:227], v[82:85]
	v_mfma_f32_16x16x32_bf16 v[70:73], v[192:195], v[232:235], v[70:73]
	v_mfma_f32_16x16x32_bf16 v[66:69], v[200:203], v[232:235], v[66:69]
	s_barrier
; #define PG8_STAGE(bufoff, gbase, voff) do { _Pragma("unroll") for (int _i = 0; _i < 2; ++_i) \
;         __builtin_amdgcn_global_load_lds((const unsigned*)((const char*)(gbase) + (voff)[_i]), (LAS unsigned*)(lds + (bufoff) + ldsw + _i * 8192), 16, 0, 0); } while (0)
; #define PG8_LDA(dst, b, h) do { _Pragma("unroll") for (int m = 0; m < 4; ++m) _Pragma("unroll") for (int k = 0; k < 2; ++k) dst[m][k] = *(const LAS bf16x8*)(lds + PG8_SA(b, h) + aoff + m * 2048 + k * 1024); } while (0)
; #define PG8_MMA(ai, bj, At, Bt) do { __builtin_amdgcn_s_setprio(1); _Pragma("unroll") for (int m = 0; m < 4; ++m) _Pragma("unroll") for (int n = 0; n < 2; ++n) _Pragma("unroll") for (int k = 0; k < 2; ++k) \
;         acc[ai][bj][m][n] = __builtin_amdgcn_mfma_f32_16x16x32_bf16(Bt[n][k], At[m][k], acc[ai][bj][m][n], 0, 0, 0); __builtin_amdgcn_s_setprio(0); } while (0)
; #define PG8_WAIT_V(n) asm volatile("s_waitcnt vmcnt(" #n ")" ::: "memory")
; #define PG8_WAIT_L(n) asm volatile("s_waitcnt lgkmcnt(" #n ")" ::: "memory")
; #define PG8_BAR __builtin_amdgcn_s_barrier()
; #define PG8_SCHED __builtin_amdgcn_sched_barrier(0)
; template <class Epi, class Sched, bool ABLK = false, bool ALIGN_EPI = true, bool SP2 = true, bool BBLK = true>
; __device__ __forceinline__ void gemm_phase(LAS unsigned char* lds, const Gemm g, const Sched& S, const Epi& E) {
;     ...
;             PG8_LDA(At, 1, 1); PG8_STAGE(PG8_SB(1, 0), b3, voffB); PG8_STAGE(PG8_SB(1, 1), b3 + hstepB, voffB); PG8_STAGE(PG8_SA(1, 0), a3, voffA);
;             PG8_WAIT_V(8); PG8_WAIT_L(0); PG8_BAR; PG8_MMA(1, 0, At, B0); PG8_MMA(1, 1, At, B1); PG8_BAR; PG8_SCHED;
	s_add_u32 s36, s34, 0x8000
	s_addc_u32 s37, s35, 0
	s_add_i32 s61, s61, s40
	s_mov_b32 m0, s61
	ds_read_b128 v[204:207], v170 offset:49152
	ds_read_b128 v[208:211], v170 offset:50176
	ds_read_b128 v[212:215], v170 offset:51200
	ds_read_b128 v[216:219], v170 offset:52224
	ds_read_b128 v[220:223], v170 offset:53248
	ds_read_b128 v[224:227], v170 offset:54272
	ds_read_b128 v[228:231], v170 offset:55296
	ds_read_b128 v[232:235], v170 offset:56320
	global_load_lds_dwordx4 v134, s[36:37]
	s_add_i32 m0, s61, 0x2000
	s_add_u32 s34, s34, 0xc000
	v_lshl_add_u64 v[236:237], s[36:37], 0, v[130:131]
	s_addc_u32 s35, s35, 0
	s_add_i32 s36, s62, s40
	global_load_lds_dwordx4 v[236:237], off
	s_mov_b32 m0, s36
	s_nop 0
	global_load_lds_dwordx4 v134, s[34:35]
	s_add_i32 m0, s36, 0x2000
	s_nop 0
	global_load_lds_dwordx4 v130, s[34:35]
	s_mov_b32 m0, s50
	s_nop 0
	global_load_lds_dwordx4 v136, s[30:31]
	s_mov_b32 m0, s51
	s_nop 0
	global_load_lds_dwordx4 v132, s[30:31]
	s_waitcnt vmcnt(8) lgkmcnt(0)
	s_barrier
	v_mfma_f32_16x16x32_bf16 v[62:65], v[172:175], v[204:207], v[62:65]
	v_mfma_f32_16x16x32_bf16 v[58:61], v[180:183], v[204:207], v[58:61]
	v_mfma_f32_16x16x32_bf16 v[46:49], v[172:175], v[212:215], v[46:49]
	v_mfma_f32_16x16x32_bf16 v[42:45], v[180:183], v[212:215], v[42:45]
	v_mfma_f32_16x16x32_bf16 v[30:33], v[172:175], v[220:223], v[30:33]
	v_mfma_f32_16x16x32_bf16 v[26:29], v[180:183], v[220:223], v[26:29]
	v_mfma_f32_16x16x32_bf16 v[14:17], v[172:175], v[228:231], v[14:17]
	v_mfma_f32_16x16x32_bf16 v[10:13], v[180:183], v[228:231], v[10:13]
	v_mfma_f32_16x16x32_bf16 v[62:65], v[176:179], v[208:211], v[62:65]
	v_mfma_f32_16x16x32_bf16 v[58:61], v[184:187], v[208:211], v[58:61]
	v_mfma_f32_16x16x32_bf16 v[46:49], v[176:179], v[216:219], v[46:49]
	v_mfma_f32_16x16x32_bf16 v[42:45], v[184:187], v[216:219], v[42:45]
	v_mfma_f32_16x16x32_bf16 v[30:33], v[176:179], v[224:227], v[30:33]
	v_mfma_f32_16x16x32_bf16 v[26:29], v[184:187], v[224:227], v[26:29]
	v_mfma_f32_16x16x32_bf16 v[14:17], v[176:179], v[232:235], v[14:17]
	v_mfma_f32_16x16x32_bf16 v[10:13], v[184:187], v[232:235], v[10:13]
	v_mfma_f32_16x16x32_bf16 v[54:57], v[188:191], v[204:207], v[54:57]
	v_mfma_f32_16x16x32_bf16 v[50:53], v[196:199], v[204:207], v[50:53]
	v_mfma_f32_16x16x32_bf16 v[38:41], v[188:191], v[212:215], v[38:41]
	v_mfma_f32_16x16x32_bf16 v[34:37], v[196:199], v[212:215], v[34:37]
	v_mfma_f32_16x16x32_bf16 v[22:25], v[188:191], v[220:223], v[22:25]
	v_mfma_f32_16x16x32_bf16 v[18:21], v[196:199], v[220:223], v[18:21]
	v_mfma_f32_16x16x32_bf16 v[6:9], v[188:191], v[228:231], v[6:9]
	v_mfma_f32_16x16x32_bf16 v[2:5], v[196:199], v[228:231], v[2:5]
	v_mfma_f32_16x16x32_bf16 v[54:57], v[192:195], v[208:211], v[54:57]
	v_mfma_f32_16x16x32_bf16 v[50:53], v[200:203], v[208:211], v[50:53]
	v_mfma_f32_16x16x32_bf16 v[38:41], v[192:195], v[216:219], v[38:41]
	v_mfma_f32_16x16x32_bf16 v[34:37], v[200:203], v[216:219], v[34:37]
	v_mfma_f32_16x16x32_bf16 v[22:25], v[192:195], v[224:227], v[22:25]
	v_mfma_f32_16x16x32_bf16 v[18:21], v[200:203], v[224:227], v[18:21]
	v_mfma_f32_16x16x32_bf16 v[6:9], v[192:195], v[232:235], v[6:9]
	v_mfma_f32_16x16x32_bf16 v[2:5], v[200:203], v[232:235], v[2:5]
	s_barrier
	s_add_i32 s60, s60, 2
	s_add_u32 s28, s28, 0x100
	s_addc_u32 s29, s29, 0
	s_add_u32 s58, s58, 0x10000
	s_addc_u32 s59, s59, 0
	s_cmp_gt_u32 s60, 29

; #define PG8_STAGE(bufoff, gbase, voff) do { _Pragma("unroll") for (int _i = 0; _i < 2; ++_i) \
;         __builtin_amdgcn_global_load_lds((const unsigned*)((const char*)(gbase) + (voff)[_i]), (LAS unsigned*)(lds + (bufoff) + ldsw + _i * 8192), 16, 0, 0); } while (0)
; #define PG8_LDA(dst, b, h) do { _Pragma("unroll") for (int m = 0; m < 4; ++m) _Pragma("unroll") for (int k = 0; k < 2; ++k) dst[m][k] = *(const LAS bf16x8*)(lds + PG8_SA(b, h) + aoff + m * 2048 + k * 1024); } while (0)
; #define PG8_LDB(dst, b, h) do { _Pragma("unroll") for (int n = 0; n < 2; ++n) _Pragma("unroll") for (int k = 0; k < 2; ++k) dst[n][k] = *(const LAS bf16x8*)(lds + PG8_SB(b, h) + boff + n * 2048 + k * 1024); } while (0)
; #define PG8_WAIT_V(n) asm volatile("s_waitcnt vmcnt(" #n ")" ::: "memory")
; #define PG8_WAIT_L(n) asm volatile("s_waitcnt lgkmcnt(" #n ")" ::: "memory")
; #define PG8_BAR __builtin_amdgcn_s_barrier()
; #define PG8_SCHED __builtin_amdgcn_sched_barrier(0)
; template <class Epi, class Sched, bool ABLK = false, bool ALIGN_EPI = true, bool SP2 = true, bool BBLK = true>
; __device__ __forceinline__ void gemm_phase(LAS unsigned char* lds, const Gemm g, const Sched& S, const Epi& E) {
;     ...
;         const bool has_next = S.next(ui + 1, nxt);
;         const int nt = cur.nt;
;         const char* nuA = has_next ? a_unit(nxt) : uA; const int ntbA = has_next ? nxt.k0 / BK : tbA; const char* nB = has_next ? (const char*)g.Bt + (size_t)nxt.pn * tstepB + b_k0(nxt.k0) : cB;
;         for (int t = 0; t < nt; t += 2) {
;             const bool last = (t == nt - 2);
;             const char* a1 = a_tile(uA, tbA + t + 1);
;             const char* a2 = last ? a_tile(nuA, ntbA) : a_tile(uA, tbA + t + 2); const char* b2 = last ? nB : cB + (size_t)(t + 2) * kstepB;
;             const char* a3 = last ? a_tile(nuA, ntbA + 1) : a_tile(uA, tbA + t + 3); const char* b3 = b2 + kstepB;
;             if (last && has_next) S.a_ready(nxt);
;             if constexpr (SP2) {
;             PG8_LDB(B0, 0, 0); PG8_LDB(B1, 0, 1); PG8_SCHED; PG8_LDA(At, 0, 0); PG8_STAGE(PG8_SA(1, 1), a1 + hstepA, voffA);
;             PG8_WAIT_V(8); PG8_WAIT_L(0); PG8_BAR; PG8_MMA(0, 0, At, B0); PG8_MMA(0, 1, At, B1); PG8_BAR; PG8_SCHED;
;             PG8_LDA(At, 0, 1); PG8_STAGE(PG8_SB(0, 0), b2, voffB); PG8_STAGE(PG8_SB(0, 1), b2 + hstepB, voffB); PG8_STAGE(PG8_SA(0, 0), a2, voffA);
.LBB0_539:
	s_ashr_i32 s81, s80, 31
	s_andn2_b64 vcc, exec, s[4:5]
	s_lshl_b64 s[30:31], s[80:81], 22
	s_add_u32 s30, s1, s30
	s_addc_u32 s31, s33, s31
	s_and_b64 s[34:35], s[4:5], exec
	s_cselect_b32 s47, s31, s43
	s_cselect_b32 s60, s30, s42
	s_ashr_i32 s34, s0, 31
	s_lshr_b32 s34, s34, 26
	s_add_i32 s34, s0, s34
	s_ashr_i32 s34, s34, 6
	s_and_b64 s[36:37], s[4:5], exec
	s_cselect_b32 s48, s34, s46
	s_ashr_i32 s79, s78, 31
	s_lshl_b64 s[36:37], s[78:79], 22
	s_add_u32 s49, s39, s36
	s_addc_u32 s61, s50, s37
	s_ashr_i32 s35, s34, 31
	s_lshl_b64 s[36:37], s[34:35], 15
	s_add_u32 s36, s49, s36
	s_addc_u32 s37, s61, s37
	v_cndmask_b32_e64 v2, 0, 1, s[4:5]
	s_and_b64 s[4:5], s[4:5], exec
	s_cselect_b32 s4, s37, s41
	s_cselect_b32 s5, s36, s40
	s_ashr_i32 s49, s48, 31
	s_lshl_b64 s[48:49], s[48:49], 15
	s_add_u32 s35, s60, s48
	s_addc_u32 s63, s47, s49
	s_add_u32 s64, s35, 0x8000
	s_addc_u32 s65, s63, 0
	s_add_u32 s66, s40, 0x10000
	s_addc_u32 s67, s41, 0
	s_ashr_i32 s47, s46, 31
	v_cmp_ne_u32_e64 s[8:9], 1, v2
	s_lshl_b64 s[40:41], s[46:47], 15
	v_lshl_add_u64 v[2:3], s[42:43], 0, v[138:139]
	s_add_u32 s75, s42, s40
	v_lshl_add_u64 v[142:143], v[2:3], 0, s[40:41]
	v_lshl_add_u64 v[2:3], s[42:43], 0, v[140:141]
	s_addc_u32 s76, s43, s41
	v_lshl_add_u64 v[144:145], v[2:3], 0, s[40:41]
	s_lshl_b32 s40, s59, 15
	s_add_i32 s40, s40, 0xfff00000
	v_mov_b32_e32 v2, 0
	s_add_u32 s77, s40, 0xf0000
	s_mov_b32 s79, 0
	s_mov_b64 s[40:41], 0
	ds_read_b128 v[152:155], v148
	ds_read_b128 v[156:159], v148 offset:1024
	ds_read_b128 v[160:163], v148 offset:2048
	ds_read_b128 v[164:167], v148 offset:3072
	ds_read_b128 v[168:171], v149
	ds_read_b128 v[172:175], v149 offset:1024
	ds_read_b128 v[176:179], v149 offset:2048
	ds_read_b128 v[180:183], v149 offset:3072
	s_add_u32 s42, s75, s40
	s_addc_u32 s43, s76, s41
	s_add_u32 s48, s42, 0x10000
	s_addc_u32 s49, s43, 0
	s_add_i32 s79, s79, 2
	s_add_u32 s46, s66, s40
	s_addc_u32 s47, s67, s41
	s_add_u32 s42, s42, 0x18000
	s_addc_u32 s43, s43, 0
	s_cmp_eq_u32 s77, s40
	s_cselect_b32 s43, s65, s43
	s_cselect_b32 s42, s64, s42
	s_cselect_b32 s47, s4, s47
	s_cselect_b32 s46, s5, s46
	s_cselect_b32 s49, s63, s49
	s_cselect_b32 s48, s35, s48
	v_lshl_add_u64 v[216:217], v[142:143], 0, s[40:41]
	s_add_i32 m0, s52, 0xc000
	ds_read_b128 v[184:187], v150
	ds_read_b128 v[188:191], v150 offset:1024
	ds_read_b128 v[192:195], v150 offset:2048
	ds_read_b128 v[196:199], v150 offset:3072
	ds_read_b128 v[200:203], v150 offset:4096
	ds_read_b128 v[204:207], v150 offset:5120
	ds_read_b128 v[208:211], v150 offset:6144
	ds_read_b128 v[212:215], v150 offset:7168
	global_load_lds_dwordx4 v[216:217], off
	v_lshl_add_u64 v[216:217], v[144:145], 0, s[40:41]
	s_add_i32 m0, s52, 0xe000
	s_nop 0
	global_load_lds_dwordx4 v[216:217], off
	s_waitcnt vmcnt(8) lgkmcnt(0)
	s_barrier
	v_mfma_f32_16x16x32_bf16 v[126:129], v[152:155], v[184:187], 0
	v_mfma_f32_16x16x32_bf16 v[122:125], v[160:163], v[184:187], 0
	v_mfma_f32_16x16x32_bf16 v[110:113], v[152:155], v[192:195], 0
	v_mfma_f32_16x16x32_bf16 v[106:109], v[160:163], v[192:195], 0
	v_mfma_f32_16x16x32_bf16 v[94:97], v[152:155], v[200:203], 0
	v_mfma_f32_16x16x32_bf16 v[90:93], v[160:163], v[200:203], 0
	v_mfma_f32_16x16x32_bf16 v[78:81], v[152:155], v[208:211], 0
	v_mfma_f32_16x16x32_bf16 v[74:77], v[160:163], v[208:211], 0
	v_mfma_f32_16x16x32_bf16 v[126:129], v[156:159], v[188:191], v[126:129]
	v_mfma_f32_16x16x32_bf16 v[122:125], v[164:167], v[188:191], v[122:125]
	v_mfma_f32_16x16x32_bf16 v[110:113], v[156:159], v[196:199], v[110:113]
	v_mfma_f32_16x16x32_bf16 v[106:109], v[164:167], v[196:199], v[106:109]
	v_mfma_f32_16x16x32_bf16 v[94:97], v[156:159], v[204:207], v[94:97]
	v_mfma_f32_16x16x32_bf16 v[90:93], v[164:167], v[204:207], v[90:93]
	v_mfma_f32_16x16x32_bf16 v[78:81], v[156:159], v[212:215], v[78:81]
	v_mfma_f32_16x16x32_bf16 v[74:77], v[164:167], v[212:215], v[74:77]
	v_mfma_f32_16x16x32_bf16 v[118:121], v[168:171], v[184:187], 0
	v_mfma_f32_16x16x32_bf16 v[114:117], v[176:179], v[184:187], 0
	v_mfma_f32_16x16x32_bf16 v[102:105], v[168:171], v[192:195], 0
	v_mfma_f32_16x16x32_bf16 v[98:101], v[176:179], v[192:195], 0
	v_mfma_f32_16x16x32_bf16 v[86:89], v[168:171], v[200:203], 0
	v_mfma_f32_16x16x32_bf16 v[82:85], v[176:179], v[200:203], 0
	v_mfma_f32_16x16x32_bf16 v[70:73], v[168:171], v[208:211], 0
	v_mfma_f32_16x16x32_bf16 v[66:69], v[176:179], v[208:211], 0
	v_mfma_f32_16x16x32_bf16 v[118:121], v[172:175], v[188:191], v[118:121]
	v_mfma_f32_16x16x32_bf16 v[114:117], v[180:183], v[188:191], v[114:117]
	v_mfma_f32_16x16x32_bf16 v[102:105], v[172:175], v[196:199], v[102:105]
	v_mfma_f32_16x16x32_bf16 v[98:101], v[180:183], v[196:199], v[98:101]
	v_mfma_f32_16x16x32_bf16 v[86:89], v[172:175], v[204:207], v[86:89]
	v_mfma_f32_16x16x32_bf16 v[82:85], v[180:183], v[204:207], v[82:85]
	v_mfma_f32_16x16x32_bf16 v[70:73], v[172:175], v[212:215], v[70:73]
	v_mfma_f32_16x16x32_bf16 v[66:69], v[180:183], v[212:215], v[66:69]
	s_barrier
	s_add_i32 s60, s72, s51
	s_mov_b32 m0, s60
	ds_read_b128 v[184:187], v150 offset:16384
	ds_read_b128 v[188:191], v150 offset:17408
	ds_read_b128 v[192:195], v150 offset:18432
	ds_read_b128 v[196:199], v150 offset:19456
	ds_read_b128 v[200:203], v150 offset:20480
	ds_read_b128 v[204:207], v150 offset:21504
	ds_read_b128 v[208:211], v150 offset:22528
	ds_read_b128 v[212:215], v150 offset:23552
	global_load_lds_dwordx4 v130, s[46:47]
	s_add_i32 m0, s60, 0x2000
	s_add_u32 s60, s46, 0x4000
	s_addc_u32 s61, s47, 0
	s_add_i32 s81, s73, s51
	global_load_lds_dwordx4 v132, s[46:47]
	s_mov_b32 m0, s81
	s_nop 0
	global_load_lds_dwordx4 v130, s[60:61]
	s_add_i32 m0, s81, 0x2000
	s_nop 0
	global_load_lds_dwordx4 v132, s[60:61]
	s_mov_b32 m0, s52
	s_nop 0
	global_load_lds_dwordx4 v130, s[48:49]
	s_mov_b32 m0, s53
	s_nop 0
	global_load_lds_dwordx4 v132, s[48:49]
	s_waitcnt vmcnt(8) lgkmcnt(0)
	s_barrier
; #define PG8_STAGE(bufoff, gbase, voff) do { _Pragma("unroll") for (int _i = 0; _i < 2; ++_i) \
;         __builtin_amdgcn_global_load_lds((const unsigned*)((const char*)(gbase) + (voff)[_i]), (LAS unsigned*)(lds + (bufoff) + ldsw + _i * 8192), 16, 0, 0); } while (0)
; #define PG8_LDA(dst, b, h) do { _Pragma("unroll") for (int m = 0; m < 4; ++m) _Pragma("unroll") for (int k = 0; k < 2; ++k) dst[m][k] = *(const LAS bf16x8*)(lds + PG8_SA(b, h) + aoff + m * 2048 + k * 1024); } while (0)
; #define PG8_LDB(dst, b, h) do { _Pragma("unroll") for (int n = 0; n < 2; ++n) _Pragma("unroll") for (int k = 0; k < 2; ++k) dst[n][k] = *(const LAS bf16x8*)(lds + PG8_SB(b, h) + boff + n * 2048 + k * 1024); } while (0)
; #define PG8_MMA(ai, bj, At, Bt) do { __builtin_amdgcn_s_setprio(1); _Pragma("unroll") for (int m = 0; m < 4; ++m) _Pragma("unroll") for (int n = 0; n < 2; ++n) _Pragma("unroll") for (int k = 0; k < 2; ++k) \
;         acc[ai][bj][m][n] = __builtin_amdgcn_mfma_f32_16x16x32_bf16(Bt[n][k], At[m][k], acc[ai][bj][m][n], 0, 0, 0); __builtin_amdgcn_s_setprio(0); } while (0)
; #define PG8_WAIT_V(n) asm volatile("s_waitcnt vmcnt(" #n ")" ::: "memory")
; #define PG8_WAIT_L(n) asm volatile("s_waitcnt lgkmcnt(" #n ")" ::: "memory")
; #define PG8_BAR __builtin_amdgcn_s_barrier()
; #define PG8_SCHED __builtin_amdgcn_sched_barrier(0)
; template <class Epi, class Sched, bool ABLK = false, bool ALIGN_EPI = true, bool SP2 = true, bool BBLK = true>
; __device__ __forceinline__ void gemm_phase(LAS unsigned char* lds, const Gemm g, const Sched& S, const Epi& E) {
;     ...
;             PG8_WAIT_V(8); PG8_WAIT_L(0); PG8_BAR; PG8_MMA(1, 0, At, B0); PG8_MMA(1, 1, At, B1); PG8_BAR; PG8_SCHED;
;             PG8_LDB(B0, 1, 0); PG8_LDB(B1, 1, 1); PG8_SCHED; PG8_LDA(At, 1, 0); PG8_STAGE(PG8_SA(0, 1), a2 + hstepA, voffA);
;             PG8_WAIT_V(8); PG8_WAIT_L(0); PG8_BAR; PG8_MMA(0, 0, At, B0); PG8_MMA(0, 1, At, B1); PG8_BAR; PG8_SCHED;
	v_mfma_f32_16x16x32_bf16 v[62:65], v[152:155], v[184:187], 0
	v_mfma_f32_16x16x32_bf16 v[58:61], v[160:163], v[184:187], 0
	v_mfma_f32_16x16x32_bf16 v[46:49], v[152:155], v[192:195], 0
	v_mfma_f32_16x16x32_bf16 v[42:45], v[160:163], v[192:195], 0
	v_mfma_f32_16x16x32_bf16 v[30:33], v[152:155], v[200:203], 0
	v_mfma_f32_16x16x32_bf16 v[26:29], v[160:163], v[200:203], 0
	v_mfma_f32_16x16x32_bf16 v[14:17], v[152:155], v[208:211], 0
	v_mfma_f32_16x16x32_bf16 v[10:13], v[160:163], v[208:211], 0
	v_mfma_f32_16x16x32_bf16 v[62:65], v[156:159], v[188:191], v[62:65]
	v_mfma_f32_16x16x32_bf16 v[58:61], v[164:167], v[188:191], v[58:61]
	v_mfma_f32_16x16x32_bf16 v[46:49], v[156:159], v[196:199], v[46:49]
	v_mfma_f32_16x16x32_bf16 v[42:45], v[164:167], v[196:199], v[42:45]
	v_mfma_f32_16x16x32_bf16 v[30:33], v[156:159], v[204:207], v[30:33]
	v_mfma_f32_16x16x32_bf16 v[26:29], v[164:167], v[204:207], v[26:29]
	v_mfma_f32_16x16x32_bf16 v[14:17], v[156:159], v[212:215], v[14:17]
	v_mfma_f32_16x16x32_bf16 v[10:13], v[164:167], v[212:215], v[10:13]
	v_mfma_f32_16x16x32_bf16 v[54:57], v[168:171], v[184:187], 0
	v_mfma_f32_16x16x32_bf16 v[50:53], v[176:179], v[184:187], 0
	v_mfma_f32_16x16x32_bf16 v[38:41], v[168:171], v[192:195], 0
	v_mfma_f32_16x16x32_bf16 v[34:37], v[176:179], v[192:195], 0
	v_mfma_f32_16x16x32_bf16 v[22:25], v[168:171], v[200:203], 0
	v_mfma_f32_16x16x32_bf16 v[18:21], v[176:179], v[200:203], 0
	v_mfma_f32_16x16x32_bf16 v[6:9], v[168:171], v[208:211], 0
	v_mfma_f32_16x16x32_bf16 v[2:5], v[176:179], v[208:211], 0
	v_mfma_f32_16x16x32_bf16 v[54:57], v[172:175], v[188:191], v[54:57]
	v_mfma_f32_16x16x32_bf16 v[50:53], v[180:183], v[188:191], v[50:53]
	v_mfma_f32_16x16x32_bf16 v[38:41], v[172:175], v[196:199], v[38:41]
	v_mfma_f32_16x16x32_bf16 v[34:37], v[180:183], v[196:199], v[34:37]
	v_mfma_f32_16x16x32_bf16 v[22:25], v[172:175], v[204:207], v[22:25]
	v_mfma_f32_16x16x32_bf16 v[18:21], v[180:183], v[204:207], v[18:21]
	v_mfma_f32_16x16x32_bf16 v[6:9], v[172:175], v[212:215], v[6:9]
	v_mfma_f32_16x16x32_bf16 v[2:5], v[180:183], v[212:215], v[2:5]
	s_barrier
	s_add_i32 s60, 0, 0x18000
	v_add_u32_e32 v151, s60, v146
	s_add_i32 s61, 0, 0x1c000
	ds_read_b128 v[152:155], v151
	ds_read_b128 v[156:159], v151 offset:1024
	ds_read_b128 v[160:163], v151 offset:2048
	ds_read_b128 v[164:167], v151 offset:3072
	v_add_u32_e32 v151, s61, v146
	ds_read_b128 v[168:171], v151
	ds_read_b128 v[172:175], v151 offset:1024
	ds_read_b128 v[176:179], v151 offset:2048
	ds_read_b128 v[180:183], v151 offset:3072
	s_add_u32 s48, s48, 0x4000
	s_addc_u32 s49, s49, 0
	s_mov_b32 m0, s54
	ds_read_b128 v[184:187], v150 offset:32768
	ds_read_b128 v[188:191], v150 offset:33792
	ds_read_b128 v[192:195], v150 offset:34816
	ds_read_b128 v[196:199], v150 offset:35840
	ds_read_b128 v[200:203], v150 offset:36864
	ds_read_b128 v[204:207], v150 offset:37888
	ds_read_b128 v[208:211], v150 offset:38912
	ds_read_b128 v[212:215], v150 offset:39936
	global_load_lds_dwordx4 v130, s[48:49]
	s_mov_b32 m0, s55
	s_nop 0
	global_load_lds_dwordx4 v132, s[48:49]
	s_waitcnt vmcnt(8) lgkmcnt(0)
	s_barrier
	v_mfma_f32_16x16x32_bf16 v[126:129], v[152:155], v[184:187], v[126:129]
	v_mfma_f32_16x16x32_bf16 v[122:125], v[160:163], v[184:187], v[122:125]
	v_mfma_f32_16x16x32_bf16 v[110:113], v[152:155], v[192:195], v[110:113]
	v_mfma_f32_16x16x32_bf16 v[106:109], v[160:163], v[192:195], v[106:109]
	v_mfma_f32_16x16x32_bf16 v[94:97], v[152:155], v[200:203], v[94:97]
	v_mfma_f32_16x16x32_bf16 v[90:93], v[160:163], v[200:203], v[90:93]
	v_mfma_f32_16x16x32_bf16 v[78:81], v[152:155], v[208:211], v[78:81]
	v_mfma_f32_16x16x32_bf16 v[74:77], v[160:163], v[208:211], v[74:77]
	v_mfma_f32_16x16x32_bf16 v[126:129], v[156:159], v[188:191], v[126:129]
	v_mfma_f32_16x16x32_bf16 v[122:125], v[164:167], v[188:191], v[122:125]
	v_mfma_f32_16x16x32_bf16 v[110:113], v[156:159], v[196:199], v[110:113]
	v_mfma_f32_16x16x32_bf16 v[106:109], v[164:167], v[196:199], v[106:109]
	v_mfma_f32_16x16x32_bf16 v[94:97], v[156:159], v[204:207], v[94:97]
	v_mfma_f32_16x16x32_bf16 v[90:93], v[164:167], v[204:207], v[90:93]
	v_mfma_f32_16x16x32_bf16 v[78:81], v[156:159], v[212:215], v[78:81]
	v_mfma_f32_16x16x32_bf16 v[74:77], v[164:167], v[212:215], v[74:77]
	v_mfma_f32_16x16x32_bf16 v[118:121], v[168:171], v[184:187], v[118:121]
	v_mfma_f32_16x16x32_bf16 v[114:117], v[176:179], v[184:187], v[114:117]
	v_mfma_f32_16x16x32_bf16 v[102:105], v[168:171], v[192:195], v[102:105]
	v_mfma_f32_16x16x32_bf16 v[98:101], v[176:179], v[192:195], v[98:101]
	v_mfma_f32_16x16x32_bf16 v[86:89], v[168:171], v[200:203], v[86:89]
	v_mfma_f32_16x16x32_bf16 v[82:85], v[176:179], v[200:203], v[82:85]
	v_mfma_f32_16x16x32_bf16 v[70:73], v[168:171], v[208:211], v[70:73]
	v_mfma_f32_16x16x32_bf16 v[66:69], v[176:179], v[208:211], v[66:69]
	v_mfma_f32_16x16x32_bf16 v[118:121], v[172:175], v[188:191], v[118:121]
	v_mfma_f32_16x16x32_bf16 v[114:117], v[180:183], v[188:191], v[114:117]
	v_mfma_f32_16x16x32_bf16 v[102:105], v[172:175], v[196:199], v[102:105]
	v_mfma_f32_16x16x32_bf16 v[98:101], v[180:183], v[196:199], v[98:101]
	v_mfma_f32_16x16x32_bf16 v[86:89], v[172:175], v[204:207], v[86:89]
	v_mfma_f32_16x16x32_bf16 v[82:85], v[180:183], v[204:207], v[82:85]
	v_mfma_f32_16x16x32_bf16 v[70:73], v[172:175], v[212:215], v[70:73]
	v_mfma_f32_16x16x32_bf16 v[66:69], v[180:183], v[212:215], v[66:69]
	s_barrier
; #define PG8_STAGE(bufoff, gbase, voff) do { _Pragma("unroll") for (int _i = 0; _i < 2; ++_i) \
;         __builtin_amdgcn_global_load_lds((const unsigned*)((const char*)(gbase) + (voff)[_i]), (LAS unsigned*)(lds + (bufoff) + ldsw + _i * 8192), 16, 0, 0); } while (0)
; #define PG8_LDA(dst, b, h) do { _Pragma("unroll") for (int m = 0; m < 4; ++m) _Pragma("unroll") for (int k = 0; k < 2; ++k) dst[m][k] = *(const LAS bf16x8*)(lds + PG8_SA(b, h) + aoff + m * 2048 + k * 1024); } while (0)
; #define PG8_MMA(ai, bj, At, Bt) do { __builtin_amdgcn_s_setprio(1); _Pragma("unroll") for (int m = 0; m < 4; ++m) _Pragma("unroll") for (int n = 0; n < 2; ++n) _Pragma("unroll") for (int k = 0; k < 2; ++k) \
;         acc[ai][bj][m][n] = __builtin_amdgcn_mfma_f32_16x16x32_bf16(Bt[n][k], At[m][k], acc[ai][bj][m][n], 0, 0, 0); __builtin_amdgcn_s_setprio(0); } while (0)
; #define PG8_WAIT_V(n) asm volatile("s_waitcnt vmcnt(" #n ")" ::: "memory")
; #define PG8_WAIT_L(n) asm volatile("s_waitcnt lgkmcnt(" #n ")" ::: "memory")
; #define PG8_BAR __builtin_amdgcn_s_barrier()
; #define PG8_SCHED __builtin_amdgcn_sched_barrier(0)
; template <class Epi, class Sched, bool ABLK = false, bool ALIGN_EPI = true, bool SP2 = true, bool BBLK = true>
; __device__ __forceinline__ void gemm_phase(LAS unsigned char* lds, const Gemm g, const Sched& S, const Epi& E) {
;     ...
;             PG8_LDA(At, 1, 1); PG8_STAGE(PG8_SB(1, 0), b3, voffB); PG8_STAGE(PG8_SB(1, 1), b3 + hstepB, voffB); PG8_STAGE(PG8_SA(1, 0), a3, voffA);
;             PG8_WAIT_V(8); PG8_WAIT_L(0); PG8_BAR; PG8_MMA(1, 0, At, B0); PG8_MMA(1, 1, At, B1); PG8_BAR; PG8_SCHED;
	s_add_u32 s48, s46, 0x8000
	s_addc_u32 s49, s47, 0
	s_add_i32 s81, s60, s51
	s_mov_b32 m0, s81
	ds_read_b128 v[184:187], v150 offset:49152
	ds_read_b128 v[188:191], v150 offset:50176
	ds_read_b128 v[192:195], v150 offset:51200
	ds_read_b128 v[196:199], v150 offset:52224
	ds_read_b128 v[200:203], v150 offset:53248
	ds_read_b128 v[204:207], v150 offset:54272
	ds_read_b128 v[208:211], v150 offset:55296
	ds_read_b128 v[212:215], v150 offset:56320
	global_load_lds_dwordx4 v130, s[48:49]
	s_add_i32 m0, s81, 0x2000
	s_add_u32 s46, s46, 0xc000
	v_lshl_add_u64 v[216:217], s[48:49], 0, v[132:133]
	s_addc_u32 s47, s47, 0
	s_add_i32 s48, s61, s51
	global_load_lds_dwordx4 v[216:217], off
	s_mov_b32 m0, s48
	s_nop 0
	global_load_lds_dwordx4 v130, s[46:47]
	s_add_i32 m0, s48, 0x2000
	s_nop 0
	global_load_lds_dwordx4 v132, s[46:47]
	s_mov_b32 m0, s56
	s_nop 0
	global_load_lds_dwordx4 v130, s[42:43]
	s_mov_b32 m0, s57
	s_nop 0
	global_load_lds_dwordx4 v132, s[42:43]
	s_waitcnt vmcnt(8) lgkmcnt(0)
	s_barrier
	v_mfma_f32_16x16x32_bf16 v[62:65], v[152:155], v[184:187], v[62:65]
	v_mfma_f32_16x16x32_bf16 v[58:61], v[160:163], v[184:187], v[58:61]
	v_mfma_f32_16x16x32_bf16 v[46:49], v[152:155], v[192:195], v[46:49]
	v_mfma_f32_16x16x32_bf16 v[42:45], v[160:163], v[192:195], v[42:45]
	v_mfma_f32_16x16x32_bf16 v[30:33], v[152:155], v[200:203], v[30:33]
	v_mfma_f32_16x16x32_bf16 v[26:29], v[160:163], v[200:203], v[26:29]
	v_mfma_f32_16x16x32_bf16 v[14:17], v[152:155], v[208:211], v[14:17]
	v_mfma_f32_16x16x32_bf16 v[10:13], v[160:163], v[208:211], v[10:13]
	v_mfma_f32_16x16x32_bf16 v[62:65], v[156:159], v[188:191], v[62:65]
	v_mfma_f32_16x16x32_bf16 v[58:61], v[164:167], v[188:191], v[58:61]
	v_mfma_f32_16x16x32_bf16 v[46:49], v[156:159], v[196:199], v[46:49]
	v_mfma_f32_16x16x32_bf16 v[42:45], v[164:167], v[196:199], v[42:45]
	v_mfma_f32_16x16x32_bf16 v[30:33], v[156:159], v[204:207], v[30:33]
	v_mfma_f32_16x16x32_bf16 v[26:29], v[164:167], v[204:207], v[26:29]
	v_mfma_f32_16x16x32_bf16 v[14:17], v[156:159], v[212:215], v[14:17]
	v_mfma_f32_16x16x32_bf16 v[10:13], v[164:167], v[212:215], v[10:13]
	v_mfma_f32_16x16x32_bf16 v[54:57], v[168:171], v[184:187], v[54:57]
	v_mfma_f32_16x16x32_bf16 v[50:53], v[176:179], v[184:187], v[50:53]
	v_mfma_f32_16x16x32_bf16 v[38:41], v[168:171], v[192:195], v[38:41]
	v_mfma_f32_16x16x32_bf16 v[34:37], v[176:179], v[192:195], v[34:37]
	v_mfma_f32_16x16x32_bf16 v[22:25], v[168:171], v[200:203], v[22:25]
	v_mfma_f32_16x16x32_bf16 v[18:21], v[176:179], v[200:203], v[18:21]
	v_mfma_f32_16x16x32_bf16 v[6:9], v[168:171], v[208:211], v[6:9]
	v_mfma_f32_16x16x32_bf16 v[2:5], v[176:179], v[208:211], v[2:5]
	v_mfma_f32_16x16x32_bf16 v[54:57], v[172:175], v[188:191], v[54:57]
	v_mfma_f32_16x16x32_bf16 v[50:53], v[180:183], v[188:191], v[50:53]
	v_mfma_f32_16x16x32_bf16 v[38:41], v[172:175], v[196:199], v[38:41]
	v_mfma_f32_16x16x32_bf16 v[34:37], v[180:183], v[196:199], v[34:37]
	v_mfma_f32_16x16x32_bf16 v[22:25], v[172:175], v[204:207], v[22:25]
	v_mfma_f32_16x16x32_bf16 v[18:21], v[180:183], v[204:207], v[18:21]
	v_mfma_f32_16x16x32_bf16 v[6:9], v[172:175], v[212:215], v[6:9]
	v_mfma_f32_16x16x32_bf16 v[2:5], v[180:183], v[212:215], v[2:5]
	s_barrier
	s_add_u32 s40, s40, 0x10000
	s_addc_u32 s41, s41, 0
	s_cmp_ge_u32 s79, s59

; #define PG8_STAGE(bufoff, gbase, voff) do { _Pragma("unroll") for (int _i = 0; _i < 2; ++_i) \
;         __builtin_amdgcn_global_load_lds((const unsigned*)((const char*)(gbase) + (voff)[_i]), (LAS unsigned*)(lds + (bufoff) + ldsw + _i * 8192), 16, 0, 0); } while (0)
; #define PG8_LDA(dst, b, h) do { _Pragma("unroll") for (int m = 0; m < 4; ++m) _Pragma("unroll") for (int k = 0; k < 2; ++k) dst[m][k] = *(const LAS bf16x8*)(lds + PG8_SA(b, h) + aoff + m * 2048 + k * 1024); } while (0)
; #define PG8_LDB(dst, b, h) do { _Pragma("unroll") for (int n = 0; n < 2; ++n) _Pragma("unroll") for (int k = 0; k < 2; ++k) dst[n][k] = *(const LAS bf16x8*)(lds + PG8_SB(b, h) + boff + n * 2048 + k * 1024); } while (0)
; #define PG8_WAIT_V(n) asm volatile("s_waitcnt vmcnt(" #n ")" ::: "memory")
; #define PG8_WAIT_L(n) asm volatile("s_waitcnt lgkmcnt(" #n ")" ::: "memory")
; #define PG8_BAR __builtin_amdgcn_s_barrier()
; #define PG8_SCHED __builtin_amdgcn_sched_barrier(0)
; template <class Epi, class Sched, bool ABLK = false, bool ALIGN_EPI = true, bool SP2 = true, bool BBLK = true>
; __device__ __forceinline__ void gemm_phase(LAS unsigned char* lds, const Gemm g, const Sched& S, const Epi& E) {
;     ...
;         const bool has_next = S.next(ui + 1, nxt);
;         const int nt = cur.nt;
;         const char* nuA = has_next ? a_unit(nxt) : uA; const int ntbA = has_next ? nxt.k0 / BK : tbA; const char* nB = has_next ? (const char*)g.Bt + (size_t)nxt.pn * tstepB + b_k0(nxt.k0) : cB;
;         for (int t = 0; t < nt; t += 2) {
;             const bool last = (t == nt - 2);
;             const char* a1 = a_tile(uA, tbA + t + 1);
;             const char* a2 = last ? a_tile(nuA, ntbA) : a_tile(uA, tbA + t + 2); const char* b2 = last ? nB : cB + (size_t)(t + 2) * kstepB;
;             const char* a3 = last ? a_tile(nuA, ntbA + 1) : a_tile(uA, tbA + t + 3); const char* b3 = b2 + kstepB;
;             if (last && has_next) S.a_ready(nxt);
;             if constexpr (SP2) {
;             PG8_LDB(B0, 0, 0); PG8_LDB(B1, 0, 1); PG8_SCHED; PG8_LDA(At, 0, 0); PG8_STAGE(PG8_SA(1, 1), a1 + hstepA, voffA);
;             PG8_WAIT_V(8); PG8_WAIT_L(0); PG8_BAR; PG8_MMA(0, 0, At, B0); PG8_MMA(0, 1, At, B1); PG8_BAR; PG8_SCHED;
;             PG8_LDA(At, 0, 1); PG8_STAGE(PG8_SB(0, 0), b2, voffB); PG8_STAGE(PG8_SB(0, 1), b2 + hstepB, voffB); PG8_STAGE(PG8_SA(0, 0), a2, voffA);
.LBB0_667:
	s_ashr_i32 s15, s14, 31
	s_lshl_b64 s[4:5], s[14:15], 20
	s_add_u32 s18, s59, s4
	s_addc_u32 s19, s62, s5
	s_and_b64 s[4:5], s[20:21], exec
	s_cselect_b32 s2, s19, s27
	s_cselect_b32 s4, s18, s26
	s_ashr_i32 s17, s16, 31
	s_lshl_b64 s[22:23], s[16:17], 20
	s_add_u32 s22, s39, s22
	s_addc_u32 s23, s40, s23
	s_and_b64 s[30:31], s[20:21], exec
	s_cselect_b32 s5, s23, s29
	s_cselect_b32 s9, s22, s28
	s_add_u32 s15, s4, 0x80
	s_addc_u32 s17, s2, 0
	s_add_u32 s52, s28, 0x10000
	v_mov_b32_e32 v2, 0
	s_addc_u32 s53, s29, 0
	v_lshl_add_u64 v[180:181], s[26:27], 0, v[176:177]
	v_lshl_add_u64 v[182:183], s[26:27], 0, v[178:179]
	s_mov_b32 s54, -2
	s_mov_b64 s[28:29], 0
	ds_read_b128 v[184:187], v153
	ds_read_b128 v[188:191], v153 offset:1024
	ds_read_b128 v[192:195], v153 offset:2048
	ds_read_b128 v[196:199], v153 offset:3072
	ds_read_b128 v[200:203], v157
	ds_read_b128 v[204:207], v157 offset:1024
	ds_read_b128 v[208:211], v157 offset:2048
	ds_read_b128 v[212:215], v157 offset:3072
	s_add_u32 s30, s26, s28
	s_addc_u32 s31, s27, s29
	s_add_u32 s36, s30, 0x100
	s_addc_u32 s37, s31, 0
	s_add_u32 s30, s30, 0x180
	s_addc_u32 s31, s31, 0
	s_cmpk_eq_i32 s28, 0xf00
	s_cselect_b32 s31, s17, s31
	s_cselect_b32 s30, s15, s30
	s_cselect_b32 s35, s5, s53
	s_cselect_b32 s34, s9, s52
	s_cselect_b32 s37, s2, s37
	s_cselect_b32 s36, s4, s36
	v_lshl_add_u64 v[248:249], v[180:181], 0, s[28:29]
	s_add_i32 m0, s25, 0xc000
	ds_read_b128 v[216:219], v149
	ds_read_b128 v[220:223], v149 offset:1024
	ds_read_b128 v[224:227], v149 offset:2048
	ds_read_b128 v[228:231], v149 offset:3072
	ds_read_b128 v[232:235], v149 offset:4096
	ds_read_b128 v[236:239], v149 offset:5120
	ds_read_b128 v[240:243], v149 offset:6144
	ds_read_b128 v[244:247], v149 offset:7168
	global_load_lds_dwordx4 v[248:249], off
	v_lshl_add_u64 v[248:249], v[182:183], 0, s[28:29]
	s_add_i32 m0, s25, 0xe000
	s_nop 0
	global_load_lds_dwordx4 v[248:249], off
	s_waitcnt vmcnt(8) lgkmcnt(0)
	s_barrier
	v_mfma_f32_16x16x32_bf16 v[126:129], v[184:187], v[216:219], 0
	v_mfma_f32_16x16x32_bf16 v[122:125], v[192:195], v[216:219], 0
	v_mfma_f32_16x16x32_bf16 v[110:113], v[184:187], v[224:227], 0
	v_mfma_f32_16x16x32_bf16 v[106:109], v[192:195], v[224:227], 0
	v_mfma_f32_16x16x32_bf16 v[94:97], v[184:187], v[232:235], 0
	v_mfma_f32_16x16x32_bf16 v[90:93], v[192:195], v[232:235], 0
	v_mfma_f32_16x16x32_bf16 v[78:81], v[184:187], v[240:243], 0
	v_mfma_f32_16x16x32_bf16 v[74:77], v[192:195], v[240:243], 0
	v_mfma_f32_16x16x32_bf16 v[126:129], v[188:191], v[220:223], v[126:129]
	v_mfma_f32_16x16x32_bf16 v[122:125], v[196:199], v[220:223], v[122:125]
	v_mfma_f32_16x16x32_bf16 v[110:113], v[188:191], v[228:231], v[110:113]
	v_mfma_f32_16x16x32_bf16 v[106:109], v[196:199], v[228:231], v[106:109]
	v_mfma_f32_16x16x32_bf16 v[94:97], v[188:191], v[236:239], v[94:97]
	v_mfma_f32_16x16x32_bf16 v[90:93], v[196:199], v[236:239], v[90:93]
	v_mfma_f32_16x16x32_bf16 v[78:81], v[188:191], v[244:247], v[78:81]
	v_mfma_f32_16x16x32_bf16 v[74:77], v[196:199], v[244:247], v[74:77]
	v_mfma_f32_16x16x32_bf16 v[118:121], v[200:203], v[216:219], 0
	v_mfma_f32_16x16x32_bf16 v[114:117], v[208:211], v[216:219], 0
	v_mfma_f32_16x16x32_bf16 v[102:105], v[200:203], v[224:227], 0
	v_mfma_f32_16x16x32_bf16 v[98:101], v[208:211], v[224:227], 0
	v_mfma_f32_16x16x32_bf16 v[86:89], v[200:203], v[232:235], 0
	v_mfma_f32_16x16x32_bf16 v[82:85], v[208:211], v[232:235], 0
	v_mfma_f32_16x16x32_bf16 v[70:73], v[200:203], v[240:243], 0
	v_mfma_f32_16x16x32_bf16 v[66:69], v[208:211], v[240:243], 0
	v_mfma_f32_16x16x32_bf16 v[118:121], v[204:207], v[220:223], v[118:121]
	v_mfma_f32_16x16x32_bf16 v[114:117], v[212:215], v[220:223], v[114:117]
	v_mfma_f32_16x16x32_bf16 v[102:105], v[204:207], v[228:231], v[102:105]
	v_mfma_f32_16x16x32_bf16 v[98:101], v[212:215], v[228:231], v[98:101]
	v_mfma_f32_16x16x32_bf16 v[86:89], v[204:207], v[236:239], v[86:89]
	v_mfma_f32_16x16x32_bf16 v[82:85], v[212:215], v[236:239], v[82:85]
	v_mfma_f32_16x16x32_bf16 v[70:73], v[204:207], v[244:247], v[70:73]
	v_mfma_f32_16x16x32_bf16 v[66:69], v[212:215], v[244:247], v[66:69]
	s_barrier
	s_add_i32 s55, s72, s41
	s_mov_b32 m0, s55
	ds_read_b128 v[216:219], v149 offset:16384
	ds_read_b128 v[220:223], v149 offset:17408
	ds_read_b128 v[224:227], v149 offset:18432
	ds_read_b128 v[228:231], v149 offset:19456
	ds_read_b128 v[232:235], v149 offset:20480
	ds_read_b128 v[236:239], v149 offset:21504
	ds_read_b128 v[240:243], v149 offset:22528
	ds_read_b128 v[244:247], v149 offset:23552
	global_load_lds_dwordx4 v132, s[34:35]
	s_add_i32 m0, s55, 0x2000
	s_add_u32 s56, s34, 0x4000
	s_addc_u32 s57, s35, 0
	s_add_i32 s55, s73, s41
	global_load_lds_dwordx4 v136, s[34:35]
	s_mov_b32 m0, s55
	s_nop 0
	global_load_lds_dwordx4 v132, s[56:57]
	s_add_i32 m0, s55, 0x2000
	s_nop 0
	global_load_lds_dwordx4 v136, s[56:57]
	s_mov_b32 m0, s25
	s_nop 0
	global_load_lds_dwordx4 v130, s[36:37]
	s_mov_b32 m0, s42
	s_nop 0
	global_load_lds_dwordx4 v134, s[36:37]
	s_waitcnt vmcnt(8) lgkmcnt(0)
	s_barrier
; #define PG8_STAGE(bufoff, gbase, voff) do { _Pragma("unroll") for (int _i = 0; _i < 2; ++_i) \
;         __builtin_amdgcn_global_load_lds((const unsigned*)((const char*)(gbase) + (voff)[_i]), (LAS unsigned*)(lds + (bufoff) + ldsw + _i * 8192), 16, 0, 0); } while (0)
; #define PG8_LDA(dst, b, h) do { _Pragma("unroll") for (int m = 0; m < 4; ++m) _Pragma("unroll") for (int k = 0; k < 2; ++k) dst[m][k] = *(const LAS bf16x8*)(lds + PG8_SA(b, h) + aoff + m * 2048 + k * 1024); } while (0)
; #define PG8_LDB(dst, b, h) do { _Pragma("unroll") for (int n = 0; n < 2; ++n) _Pragma("unroll") for (int k = 0; k < 2; ++k) dst[n][k] = *(const LAS bf16x8*)(lds + PG8_SB(b, h) + boff + n * 2048 + k * 1024); } while (0)
; #define PG8_MMA(ai, bj, At, Bt) do { __builtin_amdgcn_s_setprio(1); _Pragma("unroll") for (int m = 0; m < 4; ++m) _Pragma("unroll") for (int n = 0; n < 2; ++n) _Pragma("unroll") for (int k = 0; k < 2; ++k) \
;         acc[ai][bj][m][n] = __builtin_amdgcn_mfma_f32_16x16x32_bf16(Bt[n][k], At[m][k], acc[ai][bj][m][n], 0, 0, 0); __builtin_amdgcn_s_setprio(0); } while (0)
; #define PG8_WAIT_V(n) asm volatile("s_waitcnt vmcnt(" #n ")" ::: "memory")
; #define PG8_WAIT_L(n) asm volatile("s_waitcnt lgkmcnt(" #n ")" ::: "memory")
; #define PG8_BAR __builtin_amdgcn_s_barrier()
; #define PG8_SCHED __builtin_amdgcn_sched_barrier(0)
; template <class Epi, class Sched, bool ABLK = false, bool ALIGN_EPI = true, bool SP2 = true, bool BBLK = true>
; __device__ __forceinline__ void gemm_phase(LAS unsigned char* lds, const Gemm g, const Sched& S, const Epi& E) {
;     ...
;             PG8_WAIT_V(8); PG8_WAIT_L(0); PG8_BAR; PG8_MMA(1, 0, At, B0); PG8_MMA(1, 1, At, B1); PG8_BAR; PG8_SCHED;
;             PG8_LDB(B0, 1, 0); PG8_LDB(B1, 1, 1); PG8_SCHED; PG8_LDA(At, 1, 0); PG8_STAGE(PG8_SA(0, 1), a2 + hstepA, voffA);
;             PG8_WAIT_V(8); PG8_WAIT_L(0); PG8_BAR; PG8_MMA(0, 0, At, B0); PG8_MMA(0, 1, At, B1); PG8_BAR; PG8_SCHED;
	v_mfma_f32_16x16x32_bf16 v[62:65], v[184:187], v[216:219], 0
	v_mfma_f32_16x16x32_bf16 v[58:61], v[192:195], v[216:219], 0
	v_mfma_f32_16x16x32_bf16 v[46:49], v[184:187], v[224:227], 0
	v_mfma_f32_16x16x32_bf16 v[42:45], v[192:195], v[224:227], 0
	v_mfma_f32_16x16x32_bf16 v[30:33], v[184:187], v[232:235], 0
	v_mfma_f32_16x16x32_bf16 v[26:29], v[192:195], v[232:235], 0
	v_mfma_f32_16x16x32_bf16 v[14:17], v[184:187], v[240:243], 0
	v_mfma_f32_16x16x32_bf16 v[10:13], v[192:195], v[240:243], 0
	v_mfma_f32_16x16x32_bf16 v[62:65], v[188:191], v[220:223], v[62:65]
	v_mfma_f32_16x16x32_bf16 v[58:61], v[196:199], v[220:223], v[58:61]
	v_mfma_f32_16x16x32_bf16 v[46:49], v[188:191], v[228:231], v[46:49]
	v_mfma_f32_16x16x32_bf16 v[42:45], v[196:199], v[228:231], v[42:45]
	v_mfma_f32_16x16x32_bf16 v[30:33], v[188:191], v[236:239], v[30:33]
	v_mfma_f32_16x16x32_bf16 v[26:29], v[196:199], v[236:239], v[26:29]
	v_mfma_f32_16x16x32_bf16 v[14:17], v[188:191], v[244:247], v[14:17]
	v_mfma_f32_16x16x32_bf16 v[10:13], v[196:199], v[244:247], v[10:13]
	v_mfma_f32_16x16x32_bf16 v[54:57], v[200:203], v[216:219], 0
	v_mfma_f32_16x16x32_bf16 v[50:53], v[208:211], v[216:219], 0
	v_mfma_f32_16x16x32_bf16 v[38:41], v[200:203], v[224:227], 0
	v_mfma_f32_16x16x32_bf16 v[34:37], v[208:211], v[224:227], 0
	v_mfma_f32_16x16x32_bf16 v[22:25], v[200:203], v[232:235], 0
	v_mfma_f32_16x16x32_bf16 v[18:21], v[208:211], v[232:235], 0
	v_mfma_f32_16x16x32_bf16 v[6:9], v[200:203], v[240:243], 0
	v_mfma_f32_16x16x32_bf16 v[2:5], v[208:211], v[240:243], 0
	v_mfma_f32_16x16x32_bf16 v[54:57], v[204:207], v[220:223], v[54:57]
	v_mfma_f32_16x16x32_bf16 v[50:53], v[212:215], v[220:223], v[50:53]
	v_mfma_f32_16x16x32_bf16 v[38:41], v[204:207], v[228:231], v[38:41]
	v_mfma_f32_16x16x32_bf16 v[34:37], v[212:215], v[228:231], v[34:37]
	v_mfma_f32_16x16x32_bf16 v[22:25], v[204:207], v[236:239], v[22:25]
	v_mfma_f32_16x16x32_bf16 v[18:21], v[212:215], v[236:239], v[18:21]
	v_mfma_f32_16x16x32_bf16 v[6:9], v[204:207], v[244:247], v[6:9]
	v_mfma_f32_16x16x32_bf16 v[2:5], v[212:215], v[244:247], v[2:5]
	s_barrier
	v_add_u32_e32 v138, s60, v1
	ds_read_b128 v[184:187], v138
	ds_read_b128 v[188:191], v138 offset:1024
	ds_read_b128 v[192:195], v138 offset:2048
	ds_read_b128 v[196:199], v138 offset:3072
	v_add_u32_e32 v138, s61, v1
	ds_read_b128 v[200:203], v138
	ds_read_b128 v[204:207], v138 offset:1024
	ds_read_b128 v[208:211], v138 offset:2048
	ds_read_b128 v[212:215], v138 offset:3072
	s_add_u32 s36, s36, 0x80000
	s_addc_u32 s37, s37, 0
	s_mov_b32 m0, s43
	ds_read_b128 v[216:219], v149 offset:32768
	ds_read_b128 v[220:223], v149 offset:33792
	ds_read_b128 v[224:227], v149 offset:34816
	ds_read_b128 v[228:231], v149 offset:35840
	ds_read_b128 v[232:235], v149 offset:36864
	ds_read_b128 v[236:239], v149 offset:37888
	ds_read_b128 v[240:243], v149 offset:38912
	ds_read_b128 v[244:247], v149 offset:39936
	global_load_lds_dwordx4 v130, s[36:37]
	s_mov_b32 m0, s46
	s_nop 0
	global_load_lds_dwordx4 v134, s[36:37]
	s_waitcnt vmcnt(8) lgkmcnt(0)
	s_barrier
	v_mfma_f32_16x16x32_bf16 v[126:129], v[184:187], v[216:219], v[126:129]
	v_mfma_f32_16x16x32_bf16 v[122:125], v[192:195], v[216:219], v[122:125]
	v_mfma_f32_16x16x32_bf16 v[110:113], v[184:187], v[224:227], v[110:113]
	v_mfma_f32_16x16x32_bf16 v[106:109], v[192:195], v[224:227], v[106:109]
	v_mfma_f32_16x16x32_bf16 v[94:97], v[184:187], v[232:235], v[94:97]
	v_mfma_f32_16x16x32_bf16 v[90:93], v[192:195], v[232:235], v[90:93]
	v_mfma_f32_16x16x32_bf16 v[78:81], v[184:187], v[240:243], v[78:81]
	v_mfma_f32_16x16x32_bf16 v[74:77], v[192:195], v[240:243], v[74:77]
	v_mfma_f32_16x16x32_bf16 v[126:129], v[188:191], v[220:223], v[126:129]
	v_mfma_f32_16x16x32_bf16 v[122:125], v[196:199], v[220:223], v[122:125]
	v_mfma_f32_16x16x32_bf16 v[110:113], v[188:191], v[228:231], v[110:113]
	v_mfma_f32_16x16x32_bf16 v[106:109], v[196:199], v[228:231], v[106:109]
	v_mfma_f32_16x16x32_bf16 v[94:97], v[188:191], v[236:239], v[94:97]
	v_mfma_f32_16x16x32_bf16 v[90:93], v[196:199], v[236:239], v[90:93]
	v_mfma_f32_16x16x32_bf16 v[78:81], v[188:191], v[244:247], v[78:81]
	v_mfma_f32_16x16x32_bf16 v[74:77], v[196:199], v[244:247], v[74:77]
	v_mfma_f32_16x16x32_bf16 v[118:121], v[200:203], v[216:219], v[118:121]
	v_mfma_f32_16x16x32_bf16 v[114:117], v[208:211], v[216:219], v[114:117]
	v_mfma_f32_16x16x32_bf16 v[102:105], v[200:203], v[224:227], v[102:105]
	v_mfma_f32_16x16x32_bf16 v[98:101], v[208:211], v[224:227], v[98:101]
	v_mfma_f32_16x16x32_bf16 v[86:89], v[200:203], v[232:235], v[86:89]
	v_mfma_f32_16x16x32_bf16 v[82:85], v[208:211], v[232:235], v[82:85]
	v_mfma_f32_16x16x32_bf16 v[70:73], v[200:203], v[240:243], v[70:73]
	v_mfma_f32_16x16x32_bf16 v[66:69], v[208:211], v[240:243], v[66:69]
	v_mfma_f32_16x16x32_bf16 v[118:121], v[204:207], v[220:223], v[118:121]
	v_mfma_f32_16x16x32_bf16 v[114:117], v[212:215], v[220:223], v[114:117]
	v_mfma_f32_16x16x32_bf16 v[102:105], v[204:207], v[228:231], v[102:105]
	v_mfma_f32_16x16x32_bf16 v[98:101], v[212:215], v[228:231], v[98:101]
	v_mfma_f32_16x16x32_bf16 v[86:89], v[204:207], v[236:239], v[86:89]
	v_mfma_f32_16x16x32_bf16 v[82:85], v[212:215], v[236:239], v[82:85]
	v_mfma_f32_16x16x32_bf16 v[70:73], v[204:207], v[244:247], v[70:73]
	v_mfma_f32_16x16x32_bf16 v[66:69], v[212:215], v[244:247], v[66:69]
	s_barrier
; #define PG8_STAGE(bufoff, gbase, voff) do { _Pragma("unroll") for (int _i = 0; _i < 2; ++_i) \
;         __builtin_amdgcn_global_load_lds((const unsigned*)((const char*)(gbase) + (voff)[_i]), (LAS unsigned*)(lds + (bufoff) + ldsw + _i * 8192), 16, 0, 0); } while (0)
; #define PG8_LDA(dst, b, h) do { _Pragma("unroll") for (int m = 0; m < 4; ++m) _Pragma("unroll") for (int k = 0; k < 2; ++k) dst[m][k] = *(const LAS bf16x8*)(lds + PG8_SA(b, h) + aoff + m * 2048 + k * 1024); } while (0)
; #define PG8_MMA(ai, bj, At, Bt) do { __builtin_amdgcn_s_setprio(1); _Pragma("unroll") for (int m = 0; m < 4; ++m) _Pragma("unroll") for (int n = 0; n < 2; ++n) _Pragma("unroll") for (int k = 0; k < 2; ++k) \
;         acc[ai][bj][m][n] = __builtin_amdgcn_mfma_f32_16x16x32_bf16(Bt[n][k], At[m][k], acc[ai][bj][m][n], 0, 0, 0); __builtin_amdgcn_s_setprio(0); } while (0)
; #define PG8_WAIT_V(n) asm volatile("s_waitcnt vmcnt(" #n ")" ::: "memory")
; #define PG8_WAIT_L(n) asm volatile("s_waitcnt lgkmcnt(" #n ")" ::: "memory")
; #define PG8_BAR __builtin_amdgcn_s_barrier()
; #define PG8_SCHED __builtin_amdgcn_sched_barrier(0)
; template <class Epi, class Sched, bool ABLK = false, bool ALIGN_EPI = true, bool SP2 = true, bool BBLK = true>
; __device__ __forceinline__ void gemm_phase(LAS unsigned char* lds, const Gemm g, const Sched& S, const Epi& E) {
;     ...
;             PG8_LDA(At, 1, 1); PG8_STAGE(PG8_SB(1, 0), b3, voffB); PG8_STAGE(PG8_SB(1, 1), b3 + hstepB, voffB); PG8_STAGE(PG8_SA(1, 0), a3, voffA);
;             PG8_WAIT_V(8); PG8_WAIT_L(0); PG8_BAR; PG8_MMA(1, 0, At, B0); PG8_MMA(1, 1, At, B1); PG8_BAR; PG8_SCHED;
	s_add_u32 s36, s34, 0x8000
	s_addc_u32 s37, s35, 0
	s_add_i32 s55, s60, s41
	s_mov_b32 m0, s55
	ds_read_b128 v[216:219], v149 offset:49152
	ds_read_b128 v[220:223], v149 offset:50176
	ds_read_b128 v[224:227], v149 offset:51200
	ds_read_b128 v[228:231], v149 offset:52224
	ds_read_b128 v[232:235], v149 offset:53248
	ds_read_b128 v[236:239], v149 offset:54272
	ds_read_b128 v[240:243], v149 offset:55296
	ds_read_b128 v[244:247], v149 offset:56320
	global_load_lds_dwordx4 v132, s[36:37]
	s_add_i32 m0, s55, 0x2000
	s_add_u32 s34, s34, 0xc000
	v_lshl_add_u64 v[248:249], s[36:37], 0, v[136:137]
	s_addc_u32 s35, s35, 0
	s_add_i32 s36, s61, s41
	global_load_lds_dwordx4 v[248:249], off
	s_mov_b32 m0, s36
	s_nop 0
	global_load_lds_dwordx4 v132, s[34:35]
	s_add_i32 m0, s36, 0x2000
	s_nop 0
	global_load_lds_dwordx4 v136, s[34:35]
	s_mov_b32 m0, s47
	s_nop 0
	global_load_lds_dwordx4 v130, s[30:31]
	s_mov_b32 m0, s48
	s_nop 0
	global_load_lds_dwordx4 v134, s[30:31]
	s_waitcnt vmcnt(8) lgkmcnt(0)
	s_barrier
	v_mfma_f32_16x16x32_bf16 v[62:65], v[184:187], v[216:219], v[62:65]
	v_mfma_f32_16x16x32_bf16 v[58:61], v[192:195], v[216:219], v[58:61]
	v_mfma_f32_16x16x32_bf16 v[46:49], v[184:187], v[224:227], v[46:49]
	v_mfma_f32_16x16x32_bf16 v[42:45], v[192:195], v[224:227], v[42:45]
	v_mfma_f32_16x16x32_bf16 v[30:33], v[184:187], v[232:235], v[30:33]
	v_mfma_f32_16x16x32_bf16 v[26:29], v[192:195], v[232:235], v[26:29]
	v_mfma_f32_16x16x32_bf16 v[14:17], v[184:187], v[240:243], v[14:17]
	v_mfma_f32_16x16x32_bf16 v[10:13], v[192:195], v[240:243], v[10:13]
	v_mfma_f32_16x16x32_bf16 v[62:65], v[188:191], v[220:223], v[62:65]
	v_mfma_f32_16x16x32_bf16 v[58:61], v[196:199], v[220:223], v[58:61]
	v_mfma_f32_16x16x32_bf16 v[46:49], v[188:191], v[228:231], v[46:49]
	v_mfma_f32_16x16x32_bf16 v[42:45], v[196:199], v[228:231], v[42:45]
	v_mfma_f32_16x16x32_bf16 v[30:33], v[188:191], v[236:239], v[30:33]
	v_mfma_f32_16x16x32_bf16 v[26:29], v[196:199], v[236:239], v[26:29]
	v_mfma_f32_16x16x32_bf16 v[14:17], v[188:191], v[244:247], v[14:17]
	v_mfma_f32_16x16x32_bf16 v[10:13], v[196:199], v[244:247], v[10:13]
	v_mfma_f32_16x16x32_bf16 v[54:57], v[200:203], v[216:219], v[54:57]
	v_mfma_f32_16x16x32_bf16 v[50:53], v[208:211], v[216:219], v[50:53]
	v_mfma_f32_16x16x32_bf16 v[38:41], v[200:203], v[224:227], v[38:41]
	v_mfma_f32_16x16x32_bf16 v[34:37], v[208:211], v[224:227], v[34:37]
	v_mfma_f32_16x16x32_bf16 v[22:25], v[200:203], v[232:235], v[22:25]
	v_mfma_f32_16x16x32_bf16 v[18:21], v[208:211], v[232:235], v[18:21]
	v_mfma_f32_16x16x32_bf16 v[6:9], v[200:203], v[240:243], v[6:9]
	v_mfma_f32_16x16x32_bf16 v[2:5], v[208:211], v[240:243], v[2:5]
	v_mfma_f32_16x16x32_bf16 v[54:57], v[204:207], v[220:223], v[54:57]
	v_mfma_f32_16x16x32_bf16 v[50:53], v[212:215], v[220:223], v[50:53]
	v_mfma_f32_16x16x32_bf16 v[38:41], v[204:207], v[228:231], v[38:41]
	v_mfma_f32_16x16x32_bf16 v[34:37], v[212:215], v[228:231], v[34:37]
	v_mfma_f32_16x16x32_bf16 v[22:25], v[204:207], v[236:239], v[22:25]
	v_mfma_f32_16x16x32_bf16 v[18:21], v[212:215], v[236:239], v[18:21]
	v_mfma_f32_16x16x32_bf16 v[6:9], v[204:207], v[244:247], v[6:9]
	v_mfma_f32_16x16x32_bf16 v[2:5], v[212:215], v[244:247], v[2:5]
	s_barrier
	s_add_i32 s54, s54, 2
	s_add_u32 s28, s28, 0x100
	s_addc_u32 s29, s29, 0
	s_add_u32 s52, s52, 0x10000
	s_addc_u32 s53, s53, 0
	s_cmp_gt_u32 s54, 29

; #define PG8_STAGE(bufoff, gbase, voff) do { _Pragma("unroll") for (int _i = 0; _i < 2; ++_i) \
;         __builtin_amdgcn_global_load_lds((const unsigned*)((const char*)(gbase) + (voff)[_i]), (LAS unsigned*)(lds + (bufoff) + ldsw + _i * 8192), 16, 0, 0); } while (0)
; #define PG8_LDA(dst, b, h) do { _Pragma("unroll") for (int m = 0; m < 4; ++m) _Pragma("unroll") for (int k = 0; k < 2; ++k) dst[m][k] = *(const LAS bf16x8*)(lds + PG8_SA(b, h) + aoff + m * 2048 + k * 1024); } while (0)
; #define PG8_LDB(dst, b, h) do { _Pragma("unroll") for (int n = 0; n < 2; ++n) _Pragma("unroll") for (int k = 0; k < 2; ++k) dst[n][k] = *(const LAS bf16x8*)(lds + PG8_SB(b, h) + boff + n * 2048 + k * 1024); } while (0)
; #define PG8_WAIT_V(n) asm volatile("s_waitcnt vmcnt(" #n ")" ::: "memory")
; #define PG8_WAIT_L(n) asm volatile("s_waitcnt lgkmcnt(" #n ")" ::: "memory")
; #define PG8_BAR __builtin_amdgcn_s_barrier()
; #define PG8_SCHED __builtin_amdgcn_sched_barrier(0)
; template <class Epi, class Sched, bool ABLK = false, bool ALIGN_EPI = true, bool SP2 = true, bool BBLK = true>
; __device__ __forceinline__ void gemm_phase(LAS unsigned char* lds, const Gemm g, const Sched& S, const Epi& E) {
;     ...
;         const bool has_next = S.next(ui + 1, nxt);
;         const int nt = cur.nt;
;         const char* nuA = has_next ? a_unit(nxt) : uA; const int ntbA = has_next ? nxt.k0 / BK : tbA; const char* nB = has_next ? (const char*)g.Bt + (size_t)nxt.pn * tstepB + b_k0(nxt.k0) : cB;
;         for (int t = 0; t < nt; t += 2) {
;             const bool last = (t == nt - 2);
;             const char* a1 = a_tile(uA, tbA + t + 1);
;             const char* a2 = last ? a_tile(nuA, ntbA) : a_tile(uA, tbA + t + 2); const char* b2 = last ? nB : cB + (size_t)(t + 2) * kstepB;
;             const char* a3 = last ? a_tile(nuA, ntbA + 1) : a_tile(uA, tbA + t + 3); const char* b3 = b2 + kstepB;
;             if (last && has_next) S.a_ready(nxt);
;             if constexpr (SP2) {
;             PG8_LDB(B0, 0, 0); PG8_LDB(B1, 0, 1); PG8_SCHED; PG8_LDA(At, 0, 0); PG8_STAGE(PG8_SA(1, 1), a1 + hstepA, voffA);
;             PG8_WAIT_V(8); PG8_WAIT_L(0); PG8_BAR; PG8_MMA(0, 0, At, B0); PG8_MMA(0, 1, At, B1); PG8_BAR; PG8_SCHED;
;             PG8_LDA(At, 0, 1); PG8_STAGE(PG8_SB(0, 0), b2, voffB); PG8_STAGE(PG8_SB(0, 1), b2 + hstepB, voffB); PG8_STAGE(PG8_SA(0, 0), a2, voffA);
.LBB0_1037:
	s_ashr_i32 s81, s80, 31
	s_andn2_b64 vcc, exec, s[4:5]
	s_lshl_b64 s[14:15], s[80:81], 20
	s_add_u32 s14, s28, s14
	s_addc_u32 s15, s29, s15
	s_and_b64 s[16:17], s[4:5], exec
	s_cselect_b32 s25, s15, s23
	s_cselect_b32 s48, s14, s22
	s_ashr_i32 s16, s63, 31
	s_lshr_b32 s16, s16, 26
	s_add_i32 s16, s63, s16
	s_ashr_i32 s16, s16, 6
	s_and_b64 s[18:19], s[4:5], exec
	s_cselect_b32 s26, s16, s24
	s_ashr_i32 s79, s78, 31
	s_lshl_b64 s[18:19], s[78:79], 20
	s_add_u32 s27, s30, s18
	s_addc_u32 s49, s31, s19
	s_ashr_i32 s17, s16, 31
	s_lshl_b64 s[18:19], s[16:17], 15
	s_add_u32 s18, s27, s18
	s_addc_u32 s19, s49, s19
	v_cndmask_b32_e64 v2, 0, 1, s[4:5]
	s_and_b64 s[4:5], s[4:5], exec
	s_cselect_b32 s4, s19, s21
	s_cselect_b32 s5, s18, s20
	s_ashr_i32 s27, s26, 31
	s_lshl_b64 s[26:27], s[26:27], 7
	s_add_u32 s17, s48, s26
	s_addc_u32 s48, s25, s27
	s_add_u32 s49, s17, 0x80
	s_addc_u32 s50, s48, 0
	s_add_u32 s51, s20, 0x10000
	s_addc_u32 s55, s21, 0
	s_ashr_i32 s25, s24, 31
	v_cmp_ne_u32_e64 s[8:9], 1, v2
	s_lshl_b64 s[20:21], s[24:25], 7
	v_lshl_add_u64 v[2:3], s[22:23], 0, v[142:143]
	s_add_u32 s56, s22, s20
	v_lshl_add_u64 v[146:147], v[2:3], 0, s[20:21]
	v_lshl_add_u64 v[2:3], s[22:23], 0, v[144:145]
	s_addc_u32 s57, s23, s21
	v_lshl_add_u64 v[148:149], v[2:3], 0, s[20:21]
	s_lshl_b32 s20, s46, 7
	s_addk_i32 s20, 0xfc00
	v_mov_b32_e32 v2, 0
	s_add_u32 s64, s20, 0x300
	s_mov_b32 s65, 0
	s_mov_b64 s[20:21], 0
	ds_read_b128 v[156:159], v153
	ds_read_b128 v[160:163], v153 offset:1024
	ds_read_b128 v[164:167], v153 offset:2048
	ds_read_b128 v[168:171], v153 offset:3072
	ds_read_b128 v[172:175], v154
	ds_read_b128 v[176:179], v154 offset:1024
	ds_read_b128 v[180:183], v154 offset:2048
	ds_read_b128 v[184:187], v154 offset:3072
	s_add_u32 s22, s56, s20
	s_addc_u32 s23, s57, s21
	s_add_u32 s26, s22, 0x100
	s_addc_u32 s27, s23, 0
	s_add_i32 s65, s65, 2
	s_add_u32 s22, s22, 0x180
	s_addc_u32 s23, s23, 0
	s_cmp_eq_u32 s64, s20
	s_cselect_b32 s23, s50, s23
	s_cselect_b32 s22, s49, s22
	s_cselect_b32 s25, s4, s55
	s_cselect_b32 s24, s5, s51
	s_cselect_b32 s27, s48, s27
	s_cselect_b32 s26, s17, s26
	v_lshl_add_u64 v[220:221], v[146:147], 0, s[20:21]
	s_add_i32 m0, s35, 0xc000
	ds_read_b128 v[188:191], v155
	ds_read_b128 v[192:195], v155 offset:1024
	ds_read_b128 v[196:199], v155 offset:2048
	ds_read_b128 v[200:203], v155 offset:3072
	ds_read_b128 v[204:207], v155 offset:4096
	ds_read_b128 v[208:211], v155 offset:5120
	ds_read_b128 v[212:215], v155 offset:6144
	ds_read_b128 v[216:219], v155 offset:7168
	global_load_lds_dwordx4 v[220:221], off
	v_lshl_add_u64 v[220:221], v[148:149], 0, s[20:21]
	s_add_i32 m0, s35, 0xe000
	s_nop 0
	global_load_lds_dwordx4 v[220:221], off
	s_waitcnt vmcnt(8) lgkmcnt(0)
	s_barrier
	v_mfma_f32_16x16x32_bf16 v[126:129], v[156:159], v[188:191], 0
	v_mfma_f32_16x16x32_bf16 v[122:125], v[164:167], v[188:191], 0
	v_mfma_f32_16x16x32_bf16 v[110:113], v[156:159], v[196:199], 0
	v_mfma_f32_16x16x32_bf16 v[106:109], v[164:167], v[196:199], 0
	v_mfma_f32_16x16x32_bf16 v[94:97], v[156:159], v[204:207], 0
	v_mfma_f32_16x16x32_bf16 v[90:93], v[164:167], v[204:207], 0
	v_mfma_f32_16x16x32_bf16 v[78:81], v[156:159], v[212:215], 0
	v_mfma_f32_16x16x32_bf16 v[74:77], v[164:167], v[212:215], 0
	v_mfma_f32_16x16x32_bf16 v[126:129], v[160:163], v[192:195], v[126:129]
	v_mfma_f32_16x16x32_bf16 v[122:125], v[168:171], v[192:195], v[122:125]
	v_mfma_f32_16x16x32_bf16 v[110:113], v[160:163], v[200:203], v[110:113]
	v_mfma_f32_16x16x32_bf16 v[106:109], v[168:171], v[200:203], v[106:109]
	v_mfma_f32_16x16x32_bf16 v[94:97], v[160:163], v[208:211], v[94:97]
	v_mfma_f32_16x16x32_bf16 v[90:93], v[168:171], v[208:211], v[90:93]
	v_mfma_f32_16x16x32_bf16 v[78:81], v[160:163], v[216:219], v[78:81]
	v_mfma_f32_16x16x32_bf16 v[74:77], v[168:171], v[216:219], v[74:77]
	v_mfma_f32_16x16x32_bf16 v[118:121], v[172:175], v[188:191], 0
	v_mfma_f32_16x16x32_bf16 v[114:117], v[180:183], v[188:191], 0
	v_mfma_f32_16x16x32_bf16 v[102:105], v[172:175], v[196:199], 0
	v_mfma_f32_16x16x32_bf16 v[98:101], v[180:183], v[196:199], 0
	v_mfma_f32_16x16x32_bf16 v[86:89], v[172:175], v[204:207], 0
	v_mfma_f32_16x16x32_bf16 v[82:85], v[180:183], v[204:207], 0
	v_mfma_f32_16x16x32_bf16 v[70:73], v[172:175], v[212:215], 0
	v_mfma_f32_16x16x32_bf16 v[66:69], v[180:183], v[212:215], 0
	v_mfma_f32_16x16x32_bf16 v[118:121], v[176:179], v[192:195], v[118:121]
	v_mfma_f32_16x16x32_bf16 v[114:117], v[184:187], v[192:195], v[114:117]
	v_mfma_f32_16x16x32_bf16 v[102:105], v[176:179], v[200:203], v[102:105]
	v_mfma_f32_16x16x32_bf16 v[98:101], v[184:187], v[200:203], v[98:101]
	v_mfma_f32_16x16x32_bf16 v[86:89], v[176:179], v[208:211], v[86:89]
	v_mfma_f32_16x16x32_bf16 v[82:85], v[184:187], v[208:211], v[82:85]
	v_mfma_f32_16x16x32_bf16 v[70:73], v[176:179], v[216:219], v[70:73]
	v_mfma_f32_16x16x32_bf16 v[66:69], v[184:187], v[216:219], v[66:69]
	s_barrier
	s_add_i32 s66, s72, s34
	s_mov_b32 m0, s66
	ds_read_b128 v[188:191], v155 offset:16384
	ds_read_b128 v[192:195], v155 offset:17408
	ds_read_b128 v[196:199], v155 offset:18432
	ds_read_b128 v[200:203], v155 offset:19456
	ds_read_b128 v[204:207], v155 offset:20480
	ds_read_b128 v[208:211], v155 offset:21504
	ds_read_b128 v[212:215], v155 offset:22528
	ds_read_b128 v[216:219], v155 offset:23552
	global_load_lds_dwordx4 v132, s[24:25]
	s_add_i32 m0, s66, 0x2000
	s_add_u32 s66, s24, 0x4000
	s_addc_u32 s67, s25, 0
	s_add_i32 s75, s73, s34
	global_load_lds_dwordx4 v136, s[24:25]
	s_mov_b32 m0, s75
	s_nop 0
	global_load_lds_dwordx4 v132, s[66:67]
	s_add_i32 m0, s75, 0x2000
	s_nop 0
	global_load_lds_dwordx4 v136, s[66:67]
	s_mov_b32 m0, s35
	s_nop 0
	global_load_lds_dwordx4 v130, s[26:27]
	s_mov_b32 m0, s36
	s_nop 0
	global_load_lds_dwordx4 v134, s[26:27]
	s_waitcnt vmcnt(8) lgkmcnt(0)
	s_barrier
; #define PG8_STAGE(bufoff, gbase, voff) do { _Pragma("unroll") for (int _i = 0; _i < 2; ++_i) \
;         __builtin_amdgcn_global_load_lds((const unsigned*)((const char*)(gbase) + (voff)[_i]), (LAS unsigned*)(lds + (bufoff) + ldsw + _i * 8192), 16, 0, 0); } while (0)
; #define PG8_LDA(dst, b, h) do { _Pragma("unroll") for (int m = 0; m < 4; ++m) _Pragma("unroll") for (int k = 0; k < 2; ++k) dst[m][k] = *(const LAS bf16x8*)(lds + PG8_SA(b, h) + aoff + m * 2048 + k * 1024); } while (0)
; #define PG8_LDB(dst, b, h) do { _Pragma("unroll") for (int n = 0; n < 2; ++n) _Pragma("unroll") for (int k = 0; k < 2; ++k) dst[n][k] = *(const LAS bf16x8*)(lds + PG8_SB(b, h) + boff + n * 2048 + k * 1024); } while (0)
; #define PG8_MMA(ai, bj, At, Bt) do { __builtin_amdgcn_s_setprio(1); _Pragma("unroll") for (int m = 0; m < 4; ++m) _Pragma("unroll") for (int n = 0; n < 2; ++n) _Pragma("unroll") for (int k = 0; k < 2; ++k) \
;         acc[ai][bj][m][n] = __builtin_amdgcn_mfma_f32_16x16x32_bf16(Bt[n][k], At[m][k], acc[ai][bj][m][n], 0, 0, 0); __builtin_amdgcn_s_setprio(0); } while (0)
; #define PG8_WAIT_V(n) asm volatile("s_waitcnt vmcnt(" #n ")" ::: "memory")
; #define PG8_WAIT_L(n) asm volatile("s_waitcnt lgkmcnt(" #n ")" ::: "memory")
; #define PG8_BAR __builtin_amdgcn_s_barrier()
; #define PG8_SCHED __builtin_amdgcn_sched_barrier(0)
; template <class Epi, class Sched, bool ABLK = false, bool ALIGN_EPI = true, bool SP2 = true, bool BBLK = true>
; __device__ __forceinline__ void gemm_phase(LAS unsigned char* lds, const Gemm g, const Sched& S, const Epi& E) {
;     ...
;             PG8_WAIT_V(8); PG8_WAIT_L(0); PG8_BAR; PG8_MMA(1, 0, At, B0); PG8_MMA(1, 1, At, B1); PG8_BAR; PG8_SCHED;
;             PG8_LDB(B0, 1, 0); PG8_LDB(B1, 1, 1); PG8_SCHED; PG8_LDA(At, 1, 0); PG8_STAGE(PG8_SA(0, 1), a2 + hstepA, voffA);
;             PG8_WAIT_V(8); PG8_WAIT_L(0); PG8_BAR; PG8_MMA(0, 0, At, B0); PG8_MMA(0, 1, At, B1); PG8_BAR; PG8_SCHED;
	v_mfma_f32_16x16x32_bf16 v[62:65], v[156:159], v[188:191], 0
	v_mfma_f32_16x16x32_bf16 v[58:61], v[164:167], v[188:191], 0
	v_mfma_f32_16x16x32_bf16 v[46:49], v[156:159], v[196:199], 0
	v_mfma_f32_16x16x32_bf16 v[42:45], v[164:167], v[196:199], 0
	v_mfma_f32_16x16x32_bf16 v[30:33], v[156:159], v[204:207], 0
	v_mfma_f32_16x16x32_bf16 v[26:29], v[164:167], v[204:207], 0
	v_mfma_f32_16x16x32_bf16 v[14:17], v[156:159], v[212:215], 0
	v_mfma_f32_16x16x32_bf16 v[10:13], v[164:167], v[212:215], 0
	v_mfma_f32_16x16x32_bf16 v[62:65], v[160:163], v[192:195], v[62:65]
	v_mfma_f32_16x16x32_bf16 v[58:61], v[168:171], v[192:195], v[58:61]
	v_mfma_f32_16x16x32_bf16 v[46:49], v[160:163], v[200:203], v[46:49]
	v_mfma_f32_16x16x32_bf16 v[42:45], v[168:171], v[200:203], v[42:45]
	v_mfma_f32_16x16x32_bf16 v[30:33], v[160:163], v[208:211], v[30:33]
	v_mfma_f32_16x16x32_bf16 v[26:29], v[168:171], v[208:211], v[26:29]
	v_mfma_f32_16x16x32_bf16 v[14:17], v[160:163], v[216:219], v[14:17]
	v_mfma_f32_16x16x32_bf16 v[10:13], v[168:171], v[216:219], v[10:13]
	v_mfma_f32_16x16x32_bf16 v[54:57], v[172:175], v[188:191], 0
	v_mfma_f32_16x16x32_bf16 v[50:53], v[180:183], v[188:191], 0
	v_mfma_f32_16x16x32_bf16 v[38:41], v[172:175], v[196:199], 0
	v_mfma_f32_16x16x32_bf16 v[34:37], v[180:183], v[196:199], 0
	v_mfma_f32_16x16x32_bf16 v[22:25], v[172:175], v[204:207], 0
	v_mfma_f32_16x16x32_bf16 v[18:21], v[180:183], v[204:207], 0
	v_mfma_f32_16x16x32_bf16 v[6:9], v[172:175], v[212:215], 0
	v_mfma_f32_16x16x32_bf16 v[2:5], v[180:183], v[212:215], 0
	v_mfma_f32_16x16x32_bf16 v[54:57], v[176:179], v[192:195], v[54:57]
	v_mfma_f32_16x16x32_bf16 v[50:53], v[184:187], v[192:195], v[50:53]
	v_mfma_f32_16x16x32_bf16 v[38:41], v[176:179], v[200:203], v[38:41]
	v_mfma_f32_16x16x32_bf16 v[34:37], v[184:187], v[200:203], v[34:37]
	v_mfma_f32_16x16x32_bf16 v[22:25], v[176:179], v[208:211], v[22:25]
	v_mfma_f32_16x16x32_bf16 v[18:21], v[184:187], v[208:211], v[18:21]
	v_mfma_f32_16x16x32_bf16 v[6:9], v[176:179], v[216:219], v[6:9]
	v_mfma_f32_16x16x32_bf16 v[2:5], v[184:187], v[216:219], v[2:5]
	s_barrier
	v_add_u32_e32 v168, s60, v151
	v_add_u32_e32 v184, s61, v151
	ds_read_b128 v[156:159], v168
	ds_read_b128 v[160:163], v168 offset:1024
	ds_read_b128 v[164:167], v168 offset:2048
	ds_read_b128 v[168:171], v168 offset:3072
	ds_read_b128 v[172:175], v184
	ds_read_b128 v[176:179], v184 offset:1024
	ds_read_b128 v[180:183], v184 offset:2048
	ds_read_b128 v[184:187], v184 offset:3072
	s_add_u32 s26, s26, 0x80000
	s_addc_u32 s27, s27, 0
	s_mov_b32 m0, s37
	ds_read_b128 v[188:191], v155 offset:32768
	ds_read_b128 v[192:195], v155 offset:33792
	ds_read_b128 v[196:199], v155 offset:34816
	ds_read_b128 v[200:203], v155 offset:35840
	ds_read_b128 v[204:207], v155 offset:36864
	ds_read_b128 v[208:211], v155 offset:37888
	ds_read_b128 v[212:215], v155 offset:38912
	ds_read_b128 v[216:219], v155 offset:39936
	global_load_lds_dwordx4 v130, s[26:27]
	s_mov_b32 m0, s40
	s_nop 0
	global_load_lds_dwordx4 v134, s[26:27]
	s_waitcnt vmcnt(8) lgkmcnt(0)
	s_barrier
	v_mfma_f32_16x16x32_bf16 v[126:129], v[156:159], v[188:191], v[126:129]
	v_mfma_f32_16x16x32_bf16 v[122:125], v[164:167], v[188:191], v[122:125]
	v_mfma_f32_16x16x32_bf16 v[110:113], v[156:159], v[196:199], v[110:113]
	v_mfma_f32_16x16x32_bf16 v[106:109], v[164:167], v[196:199], v[106:109]
	v_mfma_f32_16x16x32_bf16 v[94:97], v[156:159], v[204:207], v[94:97]
	v_mfma_f32_16x16x32_bf16 v[90:93], v[164:167], v[204:207], v[90:93]
	v_mfma_f32_16x16x32_bf16 v[78:81], v[156:159], v[212:215], v[78:81]
	v_mfma_f32_16x16x32_bf16 v[74:77], v[164:167], v[212:215], v[74:77]
	v_mfma_f32_16x16x32_bf16 v[126:129], v[160:163], v[192:195], v[126:129]
	v_mfma_f32_16x16x32_bf16 v[122:125], v[168:171], v[192:195], v[122:125]
	v_mfma_f32_16x16x32_bf16 v[110:113], v[160:163], v[200:203], v[110:113]
	v_mfma_f32_16x16x32_bf16 v[106:109], v[168:171], v[200:203], v[106:109]
	v_mfma_f32_16x16x32_bf16 v[94:97], v[160:163], v[208:211], v[94:97]
	v_mfma_f32_16x16x32_bf16 v[90:93], v[168:171], v[208:211], v[90:93]
	v_mfma_f32_16x16x32_bf16 v[78:81], v[160:163], v[216:219], v[78:81]
	v_mfma_f32_16x16x32_bf16 v[74:77], v[168:171], v[216:219], v[74:77]
	v_mfma_f32_16x16x32_bf16 v[118:121], v[172:175], v[188:191], v[118:121]
	v_mfma_f32_16x16x32_bf16 v[114:117], v[180:183], v[188:191], v[114:117]
	v_mfma_f32_16x16x32_bf16 v[102:105], v[172:175], v[196:199], v[102:105]
	v_mfma_f32_16x16x32_bf16 v[98:101], v[180:183], v[196:199], v[98:101]
	v_mfma_f32_16x16x32_bf16 v[86:89], v[172:175], v[204:207], v[86:89]
	v_mfma_f32_16x16x32_bf16 v[82:85], v[180:183], v[204:207], v[82:85]
	v_mfma_f32_16x16x32_bf16 v[70:73], v[172:175], v[212:215], v[70:73]
	v_mfma_f32_16x16x32_bf16 v[66:69], v[180:183], v[212:215], v[66:69]
	v_mfma_f32_16x16x32_bf16 v[118:121], v[176:179], v[192:195], v[118:121]
	v_mfma_f32_16x16x32_bf16 v[114:117], v[184:187], v[192:195], v[114:117]
	v_mfma_f32_16x16x32_bf16 v[102:105], v[176:179], v[200:203], v[102:105]
	v_mfma_f32_16x16x32_bf16 v[98:101], v[184:187], v[200:203], v[98:101]
	v_mfma_f32_16x16x32_bf16 v[86:89], v[176:179], v[208:211], v[86:89]
	v_mfma_f32_16x16x32_bf16 v[82:85], v[184:187], v[208:211], v[82:85]
	v_mfma_f32_16x16x32_bf16 v[70:73], v[176:179], v[216:219], v[70:73]
	v_mfma_f32_16x16x32_bf16 v[66:69], v[184:187], v[216:219], v[66:69]
	s_barrier
; #define PG8_STAGE(bufoff, gbase, voff) do { _Pragma("unroll") for (int _i = 0; _i < 2; ++_i) \
;         __builtin_amdgcn_global_load_lds((const unsigned*)((const char*)(gbase) + (voff)[_i]), (LAS unsigned*)(lds + (bufoff) + ldsw + _i * 8192), 16, 0, 0); } while (0)
; #define PG8_LDA(dst, b, h) do { _Pragma("unroll") for (int m = 0; m < 4; ++m) _Pragma("unroll") for (int k = 0; k < 2; ++k) dst[m][k] = *(const LAS bf16x8*)(lds + PG8_SA(b, h) + aoff + m * 2048 + k * 1024); } while (0)
; #define PG8_MMA(ai, bj, At, Bt) do { __builtin_amdgcn_s_setprio(1); _Pragma("unroll") for (int m = 0; m < 4; ++m) _Pragma("unroll") for (int n = 0; n < 2; ++n) _Pragma("unroll") for (int k = 0; k < 2; ++k) \
;         acc[ai][bj][m][n] = __builtin_amdgcn_mfma_f32_16x16x32_bf16(Bt[n][k], At[m][k], acc[ai][bj][m][n], 0, 0, 0); __builtin_amdgcn_s_setprio(0); } while (0)
; #define PG8_WAIT_V(n) asm volatile("s_waitcnt vmcnt(" #n ")" ::: "memory")
; #define PG8_WAIT_L(n) asm volatile("s_waitcnt lgkmcnt(" #n ")" ::: "memory")
; #define PG8_BAR __builtin_amdgcn_s_barrier()
; #define PG8_SCHED __builtin_amdgcn_sched_barrier(0)
; template <class Epi, class Sched, bool ABLK = false, bool ALIGN_EPI = true, bool SP2 = true, bool BBLK = true>
; __device__ __forceinline__ void gemm_phase(LAS unsigned char* lds, const Gemm g, const Sched& S, const Epi& E) {
;     ...
;             PG8_LDA(At, 1, 1); PG8_STAGE(PG8_SB(1, 0), b3, voffB); PG8_STAGE(PG8_SB(1, 1), b3 + hstepB, voffB); PG8_STAGE(PG8_SA(1, 0), a3, voffA);
;             PG8_WAIT_V(8); PG8_WAIT_L(0); PG8_BAR; PG8_MMA(1, 0, At, B0); PG8_MMA(1, 1, At, B1); PG8_BAR; PG8_SCHED;
	s_add_u32 s26, s24, 0x8000
	s_addc_u32 s27, s25, 0
	s_add_i32 s66, s60, s34
	s_mov_b32 m0, s66
	ds_read_b128 v[188:191], v155 offset:49152
	ds_read_b128 v[192:195], v155 offset:50176
	ds_read_b128 v[196:199], v155 offset:51200
	ds_read_b128 v[200:203], v155 offset:52224
	ds_read_b128 v[204:207], v155 offset:53248
	ds_read_b128 v[208:211], v155 offset:54272
	ds_read_b128 v[212:215], v155 offset:55296
	ds_read_b128 v[216:219], v155 offset:56320
	global_load_lds_dwordx4 v132, s[26:27]
	s_add_i32 m0, s66, 0x2000
	s_add_u32 s24, s24, 0xc000
	v_lshl_add_u64 v[220:221], s[26:27], 0, v[136:137]
	s_addc_u32 s25, s25, 0
	s_add_i32 s26, s61, s34
	global_load_lds_dwordx4 v[220:221], off
	s_mov_b32 m0, s26
	s_nop 0
	global_load_lds_dwordx4 v132, s[24:25]
	s_add_i32 m0, s26, 0x2000
	s_nop 0
	global_load_lds_dwordx4 v136, s[24:25]
	s_mov_b32 m0, s41
	s_nop 0
	global_load_lds_dwordx4 v130, s[22:23]
	s_mov_b32 m0, s42
	s_nop 0
	global_load_lds_dwordx4 v134, s[22:23]
	s_waitcnt vmcnt(8) lgkmcnt(0)
	s_barrier
	v_mfma_f32_16x16x32_bf16 v[62:65], v[156:159], v[188:191], v[62:65]
	v_mfma_f32_16x16x32_bf16 v[58:61], v[164:167], v[188:191], v[58:61]
	v_mfma_f32_16x16x32_bf16 v[46:49], v[156:159], v[196:199], v[46:49]
	v_mfma_f32_16x16x32_bf16 v[42:45], v[164:167], v[196:199], v[42:45]
	v_mfma_f32_16x16x32_bf16 v[30:33], v[156:159], v[204:207], v[30:33]
	v_mfma_f32_16x16x32_bf16 v[26:29], v[164:167], v[204:207], v[26:29]
	v_mfma_f32_16x16x32_bf16 v[14:17], v[156:159], v[212:215], v[14:17]
	v_mfma_f32_16x16x32_bf16 v[10:13], v[164:167], v[212:215], v[10:13]
	v_mfma_f32_16x16x32_bf16 v[62:65], v[160:163], v[192:195], v[62:65]
	v_mfma_f32_16x16x32_bf16 v[58:61], v[168:171], v[192:195], v[58:61]
	v_mfma_f32_16x16x32_bf16 v[46:49], v[160:163], v[200:203], v[46:49]
	v_mfma_f32_16x16x32_bf16 v[42:45], v[168:171], v[200:203], v[42:45]
	v_mfma_f32_16x16x32_bf16 v[30:33], v[160:163], v[208:211], v[30:33]
	v_mfma_f32_16x16x32_bf16 v[26:29], v[168:171], v[208:211], v[26:29]
	v_mfma_f32_16x16x32_bf16 v[14:17], v[160:163], v[216:219], v[14:17]
	v_mfma_f32_16x16x32_bf16 v[10:13], v[168:171], v[216:219], v[10:13]
	v_mfma_f32_16x16x32_bf16 v[54:57], v[172:175], v[188:191], v[54:57]
	v_mfma_f32_16x16x32_bf16 v[50:53], v[180:183], v[188:191], v[50:53]
	v_mfma_f32_16x16x32_bf16 v[38:41], v[172:175], v[196:199], v[38:41]
	v_mfma_f32_16x16x32_bf16 v[34:37], v[180:183], v[196:199], v[34:37]
	v_mfma_f32_16x16x32_bf16 v[22:25], v[172:175], v[204:207], v[22:25]
	v_mfma_f32_16x16x32_bf16 v[18:21], v[180:183], v[204:207], v[18:21]
	v_mfma_f32_16x16x32_bf16 v[6:9], v[172:175], v[212:215], v[6:9]
	v_mfma_f32_16x16x32_bf16 v[2:5], v[180:183], v[212:215], v[2:5]
	v_mfma_f32_16x16x32_bf16 v[54:57], v[176:179], v[192:195], v[54:57]
	v_mfma_f32_16x16x32_bf16 v[50:53], v[184:187], v[192:195], v[50:53]
	v_mfma_f32_16x16x32_bf16 v[38:41], v[176:179], v[200:203], v[38:41]
	v_mfma_f32_16x16x32_bf16 v[34:37], v[184:187], v[200:203], v[34:37]
	v_mfma_f32_16x16x32_bf16 v[22:25], v[176:179], v[208:211], v[22:25]
	v_mfma_f32_16x16x32_bf16 v[18:21], v[184:187], v[208:211], v[18:21]
	v_mfma_f32_16x16x32_bf16 v[6:9], v[176:179], v[216:219], v[6:9]
	v_mfma_f32_16x16x32_bf16 v[2:5], v[184:187], v[216:219], v[2:5]
	s_barrier
	s_add_u32 s51, s51, 0x10000
	s_addc_u32 s55, s55, 0
	s_add_u32 s20, s20, 0x100
	s_addc_u32 s21, s21, 0
	s_cmp_ge_u32 s65, s46

; #define PG8_STAGE(bufoff, gbase, voff) do { _Pragma("unroll") for (int _i = 0; _i < 2; ++_i) \
;         __builtin_amdgcn_global_load_lds((const unsigned*)((const char*)(gbase) + (voff)[_i]), (LAS unsigned*)(lds + (bufoff) + ldsw + _i * 8192), 16, 0, 0); } while (0)
; #define PG8_LDA(dst, b, h) do { _Pragma("unroll") for (int m = 0; m < 4; ++m) _Pragma("unroll") for (int k = 0; k < 2; ++k) dst[m][k] = *(const LAS bf16x8*)(lds + PG8_SA(b, h) + aoff + m * 2048 + k * 1024); } while (0)
; #define PG8_LDB(dst, b, h) do { _Pragma("unroll") for (int n = 0; n < 2; ++n) _Pragma("unroll") for (int k = 0; k < 2; ++k) dst[n][k] = *(const LAS bf16x8*)(lds + PG8_SB(b, h) + boff + n * 2048 + k * 1024); } while (0)
; #define PG8_WAIT_V(n) asm volatile("s_waitcnt vmcnt(" #n ")" ::: "memory")
; #define PG8_WAIT_L(n) asm volatile("s_waitcnt lgkmcnt(" #n ")" ::: "memory")
; #define PG8_BAR __builtin_amdgcn_s_barrier()
; #define PG8_SCHED __builtin_amdgcn_sched_barrier(0)
; template <class Epi, class Sched, bool ABLK = false, bool ALIGN_EPI = true, bool SP2 = true, bool BBLK = true>
; __device__ __forceinline__ void gemm_phase(LAS unsigned char* lds, const Gemm g, const Sched& S, const Epi& E) {
;     ...
;         const bool has_next = S.next(ui + 1, nxt);
;         const int nt = cur.nt;
;         const char* nuA = has_next ? a_unit(nxt) : uA; const int ntbA = has_next ? nxt.k0 / BK : tbA; const char* nB = has_next ? (const char*)g.Bt + (size_t)nxt.pn * tstepB + b_k0(nxt.k0) : cB;
;         for (int t = 0; t < nt; t += 2) {
;             const bool last = (t == nt - 2);
;             const char* a1 = a_tile(uA, tbA + t + 1);
;             const char* a2 = last ? a_tile(nuA, ntbA) : a_tile(uA, tbA + t + 2); const char* b2 = last ? nB : cB + (size_t)(t + 2) * kstepB;
;             const char* a3 = last ? a_tile(nuA, ntbA + 1) : a_tile(uA, tbA + t + 3); const char* b3 = b2 + kstepB;
;             if (last && has_next) S.a_ready(nxt);
;             if constexpr (SP2) {
;             PG8_LDB(B0, 0, 0); PG8_LDB(B1, 0, 1); PG8_SCHED; PG8_LDA(At, 0, 0); PG8_STAGE(PG8_SA(1, 1), a1 + hstepA, voffA);
;             PG8_WAIT_V(8); PG8_WAIT_L(0); PG8_BAR; PG8_MMA(0, 0, At, B0); PG8_MMA(0, 1, At, B1); PG8_BAR; PG8_SCHED;
;             PG8_LDA(At, 0, 1); PG8_STAGE(PG8_SB(0, 0), b2, voffB); PG8_STAGE(PG8_SB(0, 1), b2 + hstepB, voffB); PG8_STAGE(PG8_SA(0, 0), a2, voffA);
.LBB0_1163:
	s_ashr_i32 s11, s10, 31
	s_lshl_b64 s[4:5], s[10:11], 20
	s_add_u32 s16, s59, s4
	s_addc_u32 s17, s62, s5
	s_and_b64 s[4:5], s[18:19], exec
	s_cselect_b32 s4, s17, s27
	s_cselect_b32 s5, s16, s26
	s_ashr_i32 s15, s14, 31
	s_lshl_b64 s[20:21], s[14:15], 20
	s_add_u32 s20, s40, s20
	s_addc_u32 s21, s41, s21
	s_and_b64 s[30:31], s[18:19], exec
	s_cselect_b32 s11, s21, s29
	s_cselect_b32 s15, s20, s28
	s_add_u32 s23, s5, 0x80
	s_addc_u32 s57, s4, 0
	s_add_u32 s64, s28, 0x10000
	v_mov_b32_e32 v2, 0
	s_addc_u32 s65, s29, 0
	v_lshl_add_u64 v[164:165], s[26:27], 0, v[160:161]
	v_lshl_add_u64 v[166:167], s[26:27], 0, v[162:163]
	s_mov_b32 s66, -2
	s_mov_b64 s[28:29], 0
	ds_read_b128 v[172:175], v169
	ds_read_b128 v[176:179], v169 offset:1024
	ds_read_b128 v[180:183], v169 offset:2048
	ds_read_b128 v[184:187], v169 offset:3072
	ds_read_b128 v[188:191], v170
	ds_read_b128 v[192:195], v170 offset:1024
	ds_read_b128 v[196:199], v170 offset:2048
	ds_read_b128 v[200:203], v170 offset:3072
	s_add_u32 s30, s26, s28
	s_addc_u32 s31, s27, s29
	s_add_u32 s36, s30, 0x100
	s_addc_u32 s37, s31, 0
	s_add_u32 s30, s30, 0x180
	s_addc_u32 s31, s31, 0
	s_cmpk_eq_i32 s28, 0xf00
	s_cselect_b32 s31, s57, s31
	s_cselect_b32 s30, s23, s30
	s_cselect_b32 s35, s11, s65
	s_cselect_b32 s34, s15, s64
	s_cselect_b32 s37, s4, s37
	s_cselect_b32 s36, s5, s36
	s_mov_b32 m0, s50
	v_lshl_add_u64 v[236:237], v[164:165], 0, s[28:29]
	ds_read_b128 v[204:207], v171
	ds_read_b128 v[208:211], v171 offset:1024
	ds_read_b128 v[212:215], v171 offset:2048
	ds_read_b128 v[216:219], v171 offset:3072
	ds_read_b128 v[220:223], v171 offset:4096
	ds_read_b128 v[224:227], v171 offset:5120
	ds_read_b128 v[228:231], v171 offset:6144
	ds_read_b128 v[232:235], v171 offset:7168
	global_load_lds_dwordx4 v[236:237], off
	v_lshl_add_u64 v[236:237], v[166:167], 0, s[28:29]
	s_mov_b32 m0, s51
	s_nop 0
	global_load_lds_dwordx4 v[236:237], off
	s_waitcnt vmcnt(8) lgkmcnt(0)
	s_barrier
	v_mfma_f32_16x16x32_bf16 v[126:129], v[172:175], v[204:207], 0
	v_mfma_f32_16x16x32_bf16 v[122:125], v[180:183], v[204:207], 0
	v_mfma_f32_16x16x32_bf16 v[110:113], v[172:175], v[212:215], 0
	v_mfma_f32_16x16x32_bf16 v[106:109], v[180:183], v[212:215], 0
	v_mfma_f32_16x16x32_bf16 v[94:97], v[172:175], v[220:223], 0
	v_mfma_f32_16x16x32_bf16 v[90:93], v[180:183], v[220:223], 0
	v_mfma_f32_16x16x32_bf16 v[78:81], v[172:175], v[228:231], 0
	v_mfma_f32_16x16x32_bf16 v[74:77], v[180:183], v[228:231], 0
	v_mfma_f32_16x16x32_bf16 v[126:129], v[176:179], v[208:211], v[126:129]
	v_mfma_f32_16x16x32_bf16 v[122:125], v[184:187], v[208:211], v[122:125]
	v_mfma_f32_16x16x32_bf16 v[110:113], v[176:179], v[216:219], v[110:113]
	v_mfma_f32_16x16x32_bf16 v[106:109], v[184:187], v[216:219], v[106:109]
	v_mfma_f32_16x16x32_bf16 v[94:97], v[176:179], v[224:227], v[94:97]
	v_mfma_f32_16x16x32_bf16 v[90:93], v[184:187], v[224:227], v[90:93]
	v_mfma_f32_16x16x32_bf16 v[78:81], v[176:179], v[232:235], v[78:81]
	v_mfma_f32_16x16x32_bf16 v[74:77], v[184:187], v[232:235], v[74:77]
	v_mfma_f32_16x16x32_bf16 v[118:121], v[188:191], v[204:207], 0
	v_mfma_f32_16x16x32_bf16 v[114:117], v[196:199], v[204:207], 0
	v_mfma_f32_16x16x32_bf16 v[102:105], v[188:191], v[212:215], 0
	v_mfma_f32_16x16x32_bf16 v[98:101], v[196:199], v[212:215], 0
	v_mfma_f32_16x16x32_bf16 v[86:89], v[188:191], v[220:223], 0
	v_mfma_f32_16x16x32_bf16 v[82:85], v[196:199], v[220:223], 0
	v_mfma_f32_16x16x32_bf16 v[70:73], v[188:191], v[228:231], 0
	v_mfma_f32_16x16x32_bf16 v[66:69], v[196:199], v[228:231], 0
	v_mfma_f32_16x16x32_bf16 v[118:121], v[192:195], v[208:211], v[118:121]
	v_mfma_f32_16x16x32_bf16 v[114:117], v[200:203], v[208:211], v[114:117]
	v_mfma_f32_16x16x32_bf16 v[102:105], v[192:195], v[216:219], v[102:105]
	v_mfma_f32_16x16x32_bf16 v[98:101], v[200:203], v[216:219], v[98:101]
	v_mfma_f32_16x16x32_bf16 v[86:89], v[192:195], v[224:227], v[86:89]
	v_mfma_f32_16x16x32_bf16 v[82:85], v[200:203], v[224:227], v[82:85]
	v_mfma_f32_16x16x32_bf16 v[70:73], v[192:195], v[232:235], v[70:73]
	v_mfma_f32_16x16x32_bf16 v[66:69], v[200:203], v[232:235], v[66:69]
	s_barrier
	s_mov_b32 m0, s55
	s_add_u32 s76, s34, 0x4000
	ds_read_b128 v[204:207], v171 offset:16384
	ds_read_b128 v[208:211], v171 offset:17408
	ds_read_b128 v[212:215], v171 offset:18432
	ds_read_b128 v[216:219], v171 offset:19456
	ds_read_b128 v[220:223], v171 offset:20480
	ds_read_b128 v[224:227], v171 offset:21504
	ds_read_b128 v[228:231], v171 offset:22528
	ds_read_b128 v[232:235], v171 offset:23552
	global_load_lds_dwordx4 v134, s[34:35]
	s_mov_b32 m0, s56
	s_addc_u32 s77, s35, 0
	s_add_i32 s67, s73, s42
	global_load_lds_dwordx4 v130, s[34:35]
	s_mov_b32 m0, s67
	s_nop 0
	global_load_lds_dwordx4 v134, s[76:77]
	s_add_i32 m0, s67, 0x2000
	s_nop 0
	global_load_lds_dwordx4 v130, s[76:77]
	s_mov_b32 m0, s25
	s_nop 0
	global_load_lds_dwordx4 v136, s[36:37]
	s_mov_b32 m0, s43
	s_nop 0
	global_load_lds_dwordx4 v132, s[36:37]
	s_waitcnt vmcnt(8) lgkmcnt(0)
	s_barrier
; #define PG8_STAGE(bufoff, gbase, voff) do { _Pragma("unroll") for (int _i = 0; _i < 2; ++_i) \
;         __builtin_amdgcn_global_load_lds((const unsigned*)((const char*)(gbase) + (voff)[_i]), (LAS unsigned*)(lds + (bufoff) + ldsw + _i * 8192), 16, 0, 0); } while (0)
; #define PG8_LDA(dst, b, h) do { _Pragma("unroll") for (int m = 0; m < 4; ++m) _Pragma("unroll") for (int k = 0; k < 2; ++k) dst[m][k] = *(const LAS bf16x8*)(lds + PG8_SA(b, h) + aoff + m * 2048 + k * 1024); } while (0)
; #define PG8_LDB(dst, b, h) do { _Pragma("unroll") for (int n = 0; n < 2; ++n) _Pragma("unroll") for (int k = 0; k < 2; ++k) dst[n][k] = *(const LAS bf16x8*)(lds + PG8_SB(b, h) + boff + n * 2048 + k * 1024); } while (0)
; #define PG8_MMA(ai, bj, At, Bt) do { __builtin_amdgcn_s_setprio(1); _Pragma("unroll") for (int m = 0; m < 4; ++m) _Pragma("unroll") for (int n = 0; n < 2; ++n) _Pragma("unroll") for (int k = 0; k < 2; ++k) \
;         acc[ai][bj][m][n] = __builtin_amdgcn_mfma_f32_16x16x32_bf16(Bt[n][k], At[m][k], acc[ai][bj][m][n], 0, 0, 0); __builtin_amdgcn_s_setprio(0); } while (0)
; #define PG8_WAIT_V(n) asm volatile("s_waitcnt vmcnt(" #n ")" ::: "memory")
; #define PG8_WAIT_L(n) asm volatile("s_waitcnt lgkmcnt(" #n ")" ::: "memory")
; #define PG8_BAR __builtin_amdgcn_s_barrier()
; #define PG8_SCHED __builtin_amdgcn_sched_barrier(0)
; template <class Epi, class Sched, bool ABLK = false, bool ALIGN_EPI = true, bool SP2 = true, bool BBLK = true>
; __device__ __forceinline__ void gemm_phase(LAS unsigned char* lds, const Gemm g, const Sched& S, const Epi& E) {
;     ...
;             PG8_WAIT_V(8); PG8_WAIT_L(0); PG8_BAR; PG8_MMA(1, 0, At, B0); PG8_MMA(1, 1, At, B1); PG8_BAR; PG8_SCHED;
;             PG8_LDB(B0, 1, 0); PG8_LDB(B1, 1, 1); PG8_SCHED; PG8_LDA(At, 1, 0); PG8_STAGE(PG8_SA(0, 1), a2 + hstepA, voffA);
;             PG8_WAIT_V(8); PG8_WAIT_L(0); PG8_BAR; PG8_MMA(0, 0, At, B0); PG8_MMA(0, 1, At, B1); PG8_BAR; PG8_SCHED;
	v_mfma_f32_16x16x32_bf16 v[62:65], v[172:175], v[204:207], 0
	v_mfma_f32_16x16x32_bf16 v[58:61], v[180:183], v[204:207], 0
	v_mfma_f32_16x16x32_bf16 v[46:49], v[172:175], v[212:215], 0
	v_mfma_f32_16x16x32_bf16 v[42:45], v[180:183], v[212:215], 0
	v_mfma_f32_16x16x32_bf16 v[30:33], v[172:175], v[220:223], 0
	v_mfma_f32_16x16x32_bf16 v[26:29], v[180:183], v[220:223], 0
	v_mfma_f32_16x16x32_bf16 v[14:17], v[172:175], v[228:231], 0
	v_mfma_f32_16x16x32_bf16 v[10:13], v[180:183], v[228:231], 0
	v_mfma_f32_16x16x32_bf16 v[62:65], v[176:179], v[208:211], v[62:65]
	v_mfma_f32_16x16x32_bf16 v[58:61], v[184:187], v[208:211], v[58:61]
	v_mfma_f32_16x16x32_bf16 v[46:49], v[176:179], v[216:219], v[46:49]
	v_mfma_f32_16x16x32_bf16 v[42:45], v[184:187], v[216:219], v[42:45]
	v_mfma_f32_16x16x32_bf16 v[30:33], v[176:179], v[224:227], v[30:33]
	v_mfma_f32_16x16x32_bf16 v[26:29], v[184:187], v[224:227], v[26:29]
	v_mfma_f32_16x16x32_bf16 v[14:17], v[176:179], v[232:235], v[14:17]
	v_mfma_f32_16x16x32_bf16 v[10:13], v[184:187], v[232:235], v[10:13]
	v_mfma_f32_16x16x32_bf16 v[54:57], v[188:191], v[204:207], 0
	v_mfma_f32_16x16x32_bf16 v[50:53], v[196:199], v[204:207], 0
	v_mfma_f32_16x16x32_bf16 v[38:41], v[188:191], v[212:215], 0
	v_mfma_f32_16x16x32_bf16 v[34:37], v[196:199], v[212:215], 0
	v_mfma_f32_16x16x32_bf16 v[22:25], v[188:191], v[220:223], 0
	v_mfma_f32_16x16x32_bf16 v[18:21], v[196:199], v[220:223], 0
	v_mfma_f32_16x16x32_bf16 v[6:9], v[188:191], v[228:231], 0
	v_mfma_f32_16x16x32_bf16 v[2:5], v[196:199], v[228:231], 0
	v_mfma_f32_16x16x32_bf16 v[54:57], v[192:195], v[208:211], v[54:57]
	v_mfma_f32_16x16x32_bf16 v[50:53], v[200:203], v[208:211], v[50:53]
	v_mfma_f32_16x16x32_bf16 v[38:41], v[192:195], v[216:219], v[38:41]
	v_mfma_f32_16x16x32_bf16 v[34:37], v[200:203], v[216:219], v[34:37]
	v_mfma_f32_16x16x32_bf16 v[22:25], v[192:195], v[224:227], v[22:25]
	v_mfma_f32_16x16x32_bf16 v[18:21], v[200:203], v[224:227], v[18:21]
	v_mfma_f32_16x16x32_bf16 v[6:9], v[192:195], v[232:235], v[6:9]
	v_mfma_f32_16x16x32_bf16 v[2:5], v[200:203], v[232:235], v[2:5]
	s_barrier
	v_add_u32_e32 v184, s60, v168
	v_add_u32_e32 v200, s61, v168
	ds_read_b128 v[172:175], v184
	ds_read_b128 v[176:179], v184 offset:1024
	ds_read_b128 v[180:183], v184 offset:2048
	ds_read_b128 v[184:187], v184 offset:3072
	ds_read_b128 v[188:191], v200
	ds_read_b128 v[192:195], v200 offset:1024
	ds_read_b128 v[196:199], v200 offset:2048
	ds_read_b128 v[200:203], v200 offset:3072
	s_add_u32 s36, s36, 0x80000
	s_addc_u32 s37, s37, 0
	s_mov_b32 m0, s44
	ds_read_b128 v[204:207], v171 offset:32768
	ds_read_b128 v[208:211], v171 offset:33792
	ds_read_b128 v[212:215], v171 offset:34816
	ds_read_b128 v[216:219], v171 offset:35840
	ds_read_b128 v[220:223], v171 offset:36864
	ds_read_b128 v[224:227], v171 offset:37888
	ds_read_b128 v[228:231], v171 offset:38912
	ds_read_b128 v[232:235], v171 offset:39936
	global_load_lds_dwordx4 v136, s[36:37]
	s_mov_b32 m0, s45
	s_nop 0
	global_load_lds_dwordx4 v132, s[36:37]
	s_waitcnt vmcnt(8) lgkmcnt(0)
	s_barrier
	v_mfma_f32_16x16x32_bf16 v[126:129], v[172:175], v[204:207], v[126:129]
	v_mfma_f32_16x16x32_bf16 v[122:125], v[180:183], v[204:207], v[122:125]
	v_mfma_f32_16x16x32_bf16 v[110:113], v[172:175], v[212:215], v[110:113]
	v_mfma_f32_16x16x32_bf16 v[106:109], v[180:183], v[212:215], v[106:109]
	v_mfma_f32_16x16x32_bf16 v[94:97], v[172:175], v[220:223], v[94:97]
	v_mfma_f32_16x16x32_bf16 v[90:93], v[180:183], v[220:223], v[90:93]
	v_mfma_f32_16x16x32_bf16 v[78:81], v[172:175], v[228:231], v[78:81]
	v_mfma_f32_16x16x32_bf16 v[74:77], v[180:183], v[228:231], v[74:77]
	v_mfma_f32_16x16x32_bf16 v[126:129], v[176:179], v[208:211], v[126:129]
	v_mfma_f32_16x16x32_bf16 v[122:125], v[184:187], v[208:211], v[122:125]
	v_mfma_f32_16x16x32_bf16 v[110:113], v[176:179], v[216:219], v[110:113]
	v_mfma_f32_16x16x32_bf16 v[106:109], v[184:187], v[216:219], v[106:109]
	v_mfma_f32_16x16x32_bf16 v[94:97], v[176:179], v[224:227], v[94:97]
	v_mfma_f32_16x16x32_bf16 v[90:93], v[184:187], v[224:227], v[90:93]
	v_mfma_f32_16x16x32_bf16 v[78:81], v[176:179], v[232:235], v[78:81]
	v_mfma_f32_16x16x32_bf16 v[74:77], v[184:187], v[232:235], v[74:77]
	v_mfma_f32_16x16x32_bf16 v[118:121], v[188:191], v[204:207], v[118:121]
	v_mfma_f32_16x16x32_bf16 v[114:117], v[196:199], v[204:207], v[114:117]
	v_mfma_f32_16x16x32_bf16 v[102:105], v[188:191], v[212:215], v[102:105]
	v_mfma_f32_16x16x32_bf16 v[98:101], v[196:199], v[212:215], v[98:101]
	v_mfma_f32_16x16x32_bf16 v[86:89], v[188:191], v[220:223], v[86:89]
	v_mfma_f32_16x16x32_bf16 v[82:85], v[196:199], v[220:223], v[82:85]
	v_mfma_f32_16x16x32_bf16 v[70:73], v[188:191], v[228:231], v[70:73]
	v_mfma_f32_16x16x32_bf16 v[66:69], v[196:199], v[228:231], v[66:69]
	v_mfma_f32_16x16x32_bf16 v[118:121], v[192:195], v[208:211], v[118:121]
	v_mfma_f32_16x16x32_bf16 v[114:117], v[200:203], v[208:211], v[114:117]
	v_mfma_f32_16x16x32_bf16 v[102:105], v[192:195], v[216:219], v[102:105]
	v_mfma_f32_16x16x32_bf16 v[98:101], v[200:203], v[216:219], v[98:101]
	v_mfma_f32_16x16x32_bf16 v[86:89], v[192:195], v[224:227], v[86:89]
	v_mfma_f32_16x16x32_bf16 v[82:85], v[200:203], v[224:227], v[82:85]
	v_mfma_f32_16x16x32_bf16 v[70:73], v[192:195], v[232:235], v[70:73]
	v_mfma_f32_16x16x32_bf16 v[66:69], v[200:203], v[232:235], v[66:69]
	s_barrier
; #define PG8_STAGE(bufoff, gbase, voff) do { _Pragma("unroll") for (int _i = 0; _i < 2; ++_i) \
;         __builtin_amdgcn_global_load_lds((const unsigned*)((const char*)(gbase) + (voff)[_i]), (LAS unsigned*)(lds + (bufoff) + ldsw + _i * 8192), 16, 0, 0); } while (0)
; #define PG8_LDA(dst, b, h) do { _Pragma("unroll") for (int m = 0; m < 4; ++m) _Pragma("unroll") for (int k = 0; k < 2; ++k) dst[m][k] = *(const LAS bf16x8*)(lds + PG8_SA(b, h) + aoff + m * 2048 + k * 1024); } while (0)
; #define PG8_MMA(ai, bj, At, Bt) do { __builtin_amdgcn_s_setprio(1); _Pragma("unroll") for (int m = 0; m < 4; ++m) _Pragma("unroll") for (int n = 0; n < 2; ++n) _Pragma("unroll") for (int k = 0; k < 2; ++k) \
;         acc[ai][bj][m][n] = __builtin_amdgcn_mfma_f32_16x16x32_bf16(Bt[n][k], At[m][k], acc[ai][bj][m][n], 0, 0, 0); __builtin_amdgcn_s_setprio(0); } while (0)
; #define PG8_WAIT_V(n) asm volatile("s_waitcnt vmcnt(" #n ")" ::: "memory")
; #define PG8_WAIT_L(n) asm volatile("s_waitcnt lgkmcnt(" #n ")" ::: "memory")
; #define PG8_BAR __builtin_amdgcn_s_barrier()
; #define PG8_SCHED __builtin_amdgcn_sched_barrier(0)
; template <class Epi, class Sched, bool ABLK = false, bool ALIGN_EPI = true, bool SP2 = true, bool BBLK = true>
; __device__ __forceinline__ void gemm_phase(LAS unsigned char* lds, const Gemm g, const Sched& S, const Epi& E) {
;     ...
;             PG8_LDA(At, 1, 1); PG8_STAGE(PG8_SB(1, 0), b3, voffB); PG8_STAGE(PG8_SB(1, 1), b3 + hstepB, voffB); PG8_STAGE(PG8_SA(1, 0), a3, voffA);
;             PG8_WAIT_V(8); PG8_WAIT_L(0); PG8_BAR; PG8_MMA(1, 0, At, B0); PG8_MMA(1, 1, At, B1); PG8_BAR; PG8_SCHED;
	s_add_u32 s36, s34, 0x8000
	s_addc_u32 s37, s35, 0
	s_add_i32 s67, s60, s42
	s_mov_b32 m0, s67
	ds_read_b128 v[204:207], v171 offset:49152
	ds_read_b128 v[208:211], v171 offset:50176
	ds_read_b128 v[212:215], v171 offset:51200
	ds_read_b128 v[216:219], v171 offset:52224
	ds_read_b128 v[220:223], v171 offset:53248
	ds_read_b128 v[224:227], v171 offset:54272
	ds_read_b128 v[228:231], v171 offset:55296
	ds_read_b128 v[232:235], v171 offset:56320
	global_load_lds_dwordx4 v134, s[36:37]
	s_add_i32 m0, s67, 0x2000
	s_add_u32 s34, s34, 0xc000
	v_lshl_add_u64 v[236:237], s[36:37], 0, v[130:131]
	s_addc_u32 s35, s35, 0
	s_add_i32 s36, s61, s42
	global_load_lds_dwordx4 v[236:237], off
	s_mov_b32 m0, s36
	s_nop 0
	global_load_lds_dwordx4 v134, s[34:35]
	s_add_i32 m0, s36, 0x2000
	s_nop 0
	global_load_lds_dwordx4 v130, s[34:35]
	s_mov_b32 m0, s48
	s_nop 0
	global_load_lds_dwordx4 v136, s[30:31]
	s_mov_b32 m0, s49
	s_nop 0
	global_load_lds_dwordx4 v132, s[30:31]
	s_waitcnt vmcnt(8) lgkmcnt(0)
	s_barrier
	v_mfma_f32_16x16x32_bf16 v[62:65], v[172:175], v[204:207], v[62:65]
	v_mfma_f32_16x16x32_bf16 v[58:61], v[180:183], v[204:207], v[58:61]
	v_mfma_f32_16x16x32_bf16 v[46:49], v[172:175], v[212:215], v[46:49]
	v_mfma_f32_16x16x32_bf16 v[42:45], v[180:183], v[212:215], v[42:45]
	v_mfma_f32_16x16x32_bf16 v[30:33], v[172:175], v[220:223], v[30:33]
	v_mfma_f32_16x16x32_bf16 v[26:29], v[180:183], v[220:223], v[26:29]
	v_mfma_f32_16x16x32_bf16 v[14:17], v[172:175], v[228:231], v[14:17]
	v_mfma_f32_16x16x32_bf16 v[10:13], v[180:183], v[228:231], v[10:13]
	v_mfma_f32_16x16x32_bf16 v[62:65], v[176:179], v[208:211], v[62:65]
	v_mfma_f32_16x16x32_bf16 v[58:61], v[184:187], v[208:211], v[58:61]
	v_mfma_f32_16x16x32_bf16 v[46:49], v[176:179], v[216:219], v[46:49]
	v_mfma_f32_16x16x32_bf16 v[42:45], v[184:187], v[216:219], v[42:45]
	v_mfma_f32_16x16x32_bf16 v[30:33], v[176:179], v[224:227], v[30:33]
	v_mfma_f32_16x16x32_bf16 v[26:29], v[184:187], v[224:227], v[26:29]
	v_mfma_f32_16x16x32_bf16 v[14:17], v[176:179], v[232:235], v[14:17]
	v_mfma_f32_16x16x32_bf16 v[10:13], v[184:187], v[232:235], v[10:13]
	v_mfma_f32_16x16x32_bf16 v[54:57], v[188:191], v[204:207], v[54:57]
	v_mfma_f32_16x16x32_bf16 v[50:53], v[196:199], v[204:207], v[50:53]
	v_mfma_f32_16x16x32_bf16 v[38:41], v[188:191], v[212:215], v[38:41]
	v_mfma_f32_16x16x32_bf16 v[34:37], v[196:199], v[212:215], v[34:37]
	v_mfma_f32_16x16x32_bf16 v[22:25], v[188:191], v[220:223], v[22:25]
	v_mfma_f32_16x16x32_bf16 v[18:21], v[196:199], v[220:223], v[18:21]
	v_mfma_f32_16x16x32_bf16 v[6:9], v[188:191], v[228:231], v[6:9]
	v_mfma_f32_16x16x32_bf16 v[2:5], v[196:199], v[228:231], v[2:5]
	v_mfma_f32_16x16x32_bf16 v[54:57], v[192:195], v[208:211], v[54:57]
	v_mfma_f32_16x16x32_bf16 v[50:53], v[200:203], v[208:211], v[50:53]
	v_mfma_f32_16x16x32_bf16 v[38:41], v[192:195], v[216:219], v[38:41]
	v_mfma_f32_16x16x32_bf16 v[34:37], v[200:203], v[216:219], v[34:37]
	v_mfma_f32_16x16x32_bf16 v[22:25], v[192:195], v[224:227], v[22:25]
	v_mfma_f32_16x16x32_bf16 v[18:21], v[200:203], v[224:227], v[18:21]
	v_mfma_f32_16x16x32_bf16 v[6:9], v[192:195], v[232:235], v[6:9]
	v_mfma_f32_16x16x32_bf16 v[2:5], v[200:203], v[232:235], v[2:5]
	s_barrier
	s_add_i32 s66, s66, 2
	s_add_u32 s28, s28, 0x100
	s_addc_u32 s29, s29, 0
	s_add_u32 s64, s64, 0x10000
	s_addc_u32 s65, s65, 0
	s_cmp_gt_u32 s66, 29

; #define PG8_STAGE(bufoff, gbase, voff) do { _Pragma("unroll") for (int _i = 0; _i < 2; ++_i) \
;         __builtin_amdgcn_global_load_lds((const unsigned*)((const char*)(gbase) + (voff)[_i]), (LAS unsigned*)(lds + (bufoff) + ldsw + _i * 8192), 16, 0, 0); } while (0)
; #define PG8_LDA(dst, b, h) do { _Pragma("unroll") for (int m = 0; m < 4; ++m) _Pragma("unroll") for (int k = 0; k < 2; ++k) dst[m][k] = *(const LAS bf16x8*)(lds + PG8_SA(b, h) + aoff + m * 2048 + k * 1024); } while (0)
; #define PG8_LDB(dst, b, h) do { _Pragma("unroll") for (int n = 0; n < 2; ++n) _Pragma("unroll") for (int k = 0; k < 2; ++k) dst[n][k] = *(const LAS bf16x8*)(lds + PG8_SB(b, h) + boff + n * 2048 + k * 1024); } while (0)
; #define PG8_WAIT_V(n) asm volatile("s_waitcnt vmcnt(" #n ")" ::: "memory")
; #define PG8_WAIT_L(n) asm volatile("s_waitcnt lgkmcnt(" #n ")" ::: "memory")
; #define PG8_BAR __builtin_amdgcn_s_barrier()
; #define PG8_SCHED __builtin_amdgcn_sched_barrier(0)
; template <class Epi, class Sched, bool ABLK = false, bool ALIGN_EPI = true, bool SP2 = true, bool BBLK = true>
; __device__ __forceinline__ void gemm_phase(LAS unsigned char* lds, const Gemm g, const Sched& S, const Epi& E) {
;     ...
;         const bool has_next = S.next(ui + 1, nxt);
;         const int nt = cur.nt;
;         const char* nuA = has_next ? a_unit(nxt) : uA; const int ntbA = has_next ? nxt.k0 / BK : tbA; const char* nB = has_next ? (const char*)g.Bt + (size_t)nxt.pn * tstepB + b_k0(nxt.k0) : cB;
;         for (int t = 0; t < nt; t += 2) {
;             const bool last = (t == nt - 2);
;             const char* a1 = a_tile(uA, tbA + t + 1);
;             const char* a2 = last ? a_tile(nuA, ntbA) : a_tile(uA, tbA + t + 2); const char* b2 = last ? nB : cB + (size_t)(t + 2) * kstepB;
;             const char* a3 = last ? a_tile(nuA, ntbA + 1) : a_tile(uA, tbA + t + 3); const char* b3 = b2 + kstepB;
;             if (last && has_next) S.a_ready(nxt);
;             if constexpr (SP2) {
;             PG8_LDB(B0, 0, 0); PG8_LDB(B1, 0, 1); PG8_SCHED; PG8_LDA(At, 0, 0); PG8_STAGE(PG8_SA(1, 1), a1 + hstepA, voffA);
;             PG8_WAIT_V(8); PG8_WAIT_L(0); PG8_BAR; PG8_MMA(0, 0, At, B0); PG8_MMA(0, 1, At, B1); PG8_BAR; PG8_SCHED;
;             PG8_LDA(At, 0, 1); PG8_STAGE(PG8_SB(0, 0), b2, voffB); PG8_STAGE(PG8_SB(0, 1), b2 + hstepB, voffB); PG8_STAGE(PG8_SA(0, 0), a2, voffA);
.LBB0_1228:
	s_ashr_i32 s81, s80, 31
	s_andn2_b64 vcc, exec, s[4:5]
	s_lshl_b64 s[16:17], s[80:81], 22
	s_add_u32 s16, s1, s16
	s_addc_u32 s17, s33, s17
	s_and_b64 s[18:19], s[4:5], exec
	s_cselect_b32 s27, s17, s25
	s_cselect_b32 s46, s16, s24
	s_ashr_i32 s18, s0, 31
	s_lshr_b32 s18, s18, 26
	s_add_i32 s18, s0, s18
	s_ashr_i32 s18, s18, 6
	s_and_b64 s[20:21], s[4:5], exec
	s_cselect_b32 s28, s18, s26
	s_ashr_i32 s79, s78, 31
	s_lshl_b64 s[20:21], s[78:79], 22
	s_add_u32 s29, s30, s20
	s_addc_u32 s47, s31, s21
	s_ashr_i32 s19, s18, 31
	s_lshl_b64 s[20:21], s[18:19], 15
	s_add_u32 s20, s29, s20
	s_addc_u32 s21, s47, s21
	v_cndmask_b32_e64 v2, 0, 1, s[4:5]
	s_and_b64 s[4:5], s[4:5], exec
	s_cselect_b32 s4, s21, s23
	s_cselect_b32 s5, s20, s22
	s_ashr_i32 s29, s28, 31
	s_lshl_b64 s[28:29], s[28:29], 15
	s_add_u32 s19, s46, s28
	s_addc_u32 s46, s27, s29
	s_add_u32 s47, s19, 0x8000
	s_addc_u32 s48, s46, 0
	s_add_u32 s49, s22, 0x10000
	s_addc_u32 s50, s23, 0
	s_ashr_i32 s27, s26, 31
	v_cmp_ne_u32_e64 s[10:11], 1, v2
	s_lshl_b64 s[22:23], s[26:27], 15
	v_lshl_add_u64 v[2:3], s[24:25], 0, v[138:139]
	s_add_u32 s51, s24, s22
	v_lshl_add_u64 v[142:143], v[2:3], 0, s[22:23]
	v_lshl_add_u64 v[2:3], s[24:25], 0, v[140:141]
	s_addc_u32 s55, s25, s23
	v_lshl_add_u64 v[144:145], v[2:3], 0, s[22:23]
	s_lshl_b32 s22, s44, 15
	s_add_i32 s22, s22, 0xfff00000
	v_mov_b32_e32 v2, 0
	s_add_u32 s56, s22, 0xf0000
	s_mov_b32 s57, 0
	s_mov_b64 s[22:23], 0
	ds_read_b128 v[152:155], v149
	ds_read_b128 v[156:159], v149 offset:1024
	ds_read_b128 v[160:163], v149 offset:2048
	ds_read_b128 v[164:167], v149 offset:3072
	ds_read_b128 v[168:171], v150
	ds_read_b128 v[172:175], v150 offset:1024
	ds_read_b128 v[176:179], v150 offset:2048
	ds_read_b128 v[180:183], v150 offset:3072
	s_add_u32 s24, s51, s22
	s_addc_u32 s25, s55, s23
	s_add_u32 s28, s24, 0x10000
	s_addc_u32 s29, s25, 0
	s_add_i32 s57, s57, 2
	s_add_u32 s26, s49, s22
	s_addc_u32 s27, s50, s23
	s_add_u32 s24, s24, 0x18000
	s_addc_u32 s25, s25, 0
	s_cmp_eq_u32 s56, s22
	s_cselect_b32 s25, s48, s25
	s_cselect_b32 s24, s47, s24
	s_cselect_b32 s27, s4, s27
	s_cselect_b32 s26, s5, s26
	s_cselect_b32 s29, s46, s29
	s_cselect_b32 s28, s19, s28
	v_lshl_add_u64 v[216:217], v[142:143], 0, s[22:23]
	s_add_i32 m0, s35, 0xc000
	ds_read_b128 v[184:187], v151
	ds_read_b128 v[188:191], v151 offset:1024
	ds_read_b128 v[192:195], v151 offset:2048
	ds_read_b128 v[196:199], v151 offset:3072
	ds_read_b128 v[200:203], v151 offset:4096
	ds_read_b128 v[204:207], v151 offset:5120
	ds_read_b128 v[208:211], v151 offset:6144
	ds_read_b128 v[212:215], v151 offset:7168
	global_load_lds_dwordx4 v[216:217], off
	v_lshl_add_u64 v[216:217], v[144:145], 0, s[22:23]
	s_add_i32 m0, s35, 0xe000
	s_nop 0
	global_load_lds_dwordx4 v[216:217], off
	s_waitcnt vmcnt(8) lgkmcnt(0)
	s_barrier
	v_mfma_f32_16x16x32_bf16 v[126:129], v[152:155], v[184:187], 0
	v_mfma_f32_16x16x32_bf16 v[122:125], v[160:163], v[184:187], 0
	v_mfma_f32_16x16x32_bf16 v[110:113], v[152:155], v[192:195], 0
	v_mfma_f32_16x16x32_bf16 v[106:109], v[160:163], v[192:195], 0
	v_mfma_f32_16x16x32_bf16 v[94:97], v[152:155], v[200:203], 0
	v_mfma_f32_16x16x32_bf16 v[90:93], v[160:163], v[200:203], 0
	v_mfma_f32_16x16x32_bf16 v[78:81], v[152:155], v[208:211], 0
	v_mfma_f32_16x16x32_bf16 v[74:77], v[160:163], v[208:211], 0
	v_mfma_f32_16x16x32_bf16 v[126:129], v[156:159], v[188:191], v[126:129]
	v_mfma_f32_16x16x32_bf16 v[122:125], v[164:167], v[188:191], v[122:125]
	v_mfma_f32_16x16x32_bf16 v[110:113], v[156:159], v[196:199], v[110:113]
	v_mfma_f32_16x16x32_bf16 v[106:109], v[164:167], v[196:199], v[106:109]
	v_mfma_f32_16x16x32_bf16 v[94:97], v[156:159], v[204:207], v[94:97]
	v_mfma_f32_16x16x32_bf16 v[90:93], v[164:167], v[204:207], v[90:93]
	v_mfma_f32_16x16x32_bf16 v[78:81], v[156:159], v[212:215], v[78:81]
	v_mfma_f32_16x16x32_bf16 v[74:77], v[164:167], v[212:215], v[74:77]
	v_mfma_f32_16x16x32_bf16 v[118:121], v[168:171], v[184:187], 0
	v_mfma_f32_16x16x32_bf16 v[114:117], v[176:179], v[184:187], 0
	v_mfma_f32_16x16x32_bf16 v[102:105], v[168:171], v[192:195], 0
	v_mfma_f32_16x16x32_bf16 v[98:101], v[176:179], v[192:195], 0
	v_mfma_f32_16x16x32_bf16 v[86:89], v[168:171], v[200:203], 0
	v_mfma_f32_16x16x32_bf16 v[82:85], v[176:179], v[200:203], 0
	v_mfma_f32_16x16x32_bf16 v[70:73], v[168:171], v[208:211], 0
	v_mfma_f32_16x16x32_bf16 v[66:69], v[176:179], v[208:211], 0
	v_mfma_f32_16x16x32_bf16 v[118:121], v[172:175], v[188:191], v[118:121]
	v_mfma_f32_16x16x32_bf16 v[114:117], v[180:183], v[188:191], v[114:117]
	v_mfma_f32_16x16x32_bf16 v[102:105], v[172:175], v[196:199], v[102:105]
	v_mfma_f32_16x16x32_bf16 v[98:101], v[180:183], v[196:199], v[98:101]
	v_mfma_f32_16x16x32_bf16 v[86:89], v[172:175], v[204:207], v[86:89]
	v_mfma_f32_16x16x32_bf16 v[82:85], v[180:183], v[204:207], v[82:85]
	v_mfma_f32_16x16x32_bf16 v[70:73], v[172:175], v[212:215], v[70:73]
	v_mfma_f32_16x16x32_bf16 v[66:69], v[180:183], v[212:215], v[66:69]
	s_barrier
	s_add_i32 s59, s72, s34
	s_mov_b32 m0, s59
	ds_read_b128 v[184:187], v151 offset:16384
	ds_read_b128 v[188:191], v151 offset:17408
	ds_read_b128 v[192:195], v151 offset:18432
	ds_read_b128 v[196:199], v151 offset:19456
	ds_read_b128 v[200:203], v151 offset:20480
	ds_read_b128 v[204:207], v151 offset:21504
	ds_read_b128 v[208:211], v151 offset:22528
	ds_read_b128 v[212:215], v151 offset:23552
	global_load_lds_dwordx4 v130, s[26:27]
	s_add_i32 m0, s59, 0x2000
	s_add_u32 s64, s26, 0x4000
	s_addc_u32 s65, s27, 0
	s_add_i32 s59, s73, s34
	global_load_lds_dwordx4 v132, s[26:27]
	s_mov_b32 m0, s59
	s_nop 0
	global_load_lds_dwordx4 v130, s[64:65]
	s_add_i32 m0, s59, 0x2000
	s_nop 0
	global_load_lds_dwordx4 v132, s[64:65]
	s_mov_b32 m0, s35
	s_nop 0
	global_load_lds_dwordx4 v130, s[28:29]
	s_mov_b32 m0, s36
	s_nop 0
	global_load_lds_dwordx4 v132, s[28:29]
	s_waitcnt vmcnt(8) lgkmcnt(0)
	s_barrier
; #define PG8_STAGE(bufoff, gbase, voff) do { _Pragma("unroll") for (int _i = 0; _i < 2; ++_i) \
;         __builtin_amdgcn_global_load_lds((const unsigned*)((const char*)(gbase) + (voff)[_i]), (LAS unsigned*)(lds + (bufoff) + ldsw + _i * 8192), 16, 0, 0); } while (0)
; #define PG8_LDA(dst, b, h) do { _Pragma("unroll") for (int m = 0; m < 4; ++m) _Pragma("unroll") for (int k = 0; k < 2; ++k) dst[m][k] = *(const LAS bf16x8*)(lds + PG8_SA(b, h) + aoff + m * 2048 + k * 1024); } while (0)
; #define PG8_LDB(dst, b, h) do { _Pragma("unroll") for (int n = 0; n < 2; ++n) _Pragma("unroll") for (int k = 0; k < 2; ++k) dst[n][k] = *(const LAS bf16x8*)(lds + PG8_SB(b, h) + boff + n * 2048 + k * 1024); } while (0)
; #define PG8_MMA(ai, bj, At, Bt) do { __builtin_amdgcn_s_setprio(1); _Pragma("unroll") for (int m = 0; m < 4; ++m) _Pragma("unroll") for (int n = 0; n < 2; ++n) _Pragma("unroll") for (int k = 0; k < 2; ++k) \
;         acc[ai][bj][m][n] = __builtin_amdgcn_mfma_f32_16x16x32_bf16(Bt[n][k], At[m][k], acc[ai][bj][m][n], 0, 0, 0); __builtin_amdgcn_s_setprio(0); } while (0)
; #define PG8_WAIT_V(n) asm volatile("s_waitcnt vmcnt(" #n ")" ::: "memory")
; #define PG8_WAIT_L(n) asm volatile("s_waitcnt lgkmcnt(" #n ")" ::: "memory")
; #define PG8_BAR __builtin_amdgcn_s_barrier()
; #define PG8_SCHED __builtin_amdgcn_sched_barrier(0)
; template <class Epi, class Sched, bool ABLK = false, bool ALIGN_EPI = true, bool SP2 = true, bool BBLK = true>
; __device__ __forceinline__ void gemm_phase(LAS unsigned char* lds, const Gemm g, const Sched& S, const Epi& E) {
;     ...
;             PG8_WAIT_V(8); PG8_WAIT_L(0); PG8_BAR; PG8_MMA(1, 0, At, B0); PG8_MMA(1, 1, At, B1); PG8_BAR; PG8_SCHED;
;             PG8_LDB(B0, 1, 0); PG8_LDB(B1, 1, 1); PG8_SCHED; PG8_LDA(At, 1, 0); PG8_STAGE(PG8_SA(0, 1), a2 + hstepA, voffA);
;             PG8_WAIT_V(8); PG8_WAIT_L(0); PG8_BAR; PG8_MMA(0, 0, At, B0); PG8_MMA(0, 1, At, B1); PG8_BAR; PG8_SCHED;
	v_mfma_f32_16x16x32_bf16 v[62:65], v[152:155], v[184:187], 0
	v_mfma_f32_16x16x32_bf16 v[58:61], v[160:163], v[184:187], 0
	v_mfma_f32_16x16x32_bf16 v[46:49], v[152:155], v[192:195], 0
	v_mfma_f32_16x16x32_bf16 v[42:45], v[160:163], v[192:195], 0
	v_mfma_f32_16x16x32_bf16 v[30:33], v[152:155], v[200:203], 0
	v_mfma_f32_16x16x32_bf16 v[26:29], v[160:163], v[200:203], 0
	v_mfma_f32_16x16x32_bf16 v[14:17], v[152:155], v[208:211], 0
	v_mfma_f32_16x16x32_bf16 v[10:13], v[160:163], v[208:211], 0
	v_mfma_f32_16x16x32_bf16 v[62:65], v[156:159], v[188:191], v[62:65]
	v_mfma_f32_16x16x32_bf16 v[58:61], v[164:167], v[188:191], v[58:61]
	v_mfma_f32_16x16x32_bf16 v[46:49], v[156:159], v[196:199], v[46:49]
	v_mfma_f32_16x16x32_bf16 v[42:45], v[164:167], v[196:199], v[42:45]
	v_mfma_f32_16x16x32_bf16 v[30:33], v[156:159], v[204:207], v[30:33]
	v_mfma_f32_16x16x32_bf16 v[26:29], v[164:167], v[204:207], v[26:29]
	v_mfma_f32_16x16x32_bf16 v[14:17], v[156:159], v[212:215], v[14:17]
	v_mfma_f32_16x16x32_bf16 v[10:13], v[164:167], v[212:215], v[10:13]
	v_mfma_f32_16x16x32_bf16 v[54:57], v[168:171], v[184:187], 0
	v_mfma_f32_16x16x32_bf16 v[50:53], v[176:179], v[184:187], 0
	v_mfma_f32_16x16x32_bf16 v[38:41], v[168:171], v[192:195], 0
	v_mfma_f32_16x16x32_bf16 v[34:37], v[176:179], v[192:195], 0
	v_mfma_f32_16x16x32_bf16 v[22:25], v[168:171], v[200:203], 0
	v_mfma_f32_16x16x32_bf16 v[18:21], v[176:179], v[200:203], 0
	v_mfma_f32_16x16x32_bf16 v[6:9], v[168:171], v[208:211], 0
	v_mfma_f32_16x16x32_bf16 v[2:5], v[176:179], v[208:211], 0
	v_mfma_f32_16x16x32_bf16 v[54:57], v[172:175], v[188:191], v[54:57]
	v_mfma_f32_16x16x32_bf16 v[50:53], v[180:183], v[188:191], v[50:53]
	v_mfma_f32_16x16x32_bf16 v[38:41], v[172:175], v[196:199], v[38:41]
	v_mfma_f32_16x16x32_bf16 v[34:37], v[180:183], v[196:199], v[34:37]
	v_mfma_f32_16x16x32_bf16 v[22:25], v[172:175], v[204:207], v[22:25]
	v_mfma_f32_16x16x32_bf16 v[18:21], v[180:183], v[204:207], v[18:21]
	v_mfma_f32_16x16x32_bf16 v[6:9], v[172:175], v[212:215], v[6:9]
	v_mfma_f32_16x16x32_bf16 v[2:5], v[180:183], v[212:215], v[2:5]
	s_barrier
	v_add_u32_e32 v164, s60, v147
	v_add_u32_e32 v180, s61, v147
	ds_read_b128 v[152:155], v164
	ds_read_b128 v[156:159], v164 offset:1024
	ds_read_b128 v[160:163], v164 offset:2048
	ds_read_b128 v[164:167], v164 offset:3072
	ds_read_b128 v[168:171], v180
	ds_read_b128 v[172:175], v180 offset:1024
	ds_read_b128 v[176:179], v180 offset:2048
	ds_read_b128 v[180:183], v180 offset:3072
	s_add_u32 s28, s28, 0x4000
	s_addc_u32 s29, s29, 0
	s_mov_b32 m0, s37
	ds_read_b128 v[184:187], v151 offset:32768
	ds_read_b128 v[188:191], v151 offset:33792
	ds_read_b128 v[192:195], v151 offset:34816
	ds_read_b128 v[196:199], v151 offset:35840
	ds_read_b128 v[200:203], v151 offset:36864
	ds_read_b128 v[204:207], v151 offset:37888
	ds_read_b128 v[208:211], v151 offset:38912
	ds_read_b128 v[212:215], v151 offset:39936
	global_load_lds_dwordx4 v130, s[28:29]
	s_mov_b32 m0, s40
	s_nop 0
	global_load_lds_dwordx4 v132, s[28:29]
	s_waitcnt vmcnt(8) lgkmcnt(0)
	s_barrier
	v_mfma_f32_16x16x32_bf16 v[126:129], v[152:155], v[184:187], v[126:129]
	v_mfma_f32_16x16x32_bf16 v[122:125], v[160:163], v[184:187], v[122:125]
	v_mfma_f32_16x16x32_bf16 v[110:113], v[152:155], v[192:195], v[110:113]
	v_mfma_f32_16x16x32_bf16 v[106:109], v[160:163], v[192:195], v[106:109]
	v_mfma_f32_16x16x32_bf16 v[94:97], v[152:155], v[200:203], v[94:97]
	v_mfma_f32_16x16x32_bf16 v[90:93], v[160:163], v[200:203], v[90:93]
	v_mfma_f32_16x16x32_bf16 v[78:81], v[152:155], v[208:211], v[78:81]
	v_mfma_f32_16x16x32_bf16 v[74:77], v[160:163], v[208:211], v[74:77]
	v_mfma_f32_16x16x32_bf16 v[126:129], v[156:159], v[188:191], v[126:129]
	v_mfma_f32_16x16x32_bf16 v[122:125], v[164:167], v[188:191], v[122:125]
	v_mfma_f32_16x16x32_bf16 v[110:113], v[156:159], v[196:199], v[110:113]
	v_mfma_f32_16x16x32_bf16 v[106:109], v[164:167], v[196:199], v[106:109]
	v_mfma_f32_16x16x32_bf16 v[94:97], v[156:159], v[204:207], v[94:97]
	v_mfma_f32_16x16x32_bf16 v[90:93], v[164:167], v[204:207], v[90:93]
	v_mfma_f32_16x16x32_bf16 v[78:81], v[156:159], v[212:215], v[78:81]
	v_mfma_f32_16x16x32_bf16 v[74:77], v[164:167], v[212:215], v[74:77]
	v_mfma_f32_16x16x32_bf16 v[118:121], v[168:171], v[184:187], v[118:121]
	v_mfma_f32_16x16x32_bf16 v[114:117], v[176:179], v[184:187], v[114:117]
	v_mfma_f32_16x16x32_bf16 v[102:105], v[168:171], v[192:195], v[102:105]
	v_mfma_f32_16x16x32_bf16 v[98:101], v[176:179], v[192:195], v[98:101]
	v_mfma_f32_16x16x32_bf16 v[86:89], v[168:171], v[200:203], v[86:89]
	v_mfma_f32_16x16x32_bf16 v[82:85], v[176:179], v[200:203], v[82:85]
	v_mfma_f32_16x16x32_bf16 v[70:73], v[168:171], v[208:211], v[70:73]
	v_mfma_f32_16x16x32_bf16 v[66:69], v[176:179], v[208:211], v[66:69]
	v_mfma_f32_16x16x32_bf16 v[118:121], v[172:175], v[188:191], v[118:121]
	v_mfma_f32_16x16x32_bf16 v[114:117], v[180:183], v[188:191], v[114:117]
	v_mfma_f32_16x16x32_bf16 v[102:105], v[172:175], v[196:199], v[102:105]
	v_mfma_f32_16x16x32_bf16 v[98:101], v[180:183], v[196:199], v[98:101]
	v_mfma_f32_16x16x32_bf16 v[86:89], v[172:175], v[204:207], v[86:89]
	v_mfma_f32_16x16x32_bf16 v[82:85], v[180:183], v[204:207], v[82:85]
	v_mfma_f32_16x16x32_bf16 v[70:73], v[172:175], v[212:215], v[70:73]
	v_mfma_f32_16x16x32_bf16 v[66:69], v[180:183], v[212:215], v[66:69]
	s_barrier
; #define PG8_STAGE(bufoff, gbase, voff) do { _Pragma("unroll") for (int _i = 0; _i < 2; ++_i) \
;         __builtin_amdgcn_global_load_lds((const unsigned*)((const char*)(gbase) + (voff)[_i]), (LAS unsigned*)(lds + (bufoff) + ldsw + _i * 8192), 16, 0, 0); } while (0)
; #define PG8_LDA(dst, b, h) do { _Pragma("unroll") for (int m = 0; m < 4; ++m) _Pragma("unroll") for (int k = 0; k < 2; ++k) dst[m][k] = *(const LAS bf16x8*)(lds + PG8_SA(b, h) + aoff + m * 2048 + k * 1024); } while (0)
; #define PG8_MMA(ai, bj, At, Bt) do { __builtin_amdgcn_s_setprio(1); _Pragma("unroll") for (int m = 0; m < 4; ++m) _Pragma("unroll") for (int n = 0; n < 2; ++n) _Pragma("unroll") for (int k = 0; k < 2; ++k) \
;         acc[ai][bj][m][n] = __builtin_amdgcn_mfma_f32_16x16x32_bf16(Bt[n][k], At[m][k], acc[ai][bj][m][n], 0, 0, 0); __builtin_amdgcn_s_setprio(0); } while (0)
; #define PG8_WAIT_V(n) asm volatile("s_waitcnt vmcnt(" #n ")" ::: "memory")
; #define PG8_WAIT_L(n) asm volatile("s_waitcnt lgkmcnt(" #n ")" ::: "memory")
; #define PG8_BAR __builtin_amdgcn_s_barrier()
; #define PG8_SCHED __builtin_amdgcn_sched_barrier(0)
; template <class Epi, class Sched, bool ABLK = false, bool ALIGN_EPI = true, bool SP2 = true, bool BBLK = true>
; __device__ __forceinline__ void gemm_phase(LAS unsigned char* lds, const Gemm g, const Sched& S, const Epi& E) {
;     ...
;             PG8_LDA(At, 1, 1); PG8_STAGE(PG8_SB(1, 0), b3, voffB); PG8_STAGE(PG8_SB(1, 1), b3 + hstepB, voffB); PG8_STAGE(PG8_SA(1, 0), a3, voffA);
;             PG8_WAIT_V(8); PG8_WAIT_L(0); PG8_BAR; PG8_MMA(1, 0, At, B0); PG8_MMA(1, 1, At, B1); PG8_BAR; PG8_SCHED;
	s_add_u32 s28, s26, 0x8000
	s_addc_u32 s29, s27, 0
	s_add_i32 s59, s60, s34
	s_mov_b32 m0, s59
	ds_read_b128 v[184:187], v151 offset:49152
	ds_read_b128 v[188:191], v151 offset:50176
	ds_read_b128 v[192:195], v151 offset:51200
	ds_read_b128 v[196:199], v151 offset:52224
	ds_read_b128 v[200:203], v151 offset:53248
	ds_read_b128 v[204:207], v151 offset:54272
	ds_read_b128 v[208:211], v151 offset:55296
	ds_read_b128 v[212:215], v151 offset:56320
	global_load_lds_dwordx4 v130, s[28:29]
	s_add_i32 m0, s59, 0x2000
	s_add_u32 s26, s26, 0xc000
	v_lshl_add_u64 v[216:217], s[28:29], 0, v[132:133]
	s_addc_u32 s27, s27, 0
	s_add_i32 s28, s61, s34
	global_load_lds_dwordx4 v[216:217], off
	s_mov_b32 m0, s28
	s_nop 0
	global_load_lds_dwordx4 v130, s[26:27]
	s_add_i32 m0, s28, 0x2000
	s_nop 0
	global_load_lds_dwordx4 v132, s[26:27]
	s_mov_b32 m0, s41
	s_nop 0
	global_load_lds_dwordx4 v130, s[24:25]
	s_mov_b32 m0, s42
	s_nop 0
	global_load_lds_dwordx4 v132, s[24:25]
	s_waitcnt vmcnt(8) lgkmcnt(0)
	s_barrier
	v_mfma_f32_16x16x32_bf16 v[62:65], v[152:155], v[184:187], v[62:65]
	v_mfma_f32_16x16x32_bf16 v[58:61], v[160:163], v[184:187], v[58:61]
	v_mfma_f32_16x16x32_bf16 v[46:49], v[152:155], v[192:195], v[46:49]
	v_mfma_f32_16x16x32_bf16 v[42:45], v[160:163], v[192:195], v[42:45]
	v_mfma_f32_16x16x32_bf16 v[30:33], v[152:155], v[200:203], v[30:33]
	v_mfma_f32_16x16x32_bf16 v[26:29], v[160:163], v[200:203], v[26:29]
	v_mfma_f32_16x16x32_bf16 v[14:17], v[152:155], v[208:211], v[14:17]
	v_mfma_f32_16x16x32_bf16 v[10:13], v[160:163], v[208:211], v[10:13]
	v_mfma_f32_16x16x32_bf16 v[62:65], v[156:159], v[188:191], v[62:65]
	v_mfma_f32_16x16x32_bf16 v[58:61], v[164:167], v[188:191], v[58:61]
	v_mfma_f32_16x16x32_bf16 v[46:49], v[156:159], v[196:199], v[46:49]
	v_mfma_f32_16x16x32_bf16 v[42:45], v[164:167], v[196:199], v[42:45]
	v_mfma_f32_16x16x32_bf16 v[30:33], v[156:159], v[204:207], v[30:33]
	v_mfma_f32_16x16x32_bf16 v[26:29], v[164:167], v[204:207], v[26:29]
	v_mfma_f32_16x16x32_bf16 v[14:17], v[156:159], v[212:215], v[14:17]
	v_mfma_f32_16x16x32_bf16 v[10:13], v[164:167], v[212:215], v[10:13]
	v_mfma_f32_16x16x32_bf16 v[54:57], v[168:171], v[184:187], v[54:57]
	v_mfma_f32_16x16x32_bf16 v[50:53], v[176:179], v[184:187], v[50:53]
	v_mfma_f32_16x16x32_bf16 v[38:41], v[168:171], v[192:195], v[38:41]
	v_mfma_f32_16x16x32_bf16 v[34:37], v[176:179], v[192:195], v[34:37]
	v_mfma_f32_16x16x32_bf16 v[22:25], v[168:171], v[200:203], v[22:25]
	v_mfma_f32_16x16x32_bf16 v[18:21], v[176:179], v[200:203], v[18:21]
	v_mfma_f32_16x16x32_bf16 v[6:9], v[168:171], v[208:211], v[6:9]
	v_mfma_f32_16x16x32_bf16 v[2:5], v[176:179], v[208:211], v[2:5]
	v_mfma_f32_16x16x32_bf16 v[54:57], v[172:175], v[188:191], v[54:57]
	v_mfma_f32_16x16x32_bf16 v[50:53], v[180:183], v[188:191], v[50:53]
	v_mfma_f32_16x16x32_bf16 v[38:41], v[172:175], v[196:199], v[38:41]
	v_mfma_f32_16x16x32_bf16 v[34:37], v[180:183], v[196:199], v[34:37]
	v_mfma_f32_16x16x32_bf16 v[22:25], v[172:175], v[204:207], v[22:25]
	v_mfma_f32_16x16x32_bf16 v[18:21], v[180:183], v[204:207], v[18:21]
	v_mfma_f32_16x16x32_bf16 v[6:9], v[172:175], v[212:215], v[6:9]
	v_mfma_f32_16x16x32_bf16 v[2:5], v[180:183], v[212:215], v[2:5]
	s_barrier
	s_add_u32 s22, s22, 0x10000
	s_addc_u32 s23, s23, 0
	s_cmp_ge_u32 s57, s44

; #define PG8_STAGE(bufoff, gbase, voff) do { _Pragma("unroll") for (int _i = 0; _i < 2; ++_i) \
;         __builtin_amdgcn_global_load_lds((const unsigned*)((const char*)(gbase) + (voff)[_i]), (LAS unsigned*)(lds + (bufoff) + ldsw + _i * 8192), 16, 0, 0); } while (0)
; #define PG8_LDA(dst, b, h) do { _Pragma("unroll") for (int m = 0; m < 4; ++m) _Pragma("unroll") for (int k = 0; k < 2; ++k) dst[m][k] = *(const LAS bf16x8*)(lds + PG8_SA(b, h) + aoff + m * 2048 + k * 1024); } while (0)
; #define PG8_LDB(dst, b, h) do { _Pragma("unroll") for (int n = 0; n < 2; ++n) _Pragma("unroll") for (int k = 0; k < 2; ++k) dst[n][k] = *(const LAS bf16x8*)(lds + PG8_SB(b, h) + boff + n * 2048 + k * 1024); } while (0)
; #define PG8_WAIT_V(n) asm volatile("s_waitcnt vmcnt(" #n ")" ::: "memory")
; #define PG8_WAIT_L(n) asm volatile("s_waitcnt lgkmcnt(" #n ")" ::: "memory")
; #define PG8_BAR __builtin_amdgcn_s_barrier()
; #define PG8_SCHED __builtin_amdgcn_sched_barrier(0)
; template <class Epi, class Sched, bool ABLK = false, bool ALIGN_EPI = true, bool SP2 = true, bool BBLK = true>
; __device__ __forceinline__ void gemm_phase(LAS unsigned char* lds, const Gemm g, const Sched& S, const Epi& E) {
;     ...
;         const bool has_next = S.next(ui + 1, nxt);
;         const int nt = cur.nt;
;         const char* nuA = has_next ? a_unit(nxt) : uA; const int ntbA = has_next ? nxt.k0 / BK : tbA; const char* nB = has_next ? (const char*)g.Bt + (size_t)nxt.pn * tstepB + b_k0(nxt.k0) : cB;
;         for (int t = 0; t < nt; t += 2) {
;             const bool last = (t == nt - 2);
;             const char* a1 = a_tile(uA, tbA + t + 1);
;             const char* a2 = last ? a_tile(nuA, ntbA) : a_tile(uA, tbA + t + 2); const char* b2 = last ? nB : cB + (size_t)(t + 2) * kstepB;
;             const char* a3 = last ? a_tile(nuA, ntbA + 1) : a_tile(uA, tbA + t + 3); const char* b3 = b2 + kstepB;
;             if (last && has_next) S.a_ready(nxt);
;             if constexpr (SP2) {
;             PG8_LDB(B0, 0, 0); PG8_LDB(B1, 0, 1); PG8_SCHED; PG8_LDA(At, 0, 0); PG8_STAGE(PG8_SA(1, 1), a1 + hstepA, voffA);
;             PG8_WAIT_V(8); PG8_WAIT_L(0); PG8_BAR; PG8_MMA(0, 0, At, B0); PG8_MMA(0, 1, At, B1); PG8_BAR; PG8_SCHED;
;             PG8_LDA(At, 0, 1); PG8_STAGE(PG8_SB(0, 0), b2, voffB); PG8_STAGE(PG8_SB(0, 1), b2 + hstepB, voffB); PG8_STAGE(PG8_SA(0, 0), a2, voffA);
.LBB0_1354:
	s_ashr_i32 s21, s20, 31
	s_lshl_b64 s[4:5], s[20:21], 20
	s_add_u32 s24, s76, s4
	s_addc_u32 s25, s33, s5
	s_and_b64 s[4:5], s[26:27], exec
	s_cselect_b32 s4, s25, s37
	s_cselect_b32 s5, s24, s36
	s_ashr_i32 s23, s22, 31
	s_lshl_b64 s[28:29], s[22:23], 20
	s_add_u32 s28, s1, s28
	s_addc_u32 s29, s48, s29
	s_and_b64 s[42:43], s[26:27], exec
	s_cselect_b32 s21, s29, s41
	s_cselect_b32 s23, s28, s40
	s_add_u32 s56, s5, 0x80
	s_addc_u32 s57, s4, 0
	s_add_u32 s59, s40, 0x10000
	v_mov_b32_e32 v2, 0
	s_addc_u32 s64, s41, 0
	v_lshl_add_u64 v[148:149], s[36:37], 0, v[144:145]
	v_lshl_add_u64 v[150:151], s[36:37], 0, v[146:147]
	s_mov_b32 s65, -2
	s_mov_b64 s[40:41], 0
	ds_read_b128 v[152:155], v163
	ds_read_b128 v[156:159], v163 offset:1024
	ds_read_b128 v[166:169], v163 offset:2048
	ds_read_b128 v[170:173], v163 offset:3072
	ds_read_b128 v[174:177], v164
	ds_read_b128 v[178:181], v164 offset:1024
	ds_read_b128 v[182:185], v164 offset:2048
	ds_read_b128 v[186:189], v164 offset:3072
	s_add_u32 s42, s36, s40
	s_addc_u32 s43, s37, s41
	s_add_u32 s46, s42, 0x100
	s_addc_u32 s47, s43, 0
	s_add_u32 s42, s42, 0x180
	s_addc_u32 s43, s43, 0
	s_cmpk_eq_i32 s40, 0xf00
	s_cselect_b32 s43, s57, s43
	s_cselect_b32 s42, s56, s42
	s_cselect_b32 s45, s21, s64
	s_cselect_b32 s44, s23, s59
	s_cselect_b32 s47, s4, s47
	s_cselect_b32 s46, s5, s46
	v_lshl_add_u64 v[222:223], v[148:149], 0, s[40:41]
	s_add_i32 m0, s31, 0xc000
	ds_read_b128 v[190:193], v165
	ds_read_b128 v[194:197], v165 offset:1024
	ds_read_b128 v[198:201], v165 offset:2048
	ds_read_b128 v[202:205], v165 offset:3072
	ds_read_b128 v[206:209], v165 offset:4096
	ds_read_b128 v[210:213], v165 offset:5120
	ds_read_b128 v[214:217], v165 offset:6144
	ds_read_b128 v[218:221], v165 offset:7168
	global_load_lds_dwordx4 v[222:223], off
	v_lshl_add_u64 v[222:223], v[150:151], 0, s[40:41]
	s_add_i32 m0, s31, 0xe000
	s_nop 0
	global_load_lds_dwordx4 v[222:223], off
	s_waitcnt vmcnt(8) lgkmcnt(0)
	s_barrier
	v_mfma_f32_16x16x32_bf16 v[126:129], v[152:155], v[190:193], 0
	v_mfma_f32_16x16x32_bf16 v[122:125], v[166:169], v[190:193], 0
	v_mfma_f32_16x16x32_bf16 v[110:113], v[152:155], v[198:201], 0
	v_mfma_f32_16x16x32_bf16 v[106:109], v[166:169], v[198:201], 0
	v_mfma_f32_16x16x32_bf16 v[94:97], v[152:155], v[206:209], 0
	v_mfma_f32_16x16x32_bf16 v[90:93], v[166:169], v[206:209], 0
	v_mfma_f32_16x16x32_bf16 v[78:81], v[152:155], v[214:217], 0
	v_mfma_f32_16x16x32_bf16 v[74:77], v[166:169], v[214:217], 0
	v_mfma_f32_16x16x32_bf16 v[126:129], v[156:159], v[194:197], v[126:129]
	v_mfma_f32_16x16x32_bf16 v[122:125], v[170:173], v[194:197], v[122:125]
	v_mfma_f32_16x16x32_bf16 v[110:113], v[156:159], v[202:205], v[110:113]
	v_mfma_f32_16x16x32_bf16 v[106:109], v[170:173], v[202:205], v[106:109]
	v_mfma_f32_16x16x32_bf16 v[94:97], v[156:159], v[210:213], v[94:97]
	v_mfma_f32_16x16x32_bf16 v[90:93], v[170:173], v[210:213], v[90:93]
	v_mfma_f32_16x16x32_bf16 v[78:81], v[156:159], v[218:221], v[78:81]
	v_mfma_f32_16x16x32_bf16 v[74:77], v[170:173], v[218:221], v[74:77]
	v_mfma_f32_16x16x32_bf16 v[118:121], v[174:177], v[190:193], 0
	v_mfma_f32_16x16x32_bf16 v[114:117], v[182:185], v[190:193], 0
	v_mfma_f32_16x16x32_bf16 v[102:105], v[174:177], v[198:201], 0
	v_mfma_f32_16x16x32_bf16 v[98:101], v[182:185], v[198:201], 0
	v_mfma_f32_16x16x32_bf16 v[86:89], v[174:177], v[206:209], 0
	v_mfma_f32_16x16x32_bf16 v[82:85], v[182:185], v[206:209], 0
	v_mfma_f32_16x16x32_bf16 v[70:73], v[174:177], v[214:217], 0
	v_mfma_f32_16x16x32_bf16 v[66:69], v[182:185], v[214:217], 0
	v_mfma_f32_16x16x32_bf16 v[118:121], v[178:181], v[194:197], v[118:121]
	v_mfma_f32_16x16x32_bf16 v[114:117], v[186:189], v[194:197], v[114:117]
	v_mfma_f32_16x16x32_bf16 v[102:105], v[178:181], v[202:205], v[102:105]
	v_mfma_f32_16x16x32_bf16 v[98:101], v[186:189], v[202:205], v[98:101]
	v_mfma_f32_16x16x32_bf16 v[86:89], v[178:181], v[210:213], v[86:89]
	v_mfma_f32_16x16x32_bf16 v[82:85], v[186:189], v[210:213], v[82:85]
	v_mfma_f32_16x16x32_bf16 v[70:73], v[178:181], v[218:221], v[70:73]
	v_mfma_f32_16x16x32_bf16 v[66:69], v[186:189], v[218:221], v[66:69]
	s_barrier
	s_add_i32 s66, s72, s49
	s_mov_b32 m0, s66
	ds_read_b128 v[190:193], v165 offset:16384
	ds_read_b128 v[194:197], v165 offset:17408
	ds_read_b128 v[198:201], v165 offset:18432
	ds_read_b128 v[202:205], v165 offset:19456
	ds_read_b128 v[206:209], v165 offset:20480
	ds_read_b128 v[210:213], v165 offset:21504
	ds_read_b128 v[214:217], v165 offset:22528
	ds_read_b128 v[218:221], v165 offset:23552
	global_load_lds_dwordx4 v134, s[44:45]
	s_add_i32 m0, s66, 0x2000
	s_add_u32 s66, s44, 0x4000
	s_addc_u32 s67, s45, 0
	s_add_i32 s75, s73, s49
	global_load_lds_dwordx4 v130, s[44:45]
	s_mov_b32 m0, s75
	s_nop 0
	global_load_lds_dwordx4 v134, s[66:67]
	s_add_i32 m0, s75, 0x2000
	s_nop 0
	global_load_lds_dwordx4 v130, s[66:67]
	s_mov_b32 m0, s31
	s_nop 0
	global_load_lds_dwordx4 v136, s[46:47]
	s_mov_b32 m0, s35
	s_nop 0
	global_load_lds_dwordx4 v132, s[46:47]
	s_waitcnt vmcnt(8) lgkmcnt(0)
	s_barrier
; #define PG8_STAGE(bufoff, gbase, voff) do { _Pragma("unroll") for (int _i = 0; _i < 2; ++_i) \
;         __builtin_amdgcn_global_load_lds((const unsigned*)((const char*)(gbase) + (voff)[_i]), (LAS unsigned*)(lds + (bufoff) + ldsw + _i * 8192), 16, 0, 0); } while (0)
; #define PG8_LDA(dst, b, h) do { _Pragma("unroll") for (int m = 0; m < 4; ++m) _Pragma("unroll") for (int k = 0; k < 2; ++k) dst[m][k] = *(const LAS bf16x8*)(lds + PG8_SA(b, h) + aoff + m * 2048 + k * 1024); } while (0)
; #define PG8_LDB(dst, b, h) do { _Pragma("unroll") for (int n = 0; n < 2; ++n) _Pragma("unroll") for (int k = 0; k < 2; ++k) dst[n][k] = *(const LAS bf16x8*)(lds + PG8_SB(b, h) + boff + n * 2048 + k * 1024); } while (0)
; #define PG8_MMA(ai, bj, At, Bt) do { __builtin_amdgcn_s_setprio(1); _Pragma("unroll") for (int m = 0; m < 4; ++m) _Pragma("unroll") for (int n = 0; n < 2; ++n) _Pragma("unroll") for (int k = 0; k < 2; ++k) \
;         acc[ai][bj][m][n] = __builtin_amdgcn_mfma_f32_16x16x32_bf16(Bt[n][k], At[m][k], acc[ai][bj][m][n], 0, 0, 0); __builtin_amdgcn_s_setprio(0); } while (0)
; #define PG8_WAIT_V(n) asm volatile("s_waitcnt vmcnt(" #n ")" ::: "memory")
; #define PG8_WAIT_L(n) asm volatile("s_waitcnt lgkmcnt(" #n ")" ::: "memory")
; #define PG8_BAR __builtin_amdgcn_s_barrier()
; #define PG8_SCHED __builtin_amdgcn_sched_barrier(0)
; template <class Epi, class Sched, bool ABLK = false, bool ALIGN_EPI = true, bool SP2 = true, bool BBLK = true>
; __device__ __forceinline__ void gemm_phase(LAS unsigned char* lds, const Gemm g, const Sched& S, const Epi& E) {
;     ...
;             PG8_WAIT_V(8); PG8_WAIT_L(0); PG8_BAR; PG8_MMA(1, 0, At, B0); PG8_MMA(1, 1, At, B1); PG8_BAR; PG8_SCHED;
;             PG8_LDB(B0, 1, 0); PG8_LDB(B1, 1, 1); PG8_SCHED; PG8_LDA(At, 1, 0); PG8_STAGE(PG8_SA(0, 1), a2 + hstepA, voffA);
;             PG8_WAIT_V(8); PG8_WAIT_L(0); PG8_BAR; PG8_MMA(0, 0, At, B0); PG8_MMA(0, 1, At, B1); PG8_BAR; PG8_SCHED;
	v_mfma_f32_16x16x32_bf16 v[62:65], v[152:155], v[190:193], 0
	v_mfma_f32_16x16x32_bf16 v[58:61], v[166:169], v[190:193], 0
	v_mfma_f32_16x16x32_bf16 v[46:49], v[152:155], v[198:201], 0
	v_mfma_f32_16x16x32_bf16 v[42:45], v[166:169], v[198:201], 0
	v_mfma_f32_16x16x32_bf16 v[30:33], v[152:155], v[206:209], 0
	v_mfma_f32_16x16x32_bf16 v[26:29], v[166:169], v[206:209], 0
	v_mfma_f32_16x16x32_bf16 v[14:17], v[152:155], v[214:217], 0
	v_mfma_f32_16x16x32_bf16 v[10:13], v[166:169], v[214:217], 0
	v_mfma_f32_16x16x32_bf16 v[62:65], v[156:159], v[194:197], v[62:65]
	v_mfma_f32_16x16x32_bf16 v[58:61], v[170:173], v[194:197], v[58:61]
	v_mfma_f32_16x16x32_bf16 v[46:49], v[156:159], v[202:205], v[46:49]
	v_mfma_f32_16x16x32_bf16 v[42:45], v[170:173], v[202:205], v[42:45]
	v_mfma_f32_16x16x32_bf16 v[30:33], v[156:159], v[210:213], v[30:33]
	v_mfma_f32_16x16x32_bf16 v[26:29], v[170:173], v[210:213], v[26:29]
	v_mfma_f32_16x16x32_bf16 v[14:17], v[156:159], v[218:221], v[14:17]
	v_mfma_f32_16x16x32_bf16 v[10:13], v[170:173], v[218:221], v[10:13]
	v_mfma_f32_16x16x32_bf16 v[54:57], v[174:177], v[190:193], 0
	v_mfma_f32_16x16x32_bf16 v[50:53], v[182:185], v[190:193], 0
	v_mfma_f32_16x16x32_bf16 v[38:41], v[174:177], v[198:201], 0
	v_mfma_f32_16x16x32_bf16 v[34:37], v[182:185], v[198:201], 0
	v_mfma_f32_16x16x32_bf16 v[22:25], v[174:177], v[206:209], 0
	v_mfma_f32_16x16x32_bf16 v[18:21], v[182:185], v[206:209], 0
	v_mfma_f32_16x16x32_bf16 v[6:9], v[174:177], v[214:217], 0
	v_mfma_f32_16x16x32_bf16 v[2:5], v[182:185], v[214:217], 0
	v_mfma_f32_16x16x32_bf16 v[54:57], v[178:181], v[194:197], v[54:57]
	v_mfma_f32_16x16x32_bf16 v[50:53], v[186:189], v[194:197], v[50:53]
	v_mfma_f32_16x16x32_bf16 v[38:41], v[178:181], v[202:205], v[38:41]
	v_mfma_f32_16x16x32_bf16 v[34:37], v[186:189], v[202:205], v[34:37]
	v_mfma_f32_16x16x32_bf16 v[22:25], v[178:181], v[210:213], v[22:25]
	v_mfma_f32_16x16x32_bf16 v[18:21], v[186:189], v[210:213], v[18:21]
	v_mfma_f32_16x16x32_bf16 v[6:9], v[178:181], v[218:221], v[6:9]
	v_mfma_f32_16x16x32_bf16 v[2:5], v[186:189], v[218:221], v[2:5]
	s_barrier
	v_add_u32_e32 v138, s60, v161
	ds_read_b128 v[152:155], v138
	ds_read_b128 v[156:159], v138 offset:1024
	ds_read_b128 v[166:169], v138 offset:2048
	ds_read_b128 v[170:173], v138 offset:3072
	v_add_u32_e32 v138, s61, v161
	ds_read_b128 v[174:177], v138
	ds_read_b128 v[178:181], v138 offset:1024
	ds_read_b128 v[182:185], v138 offset:2048
	ds_read_b128 v[186:189], v138 offset:3072
	s_add_u32 s46, s46, 0x80000
	s_addc_u32 s47, s47, 0
	s_mov_b32 m0, s50
	ds_read_b128 v[190:193], v165 offset:32768
	ds_read_b128 v[194:197], v165 offset:33792
	ds_read_b128 v[198:201], v165 offset:34816
	ds_read_b128 v[202:205], v165 offset:35840
	ds_read_b128 v[206:209], v165 offset:36864
	ds_read_b128 v[210:213], v165 offset:37888
	ds_read_b128 v[214:217], v165 offset:38912
	ds_read_b128 v[218:221], v165 offset:39936
	global_load_lds_dwordx4 v136, s[46:47]
	s_mov_b32 m0, s51
	s_nop 0
	global_load_lds_dwordx4 v132, s[46:47]
	s_waitcnt vmcnt(8) lgkmcnt(0)
	s_barrier
	v_mfma_f32_16x16x32_bf16 v[126:129], v[152:155], v[190:193], v[126:129]
	v_mfma_f32_16x16x32_bf16 v[122:125], v[166:169], v[190:193], v[122:125]
	v_mfma_f32_16x16x32_bf16 v[110:113], v[152:155], v[198:201], v[110:113]
	v_mfma_f32_16x16x32_bf16 v[106:109], v[166:169], v[198:201], v[106:109]
	v_mfma_f32_16x16x32_bf16 v[94:97], v[152:155], v[206:209], v[94:97]
	v_mfma_f32_16x16x32_bf16 v[90:93], v[166:169], v[206:209], v[90:93]
	v_mfma_f32_16x16x32_bf16 v[78:81], v[152:155], v[214:217], v[78:81]
	v_mfma_f32_16x16x32_bf16 v[74:77], v[166:169], v[214:217], v[74:77]
	v_mfma_f32_16x16x32_bf16 v[126:129], v[156:159], v[194:197], v[126:129]
	v_mfma_f32_16x16x32_bf16 v[122:125], v[170:173], v[194:197], v[122:125]
	v_mfma_f32_16x16x32_bf16 v[110:113], v[156:159], v[202:205], v[110:113]
	v_mfma_f32_16x16x32_bf16 v[106:109], v[170:173], v[202:205], v[106:109]
	v_mfma_f32_16x16x32_bf16 v[94:97], v[156:159], v[210:213], v[94:97]
	v_mfma_f32_16x16x32_bf16 v[90:93], v[170:173], v[210:213], v[90:93]
	v_mfma_f32_16x16x32_bf16 v[78:81], v[156:159], v[218:221], v[78:81]
	v_mfma_f32_16x16x32_bf16 v[74:77], v[170:173], v[218:221], v[74:77]
	v_mfma_f32_16x16x32_bf16 v[118:121], v[174:177], v[190:193], v[118:121]
	v_mfma_f32_16x16x32_bf16 v[114:117], v[182:185], v[190:193], v[114:117]
	v_mfma_f32_16x16x32_bf16 v[102:105], v[174:177], v[198:201], v[102:105]
	v_mfma_f32_16x16x32_bf16 v[98:101], v[182:185], v[198:201], v[98:101]
	v_mfma_f32_16x16x32_bf16 v[86:89], v[174:177], v[206:209], v[86:89]
	v_mfma_f32_16x16x32_bf16 v[82:85], v[182:185], v[206:209], v[82:85]
	v_mfma_f32_16x16x32_bf16 v[70:73], v[174:177], v[214:217], v[70:73]
	v_mfma_f32_16x16x32_bf16 v[66:69], v[182:185], v[214:217], v[66:69]
	v_mfma_f32_16x16x32_bf16 v[118:121], v[178:181], v[194:197], v[118:121]
	v_mfma_f32_16x16x32_bf16 v[114:117], v[186:189], v[194:197], v[114:117]
	v_mfma_f32_16x16x32_bf16 v[102:105], v[178:181], v[202:205], v[102:105]
	v_mfma_f32_16x16x32_bf16 v[98:101], v[186:189], v[202:205], v[98:101]
	v_mfma_f32_16x16x32_bf16 v[86:89], v[178:181], v[210:213], v[86:89]
	v_mfma_f32_16x16x32_bf16 v[82:85], v[186:189], v[210:213], v[82:85]
	v_mfma_f32_16x16x32_bf16 v[70:73], v[178:181], v[218:221], v[70:73]
	v_mfma_f32_16x16x32_bf16 v[66:69], v[186:189], v[218:221], v[66:69]
	s_barrier
; #define PG8_STAGE(bufoff, gbase, voff) do { _Pragma("unroll") for (int _i = 0; _i < 2; ++_i) \
;         __builtin_amdgcn_global_load_lds((const unsigned*)((const char*)(gbase) + (voff)[_i]), (LAS unsigned*)(lds + (bufoff) + ldsw + _i * 8192), 16, 0, 0); } while (0)
; #define PG8_LDA(dst, b, h) do { _Pragma("unroll") for (int m = 0; m < 4; ++m) _Pragma("unroll") for (int k = 0; k < 2; ++k) dst[m][k] = *(const LAS bf16x8*)(lds + PG8_SA(b, h) + aoff + m * 2048 + k * 1024); } while (0)
; #define PG8_MMA(ai, bj, At, Bt) do { __builtin_amdgcn_s_setprio(1); _Pragma("unroll") for (int m = 0; m < 4; ++m) _Pragma("unroll") for (int n = 0; n < 2; ++n) _Pragma("unroll") for (int k = 0; k < 2; ++k) \
;         acc[ai][bj][m][n] = __builtin_amdgcn_mfma_f32_16x16x32_bf16(Bt[n][k], At[m][k], acc[ai][bj][m][n], 0, 0, 0); __builtin_amdgcn_s_setprio(0); } while (0)
; #define PG8_WAIT_V(n) asm volatile("s_waitcnt vmcnt(" #n ")" ::: "memory")
; #define PG8_WAIT_L(n) asm volatile("s_waitcnt lgkmcnt(" #n ")" ::: "memory")
; #define PG8_BAR __builtin_amdgcn_s_barrier()
; #define PG8_SCHED __builtin_amdgcn_sched_barrier(0)
; template <class Epi, class Sched, bool ABLK = false, bool ALIGN_EPI = true, bool SP2 = true, bool BBLK = true>
; __device__ __forceinline__ void gemm_phase(LAS unsigned char* lds, const Gemm g, const Sched& S, const Epi& E) {
;     ...
;             PG8_LDA(At, 1, 1); PG8_STAGE(PG8_SB(1, 0), b3, voffB); PG8_STAGE(PG8_SB(1, 1), b3 + hstepB, voffB); PG8_STAGE(PG8_SA(1, 0), a3, voffA);
;             PG8_WAIT_V(8); PG8_WAIT_L(0); PG8_BAR; PG8_MMA(1, 0, At, B0); PG8_MMA(1, 1, At, B1); PG8_BAR; PG8_SCHED;
	s_add_u32 s46, s44, 0x8000
	s_addc_u32 s47, s45, 0
	s_add_i32 s66, s60, s49
	s_mov_b32 m0, s66
	ds_read_b128 v[190:193], v165 offset:49152
	ds_read_b128 v[194:197], v165 offset:50176
	ds_read_b128 v[198:201], v165 offset:51200
	ds_read_b128 v[202:205], v165 offset:52224
	ds_read_b128 v[206:209], v165 offset:53248
	ds_read_b128 v[210:213], v165 offset:54272
	ds_read_b128 v[214:217], v165 offset:55296
	ds_read_b128 v[218:221], v165 offset:56320
	global_load_lds_dwordx4 v134, s[46:47]
	s_add_i32 m0, s66, 0x2000
	s_add_u32 s44, s44, 0xc000
	v_lshl_add_u64 v[222:223], s[46:47], 0, v[130:131]
	s_addc_u32 s45, s45, 0
	s_add_i32 s46, s61, s49
	global_load_lds_dwordx4 v[222:223], off
	s_mov_b32 m0, s46
	s_nop 0
	global_load_lds_dwordx4 v134, s[44:45]
	s_add_i32 m0, s46, 0x2000
	s_nop 0
	global_load_lds_dwordx4 v130, s[44:45]
	s_mov_b32 m0, s54
	s_nop 0
	global_load_lds_dwordx4 v136, s[42:43]
	s_mov_b32 m0, s55
	s_nop 0
	global_load_lds_dwordx4 v132, s[42:43]
	s_waitcnt vmcnt(8) lgkmcnt(0)
	s_barrier
	v_mfma_f32_16x16x32_bf16 v[62:65], v[152:155], v[190:193], v[62:65]
	v_mfma_f32_16x16x32_bf16 v[58:61], v[166:169], v[190:193], v[58:61]
	v_mfma_f32_16x16x32_bf16 v[46:49], v[152:155], v[198:201], v[46:49]
	v_mfma_f32_16x16x32_bf16 v[42:45], v[166:169], v[198:201], v[42:45]
	v_mfma_f32_16x16x32_bf16 v[30:33], v[152:155], v[206:209], v[30:33]
	v_mfma_f32_16x16x32_bf16 v[26:29], v[166:169], v[206:209], v[26:29]
	v_mfma_f32_16x16x32_bf16 v[14:17], v[152:155], v[214:217], v[14:17]
	v_mfma_f32_16x16x32_bf16 v[10:13], v[166:169], v[214:217], v[10:13]
	v_mfma_f32_16x16x32_bf16 v[62:65], v[156:159], v[194:197], v[62:65]
	v_mfma_f32_16x16x32_bf16 v[58:61], v[170:173], v[194:197], v[58:61]
	v_mfma_f32_16x16x32_bf16 v[46:49], v[156:159], v[202:205], v[46:49]
	v_mfma_f32_16x16x32_bf16 v[42:45], v[170:173], v[202:205], v[42:45]
	v_mfma_f32_16x16x32_bf16 v[30:33], v[156:159], v[210:213], v[30:33]
	v_mfma_f32_16x16x32_bf16 v[26:29], v[170:173], v[210:213], v[26:29]
	v_mfma_f32_16x16x32_bf16 v[14:17], v[156:159], v[218:221], v[14:17]
	v_mfma_f32_16x16x32_bf16 v[10:13], v[170:173], v[218:221], v[10:13]
	v_mfma_f32_16x16x32_bf16 v[54:57], v[174:177], v[190:193], v[54:57]
	v_mfma_f32_16x16x32_bf16 v[50:53], v[182:185], v[190:193], v[50:53]
	v_mfma_f32_16x16x32_bf16 v[38:41], v[174:177], v[198:201], v[38:41]
	v_mfma_f32_16x16x32_bf16 v[34:37], v[182:185], v[198:201], v[34:37]
	v_mfma_f32_16x16x32_bf16 v[22:25], v[174:177], v[206:209], v[22:25]
	v_mfma_f32_16x16x32_bf16 v[18:21], v[182:185], v[206:209], v[18:21]
	v_mfma_f32_16x16x32_bf16 v[6:9], v[174:177], v[214:217], v[6:9]
	v_mfma_f32_16x16x32_bf16 v[2:5], v[182:185], v[214:217], v[2:5]
	v_mfma_f32_16x16x32_bf16 v[54:57], v[178:181], v[194:197], v[54:57]
	v_mfma_f32_16x16x32_bf16 v[50:53], v[186:189], v[194:197], v[50:53]
	v_mfma_f32_16x16x32_bf16 v[38:41], v[178:181], v[202:205], v[38:41]
	v_mfma_f32_16x16x32_bf16 v[34:37], v[186:189], v[202:205], v[34:37]
	v_mfma_f32_16x16x32_bf16 v[22:25], v[178:181], v[210:213], v[22:25]
	v_mfma_f32_16x16x32_bf16 v[18:21], v[186:189], v[210:213], v[18:21]
	v_mfma_f32_16x16x32_bf16 v[6:9], v[178:181], v[218:221], v[6:9]
	v_mfma_f32_16x16x32_bf16 v[2:5], v[186:189], v[218:221], v[2:5]
	s_barrier
	s_add_i32 s65, s65, 2
	s_add_u32 s40, s40, 0x100
	s_addc_u32 s41, s41, 0
	s_add_u32 s59, s59, 0x10000
	s_addc_u32 s64, s64, 0
	s_cmp_gt_u32 s65, 29

; #define PG8_STAGE(bufoff, gbase, voff) do { _Pragma("unroll") for (int _i = 0; _i < 2; ++_i) \
;         __builtin_amdgcn_global_load_lds((const unsigned*)((const char*)(gbase) + (voff)[_i]), (LAS unsigned*)(lds + (bufoff) + ldsw + _i * 8192), 16, 0, 0); } while (0)
; #define PG8_LDA(dst, b, h) do { _Pragma("unroll") for (int m = 0; m < 4; ++m) _Pragma("unroll") for (int k = 0; k < 2; ++k) dst[m][k] = *(const LAS bf16x8*)(lds + PG8_SA(b, h) + aoff + m * 2048 + k * 1024); } while (0)
; #define PG8_LDB(dst, b, h) do { _Pragma("unroll") for (int n = 0; n < 2; ++n) _Pragma("unroll") for (int k = 0; k < 2; ++k) dst[n][k] = *(const LAS bf16x8*)(lds + PG8_SB(b, h) + boff + n * 2048 + k * 1024); } while (0)
; #define PG8_WAIT_V(n) asm volatile("s_waitcnt vmcnt(" #n ")" ::: "memory")
; #define PG8_WAIT_L(n) asm volatile("s_waitcnt lgkmcnt(" #n ")" ::: "memory")
; #define PG8_BAR __builtin_amdgcn_s_barrier()
; #define PG8_SCHED __builtin_amdgcn_sched_barrier(0)
; template <class Epi, class Sched, bool ABLK = false, bool ALIGN_EPI = true, bool SP2 = true, bool BBLK = true>
; __device__ __forceinline__ void gemm_phase(LAS unsigned char* lds, const Gemm g, const Sched& S, const Epi& E) {
;     ...
;         const bool has_next = S.next(ui + 1, nxt);
;         const int nt = cur.nt;
;         const char* nuA = has_next ? a_unit(nxt) : uA; const int ntbA = has_next ? nxt.k0 / BK : tbA; const char* nB = has_next ? (const char*)g.Bt + (size_t)nxt.pn * tstepB + b_k0(nxt.k0) : cB;
;         for (int t = 0; t < nt; t += 2) {
;             const bool last = (t == nt - 2);
;             const char* a1 = a_tile(uA, tbA + t + 1);
;             const char* a2 = last ? a_tile(nuA, ntbA) : a_tile(uA, tbA + t + 2); const char* b2 = last ? nB : cB + (size_t)(t + 2) * kstepB;
;             const char* a3 = last ? a_tile(nuA, ntbA + 1) : a_tile(uA, tbA + t + 3); const char* b3 = b2 + kstepB;
;             if (last && has_next) S.a_ready(nxt);
;             if constexpr (SP2) {
;             PG8_LDB(B0, 0, 0); PG8_LDB(B1, 0, 1); PG8_SCHED; PG8_LDA(At, 0, 0); PG8_STAGE(PG8_SA(1, 1), a1 + hstepA, voffA);
;             PG8_WAIT_V(8); PG8_WAIT_L(0); PG8_BAR; PG8_MMA(0, 0, At, B0); PG8_MMA(0, 1, At, B1); PG8_BAR; PG8_SCHED;
;             PG8_LDA(At, 0, 1); PG8_STAGE(PG8_SB(0, 0), b2, voffB); PG8_STAGE(PG8_SB(0, 1), b2 + hstepB, voffB); PG8_STAGE(PG8_SA(0, 0), a2, voffA);
.LBB0_1715:
	s_ashr_i32 s81, s80, 31
	s_andn2_b64 vcc, exec, s[4:5]
	s_lshl_b64 s[20:21], s[80:81], 20
	s_add_u32 s20, s1, s20
	s_addc_u32 s21, s36, s21
	s_and_b64 s[22:23], s[4:5], exec
	s_cselect_b32 s31, s21, s29
	s_cselect_b32 s49, s20, s28
	s_ashr_i32 s22, s63, 31
	s_lshr_b32 s22, s22, 26
	s_add_i32 s22, s63, s22
	s_ashr_i32 s22, s22, 6
	s_and_b64 s[24:25], s[4:5], exec
	s_cselect_b32 s34, s22, s30
	s_ashr_i32 s79, s78, 31
	s_lshl_b64 s[24:25], s[78:79], 20
	s_add_u32 s35, s37, s24
	s_addc_u32 s50, s38, s25
	s_ashr_i32 s23, s22, 31
	s_lshl_b64 s[24:25], s[22:23], 15
	s_add_u32 s24, s35, s24
	s_addc_u32 s25, s50, s25
	v_cndmask_b32_e64 v2, 0, 1, s[4:5]
	s_and_b64 s[4:5], s[4:5], exec
	s_cselect_b32 s4, s25, s27
	s_cselect_b32 s5, s24, s26
	s_ashr_i32 s35, s34, 31
	s_lshl_b64 s[34:35], s[34:35], 7
	s_add_u32 s23, s49, s34
	s_addc_u32 s49, s31, s35
	s_add_u32 s50, s23, 0x80
	s_addc_u32 s51, s49, 0
	s_add_u32 s52, s26, 0x10000
	s_addc_u32 s53, s27, 0
	s_ashr_i32 s31, s30, 31
	v_cmp_ne_u32_e64 s[10:11], 1, v2
	s_lshl_b64 s[26:27], s[30:31], 7
	v_lshl_add_u64 v[2:3], s[28:29], 0, v[142:143]
	s_add_u32 s54, s28, s26
	v_lshl_add_u64 v[146:147], v[2:3], 0, s[26:27]
	v_lshl_add_u64 v[2:3], s[28:29], 0, v[144:145]
	s_addc_u32 s55, s29, s27
	v_lshl_add_u64 v[148:149], v[2:3], 0, s[26:27]
	s_lshl_b32 s26, s47, 7
	s_addk_i32 s26, 0xfc00
	v_mov_b32_e32 v2, 0
	s_add_u32 s56, s26, 0x300
	s_mov_b32 s57, 0
	s_mov_b64 s[26:27], 0
	ds_read_b128 v[156:159], v152
	ds_read_b128 v[160:163], v152 offset:1024
	ds_read_b128 v[164:167], v152 offset:2048
	ds_read_b128 v[168:171], v152 offset:3072
	ds_read_b128 v[172:175], v153
	ds_read_b128 v[176:179], v153 offset:1024
	ds_read_b128 v[180:183], v153 offset:2048
	ds_read_b128 v[184:187], v153 offset:3072
	s_add_u32 s28, s54, s26
	s_addc_u32 s29, s55, s27
	s_add_u32 s34, s28, 0x100
	s_addc_u32 s35, s29, 0
	s_add_i32 s57, s57, 2
	s_add_u32 s28, s28, 0x180
	s_addc_u32 s29, s29, 0
	s_cmp_eq_u32 s56, s26
	s_cselect_b32 s29, s51, s29
	s_cselect_b32 s28, s50, s28
	s_cselect_b32 s31, s4, s53
	s_cselect_b32 s30, s5, s52
	s_cselect_b32 s35, s49, s35
	s_cselect_b32 s34, s23, s34
	v_lshl_add_u64 v[220:221], v[146:147], 0, s[26:27]
	s_add_i32 m0, s40, 0xc000
	ds_read_b128 v[188:191], v154
	ds_read_b128 v[192:195], v154 offset:1024
	ds_read_b128 v[196:199], v154 offset:2048
	ds_read_b128 v[200:203], v154 offset:3072
	ds_read_b128 v[204:207], v154 offset:4096
	ds_read_b128 v[208:211], v154 offset:5120
	ds_read_b128 v[212:215], v154 offset:6144
	ds_read_b128 v[216:219], v154 offset:7168
	global_load_lds_dwordx4 v[220:221], off
	v_lshl_add_u64 v[220:221], v[148:149], 0, s[26:27]
	s_add_i32 m0, s40, 0xe000
	s_nop 0
	global_load_lds_dwordx4 v[220:221], off
	s_waitcnt vmcnt(8) lgkmcnt(0)
	s_barrier
	v_mfma_f32_16x16x32_bf16 v[126:129], v[156:159], v[188:191], 0
	v_mfma_f32_16x16x32_bf16 v[122:125], v[164:167], v[188:191], 0
	v_mfma_f32_16x16x32_bf16 v[110:113], v[156:159], v[196:199], 0
	v_mfma_f32_16x16x32_bf16 v[106:109], v[164:167], v[196:199], 0
	v_mfma_f32_16x16x32_bf16 v[94:97], v[156:159], v[204:207], 0
	v_mfma_f32_16x16x32_bf16 v[90:93], v[164:167], v[204:207], 0
	v_mfma_f32_16x16x32_bf16 v[78:81], v[156:159], v[212:215], 0
	v_mfma_f32_16x16x32_bf16 v[74:77], v[164:167], v[212:215], 0
	v_mfma_f32_16x16x32_bf16 v[126:129], v[160:163], v[192:195], v[126:129]
	v_mfma_f32_16x16x32_bf16 v[122:125], v[168:171], v[192:195], v[122:125]
	v_mfma_f32_16x16x32_bf16 v[110:113], v[160:163], v[200:203], v[110:113]
	v_mfma_f32_16x16x32_bf16 v[106:109], v[168:171], v[200:203], v[106:109]
	v_mfma_f32_16x16x32_bf16 v[94:97], v[160:163], v[208:211], v[94:97]
	v_mfma_f32_16x16x32_bf16 v[90:93], v[168:171], v[208:211], v[90:93]
	v_mfma_f32_16x16x32_bf16 v[78:81], v[160:163], v[216:219], v[78:81]
	v_mfma_f32_16x16x32_bf16 v[74:77], v[168:171], v[216:219], v[74:77]
	v_mfma_f32_16x16x32_bf16 v[118:121], v[172:175], v[188:191], 0
	v_mfma_f32_16x16x32_bf16 v[114:117], v[180:183], v[188:191], 0
	v_mfma_f32_16x16x32_bf16 v[102:105], v[172:175], v[196:199], 0
	v_mfma_f32_16x16x32_bf16 v[98:101], v[180:183], v[196:199], 0
	v_mfma_f32_16x16x32_bf16 v[86:89], v[172:175], v[204:207], 0
	v_mfma_f32_16x16x32_bf16 v[82:85], v[180:183], v[204:207], 0
	v_mfma_f32_16x16x32_bf16 v[70:73], v[172:175], v[212:215], 0
	v_mfma_f32_16x16x32_bf16 v[66:69], v[180:183], v[212:215], 0
	v_mfma_f32_16x16x32_bf16 v[118:121], v[176:179], v[192:195], v[118:121]
	v_mfma_f32_16x16x32_bf16 v[114:117], v[184:187], v[192:195], v[114:117]
	v_mfma_f32_16x16x32_bf16 v[102:105], v[176:179], v[200:203], v[102:105]
	v_mfma_f32_16x16x32_bf16 v[98:101], v[184:187], v[200:203], v[98:101]
	v_mfma_f32_16x16x32_bf16 v[86:89], v[176:179], v[208:211], v[86:89]
	v_mfma_f32_16x16x32_bf16 v[82:85], v[184:187], v[208:211], v[82:85]
	v_mfma_f32_16x16x32_bf16 v[70:73], v[176:179], v[216:219], v[70:73]
	v_mfma_f32_16x16x32_bf16 v[66:69], v[184:187], v[216:219], v[66:69]
	s_barrier
	s_add_i32 s58, s72, s39
	s_mov_b32 m0, s58
	ds_read_b128 v[188:191], v154 offset:16384
	ds_read_b128 v[192:195], v154 offset:17408
	ds_read_b128 v[196:199], v154 offset:18432
	ds_read_b128 v[200:203], v154 offset:19456
	ds_read_b128 v[204:207], v154 offset:20480
	ds_read_b128 v[208:211], v154 offset:21504
	ds_read_b128 v[212:215], v154 offset:22528
	ds_read_b128 v[216:219], v154 offset:23552
	global_load_lds_dwordx4 v132, s[30:31]
	s_add_i32 m0, s58, 0x2000
	s_add_u32 s58, s30, 0x4000
	s_addc_u32 s59, s31, 0
	s_add_i32 s64, s73, s39
	global_load_lds_dwordx4 v136, s[30:31]
	s_mov_b32 m0, s64
	s_nop 0
	global_load_lds_dwordx4 v132, s[58:59]
	s_add_i32 m0, s64, 0x2000
	s_nop 0
	global_load_lds_dwordx4 v136, s[58:59]
	s_mov_b32 m0, s40
	s_nop 0
	global_load_lds_dwordx4 v130, s[34:35]
	s_mov_b32 m0, s41
	s_nop 0
	global_load_lds_dwordx4 v134, s[34:35]
	s_waitcnt vmcnt(8) lgkmcnt(0)
	s_barrier
; #define PG8_STAGE(bufoff, gbase, voff) do { _Pragma("unroll") for (int _i = 0; _i < 2; ++_i) \
;         __builtin_amdgcn_global_load_lds((const unsigned*)((const char*)(gbase) + (voff)[_i]), (LAS unsigned*)(lds + (bufoff) + ldsw + _i * 8192), 16, 0, 0); } while (0)
; #define PG8_LDA(dst, b, h) do { _Pragma("unroll") for (int m = 0; m < 4; ++m) _Pragma("unroll") for (int k = 0; k < 2; ++k) dst[m][k] = *(const LAS bf16x8*)(lds + PG8_SA(b, h) + aoff + m * 2048 + k * 1024); } while (0)
; #define PG8_LDB(dst, b, h) do { _Pragma("unroll") for (int n = 0; n < 2; ++n) _Pragma("unroll") for (int k = 0; k < 2; ++k) dst[n][k] = *(const LAS bf16x8*)(lds + PG8_SB(b, h) + boff + n * 2048 + k * 1024); } while (0)
; #define PG8_MMA(ai, bj, At, Bt) do { __builtin_amdgcn_s_setprio(1); _Pragma("unroll") for (int m = 0; m < 4; ++m) _Pragma("unroll") for (int n = 0; n < 2; ++n) _Pragma("unroll") for (int k = 0; k < 2; ++k) \
;         acc[ai][bj][m][n] = __builtin_amdgcn_mfma_f32_16x16x32_bf16(Bt[n][k], At[m][k], acc[ai][bj][m][n], 0, 0, 0); __builtin_amdgcn_s_setprio(0); } while (0)
; #define PG8_WAIT_V(n) asm volatile("s_waitcnt vmcnt(" #n ")" ::: "memory")
; #define PG8_WAIT_L(n) asm volatile("s_waitcnt lgkmcnt(" #n ")" ::: "memory")
; #define PG8_BAR __builtin_amdgcn_s_barrier()
; #define PG8_SCHED __builtin_amdgcn_sched_barrier(0)
; template <class Epi, class Sched, bool ABLK = false, bool ALIGN_EPI = true, bool SP2 = true, bool BBLK = true>
; __device__ __forceinline__ void gemm_phase(LAS unsigned char* lds, const Gemm g, const Sched& S, const Epi& E) {
;     ...
;             PG8_WAIT_V(8); PG8_WAIT_L(0); PG8_BAR; PG8_MMA(1, 0, At, B0); PG8_MMA(1, 1, At, B1); PG8_BAR; PG8_SCHED;
;             PG8_LDB(B0, 1, 0); PG8_LDB(B1, 1, 1); PG8_SCHED; PG8_LDA(At, 1, 0); PG8_STAGE(PG8_SA(0, 1), a2 + hstepA, voffA);
;             PG8_WAIT_V(8); PG8_WAIT_L(0); PG8_BAR; PG8_MMA(0, 0, At, B0); PG8_MMA(0, 1, At, B1); PG8_BAR; PG8_SCHED;
	v_mfma_f32_16x16x32_bf16 v[62:65], v[156:159], v[188:191], 0
	v_mfma_f32_16x16x32_bf16 v[58:61], v[164:167], v[188:191], 0
	v_mfma_f32_16x16x32_bf16 v[46:49], v[156:159], v[196:199], 0
	v_mfma_f32_16x16x32_bf16 v[42:45], v[164:167], v[196:199], 0
	v_mfma_f32_16x16x32_bf16 v[30:33], v[156:159], v[204:207], 0
	v_mfma_f32_16x16x32_bf16 v[26:29], v[164:167], v[204:207], 0
	v_mfma_f32_16x16x32_bf16 v[14:17], v[156:159], v[212:215], 0
	v_mfma_f32_16x16x32_bf16 v[10:13], v[164:167], v[212:215], 0
	v_mfma_f32_16x16x32_bf16 v[62:65], v[160:163], v[192:195], v[62:65]
	v_mfma_f32_16x16x32_bf16 v[58:61], v[168:171], v[192:195], v[58:61]
	v_mfma_f32_16x16x32_bf16 v[46:49], v[160:163], v[200:203], v[46:49]
	v_mfma_f32_16x16x32_bf16 v[42:45], v[168:171], v[200:203], v[42:45]
	v_mfma_f32_16x16x32_bf16 v[30:33], v[160:163], v[208:211], v[30:33]
	v_mfma_f32_16x16x32_bf16 v[26:29], v[168:171], v[208:211], v[26:29]
	v_mfma_f32_16x16x32_bf16 v[14:17], v[160:163], v[216:219], v[14:17]
	v_mfma_f32_16x16x32_bf16 v[10:13], v[168:171], v[216:219], v[10:13]
	v_mfma_f32_16x16x32_bf16 v[54:57], v[172:175], v[188:191], 0
	v_mfma_f32_16x16x32_bf16 v[50:53], v[180:183], v[188:191], 0
	v_mfma_f32_16x16x32_bf16 v[38:41], v[172:175], v[196:199], 0
	v_mfma_f32_16x16x32_bf16 v[34:37], v[180:183], v[196:199], 0
	v_mfma_f32_16x16x32_bf16 v[22:25], v[172:175], v[204:207], 0
	v_mfma_f32_16x16x32_bf16 v[18:21], v[180:183], v[204:207], 0
	v_mfma_f32_16x16x32_bf16 v[6:9], v[172:175], v[212:215], 0
	v_mfma_f32_16x16x32_bf16 v[2:5], v[180:183], v[212:215], 0
	v_mfma_f32_16x16x32_bf16 v[54:57], v[176:179], v[192:195], v[54:57]
	v_mfma_f32_16x16x32_bf16 v[50:53], v[184:187], v[192:195], v[50:53]
	v_mfma_f32_16x16x32_bf16 v[38:41], v[176:179], v[200:203], v[38:41]
	v_mfma_f32_16x16x32_bf16 v[34:37], v[184:187], v[200:203], v[34:37]
	v_mfma_f32_16x16x32_bf16 v[22:25], v[176:179], v[208:211], v[22:25]
	v_mfma_f32_16x16x32_bf16 v[18:21], v[184:187], v[208:211], v[18:21]
	v_mfma_f32_16x16x32_bf16 v[6:9], v[176:179], v[216:219], v[6:9]
	v_mfma_f32_16x16x32_bf16 v[2:5], v[184:187], v[216:219], v[2:5]
	s_barrier
	v_add_u32_e32 v155, s60, v150
	ds_read_b128 v[156:159], v155
	ds_read_b128 v[160:163], v155 offset:1024
	ds_read_b128 v[164:167], v155 offset:2048
	ds_read_b128 v[168:171], v155 offset:3072
	v_add_u32_e32 v155, s61, v150
	ds_read_b128 v[172:175], v155
	ds_read_b128 v[176:179], v155 offset:1024
	ds_read_b128 v[180:183], v155 offset:2048
	ds_read_b128 v[184:187], v155 offset:3072
	s_add_u32 s34, s34, 0x80000
	s_addc_u32 s35, s35, 0
	s_mov_b32 m0, s42
	ds_read_b128 v[188:191], v154 offset:32768
	ds_read_b128 v[192:195], v154 offset:33792
	ds_read_b128 v[196:199], v154 offset:34816
	ds_read_b128 v[200:203], v154 offset:35840
	ds_read_b128 v[204:207], v154 offset:36864
	ds_read_b128 v[208:211], v154 offset:37888
	ds_read_b128 v[212:215], v154 offset:38912
	ds_read_b128 v[216:219], v154 offset:39936
	global_load_lds_dwordx4 v130, s[34:35]
	s_mov_b32 m0, s43
	s_nop 0
	global_load_lds_dwordx4 v134, s[34:35]
	s_waitcnt vmcnt(8) lgkmcnt(0)
	s_barrier
	v_mfma_f32_16x16x32_bf16 v[126:129], v[156:159], v[188:191], v[126:129]
	v_mfma_f32_16x16x32_bf16 v[122:125], v[164:167], v[188:191], v[122:125]
	v_mfma_f32_16x16x32_bf16 v[110:113], v[156:159], v[196:199], v[110:113]
	v_mfma_f32_16x16x32_bf16 v[106:109], v[164:167], v[196:199], v[106:109]
	v_mfma_f32_16x16x32_bf16 v[94:97], v[156:159], v[204:207], v[94:97]
	v_mfma_f32_16x16x32_bf16 v[90:93], v[164:167], v[204:207], v[90:93]
	v_mfma_f32_16x16x32_bf16 v[78:81], v[156:159], v[212:215], v[78:81]
	v_mfma_f32_16x16x32_bf16 v[74:77], v[164:167], v[212:215], v[74:77]
	v_mfma_f32_16x16x32_bf16 v[126:129], v[160:163], v[192:195], v[126:129]
	v_mfma_f32_16x16x32_bf16 v[122:125], v[168:171], v[192:195], v[122:125]
	v_mfma_f32_16x16x32_bf16 v[110:113], v[160:163], v[200:203], v[110:113]
	v_mfma_f32_16x16x32_bf16 v[106:109], v[168:171], v[200:203], v[106:109]
	v_mfma_f32_16x16x32_bf16 v[94:97], v[160:163], v[208:211], v[94:97]
	v_mfma_f32_16x16x32_bf16 v[90:93], v[168:171], v[208:211], v[90:93]
	v_mfma_f32_16x16x32_bf16 v[78:81], v[160:163], v[216:219], v[78:81]
	v_mfma_f32_16x16x32_bf16 v[74:77], v[168:171], v[216:219], v[74:77]
	v_mfma_f32_16x16x32_bf16 v[118:121], v[172:175], v[188:191], v[118:121]
	v_mfma_f32_16x16x32_bf16 v[114:117], v[180:183], v[188:191], v[114:117]
	v_mfma_f32_16x16x32_bf16 v[102:105], v[172:175], v[196:199], v[102:105]
	v_mfma_f32_16x16x32_bf16 v[98:101], v[180:183], v[196:199], v[98:101]
	v_mfma_f32_16x16x32_bf16 v[86:89], v[172:175], v[204:207], v[86:89]
	v_mfma_f32_16x16x32_bf16 v[82:85], v[180:183], v[204:207], v[82:85]
	v_mfma_f32_16x16x32_bf16 v[70:73], v[172:175], v[212:215], v[70:73]
	v_mfma_f32_16x16x32_bf16 v[66:69], v[180:183], v[212:215], v[66:69]
	v_mfma_f32_16x16x32_bf16 v[118:121], v[176:179], v[192:195], v[118:121]
	v_mfma_f32_16x16x32_bf16 v[114:117], v[184:187], v[192:195], v[114:117]
	v_mfma_f32_16x16x32_bf16 v[102:105], v[176:179], v[200:203], v[102:105]
	v_mfma_f32_16x16x32_bf16 v[98:101], v[184:187], v[200:203], v[98:101]
	v_mfma_f32_16x16x32_bf16 v[86:89], v[176:179], v[208:211], v[86:89]
	v_mfma_f32_16x16x32_bf16 v[82:85], v[184:187], v[208:211], v[82:85]
	v_mfma_f32_16x16x32_bf16 v[70:73], v[176:179], v[216:219], v[70:73]
	v_mfma_f32_16x16x32_bf16 v[66:69], v[184:187], v[216:219], v[66:69]
	s_barrier
; #define PG8_STAGE(bufoff, gbase, voff) do { _Pragma("unroll") for (int _i = 0; _i < 2; ++_i) \
;         __builtin_amdgcn_global_load_lds((const unsigned*)((const char*)(gbase) + (voff)[_i]), (LAS unsigned*)(lds + (bufoff) + ldsw + _i * 8192), 16, 0, 0); } while (0)
; #define PG8_LDA(dst, b, h) do { _Pragma("unroll") for (int m = 0; m < 4; ++m) _Pragma("unroll") for (int k = 0; k < 2; ++k) dst[m][k] = *(const LAS bf16x8*)(lds + PG8_SA(b, h) + aoff + m * 2048 + k * 1024); } while (0)
; #define PG8_MMA(ai, bj, At, Bt) do { __builtin_amdgcn_s_setprio(1); _Pragma("unroll") for (int m = 0; m < 4; ++m) _Pragma("unroll") for (int n = 0; n < 2; ++n) _Pragma("unroll") for (int k = 0; k < 2; ++k) \
;         acc[ai][bj][m][n] = __builtin_amdgcn_mfma_f32_16x16x32_bf16(Bt[n][k], At[m][k], acc[ai][bj][m][n], 0, 0, 0); __builtin_amdgcn_s_setprio(0); } while (0)
; #define PG8_WAIT_V(n) asm volatile("s_waitcnt vmcnt(" #n ")" ::: "memory")
; #define PG8_WAIT_L(n) asm volatile("s_waitcnt lgkmcnt(" #n ")" ::: "memory")
; #define PG8_BAR __builtin_amdgcn_s_barrier()
; #define PG8_SCHED __builtin_amdgcn_sched_barrier(0)
; template <class Epi, class Sched, bool ABLK = false, bool ALIGN_EPI = true, bool SP2 = true, bool BBLK = true>
; __device__ __forceinline__ void gemm_phase(LAS unsigned char* lds, const Gemm g, const Sched& S, const Epi& E) {
;     ...
;             PG8_LDA(At, 1, 1); PG8_STAGE(PG8_SB(1, 0), b3, voffB); PG8_STAGE(PG8_SB(1, 1), b3 + hstepB, voffB); PG8_STAGE(PG8_SA(1, 0), a3, voffA);
;             PG8_WAIT_V(8); PG8_WAIT_L(0); PG8_BAR; PG8_MMA(1, 0, At, B0); PG8_MMA(1, 1, At, B1); PG8_BAR; PG8_SCHED;
	s_add_u32 s34, s30, 0x8000
	s_addc_u32 s35, s31, 0
	s_add_i32 s58, s60, s39
	s_mov_b32 m0, s58
	ds_read_b128 v[188:191], v154 offset:49152
	ds_read_b128 v[192:195], v154 offset:50176
	ds_read_b128 v[196:199], v154 offset:51200
	ds_read_b128 v[200:203], v154 offset:52224
	ds_read_b128 v[204:207], v154 offset:53248
	ds_read_b128 v[208:211], v154 offset:54272
	ds_read_b128 v[212:215], v154 offset:55296
	ds_read_b128 v[216:219], v154 offset:56320
	global_load_lds_dwordx4 v132, s[34:35]
	s_add_i32 m0, s58, 0x2000
	s_add_u32 s30, s30, 0xc000
	v_lshl_add_u64 v[220:221], s[34:35], 0, v[136:137]
	s_addc_u32 s31, s31, 0
	s_add_i32 s34, s61, s39
	global_load_lds_dwordx4 v[220:221], off
	s_mov_b32 m0, s34
	s_nop 0
	global_load_lds_dwordx4 v132, s[30:31]
	s_add_i32 m0, s34, 0x2000
	s_nop 0
	global_load_lds_dwordx4 v136, s[30:31]
	s_mov_b32 m0, s44
	s_nop 0
	global_load_lds_dwordx4 v130, s[28:29]
	s_mov_b32 m0, s45
	s_nop 0
	global_load_lds_dwordx4 v134, s[28:29]
	s_waitcnt vmcnt(8) lgkmcnt(0)
	s_barrier
	v_mfma_f32_16x16x32_bf16 v[62:65], v[156:159], v[188:191], v[62:65]
	v_mfma_f32_16x16x32_bf16 v[58:61], v[164:167], v[188:191], v[58:61]
	v_mfma_f32_16x16x32_bf16 v[46:49], v[156:159], v[196:199], v[46:49]
	v_mfma_f32_16x16x32_bf16 v[42:45], v[164:167], v[196:199], v[42:45]
	v_mfma_f32_16x16x32_bf16 v[30:33], v[156:159], v[204:207], v[30:33]
	v_mfma_f32_16x16x32_bf16 v[26:29], v[164:167], v[204:207], v[26:29]
	v_mfma_f32_16x16x32_bf16 v[14:17], v[156:159], v[212:215], v[14:17]
	v_mfma_f32_16x16x32_bf16 v[10:13], v[164:167], v[212:215], v[10:13]
	v_mfma_f32_16x16x32_bf16 v[62:65], v[160:163], v[192:195], v[62:65]
	v_mfma_f32_16x16x32_bf16 v[58:61], v[168:171], v[192:195], v[58:61]
	v_mfma_f32_16x16x32_bf16 v[46:49], v[160:163], v[200:203], v[46:49]
	v_mfma_f32_16x16x32_bf16 v[42:45], v[168:171], v[200:203], v[42:45]
	v_mfma_f32_16x16x32_bf16 v[30:33], v[160:163], v[208:211], v[30:33]
	v_mfma_f32_16x16x32_bf16 v[26:29], v[168:171], v[208:211], v[26:29]
	v_mfma_f32_16x16x32_bf16 v[14:17], v[160:163], v[216:219], v[14:17]
	v_mfma_f32_16x16x32_bf16 v[10:13], v[168:171], v[216:219], v[10:13]
	v_mfma_f32_16x16x32_bf16 v[54:57], v[172:175], v[188:191], v[54:57]
	v_mfma_f32_16x16x32_bf16 v[50:53], v[180:183], v[188:191], v[50:53]
	v_mfma_f32_16x16x32_bf16 v[38:41], v[172:175], v[196:199], v[38:41]
	v_mfma_f32_16x16x32_bf16 v[34:37], v[180:183], v[196:199], v[34:37]
	v_mfma_f32_16x16x32_bf16 v[22:25], v[172:175], v[204:207], v[22:25]
	v_mfma_f32_16x16x32_bf16 v[18:21], v[180:183], v[204:207], v[18:21]
	v_mfma_f32_16x16x32_bf16 v[6:9], v[172:175], v[212:215], v[6:9]
	v_mfma_f32_16x16x32_bf16 v[2:5], v[180:183], v[212:215], v[2:5]
	v_mfma_f32_16x16x32_bf16 v[54:57], v[176:179], v[192:195], v[54:57]
	v_mfma_f32_16x16x32_bf16 v[50:53], v[184:187], v[192:195], v[50:53]
	v_mfma_f32_16x16x32_bf16 v[38:41], v[176:179], v[200:203], v[38:41]
	v_mfma_f32_16x16x32_bf16 v[34:37], v[184:187], v[200:203], v[34:37]
	v_mfma_f32_16x16x32_bf16 v[22:25], v[176:179], v[208:211], v[22:25]
	v_mfma_f32_16x16x32_bf16 v[18:21], v[184:187], v[208:211], v[18:21]
	v_mfma_f32_16x16x32_bf16 v[6:9], v[176:179], v[216:219], v[6:9]
	v_mfma_f32_16x16x32_bf16 v[2:5], v[184:187], v[216:219], v[2:5]
	s_barrier
	s_add_u32 s52, s52, 0x10000
	s_addc_u32 s53, s53, 0
	s_add_u32 s26, s26, 0x100
	s_addc_u32 s27, s27, 0
	s_cmp_ge_u32 s57, s47

; #define PG8_STAGE(bufoff, gbase, voff) do { _Pragma("unroll") for (int _i = 0; _i < 2; ++_i) \
;         __builtin_amdgcn_global_load_lds((const unsigned*)((const char*)(gbase) + (voff)[_i]), (LAS unsigned*)(lds + (bufoff) + ldsw + _i * 8192), 16, 0, 0); } while (0)
; #define PG8_LDA(dst, b, h) do { _Pragma("unroll") for (int m = 0; m < 4; ++m) _Pragma("unroll") for (int k = 0; k < 2; ++k) dst[m][k] = *(const LAS bf16x8*)(lds + PG8_SA(b, h) + aoff + m * 2048 + k * 1024); } while (0)
; #define PG8_LDB(dst, b, h) do { _Pragma("unroll") for (int n = 0; n < 2; ++n) _Pragma("unroll") for (int k = 0; k < 2; ++k) dst[n][k] = *(const LAS bf16x8*)(lds + PG8_SB(b, h) + boff + n * 2048 + k * 1024); } while (0)
; #define PG8_WAIT_V(n) asm volatile("s_waitcnt vmcnt(" #n ")" ::: "memory")
; #define PG8_WAIT_L(n) asm volatile("s_waitcnt lgkmcnt(" #n ")" ::: "memory")
; #define PG8_BAR __builtin_amdgcn_s_barrier()
; #define PG8_SCHED __builtin_amdgcn_sched_barrier(0)
; template <class Epi, class Sched, bool ABLK = false, bool ALIGN_EPI = true, bool SP2 = true, bool BBLK = true>
; __device__ __forceinline__ void gemm_phase(LAS unsigned char* lds, const Gemm g, const Sched& S, const Epi& E) {
;     ...
;         const bool has_next = S.next(ui + 1, nxt);
;         const int nt = cur.nt;
;         const char* nuA = has_next ? a_unit(nxt) : uA; const int ntbA = has_next ? nxt.k0 / BK : tbA; const char* nB = has_next ? (const char*)g.Bt + (size_t)nxt.pn * tstepB + b_k0(nxt.k0) : cB;
;         for (int t = 0; t < nt; t += 2) {
;             const bool last = (t == nt - 2);
;             const char* a1 = a_tile(uA, tbA + t + 1);
;             const char* a2 = last ? a_tile(nuA, ntbA) : a_tile(uA, tbA + t + 2); const char* b2 = last ? nB : cB + (size_t)(t + 2) * kstepB;
;             const char* a3 = last ? a_tile(nuA, ntbA + 1) : a_tile(uA, tbA + t + 3); const char* b3 = b2 + kstepB;
;             if (last && has_next) S.a_ready(nxt);
;             if constexpr (SP2) {
;             PG8_LDB(B0, 0, 0); PG8_LDB(B1, 0, 1); PG8_SCHED; PG8_LDA(At, 0, 0); PG8_STAGE(PG8_SA(1, 1), a1 + hstepA, voffA);
;             PG8_WAIT_V(8); PG8_WAIT_L(0); PG8_BAR; PG8_MMA(0, 0, At, B0); PG8_MMA(0, 1, At, B1); PG8_BAR; PG8_SCHED;
;             PG8_LDA(At, 0, 1); PG8_STAGE(PG8_SB(0, 0), b2, voffB); PG8_STAGE(PG8_SB(0, 1), b2 + hstepB, voffB); PG8_STAGE(PG8_SA(0, 0), a2, voffA);
.LBB0_1841:
	s_ashr_i32 s11, s10, 31
	s_lshl_b64 s[4:5], s[10:11], 20
	s_add_u32 s16, s76, s4
	s_addc_u32 s17, s33, s5
	s_and_b64 s[4:5], s[18:19], exec
	s_cselect_b32 s4, s17, s27
	s_cselect_b32 s5, s16, s26
	s_ashr_i32 s15, s14, 31
	s_lshl_b64 s[20:21], s[14:15], 20
	s_add_u32 s20, s1, s20
	s_addc_u32 s21, s38, s21
	s_and_b64 s[30:31], s[18:19], exec
	s_cselect_b32 s11, s21, s29
	s_cselect_b32 s15, s20, s28
	s_add_u32 s23, s5, 0x80
	s_addc_u32 s51, s4, 0
	s_add_u32 s52, s28, 0x10000
	v_mov_b32_e32 v2, 0
	s_addc_u32 s53, s29, 0
	v_lshl_add_u64 v[164:165], s[26:27], 0, v[160:161]
	v_lshl_add_u64 v[166:167], s[26:27], 0, v[162:163]
	s_mov_b32 s54, -2
	s_mov_b64 s[28:29], 0
	ds_read_b128 v[172:175], v168
	ds_read_b128 v[176:179], v168 offset:1024
	ds_read_b128 v[180:183], v168 offset:2048
	ds_read_b128 v[184:187], v168 offset:3072
	ds_read_b128 v[188:191], v169
	ds_read_b128 v[192:195], v169 offset:1024
	ds_read_b128 v[196:199], v169 offset:2048
	ds_read_b128 v[200:203], v169 offset:3072
	s_add_u32 s30, s26, s28
	s_addc_u32 s31, s27, s29
	s_add_u32 s36, s30, 0x100
	s_addc_u32 s37, s31, 0
	s_add_u32 s30, s30, 0x180
	s_addc_u32 s31, s31, 0
	s_cmpk_eq_i32 s28, 0xf00
	s_cselect_b32 s31, s51, s31
	s_cselect_b32 s30, s23, s30
	s_cselect_b32 s35, s11, s53
	s_cselect_b32 s34, s15, s52
	s_cselect_b32 s37, s4, s37
	s_cselect_b32 s36, s5, s36
	s_mov_b32 m0, s47
	v_lshl_add_u64 v[236:237], v[164:165], 0, s[28:29]
	ds_read_b128 v[204:207], v170
	ds_read_b128 v[208:211], v170 offset:1024
	ds_read_b128 v[212:215], v170 offset:2048
	ds_read_b128 v[216:219], v170 offset:3072
	ds_read_b128 v[220:223], v170 offset:4096
	ds_read_b128 v[224:227], v170 offset:5120
	ds_read_b128 v[228:231], v170 offset:6144
	ds_read_b128 v[232:235], v170 offset:7168
	global_load_lds_dwordx4 v[236:237], off
	v_lshl_add_u64 v[236:237], v[166:167], 0, s[28:29]
	s_mov_b32 m0, s48
	s_nop 0
	global_load_lds_dwordx4 v[236:237], off
	s_waitcnt vmcnt(8) lgkmcnt(0)
	s_barrier
	v_mfma_f32_16x16x32_bf16 v[126:129], v[172:175], v[204:207], 0
	v_mfma_f32_16x16x32_bf16 v[122:125], v[180:183], v[204:207], 0
	v_mfma_f32_16x16x32_bf16 v[110:113], v[172:175], v[212:215], 0
	v_mfma_f32_16x16x32_bf16 v[106:109], v[180:183], v[212:215], 0
	v_mfma_f32_16x16x32_bf16 v[94:97], v[172:175], v[220:223], 0
	v_mfma_f32_16x16x32_bf16 v[90:93], v[180:183], v[220:223], 0
	v_mfma_f32_16x16x32_bf16 v[78:81], v[172:175], v[228:231], 0
	v_mfma_f32_16x16x32_bf16 v[74:77], v[180:183], v[228:231], 0
	v_mfma_f32_16x16x32_bf16 v[126:129], v[176:179], v[208:211], v[126:129]
	v_mfma_f32_16x16x32_bf16 v[122:125], v[184:187], v[208:211], v[122:125]
	v_mfma_f32_16x16x32_bf16 v[110:113], v[176:179], v[216:219], v[110:113]
	v_mfma_f32_16x16x32_bf16 v[106:109], v[184:187], v[216:219], v[106:109]
	v_mfma_f32_16x16x32_bf16 v[94:97], v[176:179], v[224:227], v[94:97]
	v_mfma_f32_16x16x32_bf16 v[90:93], v[184:187], v[224:227], v[90:93]
	v_mfma_f32_16x16x32_bf16 v[78:81], v[176:179], v[232:235], v[78:81]
	v_mfma_f32_16x16x32_bf16 v[74:77], v[184:187], v[232:235], v[74:77]
	v_mfma_f32_16x16x32_bf16 v[118:121], v[188:191], v[204:207], 0
	v_mfma_f32_16x16x32_bf16 v[114:117], v[196:199], v[204:207], 0
	v_mfma_f32_16x16x32_bf16 v[102:105], v[188:191], v[212:215], 0
	v_mfma_f32_16x16x32_bf16 v[98:101], v[196:199], v[212:215], 0
	v_mfma_f32_16x16x32_bf16 v[86:89], v[188:191], v[220:223], 0
	v_mfma_f32_16x16x32_bf16 v[82:85], v[196:199], v[220:223], 0
	v_mfma_f32_16x16x32_bf16 v[70:73], v[188:191], v[228:231], 0
	v_mfma_f32_16x16x32_bf16 v[66:69], v[196:199], v[228:231], 0
	v_mfma_f32_16x16x32_bf16 v[118:121], v[192:195], v[208:211], v[118:121]
	v_mfma_f32_16x16x32_bf16 v[114:117], v[200:203], v[208:211], v[114:117]
	v_mfma_f32_16x16x32_bf16 v[102:105], v[192:195], v[216:219], v[102:105]
	v_mfma_f32_16x16x32_bf16 v[98:101], v[200:203], v[216:219], v[98:101]
	v_mfma_f32_16x16x32_bf16 v[86:89], v[192:195], v[224:227], v[86:89]
	v_mfma_f32_16x16x32_bf16 v[82:85], v[200:203], v[224:227], v[82:85]
	v_mfma_f32_16x16x32_bf16 v[70:73], v[192:195], v[232:235], v[70:73]
	v_mfma_f32_16x16x32_bf16 v[66:69], v[200:203], v[232:235], v[66:69]
	s_barrier
	s_mov_b32 m0, s49
	s_add_u32 s56, s34, 0x4000
	ds_read_b128 v[204:207], v170 offset:16384
	ds_read_b128 v[208:211], v170 offset:17408
	ds_read_b128 v[212:215], v170 offset:18432
	ds_read_b128 v[216:219], v170 offset:19456
	ds_read_b128 v[220:223], v170 offset:20480
	ds_read_b128 v[224:227], v170 offset:21504
	ds_read_b128 v[228:231], v170 offset:22528
	ds_read_b128 v[232:235], v170 offset:23552
	global_load_lds_dwordx4 v134, s[34:35]
	s_mov_b32 m0, s50
	s_addc_u32 s57, s35, 0
	s_add_i32 s55, s73, s39
	global_load_lds_dwordx4 v130, s[34:35]
	s_mov_b32 m0, s55
	s_nop 0
	global_load_lds_dwordx4 v134, s[56:57]
	s_add_i32 m0, s55, 0x2000
	s_nop 0
	global_load_lds_dwordx4 v130, s[56:57]
	s_mov_b32 m0, s25
	s_nop 0
	global_load_lds_dwordx4 v136, s[36:37]
	s_mov_b32 m0, s40
	s_nop 0
	global_load_lds_dwordx4 v132, s[36:37]
	s_waitcnt vmcnt(8) lgkmcnt(0)
	s_barrier
; #define PG8_STAGE(bufoff, gbase, voff) do { _Pragma("unroll") for (int _i = 0; _i < 2; ++_i) \
;         __builtin_amdgcn_global_load_lds((const unsigned*)((const char*)(gbase) + (voff)[_i]), (LAS unsigned*)(lds + (bufoff) + ldsw + _i * 8192), 16, 0, 0); } while (0)
; #define PG8_LDA(dst, b, h) do { _Pragma("unroll") for (int m = 0; m < 4; ++m) _Pragma("unroll") for (int k = 0; k < 2; ++k) dst[m][k] = *(const LAS bf16x8*)(lds + PG8_SA(b, h) + aoff + m * 2048 + k * 1024); } while (0)
; #define PG8_LDB(dst, b, h) do { _Pragma("unroll") for (int n = 0; n < 2; ++n) _Pragma("unroll") for (int k = 0; k < 2; ++k) dst[n][k] = *(const LAS bf16x8*)(lds + PG8_SB(b, h) + boff + n * 2048 + k * 1024); } while (0)
; #define PG8_MMA(ai, bj, At, Bt) do { __builtin_amdgcn_s_setprio(1); _Pragma("unroll") for (int m = 0; m < 4; ++m) _Pragma("unroll") for (int n = 0; n < 2; ++n) _Pragma("unroll") for (int k = 0; k < 2; ++k) \
;         acc[ai][bj][m][n] = __builtin_amdgcn_mfma_f32_16x16x32_bf16(Bt[n][k], At[m][k], acc[ai][bj][m][n], 0, 0, 0); __builtin_amdgcn_s_setprio(0); } while (0)
; #define PG8_WAIT_V(n) asm volatile("s_waitcnt vmcnt(" #n ")" ::: "memory")
; #define PG8_WAIT_L(n) asm volatile("s_waitcnt lgkmcnt(" #n ")" ::: "memory")
; #define PG8_BAR __builtin_amdgcn_s_barrier()
; #define PG8_SCHED __builtin_amdgcn_sched_barrier(0)
; template <class Epi, class Sched, bool ABLK = false, bool ALIGN_EPI = true, bool SP2 = true, bool BBLK = true>
; __device__ __forceinline__ void gemm_phase(LAS unsigned char* lds, const Gemm g, const Sched& S, const Epi& E) {
;     ...
;             PG8_WAIT_V(8); PG8_WAIT_L(0); PG8_BAR; PG8_MMA(1, 0, At, B0); PG8_MMA(1, 1, At, B1); PG8_BAR; PG8_SCHED;
;             PG8_LDB(B0, 1, 0); PG8_LDB(B1, 1, 1); PG8_SCHED; PG8_LDA(At, 1, 0); PG8_STAGE(PG8_SA(0, 1), a2 + hstepA, voffA);
;             PG8_WAIT_V(8); PG8_WAIT_L(0); PG8_BAR; PG8_MMA(0, 0, At, B0); PG8_MMA(0, 1, At, B1); PG8_BAR; PG8_SCHED;
	v_mfma_f32_16x16x32_bf16 v[62:65], v[172:175], v[204:207], 0
	v_mfma_f32_16x16x32_bf16 v[58:61], v[180:183], v[204:207], 0
	v_mfma_f32_16x16x32_bf16 v[46:49], v[172:175], v[212:215], 0
	v_mfma_f32_16x16x32_bf16 v[42:45], v[180:183], v[212:215], 0
	v_mfma_f32_16x16x32_bf16 v[30:33], v[172:175], v[220:223], 0
	v_mfma_f32_16x16x32_bf16 v[26:29], v[180:183], v[220:223], 0
	v_mfma_f32_16x16x32_bf16 v[14:17], v[172:175], v[228:231], 0
	v_mfma_f32_16x16x32_bf16 v[10:13], v[180:183], v[228:231], 0
	v_mfma_f32_16x16x32_bf16 v[62:65], v[176:179], v[208:211], v[62:65]
	v_mfma_f32_16x16x32_bf16 v[58:61], v[184:187], v[208:211], v[58:61]
	v_mfma_f32_16x16x32_bf16 v[46:49], v[176:179], v[216:219], v[46:49]
	v_mfma_f32_16x16x32_bf16 v[42:45], v[184:187], v[216:219], v[42:45]
	v_mfma_f32_16x16x32_bf16 v[30:33], v[176:179], v[224:227], v[30:33]
	v_mfma_f32_16x16x32_bf16 v[26:29], v[184:187], v[224:227], v[26:29]
	v_mfma_f32_16x16x32_bf16 v[14:17], v[176:179], v[232:235], v[14:17]
	v_mfma_f32_16x16x32_bf16 v[10:13], v[184:187], v[232:235], v[10:13]
	v_mfma_f32_16x16x32_bf16 v[54:57], v[188:191], v[204:207], 0
	v_mfma_f32_16x16x32_bf16 v[50:53], v[196:199], v[204:207], 0
	v_mfma_f32_16x16x32_bf16 v[38:41], v[188:191], v[212:215], 0
	v_mfma_f32_16x16x32_bf16 v[34:37], v[196:199], v[212:215], 0
	v_mfma_f32_16x16x32_bf16 v[22:25], v[188:191], v[220:223], 0
	v_mfma_f32_16x16x32_bf16 v[18:21], v[196:199], v[220:223], 0
	v_mfma_f32_16x16x32_bf16 v[6:9], v[188:191], v[228:231], 0
	v_mfma_f32_16x16x32_bf16 v[2:5], v[196:199], v[228:231], 0
	v_mfma_f32_16x16x32_bf16 v[54:57], v[192:195], v[208:211], v[54:57]
	v_mfma_f32_16x16x32_bf16 v[50:53], v[200:203], v[208:211], v[50:53]
	v_mfma_f32_16x16x32_bf16 v[38:41], v[192:195], v[216:219], v[38:41]
	v_mfma_f32_16x16x32_bf16 v[34:37], v[200:203], v[216:219], v[34:37]
	v_mfma_f32_16x16x32_bf16 v[22:25], v[192:195], v[224:227], v[22:25]
	v_mfma_f32_16x16x32_bf16 v[18:21], v[200:203], v[224:227], v[18:21]
	v_mfma_f32_16x16x32_bf16 v[6:9], v[192:195], v[232:235], v[6:9]
	v_mfma_f32_16x16x32_bf16 v[2:5], v[200:203], v[232:235], v[2:5]
	s_barrier
	v_add_u32_e32 v171, s60, v1
	ds_read_b128 v[172:175], v171
	ds_read_b128 v[176:179], v171 offset:1024
	ds_read_b128 v[180:183], v171 offset:2048
	ds_read_b128 v[184:187], v171 offset:3072
	v_add_u32_e32 v171, s61, v1
	ds_read_b128 v[188:191], v171
	ds_read_b128 v[192:195], v171 offset:1024
	ds_read_b128 v[196:199], v171 offset:2048
	ds_read_b128 v[200:203], v171 offset:3072
	s_add_u32 s36, s36, 0x80000
	s_addc_u32 s37, s37, 0
	s_mov_b32 m0, s41
	ds_read_b128 v[204:207], v170 offset:32768
	ds_read_b128 v[208:211], v170 offset:33792
	ds_read_b128 v[212:215], v170 offset:34816
	ds_read_b128 v[216:219], v170 offset:35840
	ds_read_b128 v[220:223], v170 offset:36864
	ds_read_b128 v[224:227], v170 offset:37888
	ds_read_b128 v[228:231], v170 offset:38912
	ds_read_b128 v[232:235], v170 offset:39936
	global_load_lds_dwordx4 v136, s[36:37]
	s_mov_b32 m0, s42
	s_nop 0
	global_load_lds_dwordx4 v132, s[36:37]
	s_waitcnt vmcnt(8) lgkmcnt(0)
	s_barrier
	v_mfma_f32_16x16x32_bf16 v[126:129], v[172:175], v[204:207], v[126:129]
	v_mfma_f32_16x16x32_bf16 v[122:125], v[180:183], v[204:207], v[122:125]
	v_mfma_f32_16x16x32_bf16 v[110:113], v[172:175], v[212:215], v[110:113]
	v_mfma_f32_16x16x32_bf16 v[106:109], v[180:183], v[212:215], v[106:109]
	v_mfma_f32_16x16x32_bf16 v[94:97], v[172:175], v[220:223], v[94:97]
	v_mfma_f32_16x16x32_bf16 v[90:93], v[180:183], v[220:223], v[90:93]
	v_mfma_f32_16x16x32_bf16 v[78:81], v[172:175], v[228:231], v[78:81]
	v_mfma_f32_16x16x32_bf16 v[74:77], v[180:183], v[228:231], v[74:77]
	v_mfma_f32_16x16x32_bf16 v[126:129], v[176:179], v[208:211], v[126:129]
	v_mfma_f32_16x16x32_bf16 v[122:125], v[184:187], v[208:211], v[122:125]
	v_mfma_f32_16x16x32_bf16 v[110:113], v[176:179], v[216:219], v[110:113]
	v_mfma_f32_16x16x32_bf16 v[106:109], v[184:187], v[216:219], v[106:109]
	v_mfma_f32_16x16x32_bf16 v[94:97], v[176:179], v[224:227], v[94:97]
	v_mfma_f32_16x16x32_bf16 v[90:93], v[184:187], v[224:227], v[90:93]
	v_mfma_f32_16x16x32_bf16 v[78:81], v[176:179], v[232:235], v[78:81]
	v_mfma_f32_16x16x32_bf16 v[74:77], v[184:187], v[232:235], v[74:77]
	v_mfma_f32_16x16x32_bf16 v[118:121], v[188:191], v[204:207], v[118:121]
	v_mfma_f32_16x16x32_bf16 v[114:117], v[196:199], v[204:207], v[114:117]
	v_mfma_f32_16x16x32_bf16 v[102:105], v[188:191], v[212:215], v[102:105]
	v_mfma_f32_16x16x32_bf16 v[98:101], v[196:199], v[212:215], v[98:101]
	v_mfma_f32_16x16x32_bf16 v[86:89], v[188:191], v[220:223], v[86:89]
	v_mfma_f32_16x16x32_bf16 v[82:85], v[196:199], v[220:223], v[82:85]
	v_mfma_f32_16x16x32_bf16 v[70:73], v[188:191], v[228:231], v[70:73]
	v_mfma_f32_16x16x32_bf16 v[66:69], v[196:199], v[228:231], v[66:69]
	v_mfma_f32_16x16x32_bf16 v[118:121], v[192:195], v[208:211], v[118:121]
	v_mfma_f32_16x16x32_bf16 v[114:117], v[200:203], v[208:211], v[114:117]
	v_mfma_f32_16x16x32_bf16 v[102:105], v[192:195], v[216:219], v[102:105]
	v_mfma_f32_16x16x32_bf16 v[98:101], v[200:203], v[216:219], v[98:101]
	v_mfma_f32_16x16x32_bf16 v[86:89], v[192:195], v[224:227], v[86:89]
	v_mfma_f32_16x16x32_bf16 v[82:85], v[200:203], v[224:227], v[82:85]
	v_mfma_f32_16x16x32_bf16 v[70:73], v[192:195], v[232:235], v[70:73]
	v_mfma_f32_16x16x32_bf16 v[66:69], v[200:203], v[232:235], v[66:69]
	s_barrier
; #define PG8_STAGE(bufoff, gbase, voff) do { _Pragma("unroll") for (int _i = 0; _i < 2; ++_i) \
;         __builtin_amdgcn_global_load_lds((const unsigned*)((const char*)(gbase) + (voff)[_i]), (LAS unsigned*)(lds + (bufoff) + ldsw + _i * 8192), 16, 0, 0); } while (0)
; #define PG8_LDA(dst, b, h) do { _Pragma("unroll") for (int m = 0; m < 4; ++m) _Pragma("unroll") for (int k = 0; k < 2; ++k) dst[m][k] = *(const LAS bf16x8*)(lds + PG8_SA(b, h) + aoff + m * 2048 + k * 1024); } while (0)
; #define PG8_WAIT_V(n) asm volatile("s_waitcnt vmcnt(" #n ")" ::: "memory")
; #define PG8_WAIT_L(n) asm volatile("s_waitcnt lgkmcnt(" #n ")" ::: "memory")
; template <class Epi, class Sched, bool ABLK = false, bool ALIGN_EPI = true, bool SP2 = true, bool BBLK = true>
; __device__ __forceinline__ void gemm_phase(LAS unsigned char* lds, const Gemm g, const Sched& S, const Epi& E) {
;     ...
;         for (int t = 0; t < nt; t += 2) {
;             const bool last = (t == nt - 2);
;             const char* a1 = a_tile(uA, tbA + t + 1);
;             const char* a2 = last ? a_tile(nuA, ntbA) : a_tile(uA, tbA + t + 2); const char* b2 = last ? nB : cB + (size_t)(t + 2) * kstepB;
;             const char* a3 = last ? a_tile(nuA, ntbA + 1) : a_tile(uA, tbA + t + 3); const char* b3 = b2 + kstepB;
;             if (last && has_next) S.a_ready(nxt);
;             if constexpr (SP2) {
;             PG8_LDB(B0, 0, 0); PG8_LDB(B1, 0, 1); PG8_SCHED; PG8_LDA(At, 0, 0); PG8_STAGE(PG8_SA(1, 1), a1 + hstepA, voffA);
;             PG8_WAIT_V(8); PG8_WAIT_L(0); PG8_BAR; PG8_MMA(0, 0, At, B0); PG8_MMA(0, 1, At, B1); PG8_BAR; PG8_SCHED;
;             PG8_LDA(At, 0, 1); PG8_STAGE(PG8_SB(0, 0), b2, voffB); PG8_STAGE(PG8_SB(0, 1), b2 + hstepB, voffB); PG8_STAGE(PG8_SA(0, 0), a2, voffA);
;             PG8_WAIT_V(8); PG8_WAIT_L(0); PG8_BAR; PG8_MMA(1, 0, At, B0); PG8_MMA(1, 1, At, B1); PG8_BAR; PG8_SCHED;
;             PG8_LDB(B0, 1, 0); PG8_LDB(B1, 1, 1); PG8_SCHED; PG8_LDA(At, 1, 0); PG8_STAGE(PG8_SA(0, 1), a2 + hstepA, voffA);
;             PG8_WAIT_V(8); PG8_WAIT_L(0); PG8_BAR; PG8_MMA(0, 0, At, B0); PG8_MMA(0, 1, At, B1); PG8_BAR; PG8_SCHED;
;             PG8_LDA(At, 1, 1); PG8_STAGE(PG8_SB(1, 0), b3, voffB); PG8_STAGE(PG8_SB(1, 1), b3 + hstepB, voffB); PG8_STAGE(PG8_SA(1, 0), a3, voffA);
;             PG8_WAIT_V(8); PG8_WAIT_L(0); PG8_BAR; PG8_MMA(1, 0, At, B0); PG8_MMA(1, 1, At, B1); PG8_BAR; PG8_SCHED;
	s_add_u32 s36, s34, 0x8000
	s_addc_u32 s37, s35, 0
	s_add_i32 s55, s60, s39
	s_mov_b32 m0, s55
	ds_read_b128 v[204:207], v170 offset:49152
	ds_read_b128 v[208:211], v170 offset:50176
	ds_read_b128 v[212:215], v170 offset:51200
	ds_read_b128 v[216:219], v170 offset:52224
	ds_read_b128 v[220:223], v170 offset:53248
	ds_read_b128 v[224:227], v170 offset:54272
	ds_read_b128 v[228:231], v170 offset:55296
	ds_read_b128 v[232:235], v170 offset:56320
	global_load_lds_dwordx4 v134, s[36:37]
	s_add_i32 m0, s55, 0x2000
	s_add_u32 s34, s34, 0xc000
	v_lshl_add_u64 v[236:237], s[36:37], 0, v[130:131]
	s_addc_u32 s35, s35, 0
	s_add_i32 s36, s61, s39
	global_load_lds_dwordx4 v[236:237], off
	s_mov_b32 m0, s36
	s_nop 0
	global_load_lds_dwordx4 v134, s[34:35]
	s_add_i32 m0, s36, 0x2000
	s_nop 0
	global_load_lds_dwordx4 v130, s[34:35]
	s_mov_b32 m0, s45
	s_nop 0
	global_load_lds_dwordx4 v136, s[30:31]
	s_mov_b32 m0, s46
	s_nop 0
	global_load_lds_dwordx4 v132, s[30:31]
	s_waitcnt vmcnt(8) lgkmcnt(0)
	s_barrier
	v_mfma_f32_16x16x32_bf16 v[62:65], v[172:175], v[204:207], v[62:65]
	v_mfma_f32_16x16x32_bf16 v[58:61], v[180:183], v[204:207], v[58:61]
	v_mfma_f32_16x16x32_bf16 v[46:49], v[172:175], v[212:215], v[46:49]
	v_mfma_f32_16x16x32_bf16 v[42:45], v[180:183], v[212:215], v[42:45]
	v_mfma_f32_16x16x32_bf16 v[30:33], v[172:175], v[220:223], v[30:33]
	v_mfma_f32_16x16x32_bf16 v[26:29], v[180:183], v[220:223], v[26:29]
	v_mfma_f32_16x16x32_bf16 v[14:17], v[172:175], v[228:231], v[14:17]
	v_mfma_f32_16x16x32_bf16 v[10:13], v[180:183], v[228:231], v[10:13]
	v_mfma_f32_16x16x32_bf16 v[62:65], v[176:179], v[208:211], v[62:65]
	v_mfma_f32_16x16x32_bf16 v[58:61], v[184:187], v[208:211], v[58:61]
	v_mfma_f32_16x16x32_bf16 v[46:49], v[176:179], v[216:219], v[46:49]
	v_mfma_f32_16x16x32_bf16 v[42:45], v[184:187], v[216:219], v[42:45]
	v_mfma_f32_16x16x32_bf16 v[30:33], v[176:179], v[224:227], v[30:33]
	v_mfma_f32_16x16x32_bf16 v[26:29], v[184:187], v[224:227], v[26:29]
	v_mfma_f32_16x16x32_bf16 v[14:17], v[176:179], v[232:235], v[14:17]
	v_mfma_f32_16x16x32_bf16 v[10:13], v[184:187], v[232:235], v[10:13]
	v_mfma_f32_16x16x32_bf16 v[54:57], v[188:191], v[204:207], v[54:57]
	v_mfma_f32_16x16x32_bf16 v[50:53], v[196:199], v[204:207], v[50:53]
	v_mfma_f32_16x16x32_bf16 v[38:41], v[188:191], v[212:215], v[38:41]
	v_mfma_f32_16x16x32_bf16 v[34:37], v[196:199], v[212:215], v[34:37]
	v_mfma_f32_16x16x32_bf16 v[22:25], v[188:191], v[220:223], v[22:25]
	v_mfma_f32_16x16x32_bf16 v[18:21], v[196:199], v[220:223], v[18:21]
	v_mfma_f32_16x16x32_bf16 v[6:9], v[188:191], v[228:231], v[6:9]
	v_mfma_f32_16x16x32_bf16 v[2:5], v[196:199], v[228:231], v[2:5]
	v_mfma_f32_16x16x32_bf16 v[54:57], v[192:195], v[208:211], v[54:57]
	v_mfma_f32_16x16x32_bf16 v[50:53], v[200:203], v[208:211], v[50:53]
	v_mfma_f32_16x16x32_bf16 v[38:41], v[192:195], v[216:219], v[38:41]
	v_mfma_f32_16x16x32_bf16 v[34:37], v[200:203], v[216:219], v[34:37]
	v_mfma_f32_16x16x32_bf16 v[22:25], v[192:195], v[224:227], v[22:25]
	v_mfma_f32_16x16x32_bf16 v[18:21], v[200:203], v[224:227], v[18:21]
	v_mfma_f32_16x16x32_bf16 v[6:9], v[192:195], v[232:235], v[6:9]
	v_mfma_f32_16x16x32_bf16 v[2:5], v[200:203], v[232:235], v[2:5]
	s_barrier
	s_add_i32 s54, s54, 2
	s_add_u32 s28, s28, 0x100
	s_addc_u32 s29, s29, 0
	s_add_u32 s52, s52, 0x10000
	s_addc_u32 s53, s53, 0
	s_cmp_gt_u32 s54, 29

; template <class Epi, class Sched, bool ABLK = false, bool ALIGN_EPI = true, bool SP2 = true, bool BBLK = true>
; __device__ __forceinline__ void gemm_phase(LAS unsigned char* lds, const Gemm g, const Sched& S, const Epi& E) {
;     ...
;     auto a_unit = [&](const Unit& u) -> const char* { return ABLK ? (const char*)g.A + (size_t)u.pm * ((size_t)g.lda / 64) * 32768 : (const char*)g.A + (size_t)u.pm * 2 * hstepA; };
;     auto a_tile = [&](const char* ub, int tau) -> const char* { return ub + (size_t)tau * (ABLK ? (size_t)32768 : kstep); };
;     ...
;     for (;;) {
;         const bool has_next = S.next(ui + 1, nxt);
;         const int nt = cur.nt;
;         const char* nuA = has_next ? a_unit(nxt) : uA; const int ntbA = has_next ? nxt.k0 / BK : tbA; const char* nB = has_next ? (const char*)g.Bt + (size_t)nxt.pn * tstepB + b_k0(nxt.k0) : cB;
;         for (int t = 0; t < nt; t += 2) {
;             const bool last = (t == nt - 2);
;             const char* a1 = a_tile(uA, tbA + t + 1);
;             const char* a2 = last ? a_tile(nuA, ntbA) : a_tile(uA, tbA + t + 2); const char* b2 = last ? nB : cB + (size_t)(t + 2) * kstepB;
;             const char* a3 = last ? a_tile(nuA, ntbA + 1) : a_tile(uA, tbA + t + 3); const char* b3 = b2 + kstepB;
;             if (last && has_next) S.a_ready(nxt);
;             if constexpr (SP2) {
;             PG8_LDB(B0, 0, 0); PG8_LDB(B1, 0, 1); PG8_SCHED; PG8_LDA(At, 0, 0); PG8_STAGE(PG8_SA(1, 1), a1 + hstepA, voffA);
;             PG8_WAIT_V(8); PG8_WAIT_L(0); PG8_BAR; PG8_MMA(0, 0, At, B0); PG8_MMA(0, 1, At, B1); PG8_BAR; PG8_SCHED;
;             PG8_LDA(At, 0, 1); PG8_STAGE(PG8_SB(0, 0), b2, voffB); PG8_STAGE(PG8_SB(0, 1), b2 + hstepB, voffB); PG8_STAGE(PG8_SA(0, 0), a2, voffA);
;             PG8_WAIT_V(8); PG8_WAIT_L(0); PG8_BAR; PG8_MMA(1, 0, At, B0); PG8_MMA(1, 1, At, B1); PG8_BAR; PG8_SCHED;
;             PG8_LDB(B0, 1, 0); PG8_LDB(B1, 1, 1); PG8_SCHED; PG8_LDA(At, 1, 0); PG8_STAGE(PG8_SA(0, 1), a2 + hstepA, voffA);
;             PG8_WAIT_V(8); PG8_WAIT_L(0); PG8_BAR; PG8_MMA(0, 0, At, B0); PG8_MMA(0, 1, At, B1); PG8_BAR; PG8_SCHED;
;             PG8_LDA(At, 1, 1); PG8_STAGE(PG8_SB(1, 0), b3, voffB); PG8_STAGE(PG8_SB(1, 1), b3 + hstepB, voffB); PG8_STAGE(PG8_SA(1, 0), a3, voffA);
;             PG8_WAIT_V(8); PG8_WAIT_L(0); PG8_BAR; PG8_MMA(1, 0, At, B0); PG8_MMA(1, 1, At, B1); PG8_BAR; PG8_SCHED;
.LBB0_1906:
	s_ashr_i32 s81, s80, 31
	s_andn2_b64 vcc, exec, s[4:5]
	s_lshl_b64 s[24:25], s[80:81], 22
	s_add_u32 s24, s62, s24
	s_addc_u32 s25, s83, s25
	s_and_b64 s[26:27], s[4:5], exec
	s_cselect_b32 s37, s25, s35
	s_cselect_b32 s50, s24, s34
	s_ashr_i32 s26, s0, 31
	s_lshr_b32 s26, s26, 26
	s_add_i32 s26, s0, s26
	s_ashr_i32 s26, s26, 6
	s_and_b64 s[28:29], s[4:5], exec
	s_cselect_b32 s38, s26, s36
	s_ashr_i32 s79, s78, 31
	s_lshl_b64 s[28:29], s[78:79], 22
	s_add_u32 s39, s1, s28
	s_addc_u32 s51, s33, s29
	s_ashr_i32 s27, s26, 31
	s_lshl_b64 s[28:29], s[26:27], 15
	s_add_u32 s28, s39, s28
	s_addc_u32 s29, s51, s29
	v_cndmask_b32_e64 v2, 0, 1, s[4:5]
	s_and_b64 s[4:5], s[4:5], exec
	s_cselect_b32 s4, s29, s31
	s_cselect_b32 s5, s28, s30
	s_ashr_i32 s39, s38, 31
	s_lshl_b64 s[38:39], s[38:39], 15
	s_add_u32 s27, s50, s38
	s_addc_u32 s50, s37, s39
	s_add_u32 s51, s27, 0x8000
	s_addc_u32 s52, s50, 0
	s_add_u32 s53, s30, 0x10000
	s_addc_u32 s54, s31, 0
	s_ashr_i32 s37, s36, 31
	v_cmp_ne_u32_e64 s[10:11], 1, v2
	s_lshl_b64 s[30:31], s[36:37], 15
	v_lshl_add_u64 v[2:3], s[34:35], 0, v[138:139]
	s_add_u32 s55, s34, s30
	v_lshl_add_u64 v[142:143], v[2:3], 0, s[30:31]
	v_lshl_add_u64 v[2:3], s[34:35], 0, v[140:141]
	s_addc_u32 s56, s35, s31
	v_lshl_add_u64 v[144:145], v[2:3], 0, s[30:31]
	s_lshl_b32 s30, s48, 15
	s_add_i32 s30, s30, 0xfff00000
	v_mov_b32_e32 v2, 0
	s_add_u32 s57, s30, 0xf0000
	s_mov_b32 s58, 0
	s_mov_b64 s[30:31], 0
	ds_read_b128 v[152:155], v148
	ds_read_b128 v[156:159], v148 offset:1024
	ds_read_b128 v[160:163], v148 offset:2048
	ds_read_b128 v[164:167], v148 offset:3072
	ds_read_b128 v[168:171], v149
	ds_read_b128 v[172:175], v149 offset:1024
	ds_read_b128 v[176:179], v149 offset:2048
	ds_read_b128 v[180:183], v149 offset:3072
	s_add_u32 s34, s55, s30
	s_addc_u32 s35, s56, s31
	s_add_u32 s38, s34, 0x10000
	s_addc_u32 s39, s35, 0
	s_add_i32 s58, s58, 2
	s_add_u32 s36, s53, s30
	s_addc_u32 s37, s54, s31
	s_add_u32 s34, s34, 0x18000
	s_addc_u32 s35, s35, 0
	s_cmp_eq_u32 s57, s30
	s_cselect_b32 s35, s52, s35
	s_cselect_b32 s34, s51, s34
	s_cselect_b32 s37, s4, s37
	s_cselect_b32 s36, s5, s36
	s_cselect_b32 s39, s50, s39
	s_cselect_b32 s38, s27, s38
	v_lshl_add_u64 v[216:217], v[142:143], 0, s[30:31]
	s_add_i32 m0, s41, 0xc000
	ds_read_b128 v[184:187], v150
	ds_read_b128 v[188:191], v150 offset:1024
	ds_read_b128 v[192:195], v150 offset:2048
	ds_read_b128 v[196:199], v150 offset:3072
	ds_read_b128 v[200:203], v150 offset:4096
	ds_read_b128 v[204:207], v150 offset:5120
	ds_read_b128 v[208:211], v150 offset:6144
	ds_read_b128 v[212:215], v150 offset:7168
	global_load_lds_dwordx4 v[216:217], off
	v_lshl_add_u64 v[216:217], v[144:145], 0, s[30:31]
	s_add_i32 m0, s41, 0xe000
	s_nop 0
	global_load_lds_dwordx4 v[216:217], off
	s_waitcnt vmcnt(8) lgkmcnt(0)
	s_barrier
	v_mfma_f32_16x16x32_bf16 v[126:129], v[152:155], v[184:187], 0
	v_mfma_f32_16x16x32_bf16 v[122:125], v[160:163], v[184:187], 0
	v_mfma_f32_16x16x32_bf16 v[110:113], v[152:155], v[192:195], 0
	v_mfma_f32_16x16x32_bf16 v[106:109], v[160:163], v[192:195], 0
	v_mfma_f32_16x16x32_bf16 v[94:97], v[152:155], v[200:203], 0
	v_mfma_f32_16x16x32_bf16 v[90:93], v[160:163], v[200:203], 0
	v_mfma_f32_16x16x32_bf16 v[78:81], v[152:155], v[208:211], 0
	v_mfma_f32_16x16x32_bf16 v[74:77], v[160:163], v[208:211], 0
	v_mfma_f32_16x16x32_bf16 v[126:129], v[156:159], v[188:191], v[126:129]
	v_mfma_f32_16x16x32_bf16 v[122:125], v[164:167], v[188:191], v[122:125]
	v_mfma_f32_16x16x32_bf16 v[110:113], v[156:159], v[196:199], v[110:113]
	v_mfma_f32_16x16x32_bf16 v[106:109], v[164:167], v[196:199], v[106:109]
	v_mfma_f32_16x16x32_bf16 v[94:97], v[156:159], v[204:207], v[94:97]
	v_mfma_f32_16x16x32_bf16 v[90:93], v[164:167], v[204:207], v[90:93]
	v_mfma_f32_16x16x32_bf16 v[78:81], v[156:159], v[212:215], v[78:81]
	v_mfma_f32_16x16x32_bf16 v[74:77], v[164:167], v[212:215], v[74:77]
	v_mfma_f32_16x16x32_bf16 v[118:121], v[168:171], v[184:187], 0
	v_mfma_f32_16x16x32_bf16 v[114:117], v[176:179], v[184:187], 0
	v_mfma_f32_16x16x32_bf16 v[102:105], v[168:171], v[192:195], 0
	v_mfma_f32_16x16x32_bf16 v[98:101], v[176:179], v[192:195], 0
	v_mfma_f32_16x16x32_bf16 v[86:89], v[168:171], v[200:203], 0
	v_mfma_f32_16x16x32_bf16 v[82:85], v[176:179], v[200:203], 0
	v_mfma_f32_16x16x32_bf16 v[70:73], v[168:171], v[208:211], 0
	v_mfma_f32_16x16x32_bf16 v[66:69], v[176:179], v[208:211], 0
	v_mfma_f32_16x16x32_bf16 v[118:121], v[172:175], v[188:191], v[118:121]
	v_mfma_f32_16x16x32_bf16 v[114:117], v[180:183], v[188:191], v[114:117]
	v_mfma_f32_16x16x32_bf16 v[102:105], v[172:175], v[196:199], v[102:105]
	v_mfma_f32_16x16x32_bf16 v[98:101], v[180:183], v[196:199], v[98:101]
	v_mfma_f32_16x16x32_bf16 v[86:89], v[172:175], v[204:207], v[86:89]
	v_mfma_f32_16x16x32_bf16 v[82:85], v[180:183], v[204:207], v[82:85]
	v_mfma_f32_16x16x32_bf16 v[70:73], v[172:175], v[212:215], v[70:73]
	v_mfma_f32_16x16x32_bf16 v[66:69], v[180:183], v[212:215], v[66:69]
	s_barrier
	s_add_i32 s59, s72, s40
	s_mov_b32 m0, s59
	ds_read_b128 v[184:187], v150 offset:16384
	ds_read_b128 v[188:191], v150 offset:17408
	ds_read_b128 v[192:195], v150 offset:18432
	ds_read_b128 v[196:199], v150 offset:19456
	ds_read_b128 v[200:203], v150 offset:20480
	ds_read_b128 v[204:207], v150 offset:21504
	ds_read_b128 v[208:211], v150 offset:22528
	ds_read_b128 v[212:215], v150 offset:23552
	global_load_lds_dwordx4 v130, s[36:37]
	s_add_i32 m0, s59, 0x2000
	s_add_u32 s64, s36, 0x4000
	s_addc_u32 s65, s37, 0
	s_add_i32 s59, s73, s40
	global_load_lds_dwordx4 v132, s[36:37]
	s_mov_b32 m0, s59
	s_nop 0
	global_load_lds_dwordx4 v130, s[64:65]
	s_add_i32 m0, s59, 0x2000
	s_nop 0
	global_load_lds_dwordx4 v132, s[64:65]
	s_mov_b32 m0, s41
	s_nop 0
	global_load_lds_dwordx4 v130, s[38:39]
	s_mov_b32 m0, s42
	s_nop 0
	global_load_lds_dwordx4 v132, s[38:39]
	s_waitcnt vmcnt(8) lgkmcnt(0)
	s_barrier
; #define PG8_STAGE(bufoff, gbase, voff) do { _Pragma("unroll") for (int _i = 0; _i < 2; ++_i) \
;         __builtin_amdgcn_global_load_lds((const unsigned*)((const char*)(gbase) + (voff)[_i]), (LAS unsigned*)(lds + (bufoff) + ldsw + _i * 8192), 16, 0, 0); } while (0)
; #define PG8_LDA(dst, b, h) do { _Pragma("unroll") for (int m = 0; m < 4; ++m) _Pragma("unroll") for (int k = 0; k < 2; ++k) dst[m][k] = *(const LAS bf16x8*)(lds + PG8_SA(b, h) + aoff + m * 2048 + k * 1024); } while (0)
; #define PG8_LDB(dst, b, h) do { _Pragma("unroll") for (int n = 0; n < 2; ++n) _Pragma("unroll") for (int k = 0; k < 2; ++k) dst[n][k] = *(const LAS bf16x8*)(lds + PG8_SB(b, h) + boff + n * 2048 + k * 1024); } while (0)
; #define PG8_MMA(ai, bj, At, Bt) do { __builtin_amdgcn_s_setprio(1); _Pragma("unroll") for (int m = 0; m < 4; ++m) _Pragma("unroll") for (int n = 0; n < 2; ++n) _Pragma("unroll") for (int k = 0; k < 2; ++k) \
;         acc[ai][bj][m][n] = __builtin_amdgcn_mfma_f32_16x16x32_bf16(Bt[n][k], At[m][k], acc[ai][bj][m][n], 0, 0, 0); __builtin_amdgcn_s_setprio(0); } while (0)
; #define PG8_BAR __builtin_amdgcn_s_barrier()
; template <class Epi, class Sched, bool ABLK = false, bool ALIGN_EPI = true, bool SP2 = true, bool BBLK = true>
; __device__ __forceinline__ void gemm_phase(LAS unsigned char* lds, const Gemm g, const Sched& S, const Epi& E) {
;     ...
;             PG8_LDB(B0, 0, 0); PG8_LDB(B1, 0, 1); PG8_SCHED; PG8_LDA(At, 0, 0); PG8_STAGE(PG8_SA(1, 1), a1 + hstepA, voffA);
;             PG8_WAIT_V(8); PG8_WAIT_L(0); PG8_BAR; PG8_MMA(0, 0, At, B0); PG8_MMA(0, 1, At, B1); PG8_BAR; PG8_SCHED;
;             PG8_LDA(At, 0, 1); PG8_STAGE(PG8_SB(0, 0), b2, voffB); PG8_STAGE(PG8_SB(0, 1), b2 + hstepB, voffB); PG8_STAGE(PG8_SA(0, 0), a2, voffA);
;             PG8_WAIT_V(8); PG8_WAIT_L(0); PG8_BAR; PG8_MMA(1, 0, At, B0); PG8_MMA(1, 1, At, B1); PG8_BAR; PG8_SCHED;
;             PG8_LDB(B0, 1, 0); PG8_LDB(B1, 1, 1); PG8_SCHED; PG8_LDA(At, 1, 0); PG8_STAGE(PG8_SA(0, 1), a2 + hstepA, voffA);
;             PG8_WAIT_V(8); PG8_WAIT_L(0); PG8_BAR; PG8_MMA(0, 0, At, B0); PG8_MMA(0, 1, At, B1); PG8_BAR; PG8_SCHED;
;             PG8_LDA(At, 1, 1); PG8_STAGE(PG8_SB(1, 0), b3, voffB); PG8_STAGE(PG8_SB(1, 1), b3 + hstepB, voffB); PG8_STAGE(PG8_SA(1, 0), a3, voffA);
;             PG8_WAIT_V(8); PG8_WAIT_L(0); PG8_BAR; PG8_MMA(1, 0, At, B0); PG8_MMA(1, 1, At, B1); PG8_BAR; PG8_SCHED;
	v_mfma_f32_16x16x32_bf16 v[62:65], v[152:155], v[184:187], 0
	v_mfma_f32_16x16x32_bf16 v[58:61], v[160:163], v[184:187], 0
	v_mfma_f32_16x16x32_bf16 v[46:49], v[152:155], v[192:195], 0
	v_mfma_f32_16x16x32_bf16 v[42:45], v[160:163], v[192:195], 0
	v_mfma_f32_16x16x32_bf16 v[30:33], v[152:155], v[200:203], 0
	v_mfma_f32_16x16x32_bf16 v[26:29], v[160:163], v[200:203], 0
	v_mfma_f32_16x16x32_bf16 v[14:17], v[152:155], v[208:211], 0
	v_mfma_f32_16x16x32_bf16 v[10:13], v[160:163], v[208:211], 0
	v_mfma_f32_16x16x32_bf16 v[62:65], v[156:159], v[188:191], v[62:65]
	v_mfma_f32_16x16x32_bf16 v[58:61], v[164:167], v[188:191], v[58:61]
	v_mfma_f32_16x16x32_bf16 v[46:49], v[156:159], v[196:199], v[46:49]
	v_mfma_f32_16x16x32_bf16 v[42:45], v[164:167], v[196:199], v[42:45]
	v_mfma_f32_16x16x32_bf16 v[30:33], v[156:159], v[204:207], v[30:33]
	v_mfma_f32_16x16x32_bf16 v[26:29], v[164:167], v[204:207], v[26:29]
	v_mfma_f32_16x16x32_bf16 v[14:17], v[156:159], v[212:215], v[14:17]
	v_mfma_f32_16x16x32_bf16 v[10:13], v[164:167], v[212:215], v[10:13]
	v_mfma_f32_16x16x32_bf16 v[54:57], v[168:171], v[184:187], 0
	v_mfma_f32_16x16x32_bf16 v[50:53], v[176:179], v[184:187], 0
	v_mfma_f32_16x16x32_bf16 v[38:41], v[168:171], v[192:195], 0
	v_mfma_f32_16x16x32_bf16 v[34:37], v[176:179], v[192:195], 0
	v_mfma_f32_16x16x32_bf16 v[22:25], v[168:171], v[200:203], 0
	v_mfma_f32_16x16x32_bf16 v[18:21], v[176:179], v[200:203], 0
	v_mfma_f32_16x16x32_bf16 v[6:9], v[168:171], v[208:211], 0
	v_mfma_f32_16x16x32_bf16 v[2:5], v[176:179], v[208:211], 0
	v_mfma_f32_16x16x32_bf16 v[54:57], v[172:175], v[188:191], v[54:57]
	v_mfma_f32_16x16x32_bf16 v[50:53], v[180:183], v[188:191], v[50:53]
	v_mfma_f32_16x16x32_bf16 v[38:41], v[172:175], v[196:199], v[38:41]
	v_mfma_f32_16x16x32_bf16 v[34:37], v[180:183], v[196:199], v[34:37]
	v_mfma_f32_16x16x32_bf16 v[22:25], v[172:175], v[204:207], v[22:25]
	v_mfma_f32_16x16x32_bf16 v[18:21], v[180:183], v[204:207], v[18:21]
	v_mfma_f32_16x16x32_bf16 v[6:9], v[172:175], v[212:215], v[6:9]
	v_mfma_f32_16x16x32_bf16 v[2:5], v[180:183], v[212:215], v[2:5]
	s_barrier
	v_add_u32_e32 v151, s60, v146
	ds_read_b128 v[152:155], v151
	ds_read_b128 v[156:159], v151 offset:1024
	ds_read_b128 v[160:163], v151 offset:2048
	ds_read_b128 v[164:167], v151 offset:3072
	v_add_u32_e32 v151, s61, v146
	ds_read_b128 v[168:171], v151
	ds_read_b128 v[172:175], v151 offset:1024
	ds_read_b128 v[176:179], v151 offset:2048
	ds_read_b128 v[180:183], v151 offset:3072
	s_add_u32 s38, s38, 0x4000
	s_addc_u32 s39, s39, 0
	s_mov_b32 m0, s43
	ds_read_b128 v[184:187], v150 offset:32768
	ds_read_b128 v[188:191], v150 offset:33792
	ds_read_b128 v[192:195], v150 offset:34816
	ds_read_b128 v[196:199], v150 offset:35840
	ds_read_b128 v[200:203], v150 offset:36864
	ds_read_b128 v[204:207], v150 offset:37888
	ds_read_b128 v[208:211], v150 offset:38912
	ds_read_b128 v[212:215], v150 offset:39936
	global_load_lds_dwordx4 v130, s[38:39]
	s_mov_b32 m0, s44
	s_nop 0
	global_load_lds_dwordx4 v132, s[38:39]
	s_waitcnt vmcnt(8) lgkmcnt(0)
	s_barrier
	v_mfma_f32_16x16x32_bf16 v[126:129], v[152:155], v[184:187], v[126:129]
	v_mfma_f32_16x16x32_bf16 v[122:125], v[160:163], v[184:187], v[122:125]
	v_mfma_f32_16x16x32_bf16 v[110:113], v[152:155], v[192:195], v[110:113]
	v_mfma_f32_16x16x32_bf16 v[106:109], v[160:163], v[192:195], v[106:109]
	v_mfma_f32_16x16x32_bf16 v[94:97], v[152:155], v[200:203], v[94:97]
	v_mfma_f32_16x16x32_bf16 v[90:93], v[160:163], v[200:203], v[90:93]
	v_mfma_f32_16x16x32_bf16 v[78:81], v[152:155], v[208:211], v[78:81]
	v_mfma_f32_16x16x32_bf16 v[74:77], v[160:163], v[208:211], v[74:77]
	v_mfma_f32_16x16x32_bf16 v[126:129], v[156:159], v[188:191], v[126:129]
	v_mfma_f32_16x16x32_bf16 v[122:125], v[164:167], v[188:191], v[122:125]
	v_mfma_f32_16x16x32_bf16 v[110:113], v[156:159], v[196:199], v[110:113]
	v_mfma_f32_16x16x32_bf16 v[106:109], v[164:167], v[196:199], v[106:109]
	v_mfma_f32_16x16x32_bf16 v[94:97], v[156:159], v[204:207], v[94:97]
	v_mfma_f32_16x16x32_bf16 v[90:93], v[164:167], v[204:207], v[90:93]
	v_mfma_f32_16x16x32_bf16 v[78:81], v[156:159], v[212:215], v[78:81]
	v_mfma_f32_16x16x32_bf16 v[74:77], v[164:167], v[212:215], v[74:77]
	v_mfma_f32_16x16x32_bf16 v[118:121], v[168:171], v[184:187], v[118:121]
	v_mfma_f32_16x16x32_bf16 v[114:117], v[176:179], v[184:187], v[114:117]
	v_mfma_f32_16x16x32_bf16 v[102:105], v[168:171], v[192:195], v[102:105]
	v_mfma_f32_16x16x32_bf16 v[98:101], v[176:179], v[192:195], v[98:101]
	v_mfma_f32_16x16x32_bf16 v[86:89], v[168:171], v[200:203], v[86:89]
	v_mfma_f32_16x16x32_bf16 v[82:85], v[176:179], v[200:203], v[82:85]
	v_mfma_f32_16x16x32_bf16 v[70:73], v[168:171], v[208:211], v[70:73]
	v_mfma_f32_16x16x32_bf16 v[66:69], v[176:179], v[208:211], v[66:69]
	v_mfma_f32_16x16x32_bf16 v[118:121], v[172:175], v[188:191], v[118:121]
	v_mfma_f32_16x16x32_bf16 v[114:117], v[180:183], v[188:191], v[114:117]
	v_mfma_f32_16x16x32_bf16 v[102:105], v[172:175], v[196:199], v[102:105]
	v_mfma_f32_16x16x32_bf16 v[98:101], v[180:183], v[196:199], v[98:101]
	v_mfma_f32_16x16x32_bf16 v[86:89], v[172:175], v[204:207], v[86:89]
	v_mfma_f32_16x16x32_bf16 v[82:85], v[180:183], v[204:207], v[82:85]
	v_mfma_f32_16x16x32_bf16 v[70:73], v[172:175], v[212:215], v[70:73]
	v_mfma_f32_16x16x32_bf16 v[66:69], v[180:183], v[212:215], v[66:69]
	s_barrier
; #define PG8_STAGE(bufoff, gbase, voff) do { _Pragma("unroll") for (int _i = 0; _i < 2; ++_i) \
;         __builtin_amdgcn_global_load_lds((const unsigned*)((const char*)(gbase) + (voff)[_i]), (LAS unsigned*)(lds + (bufoff) + ldsw + _i * 8192), 16, 0, 0); } while (0)
; #define PG8_LDA(dst, b, h) do { _Pragma("unroll") for (int m = 0; m < 4; ++m) _Pragma("unroll") for (int k = 0; k < 2; ++k) dst[m][k] = *(const LAS bf16x8*)(lds + PG8_SA(b, h) + aoff + m * 2048 + k * 1024); } while (0)
; #define PG8_LDB(dst, b, h) do { _Pragma("unroll") for (int n = 0; n < 2; ++n) _Pragma("unroll") for (int k = 0; k < 2; ++k) dst[n][k] = *(const LAS bf16x8*)(lds + PG8_SB(b, h) + boff + n * 2048 + k * 1024); } while (0)
; #define PG8_MMA(ai, bj, At, Bt) do { __builtin_amdgcn_s_setprio(1); _Pragma("unroll") for (int m = 0; m < 4; ++m) _Pragma("unroll") for (int n = 0; n < 2; ++n) _Pragma("unroll") for (int k = 0; k < 2; ++k) \
;         acc[ai][bj][m][n] = __builtin_amdgcn_mfma_f32_16x16x32_bf16(Bt[n][k], At[m][k], acc[ai][bj][m][n], 0, 0, 0); __builtin_amdgcn_s_setprio(0); } while (0)
; template <class Epi, class Sched, bool ABLK = false, bool ALIGN_EPI = true, bool SP2 = true, bool BBLK = true>
; __device__ __forceinline__ void gemm_phase(LAS unsigned char* lds, const Gemm g, const Sched& S, const Epi& E) {
;     ...
;         for (int t = 0; t < nt; t += 2) {
;     ...
;             PG8_LDB(B0, 0, 0); PG8_LDB(B1, 0, 1); PG8_SCHED; PG8_LDA(At, 0, 0); PG8_STAGE(PG8_SA(1, 1), a1 + hstepA, voffA);
;             PG8_WAIT_V(8); PG8_WAIT_L(0); PG8_BAR; PG8_MMA(0, 0, At, B0); PG8_MMA(0, 1, At, B1); PG8_BAR; PG8_SCHED;
;             PG8_LDA(At, 0, 1); PG8_STAGE(PG8_SB(0, 0), b2, voffB); PG8_STAGE(PG8_SB(0, 1), b2 + hstepB, voffB); PG8_STAGE(PG8_SA(0, 0), a2, voffA);
;             PG8_WAIT_V(8); PG8_WAIT_L(0); PG8_BAR; PG8_MMA(1, 0, At, B0); PG8_MMA(1, 1, At, B1); PG8_BAR; PG8_SCHED;
;             PG8_LDB(B0, 1, 0); PG8_LDB(B1, 1, 1); PG8_SCHED; PG8_LDA(At, 1, 0); PG8_STAGE(PG8_SA(0, 1), a2 + hstepA, voffA);
;             PG8_WAIT_V(8); PG8_WAIT_L(0); PG8_BAR; PG8_MMA(0, 0, At, B0); PG8_MMA(0, 1, At, B1); PG8_BAR; PG8_SCHED;
;             PG8_LDA(At, 1, 1); PG8_STAGE(PG8_SB(1, 0), b3, voffB); PG8_STAGE(PG8_SB(1, 1), b3 + hstepB, voffB); PG8_STAGE(PG8_SA(1, 0), a3, voffA);
;             PG8_WAIT_V(8); PG8_WAIT_L(0); PG8_BAR; PG8_MMA(1, 0, At, B0); PG8_MMA(1, 1, At, B1); PG8_BAR; PG8_SCHED;
	s_add_u32 s38, s36, 0x8000
	s_addc_u32 s39, s37, 0
	s_add_i32 s59, s60, s40
	s_mov_b32 m0, s59
	ds_read_b128 v[184:187], v150 offset:49152
	ds_read_b128 v[188:191], v150 offset:50176
	ds_read_b128 v[192:195], v150 offset:51200
	ds_read_b128 v[196:199], v150 offset:52224
	ds_read_b128 v[200:203], v150 offset:53248
	ds_read_b128 v[204:207], v150 offset:54272
	ds_read_b128 v[208:211], v150 offset:55296
	ds_read_b128 v[212:215], v150 offset:56320
	global_load_lds_dwordx4 v130, s[38:39]
	s_add_i32 m0, s59, 0x2000
	s_add_u32 s36, s36, 0xc000
	v_lshl_add_u64 v[216:217], s[38:39], 0, v[132:133]
	s_addc_u32 s37, s37, 0
	s_add_i32 s38, s61, s40
	global_load_lds_dwordx4 v[216:217], off
	s_mov_b32 m0, s38
	s_nop 0
	global_load_lds_dwordx4 v130, s[36:37]
	s_add_i32 m0, s38, 0x2000
	s_nop 0
	global_load_lds_dwordx4 v132, s[36:37]
	s_mov_b32 m0, s45
	s_nop 0
	global_load_lds_dwordx4 v130, s[34:35]
	s_mov_b32 m0, s46
	s_nop 0
	global_load_lds_dwordx4 v132, s[34:35]
	s_waitcnt vmcnt(8) lgkmcnt(0)
	s_barrier
	v_mfma_f32_16x16x32_bf16 v[62:65], v[152:155], v[184:187], v[62:65]
	v_mfma_f32_16x16x32_bf16 v[58:61], v[160:163], v[184:187], v[58:61]
	v_mfma_f32_16x16x32_bf16 v[46:49], v[152:155], v[192:195], v[46:49]
	v_mfma_f32_16x16x32_bf16 v[42:45], v[160:163], v[192:195], v[42:45]
	v_mfma_f32_16x16x32_bf16 v[30:33], v[152:155], v[200:203], v[30:33]
	v_mfma_f32_16x16x32_bf16 v[26:29], v[160:163], v[200:203], v[26:29]
	v_mfma_f32_16x16x32_bf16 v[14:17], v[152:155], v[208:211], v[14:17]
	v_mfma_f32_16x16x32_bf16 v[10:13], v[160:163], v[208:211], v[10:13]
	v_mfma_f32_16x16x32_bf16 v[62:65], v[156:159], v[188:191], v[62:65]
	v_mfma_f32_16x16x32_bf16 v[58:61], v[164:167], v[188:191], v[58:61]
	v_mfma_f32_16x16x32_bf16 v[46:49], v[156:159], v[196:199], v[46:49]
	v_mfma_f32_16x16x32_bf16 v[42:45], v[164:167], v[196:199], v[42:45]
	v_mfma_f32_16x16x32_bf16 v[30:33], v[156:159], v[204:207], v[30:33]
	v_mfma_f32_16x16x32_bf16 v[26:29], v[164:167], v[204:207], v[26:29]
	v_mfma_f32_16x16x32_bf16 v[14:17], v[156:159], v[212:215], v[14:17]
	v_mfma_f32_16x16x32_bf16 v[10:13], v[164:167], v[212:215], v[10:13]
	v_mfma_f32_16x16x32_bf16 v[54:57], v[168:171], v[184:187], v[54:57]
	v_mfma_f32_16x16x32_bf16 v[50:53], v[176:179], v[184:187], v[50:53]
	v_mfma_f32_16x16x32_bf16 v[38:41], v[168:171], v[192:195], v[38:41]
	v_mfma_f32_16x16x32_bf16 v[34:37], v[176:179], v[192:195], v[34:37]
	v_mfma_f32_16x16x32_bf16 v[22:25], v[168:171], v[200:203], v[22:25]
	v_mfma_f32_16x16x32_bf16 v[18:21], v[176:179], v[200:203], v[18:21]
	v_mfma_f32_16x16x32_bf16 v[6:9], v[168:171], v[208:211], v[6:9]
	v_mfma_f32_16x16x32_bf16 v[2:5], v[176:179], v[208:211], v[2:5]
	v_mfma_f32_16x16x32_bf16 v[54:57], v[172:175], v[188:191], v[54:57]
	v_mfma_f32_16x16x32_bf16 v[50:53], v[180:183], v[188:191], v[50:53]
	v_mfma_f32_16x16x32_bf16 v[38:41], v[172:175], v[196:199], v[38:41]
	v_mfma_f32_16x16x32_bf16 v[34:37], v[180:183], v[196:199], v[34:37]
	v_mfma_f32_16x16x32_bf16 v[22:25], v[172:175], v[204:207], v[22:25]
	v_mfma_f32_16x16x32_bf16 v[18:21], v[180:183], v[204:207], v[18:21]
	v_mfma_f32_16x16x32_bf16 v[6:9], v[172:175], v[212:215], v[6:9]
	v_mfma_f32_16x16x32_bf16 v[2:5], v[180:183], v[212:215], v[2:5]
	s_barrier
	s_add_u32 s30, s30, 0x10000
	s_addc_u32 s31, s31, 0
	s_cmp_ge_u32 s58, s48

; template <class Epi, class Sched, bool ABLK = false, bool ALIGN_EPI = true, bool SP2 = true, bool BBLK = true>
; __device__ __forceinline__ void gemm_phase(LAS unsigned char* lds, const Gemm g, const Sched& S, const Epi& E) {
;     ...
;     auto a_unit = [&](const Unit& u) -> const char* { return ABLK ? (const char*)g.A + (size_t)u.pm * ((size_t)g.lda / 64) * 32768 : (const char*)g.A + (size_t)u.pm * 2 * hstepA; };
;     auto a_tile = [&](const char* ub, int tau) -> const char* { return ub + (size_t)tau * (ABLK ? (size_t)32768 : kstep); };
;     ...
;     for (;;) {
;         const bool has_next = S.next(ui + 1, nxt);
;         const int nt = cur.nt;
;         const char* nuA = has_next ? a_unit(nxt) : uA; const int ntbA = has_next ? nxt.k0 / BK : tbA; const char* nB = has_next ? (const char*)g.Bt + (size_t)nxt.pn * tstepB + b_k0(nxt.k0) : cB;
;         for (int t = 0; t < nt; t += 2) {
;             const bool last = (t == nt - 2);
;             const char* a1 = a_tile(uA, tbA + t + 1);
;             const char* a2 = last ? a_tile(nuA, ntbA) : a_tile(uA, tbA + t + 2); const char* b2 = last ? nB : cB + (size_t)(t + 2) * kstepB;
;             const char* a3 = last ? a_tile(nuA, ntbA + 1) : a_tile(uA, tbA + t + 3); const char* b3 = b2 + kstepB;
;             if (last && has_next) S.a_ready(nxt);
;             if constexpr (SP2) {
;             PG8_LDB(B0, 0, 0); PG8_LDB(B1, 0, 1); PG8_SCHED; PG8_LDA(At, 0, 0); PG8_STAGE(PG8_SA(1, 1), a1 + hstepA, voffA);
;             PG8_WAIT_V(8); PG8_WAIT_L(0); PG8_BAR; PG8_MMA(0, 0, At, B0); PG8_MMA(0, 1, At, B1); PG8_BAR; PG8_SCHED;
;             PG8_LDA(At, 0, 1); PG8_STAGE(PG8_SB(0, 0), b2, voffB); PG8_STAGE(PG8_SB(0, 1), b2 + hstepB, voffB); PG8_STAGE(PG8_SA(0, 0), a2, voffA);
;             PG8_WAIT_V(8); PG8_WAIT_L(0); PG8_BAR; PG8_MMA(1, 0, At, B0); PG8_MMA(1, 1, At, B1); PG8_BAR; PG8_SCHED;
;             PG8_LDB(B0, 1, 0); PG8_LDB(B1, 1, 1); PG8_SCHED; PG8_LDA(At, 1, 0); PG8_STAGE(PG8_SA(0, 1), a2 + hstepA, voffA);
;             PG8_WAIT_V(8); PG8_WAIT_L(0); PG8_BAR; PG8_MMA(0, 0, At, B0); PG8_MMA(0, 1, At, B1); PG8_BAR; PG8_SCHED;
;             PG8_LDA(At, 1, 1); PG8_STAGE(PG8_SB(1, 0), b3, voffB); PG8_STAGE(PG8_SB(1, 1), b3 + hstepB, voffB); PG8_STAGE(PG8_SA(1, 0), a3, voffA);
;             PG8_WAIT_V(8); PG8_WAIT_L(0); PG8_BAR; PG8_MMA(1, 0, At, B0); PG8_MMA(1, 1, At, B1); PG8_BAR; PG8_SCHED;
.LBB0_2137:
	s_ashr_i32 s11, s10, 31
	s_lshl_b64 s[4:5], s[10:11], 20
	s_add_u32 s14, s37, s4
	s_addc_u32 s15, s38, s5
	s_and_b64 s[4:5], s[16:17], exec
	s_cselect_b32 s4, s15, s25
	s_cselect_b32 s5, s14, s24
	s_ashr_i32 s13, s12, 31
	s_lshl_b64 s[18:19], s[12:13], 20
	s_add_u32 s18, s1, s18
	s_addc_u32 s19, s33, s19
	s_and_b64 s[28:29], s[16:17], exec
	s_cselect_b32 s11, s19, s27
	s_cselect_b32 s13, s18, s26
	s_add_u32 s48, s5, 0x80
	s_addc_u32 s49, s4, 0
	s_add_u32 s50, s26, 0x10000
	v_mov_b32_e32 v2, 0
	s_addc_u32 s51, s27, 0
	v_lshl_add_u64 v[142:143], s[24:25], 0, v[138:139]
	v_lshl_add_u64 v[144:145], s[24:25], 0, v[140:141]
	s_mov_b32 s52, -2
	s_mov_b64 s[26:27], 0
	ds_read_b128 v[152:155], v148
	ds_read_b128 v[156:159], v148 offset:1024
	ds_read_b128 v[160:163], v148 offset:2048
	ds_read_b128 v[164:167], v148 offset:3072
	ds_read_b128 v[168:171], v149
	ds_read_b128 v[172:175], v149 offset:1024
	ds_read_b128 v[176:179], v149 offset:2048
	ds_read_b128 v[180:183], v149 offset:3072
	s_add_u32 s28, s24, s26
	s_addc_u32 s29, s25, s27
	s_add_u32 s34, s28, 0x100
	s_addc_u32 s35, s29, 0
	s_add_u32 s28, s28, 0x180
	s_addc_u32 s29, s29, 0
	s_cmpk_eq_i32 s26, 0xf00
	s_cselect_b32 s29, s49, s29
	s_cselect_b32 s28, s48, s28
	s_cselect_b32 s31, s11, s51
	s_cselect_b32 s30, s13, s50
	s_cselect_b32 s35, s4, s35
	s_cselect_b32 s34, s5, s34
	s_mov_b32 m0, s47
	v_lshl_add_u64 v[216:217], v[142:143], 0, s[26:27]
	ds_read_b128 v[184:187], v150
	ds_read_b128 v[188:191], v150 offset:1024
	ds_read_b128 v[192:195], v150 offset:2048
	ds_read_b128 v[196:199], v150 offset:3072
	ds_read_b128 v[200:203], v150 offset:4096
	ds_read_b128 v[204:207], v150 offset:5120
	ds_read_b128 v[208:211], v150 offset:6144
	ds_read_b128 v[212:215], v150 offset:7168
	global_load_lds_dwordx4 v[216:217], off
	v_lshl_add_u64 v[216:217], v[144:145], 0, s[26:27]
	s_add_i32 m0, s21, 0xe000
	s_nop 0
	global_load_lds_dwordx4 v[216:217], off
	s_waitcnt vmcnt(8) lgkmcnt(0)
	s_barrier
	v_mfma_f32_16x16x32_bf16 v[122:125], v[152:155], v[184:187], 0
	v_mfma_f32_16x16x32_bf16 v[118:121], v[160:163], v[184:187], 0
	v_mfma_f32_16x16x32_bf16 v[106:109], v[152:155], v[192:195], 0
	v_mfma_f32_16x16x32_bf16 v[102:105], v[160:163], v[192:195], 0
	v_mfma_f32_16x16x32_bf16 v[90:93], v[152:155], v[200:203], 0
	v_mfma_f32_16x16x32_bf16 v[86:89], v[160:163], v[200:203], 0
	v_mfma_f32_16x16x32_bf16 v[74:77], v[152:155], v[208:211], 0
	v_mfma_f32_16x16x32_bf16 v[70:73], v[160:163], v[208:211], 0
	v_mfma_f32_16x16x32_bf16 v[122:125], v[156:159], v[188:191], v[122:125]
	v_mfma_f32_16x16x32_bf16 v[118:121], v[164:167], v[188:191], v[118:121]
	v_mfma_f32_16x16x32_bf16 v[106:109], v[156:159], v[196:199], v[106:109]
	v_mfma_f32_16x16x32_bf16 v[102:105], v[164:167], v[196:199], v[102:105]
	v_mfma_f32_16x16x32_bf16 v[90:93], v[156:159], v[204:207], v[90:93]
	v_mfma_f32_16x16x32_bf16 v[86:89], v[164:167], v[204:207], v[86:89]
	v_mfma_f32_16x16x32_bf16 v[74:77], v[156:159], v[212:215], v[74:77]
	v_mfma_f32_16x16x32_bf16 v[70:73], v[164:167], v[212:215], v[70:73]
	v_mfma_f32_16x16x32_bf16 v[126:129], v[168:171], v[184:187], 0
	v_mfma_f32_16x16x32_bf16 v[114:117], v[176:179], v[184:187], 0
	v_mfma_f32_16x16x32_bf16 v[110:113], v[168:171], v[192:195], 0
	v_mfma_f32_16x16x32_bf16 v[98:101], v[176:179], v[192:195], 0
	v_mfma_f32_16x16x32_bf16 v[94:97], v[168:171], v[200:203], 0
	v_mfma_f32_16x16x32_bf16 v[82:85], v[176:179], v[200:203], 0
	v_mfma_f32_16x16x32_bf16 v[78:81], v[168:171], v[208:211], 0
	v_mfma_f32_16x16x32_bf16 v[66:69], v[176:179], v[208:211], 0
	v_mfma_f32_16x16x32_bf16 v[126:129], v[172:175], v[188:191], v[126:129]
	v_mfma_f32_16x16x32_bf16 v[114:117], v[180:183], v[188:191], v[114:117]
	v_mfma_f32_16x16x32_bf16 v[110:113], v[172:175], v[196:199], v[110:113]
	v_mfma_f32_16x16x32_bf16 v[98:101], v[180:183], v[196:199], v[98:101]
	v_mfma_f32_16x16x32_bf16 v[94:97], v[172:175], v[204:207], v[94:97]
	v_mfma_f32_16x16x32_bf16 v[82:85], v[180:183], v[204:207], v[82:85]
	v_mfma_f32_16x16x32_bf16 v[78:81], v[172:175], v[212:215], v[78:81]
	v_mfma_f32_16x16x32_bf16 v[66:69], v[180:183], v[212:215], v[66:69]
	s_barrier
	s_add_i32 s53, s72, s36
	s_mov_b32 m0, s53
	ds_read_b128 v[184:187], v150 offset:16384
	ds_read_b128 v[188:191], v150 offset:17408
	ds_read_b128 v[192:195], v150 offset:18432
	ds_read_b128 v[196:199], v150 offset:19456
	ds_read_b128 v[200:203], v150 offset:20480
	ds_read_b128 v[204:207], v150 offset:21504
	ds_read_b128 v[208:211], v150 offset:22528
	ds_read_b128 v[212:215], v150 offset:23552
	global_load_lds_dwordx4 v134, s[30:31]
	s_add_i32 m0, s53, 0x2000
	s_add_u32 s54, s30, 0x4000
	s_addc_u32 s55, s31, 0
	s_add_i32 s53, s73, s36
	global_load_lds_dwordx4 v130, s[30:31]
	s_mov_b32 m0, s53
	s_nop 0
	global_load_lds_dwordx4 v134, s[54:55]
	s_add_i32 m0, s53, 0x2000
	s_nop 0
	global_load_lds_dwordx4 v130, s[54:55]
	s_mov_b32 m0, s21
	s_nop 0
	global_load_lds_dwordx4 v136, s[34:35]
	s_mov_b32 m0, s23
	s_nop 0
	global_load_lds_dwordx4 v132, s[34:35]
	s_waitcnt vmcnt(8) lgkmcnt(0)
	s_barrier
; #define PG8_STAGE(bufoff, gbase, voff) do { _Pragma("unroll") for (int _i = 0; _i < 2; ++_i) \
;         __builtin_amdgcn_global_load_lds((const unsigned*)((const char*)(gbase) + (voff)[_i]), (LAS unsigned*)(lds + (bufoff) + ldsw + _i * 8192), 16, 0, 0); } while (0)
; #define PG8_LDA(dst, b, h) do { _Pragma("unroll") for (int m = 0; m < 4; ++m) _Pragma("unroll") for (int k = 0; k < 2; ++k) dst[m][k] = *(const LAS bf16x8*)(lds + PG8_SA(b, h) + aoff + m * 2048 + k * 1024); } while (0)
; #define PG8_LDB(dst, b, h) do { _Pragma("unroll") for (int n = 0; n < 2; ++n) _Pragma("unroll") for (int k = 0; k < 2; ++k) dst[n][k] = *(const LAS bf16x8*)(lds + PG8_SB(b, h) + boff + n * 2048 + k * 1024); } while (0)
; #define PG8_MMA(ai, bj, At, Bt) do { __builtin_amdgcn_s_setprio(1); _Pragma("unroll") for (int m = 0; m < 4; ++m) _Pragma("unroll") for (int n = 0; n < 2; ++n) _Pragma("unroll") for (int k = 0; k < 2; ++k) \
;         acc[ai][bj][m][n] = __builtin_amdgcn_mfma_f32_16x16x32_bf16(Bt[n][k], At[m][k], acc[ai][bj][m][n], 0, 0, 0); __builtin_amdgcn_s_setprio(0); } while (0)
; #define PG8_BAR __builtin_amdgcn_s_barrier()
; template <class Epi, class Sched, bool ABLK = false, bool ALIGN_EPI = true, bool SP2 = true, bool BBLK = true>
; __device__ __forceinline__ void gemm_phase(LAS unsigned char* lds, const Gemm g, const Sched& S, const Epi& E) {
;     ...
;             PG8_LDB(B0, 0, 0); PG8_LDB(B1, 0, 1); PG8_SCHED; PG8_LDA(At, 0, 0); PG8_STAGE(PG8_SA(1, 1), a1 + hstepA, voffA);
;             PG8_WAIT_V(8); PG8_WAIT_L(0); PG8_BAR; PG8_MMA(0, 0, At, B0); PG8_MMA(0, 1, At, B1); PG8_BAR; PG8_SCHED;
;             PG8_LDA(At, 0, 1); PG8_STAGE(PG8_SB(0, 0), b2, voffB); PG8_STAGE(PG8_SB(0, 1), b2 + hstepB, voffB); PG8_STAGE(PG8_SA(0, 0), a2, voffA);
;             PG8_WAIT_V(8); PG8_WAIT_L(0); PG8_BAR; PG8_MMA(1, 0, At, B0); PG8_MMA(1, 1, At, B1); PG8_BAR; PG8_SCHED;
;             PG8_LDB(B0, 1, 0); PG8_LDB(B1, 1, 1); PG8_SCHED; PG8_LDA(At, 1, 0); PG8_STAGE(PG8_SA(0, 1), a2 + hstepA, voffA);
;             PG8_WAIT_V(8); PG8_WAIT_L(0); PG8_BAR; PG8_MMA(0, 0, At, B0); PG8_MMA(0, 1, At, B1); PG8_BAR; PG8_SCHED;
;             PG8_LDA(At, 1, 1); PG8_STAGE(PG8_SB(1, 0), b3, voffB); PG8_STAGE(PG8_SB(1, 1), b3 + hstepB, voffB); PG8_STAGE(PG8_SA(1, 0), a3, voffA);
;             PG8_WAIT_V(8); PG8_WAIT_L(0); PG8_BAR; PG8_MMA(1, 0, At, B0); PG8_MMA(1, 1, At, B1); PG8_BAR; PG8_SCHED;
	v_mfma_f32_16x16x32_bf16 v[58:61], v[152:155], v[184:187], 0
	v_mfma_f32_16x16x32_bf16 v[54:57], v[160:163], v[184:187], 0
	v_mfma_f32_16x16x32_bf16 v[42:45], v[152:155], v[192:195], 0
	v_mfma_f32_16x16x32_bf16 v[38:41], v[160:163], v[192:195], 0
	v_mfma_f32_16x16x32_bf16 v[26:29], v[152:155], v[200:203], 0
	v_mfma_f32_16x16x32_bf16 v[22:25], v[160:163], v[200:203], 0
	v_mfma_f32_16x16x32_bf16 v[10:13], v[152:155], v[208:211], 0
	v_mfma_f32_16x16x32_bf16 v[6:9], v[160:163], v[208:211], 0
	v_mfma_f32_16x16x32_bf16 v[58:61], v[156:159], v[188:191], v[58:61]
	v_mfma_f32_16x16x32_bf16 v[54:57], v[164:167], v[188:191], v[54:57]
	v_mfma_f32_16x16x32_bf16 v[42:45], v[156:159], v[196:199], v[42:45]
	v_mfma_f32_16x16x32_bf16 v[38:41], v[164:167], v[196:199], v[38:41]
	v_mfma_f32_16x16x32_bf16 v[26:29], v[156:159], v[204:207], v[26:29]
	v_mfma_f32_16x16x32_bf16 v[22:25], v[164:167], v[204:207], v[22:25]
	v_mfma_f32_16x16x32_bf16 v[10:13], v[156:159], v[212:215], v[10:13]
	v_mfma_f32_16x16x32_bf16 v[6:9], v[164:167], v[212:215], v[6:9]
	v_mfma_f32_16x16x32_bf16 v[62:65], v[168:171], v[184:187], 0
	v_mfma_f32_16x16x32_bf16 v[50:53], v[176:179], v[184:187], 0
	v_mfma_f32_16x16x32_bf16 v[46:49], v[168:171], v[192:195], 0
	v_mfma_f32_16x16x32_bf16 v[34:37], v[176:179], v[192:195], 0
	v_mfma_f32_16x16x32_bf16 v[30:33], v[168:171], v[200:203], 0
	v_mfma_f32_16x16x32_bf16 v[18:21], v[176:179], v[200:203], 0
	v_mfma_f32_16x16x32_bf16 v[14:17], v[168:171], v[208:211], 0
	v_mfma_f32_16x16x32_bf16 v[2:5], v[176:179], v[208:211], 0
	v_mfma_f32_16x16x32_bf16 v[62:65], v[172:175], v[188:191], v[62:65]
	v_mfma_f32_16x16x32_bf16 v[50:53], v[180:183], v[188:191], v[50:53]
	v_mfma_f32_16x16x32_bf16 v[46:49], v[172:175], v[196:199], v[46:49]
	v_mfma_f32_16x16x32_bf16 v[34:37], v[180:183], v[196:199], v[34:37]
	v_mfma_f32_16x16x32_bf16 v[30:33], v[172:175], v[204:207], v[30:33]
	v_mfma_f32_16x16x32_bf16 v[18:21], v[180:183], v[204:207], v[18:21]
	v_mfma_f32_16x16x32_bf16 v[14:17], v[172:175], v[212:215], v[14:17]
	v_mfma_f32_16x16x32_bf16 v[2:5], v[180:183], v[212:215], v[2:5]
	s_barrier
	v_add_u32_e32 v151, s60, v146
	ds_read_b128 v[152:155], v151
	ds_read_b128 v[156:159], v151 offset:1024
	ds_read_b128 v[160:163], v151 offset:2048
	ds_read_b128 v[164:167], v151 offset:3072
	v_add_u32_e32 v151, s61, v146
	ds_read_b128 v[168:171], v151
	ds_read_b128 v[172:175], v151 offset:1024
	ds_read_b128 v[176:179], v151 offset:2048
	ds_read_b128 v[180:183], v151 offset:3072
	s_add_u32 s34, s34, 0x80000
	s_addc_u32 s35, s35, 0
	s_mov_b32 m0, s39
	ds_read_b128 v[184:187], v150 offset:32768
	ds_read_b128 v[188:191], v150 offset:33792
	ds_read_b128 v[192:195], v150 offset:34816
	ds_read_b128 v[196:199], v150 offset:35840
	ds_read_b128 v[200:203], v150 offset:36864
	ds_read_b128 v[204:207], v150 offset:37888
	ds_read_b128 v[208:211], v150 offset:38912
	ds_read_b128 v[212:215], v150 offset:39936
	global_load_lds_dwordx4 v136, s[34:35]
	s_mov_b32 m0, s40
	s_nop 0
	global_load_lds_dwordx4 v132, s[34:35]
	s_waitcnt vmcnt(8) lgkmcnt(0)
	s_barrier
	v_mfma_f32_16x16x32_bf16 v[122:125], v[152:155], v[184:187], v[122:125]
	v_mfma_f32_16x16x32_bf16 v[118:121], v[160:163], v[184:187], v[118:121]
	v_mfma_f32_16x16x32_bf16 v[106:109], v[152:155], v[192:195], v[106:109]
	v_mfma_f32_16x16x32_bf16 v[102:105], v[160:163], v[192:195], v[102:105]
	v_mfma_f32_16x16x32_bf16 v[90:93], v[152:155], v[200:203], v[90:93]
	v_mfma_f32_16x16x32_bf16 v[86:89], v[160:163], v[200:203], v[86:89]
	v_mfma_f32_16x16x32_bf16 v[74:77], v[152:155], v[208:211], v[74:77]
	v_mfma_f32_16x16x32_bf16 v[70:73], v[160:163], v[208:211], v[70:73]
	v_mfma_f32_16x16x32_bf16 v[122:125], v[156:159], v[188:191], v[122:125]
	v_mfma_f32_16x16x32_bf16 v[118:121], v[164:167], v[188:191], v[118:121]
	v_mfma_f32_16x16x32_bf16 v[106:109], v[156:159], v[196:199], v[106:109]
	v_mfma_f32_16x16x32_bf16 v[102:105], v[164:167], v[196:199], v[102:105]
	v_mfma_f32_16x16x32_bf16 v[90:93], v[156:159], v[204:207], v[90:93]
	v_mfma_f32_16x16x32_bf16 v[86:89], v[164:167], v[204:207], v[86:89]
	v_mfma_f32_16x16x32_bf16 v[74:77], v[156:159], v[212:215], v[74:77]
	v_mfma_f32_16x16x32_bf16 v[70:73], v[164:167], v[212:215], v[70:73]
	v_mfma_f32_16x16x32_bf16 v[126:129], v[168:171], v[184:187], v[126:129]
	v_mfma_f32_16x16x32_bf16 v[114:117], v[176:179], v[184:187], v[114:117]
	v_mfma_f32_16x16x32_bf16 v[110:113], v[168:171], v[192:195], v[110:113]
	v_mfma_f32_16x16x32_bf16 v[98:101], v[176:179], v[192:195], v[98:101]
	v_mfma_f32_16x16x32_bf16 v[94:97], v[168:171], v[200:203], v[94:97]
	v_mfma_f32_16x16x32_bf16 v[82:85], v[176:179], v[200:203], v[82:85]
	v_mfma_f32_16x16x32_bf16 v[78:81], v[168:171], v[208:211], v[78:81]
	v_mfma_f32_16x16x32_bf16 v[66:69], v[176:179], v[208:211], v[66:69]
	v_mfma_f32_16x16x32_bf16 v[126:129], v[172:175], v[188:191], v[126:129]
	v_mfma_f32_16x16x32_bf16 v[114:117], v[180:183], v[188:191], v[114:117]
	v_mfma_f32_16x16x32_bf16 v[110:113], v[172:175], v[196:199], v[110:113]
	v_mfma_f32_16x16x32_bf16 v[98:101], v[180:183], v[196:199], v[98:101]
	v_mfma_f32_16x16x32_bf16 v[94:97], v[172:175], v[204:207], v[94:97]
	v_mfma_f32_16x16x32_bf16 v[82:85], v[180:183], v[204:207], v[82:85]
	v_mfma_f32_16x16x32_bf16 v[78:81], v[172:175], v[212:215], v[78:81]
	v_mfma_f32_16x16x32_bf16 v[66:69], v[180:183], v[212:215], v[66:69]
	s_barrier
; #define PG8_STAGE(bufoff, gbase, voff) do { _Pragma("unroll") for (int _i = 0; _i < 2; ++_i) \
;         __builtin_amdgcn_global_load_lds((const unsigned*)((const char*)(gbase) + (voff)[_i]), (LAS unsigned*)(lds + (bufoff) + ldsw + _i * 8192), 16, 0, 0); } while (0)
; #define PG8_LDA(dst, b, h) do { _Pragma("unroll") for (int m = 0; m < 4; ++m) _Pragma("unroll") for (int k = 0; k < 2; ++k) dst[m][k] = *(const LAS bf16x8*)(lds + PG8_SA(b, h) + aoff + m * 2048 + k * 1024); } while (0)
; #define PG8_LDB(dst, b, h) do { _Pragma("unroll") for (int n = 0; n < 2; ++n) _Pragma("unroll") for (int k = 0; k < 2; ++k) dst[n][k] = *(const LAS bf16x8*)(lds + PG8_SB(b, h) + boff + n * 2048 + k * 1024); } while (0)
; #define PG8_MMA(ai, bj, At, Bt) do { __builtin_amdgcn_s_setprio(1); _Pragma("unroll") for (int m = 0; m < 4; ++m) _Pragma("unroll") for (int n = 0; n < 2; ++n) _Pragma("unroll") for (int k = 0; k < 2; ++k) \
;         acc[ai][bj][m][n] = __builtin_amdgcn_mfma_f32_16x16x32_bf16(Bt[n][k], At[m][k], acc[ai][bj][m][n], 0, 0, 0); __builtin_amdgcn_s_setprio(0); } while (0)
; template <class Epi, class Sched, bool ABLK = false, bool ALIGN_EPI = true, bool SP2 = true, bool BBLK = true>
; __device__ __forceinline__ void gemm_phase(LAS unsigned char* lds, const Gemm g, const Sched& S, const Epi& E) {
;     ...
;         for (int t = 0; t < nt; t += 2) {
;     ...
;             PG8_LDB(B0, 0, 0); PG8_LDB(B1, 0, 1); PG8_SCHED; PG8_LDA(At, 0, 0); PG8_STAGE(PG8_SA(1, 1), a1 + hstepA, voffA);
;             PG8_WAIT_V(8); PG8_WAIT_L(0); PG8_BAR; PG8_MMA(0, 0, At, B0); PG8_MMA(0, 1, At, B1); PG8_BAR; PG8_SCHED;
;             PG8_LDA(At, 0, 1); PG8_STAGE(PG8_SB(0, 0), b2, voffB); PG8_STAGE(PG8_SB(0, 1), b2 + hstepB, voffB); PG8_STAGE(PG8_SA(0, 0), a2, voffA);
;             PG8_WAIT_V(8); PG8_WAIT_L(0); PG8_BAR; PG8_MMA(1, 0, At, B0); PG8_MMA(1, 1, At, B1); PG8_BAR; PG8_SCHED;
;             PG8_LDB(B0, 1, 0); PG8_LDB(B1, 1, 1); PG8_SCHED; PG8_LDA(At, 1, 0); PG8_STAGE(PG8_SA(0, 1), a2 + hstepA, voffA);
;             PG8_WAIT_V(8); PG8_WAIT_L(0); PG8_BAR; PG8_MMA(0, 0, At, B0); PG8_MMA(0, 1, At, B1); PG8_BAR; PG8_SCHED;
;             PG8_LDA(At, 1, 1); PG8_STAGE(PG8_SB(1, 0), b3, voffB); PG8_STAGE(PG8_SB(1, 1), b3 + hstepB, voffB); PG8_STAGE(PG8_SA(1, 0), a3, voffA);
;             PG8_WAIT_V(8); PG8_WAIT_L(0); PG8_BAR; PG8_MMA(1, 0, At, B0); PG8_MMA(1, 1, At, B1); PG8_BAR; PG8_SCHED;
	s_add_u32 s34, s30, 0x8000
	s_addc_u32 s35, s31, 0
	s_add_i32 s53, s60, s36
	s_mov_b32 m0, s53
	ds_read_b128 v[184:187], v150 offset:49152
	ds_read_b128 v[188:191], v150 offset:50176
	ds_read_b128 v[192:195], v150 offset:51200
	ds_read_b128 v[196:199], v150 offset:52224
	ds_read_b128 v[200:203], v150 offset:53248
	ds_read_b128 v[204:207], v150 offset:54272
	ds_read_b128 v[208:211], v150 offset:55296
	ds_read_b128 v[212:215], v150 offset:56320
	global_load_lds_dwordx4 v134, s[34:35]
	s_add_i32 m0, s53, 0x2000
	s_add_u32 s30, s30, 0xc000
	v_lshl_add_u64 v[216:217], s[34:35], 0, v[130:131]
	s_addc_u32 s31, s31, 0
	s_add_i32 s34, s61, s36
	global_load_lds_dwordx4 v[216:217], off
	s_mov_b32 m0, s34
	s_nop 0
	global_load_lds_dwordx4 v134, s[30:31]
	s_add_i32 m0, s34, 0x2000
	s_nop 0
	global_load_lds_dwordx4 v130, s[30:31]
	s_mov_b32 m0, s42
	s_nop 0
	global_load_lds_dwordx4 v136, s[28:29]
	s_mov_b32 m0, s43
	s_nop 0
	global_load_lds_dwordx4 v132, s[28:29]
	s_waitcnt vmcnt(8) lgkmcnt(0)
	s_barrier
	v_mfma_f32_16x16x32_bf16 v[58:61], v[152:155], v[184:187], v[58:61]
	v_mfma_f32_16x16x32_bf16 v[54:57], v[160:163], v[184:187], v[54:57]
	v_mfma_f32_16x16x32_bf16 v[42:45], v[152:155], v[192:195], v[42:45]
	v_mfma_f32_16x16x32_bf16 v[38:41], v[160:163], v[192:195], v[38:41]
	v_mfma_f32_16x16x32_bf16 v[26:29], v[152:155], v[200:203], v[26:29]
	v_mfma_f32_16x16x32_bf16 v[22:25], v[160:163], v[200:203], v[22:25]
	v_mfma_f32_16x16x32_bf16 v[10:13], v[152:155], v[208:211], v[10:13]
	v_mfma_f32_16x16x32_bf16 v[6:9], v[160:163], v[208:211], v[6:9]
	v_mfma_f32_16x16x32_bf16 v[58:61], v[156:159], v[188:191], v[58:61]
	v_mfma_f32_16x16x32_bf16 v[54:57], v[164:167], v[188:191], v[54:57]
	v_mfma_f32_16x16x32_bf16 v[42:45], v[156:159], v[196:199], v[42:45]
	v_mfma_f32_16x16x32_bf16 v[38:41], v[164:167], v[196:199], v[38:41]
	v_mfma_f32_16x16x32_bf16 v[26:29], v[156:159], v[204:207], v[26:29]
	v_mfma_f32_16x16x32_bf16 v[22:25], v[164:167], v[204:207], v[22:25]
	v_mfma_f32_16x16x32_bf16 v[10:13], v[156:159], v[212:215], v[10:13]
	v_mfma_f32_16x16x32_bf16 v[6:9], v[164:167], v[212:215], v[6:9]
	v_mfma_f32_16x16x32_bf16 v[62:65], v[168:171], v[184:187], v[62:65]
	v_mfma_f32_16x16x32_bf16 v[50:53], v[176:179], v[184:187], v[50:53]
	v_mfma_f32_16x16x32_bf16 v[46:49], v[168:171], v[192:195], v[46:49]
	v_mfma_f32_16x16x32_bf16 v[34:37], v[176:179], v[192:195], v[34:37]
	v_mfma_f32_16x16x32_bf16 v[30:33], v[168:171], v[200:203], v[30:33]
	v_mfma_f32_16x16x32_bf16 v[18:21], v[176:179], v[200:203], v[18:21]
	v_mfma_f32_16x16x32_bf16 v[14:17], v[168:171], v[208:211], v[14:17]
	v_mfma_f32_16x16x32_bf16 v[2:5], v[176:179], v[208:211], v[2:5]
	v_mfma_f32_16x16x32_bf16 v[62:65], v[172:175], v[188:191], v[62:65]
	v_mfma_f32_16x16x32_bf16 v[50:53], v[180:183], v[188:191], v[50:53]
	v_mfma_f32_16x16x32_bf16 v[46:49], v[172:175], v[196:199], v[46:49]
	v_mfma_f32_16x16x32_bf16 v[34:37], v[180:183], v[196:199], v[34:37]
	v_mfma_f32_16x16x32_bf16 v[30:33], v[172:175], v[204:207], v[30:33]
	v_mfma_f32_16x16x32_bf16 v[18:21], v[180:183], v[204:207], v[18:21]
	v_mfma_f32_16x16x32_bf16 v[14:17], v[172:175], v[212:215], v[14:17]
	v_mfma_f32_16x16x32_bf16 v[2:5], v[180:183], v[212:215], v[2:5]
	s_barrier
	s_add_i32 s52, s52, 2
	s_add_u32 s26, s26, 0x100
	s_addc_u32 s27, s27, 0
	s_add_u32 s50, s50, 0x10000
	s_addc_u32 s51, s51, 0
	s_cmp_gt_u32 s52, 29

; template <class Epi, class Sched, bool ABLK = false, bool ALIGN_EPI = true, bool SP2 = true, bool BBLK = true>
; __device__ __forceinline__ void gemm_phase(LAS unsigned char* lds, const Gemm g, const Sched& S, const Epi& E) {
;     ...
;     auto a_unit = [&](const Unit& u) -> const char* { return ABLK ? (const char*)g.A + (size_t)u.pm * ((size_t)g.lda / 64) * 32768 : (const char*)g.A + (size_t)u.pm * 2 * hstepA; };
;     auto a_tile = [&](const char* ub, int tau) -> const char* { return ub + (size_t)tau * (ABLK ? (size_t)32768 : kstep); };
;     ...
;     for (;;) {
;         const bool has_next = S.next(ui + 1, nxt);
;         const int nt = cur.nt;
;         const char* nuA = has_next ? a_unit(nxt) : uA; const int ntbA = has_next ? nxt.k0 / BK : tbA; const char* nB = has_next ? (const char*)g.Bt + (size_t)nxt.pn * tstepB + b_k0(nxt.k0) : cB;
;         for (int t = 0; t < nt; t += 2) {
;             const bool last = (t == nt - 2);
;             const char* a1 = a_tile(uA, tbA + t + 1);
;             const char* a2 = last ? a_tile(nuA, ntbA) : a_tile(uA, tbA + t + 2); const char* b2 = last ? nB : cB + (size_t)(t + 2) * kstepB;
;             const char* a3 = last ? a_tile(nuA, ntbA + 1) : a_tile(uA, tbA + t + 3); const char* b3 = b2 + kstepB;
;             if (last && has_next) S.a_ready(nxt);
;             if constexpr (SP2) {
;             PG8_LDB(B0, 0, 0); PG8_LDB(B1, 0, 1); PG8_SCHED; PG8_LDA(At, 0, 0); PG8_STAGE(PG8_SA(1, 1), a1 + hstepA, voffA);
;             PG8_WAIT_V(8); PG8_WAIT_L(0); PG8_BAR; PG8_MMA(0, 0, At, B0); PG8_MMA(0, 1, At, B1); PG8_BAR; PG8_SCHED;
;             PG8_LDA(At, 0, 1); PG8_STAGE(PG8_SB(0, 0), b2, voffB); PG8_STAGE(PG8_SB(0, 1), b2 + hstepB, voffB); PG8_STAGE(PG8_SA(0, 0), a2, voffA);
;             PG8_WAIT_V(8); PG8_WAIT_L(0); PG8_BAR; PG8_MMA(1, 0, At, B0); PG8_MMA(1, 1, At, B1); PG8_BAR; PG8_SCHED;
;             PG8_LDB(B0, 1, 0); PG8_LDB(B1, 1, 1); PG8_SCHED; PG8_LDA(At, 1, 0); PG8_STAGE(PG8_SA(0, 1), a2 + hstepA, voffA);
;             PG8_WAIT_V(8); PG8_WAIT_L(0); PG8_BAR; PG8_MMA(0, 0, At, B0); PG8_MMA(0, 1, At, B1); PG8_BAR; PG8_SCHED;
;             PG8_LDA(At, 1, 1); PG8_STAGE(PG8_SB(1, 0), b3, voffB); PG8_STAGE(PG8_SB(1, 1), b3 + hstepB, voffB); PG8_STAGE(PG8_SA(1, 0), a3, voffA);
;             PG8_WAIT_V(8); PG8_WAIT_L(0); PG8_BAR; PG8_MMA(1, 0, At, B0); PG8_MMA(1, 1, At, B1); PG8_BAR; PG8_SCHED;
.LBB0_2262:
	s_ashr_i32 s13, s12, 31
	s_lshl_b64 s[4:5], s[12:13], 20
	s_add_u32 s16, s41, s4
	s_addc_u32 s17, s42, s5
	s_and_b64 s[4:5], s[18:19], exec
	s_cselect_b32 s4, s17, s27
	s_cselect_b32 s5, s16, s26
	s_ashr_i32 s15, s14, 31
	s_lshl_b64 s[20:21], s[14:15], 20
	s_add_u32 s20, s38, s20
	s_addc_u32 s21, s39, s21
	s_and_b64 s[30:31], s[18:19], exec
	s_cselect_b32 s13, s21, s29
	s_cselect_b32 s15, s20, s28
	s_add_u32 s23, s5, 0x80
	s_addc_u32 s54, s4, 0
	s_add_u32 s55, s28, 0x10000
	v_mov_b32_e32 v2, 0
	s_addc_u32 s56, s29, 0
	v_lshl_add_u64 v[164:165], s[26:27], 0, v[160:161]
	v_lshl_add_u64 v[166:167], s[26:27], 0, v[162:163]
	s_mov_b32 s57, -2
	s_mov_b64 s[28:29], 0
	ds_read_b128 v[172:175], v168
	ds_read_b128 v[176:179], v168 offset:1024
	ds_read_b128 v[180:183], v168 offset:2048
	ds_read_b128 v[184:187], v168 offset:3072
	ds_read_b128 v[188:191], v169
	ds_read_b128 v[192:195], v169 offset:1024
	ds_read_b128 v[196:199], v169 offset:2048
	ds_read_b128 v[200:203], v169 offset:3072
	s_add_u32 s30, s26, s28
	s_addc_u32 s31, s27, s29
	s_add_u32 s36, s30, 0x100
	s_addc_u32 s37, s31, 0
	s_add_u32 s30, s30, 0x180
	s_addc_u32 s31, s31, 0
	s_cmpk_eq_i32 s28, 0xf00
	s_cselect_b32 s31, s54, s31
	s_cselect_b32 s30, s23, s30
	s_cselect_b32 s35, s13, s56
	s_cselect_b32 s34, s15, s55
	s_cselect_b32 s37, s4, s37
	s_cselect_b32 s36, s5, s36
	s_mov_b32 m0, s50
	v_lshl_add_u64 v[236:237], v[164:165], 0, s[28:29]
	ds_read_b128 v[204:207], v170
	ds_read_b128 v[208:211], v170 offset:1024
	ds_read_b128 v[212:215], v170 offset:2048
	ds_read_b128 v[216:219], v170 offset:3072
	ds_read_b128 v[220:223], v170 offset:4096
	ds_read_b128 v[224:227], v170 offset:5120
	ds_read_b128 v[228:231], v170 offset:6144
	ds_read_b128 v[232:235], v170 offset:7168
	global_load_lds_dwordx4 v[236:237], off
	v_lshl_add_u64 v[236:237], v[166:167], 0, s[28:29]
	s_mov_b32 m0, s51
	s_nop 0
	global_load_lds_dwordx4 v[236:237], off
	s_waitcnt vmcnt(8) lgkmcnt(0)
	s_barrier
	v_mfma_f32_16x16x32_bf16 v[126:129], v[172:175], v[204:207], 0
	v_mfma_f32_16x16x32_bf16 v[122:125], v[180:183], v[204:207], 0
	v_mfma_f32_16x16x32_bf16 v[110:113], v[172:175], v[212:215], 0
	v_mfma_f32_16x16x32_bf16 v[106:109], v[180:183], v[212:215], 0
	v_mfma_f32_16x16x32_bf16 v[94:97], v[172:175], v[220:223], 0
	v_mfma_f32_16x16x32_bf16 v[90:93], v[180:183], v[220:223], 0
	v_mfma_f32_16x16x32_bf16 v[78:81], v[172:175], v[228:231], 0
	v_mfma_f32_16x16x32_bf16 v[74:77], v[180:183], v[228:231], 0
	v_mfma_f32_16x16x32_bf16 v[126:129], v[176:179], v[208:211], v[126:129]
	v_mfma_f32_16x16x32_bf16 v[122:125], v[184:187], v[208:211], v[122:125]
	v_mfma_f32_16x16x32_bf16 v[110:113], v[176:179], v[216:219], v[110:113]
	v_mfma_f32_16x16x32_bf16 v[106:109], v[184:187], v[216:219], v[106:109]
	v_mfma_f32_16x16x32_bf16 v[94:97], v[176:179], v[224:227], v[94:97]
	v_mfma_f32_16x16x32_bf16 v[90:93], v[184:187], v[224:227], v[90:93]
	v_mfma_f32_16x16x32_bf16 v[78:81], v[176:179], v[232:235], v[78:81]
	v_mfma_f32_16x16x32_bf16 v[74:77], v[184:187], v[232:235], v[74:77]
	v_mfma_f32_16x16x32_bf16 v[118:121], v[188:191], v[204:207], 0
	v_mfma_f32_16x16x32_bf16 v[114:117], v[196:199], v[204:207], 0
	v_mfma_f32_16x16x32_bf16 v[102:105], v[188:191], v[212:215], 0
	v_mfma_f32_16x16x32_bf16 v[98:101], v[196:199], v[212:215], 0
	v_mfma_f32_16x16x32_bf16 v[86:89], v[188:191], v[220:223], 0
	v_mfma_f32_16x16x32_bf16 v[82:85], v[196:199], v[220:223], 0
	v_mfma_f32_16x16x32_bf16 v[70:73], v[188:191], v[228:231], 0
	v_mfma_f32_16x16x32_bf16 v[66:69], v[196:199], v[228:231], 0
	v_mfma_f32_16x16x32_bf16 v[118:121], v[192:195], v[208:211], v[118:121]
	v_mfma_f32_16x16x32_bf16 v[114:117], v[200:203], v[208:211], v[114:117]
	v_mfma_f32_16x16x32_bf16 v[102:105], v[192:195], v[216:219], v[102:105]
	v_mfma_f32_16x16x32_bf16 v[98:101], v[200:203], v[216:219], v[98:101]
	v_mfma_f32_16x16x32_bf16 v[86:89], v[192:195], v[224:227], v[86:89]
	v_mfma_f32_16x16x32_bf16 v[82:85], v[200:203], v[224:227], v[82:85]
	v_mfma_f32_16x16x32_bf16 v[70:73], v[192:195], v[232:235], v[70:73]
	v_mfma_f32_16x16x32_bf16 v[66:69], v[200:203], v[232:235], v[66:69]
	s_barrier
	s_mov_b32 m0, s52
	s_add_u32 s58, s34, 0x4000
	ds_read_b128 v[204:207], v170 offset:16384
	ds_read_b128 v[208:211], v170 offset:17408
	ds_read_b128 v[212:215], v170 offset:18432
	ds_read_b128 v[216:219], v170 offset:19456
	ds_read_b128 v[220:223], v170 offset:20480
	ds_read_b128 v[224:227], v170 offset:21504
	ds_read_b128 v[228:231], v170 offset:22528
	ds_read_b128 v[232:235], v170 offset:23552
	global_load_lds_dwordx4 v134, s[34:35]
	s_mov_b32 m0, s53
	s_addc_u32 s59, s35, 0
	s_add_i32 s62, s73, s40
	global_load_lds_dwordx4 v130, s[34:35]
	s_mov_b32 m0, s62
	s_nop 0
	global_load_lds_dwordx4 v134, s[58:59]
	s_add_i32 m0, s62, 0x2000
	s_nop 0
	global_load_lds_dwordx4 v130, s[58:59]
	s_mov_b32 m0, s25
	s_nop 0
	global_load_lds_dwordx4 v136, s[36:37]
	s_mov_b32 m0, s43
	s_nop 0
	global_load_lds_dwordx4 v132, s[36:37]
	s_waitcnt vmcnt(8) lgkmcnt(0)
	s_barrier
; #define PG8_STAGE(bufoff, gbase, voff) do { _Pragma("unroll") for (int _i = 0; _i < 2; ++_i) \
;         __builtin_amdgcn_global_load_lds((const unsigned*)((const char*)(gbase) + (voff)[_i]), (LAS unsigned*)(lds + (bufoff) + ldsw + _i * 8192), 16, 0, 0); } while (0)
; #define PG8_LDA(dst, b, h) do { _Pragma("unroll") for (int m = 0; m < 4; ++m) _Pragma("unroll") for (int k = 0; k < 2; ++k) dst[m][k] = *(const LAS bf16x8*)(lds + PG8_SA(b, h) + aoff + m * 2048 + k * 1024); } while (0)
; #define PG8_LDB(dst, b, h) do { _Pragma("unroll") for (int n = 0; n < 2; ++n) _Pragma("unroll") for (int k = 0; k < 2; ++k) dst[n][k] = *(const LAS bf16x8*)(lds + PG8_SB(b, h) + boff + n * 2048 + k * 1024); } while (0)
; #define PG8_MMA(ai, bj, At, Bt) do { __builtin_amdgcn_s_setprio(1); _Pragma("unroll") for (int m = 0; m < 4; ++m) _Pragma("unroll") for (int n = 0; n < 2; ++n) _Pragma("unroll") for (int k = 0; k < 2; ++k) \
;         acc[ai][bj][m][n] = __builtin_amdgcn_mfma_f32_16x16x32_bf16(Bt[n][k], At[m][k], acc[ai][bj][m][n], 0, 0, 0); __builtin_amdgcn_s_setprio(0); } while (0)
; #define PG8_BAR __builtin_amdgcn_s_barrier()
; template <class Epi, class Sched, bool ABLK = false, bool ALIGN_EPI = true, bool SP2 = true, bool BBLK = true>
; __device__ __forceinline__ void gemm_phase(LAS unsigned char* lds, const Gemm g, const Sched& S, const Epi& E) {
;     ...
;             PG8_LDB(B0, 0, 0); PG8_LDB(B1, 0, 1); PG8_SCHED; PG8_LDA(At, 0, 0); PG8_STAGE(PG8_SA(1, 1), a1 + hstepA, voffA);
;             PG8_WAIT_V(8); PG8_WAIT_L(0); PG8_BAR; PG8_MMA(0, 0, At, B0); PG8_MMA(0, 1, At, B1); PG8_BAR; PG8_SCHED;
;             PG8_LDA(At, 0, 1); PG8_STAGE(PG8_SB(0, 0), b2, voffB); PG8_STAGE(PG8_SB(0, 1), b2 + hstepB, voffB); PG8_STAGE(PG8_SA(0, 0), a2, voffA);
;             PG8_WAIT_V(8); PG8_WAIT_L(0); PG8_BAR; PG8_MMA(1, 0, At, B0); PG8_MMA(1, 1, At, B1); PG8_BAR; PG8_SCHED;
;             PG8_LDB(B0, 1, 0); PG8_LDB(B1, 1, 1); PG8_SCHED; PG8_LDA(At, 1, 0); PG8_STAGE(PG8_SA(0, 1), a2 + hstepA, voffA);
;             PG8_WAIT_V(8); PG8_WAIT_L(0); PG8_BAR; PG8_MMA(0, 0, At, B0); PG8_MMA(0, 1, At, B1); PG8_BAR; PG8_SCHED;
;             PG8_LDA(At, 1, 1); PG8_STAGE(PG8_SB(1, 0), b3, voffB); PG8_STAGE(PG8_SB(1, 1), b3 + hstepB, voffB); PG8_STAGE(PG8_SA(1, 0), a3, voffA);
;             PG8_WAIT_V(8); PG8_WAIT_L(0); PG8_BAR; PG8_MMA(1, 0, At, B0); PG8_MMA(1, 1, At, B1); PG8_BAR; PG8_SCHED;
	v_mfma_f32_16x16x32_bf16 v[62:65], v[172:175], v[204:207], 0
	v_mfma_f32_16x16x32_bf16 v[58:61], v[180:183], v[204:207], 0
	v_mfma_f32_16x16x32_bf16 v[46:49], v[172:175], v[212:215], 0
	v_mfma_f32_16x16x32_bf16 v[42:45], v[180:183], v[212:215], 0
	v_mfma_f32_16x16x32_bf16 v[30:33], v[172:175], v[220:223], 0
	v_mfma_f32_16x16x32_bf16 v[26:29], v[180:183], v[220:223], 0
	v_mfma_f32_16x16x32_bf16 v[14:17], v[172:175], v[228:231], 0
	v_mfma_f32_16x16x32_bf16 v[10:13], v[180:183], v[228:231], 0
	v_mfma_f32_16x16x32_bf16 v[62:65], v[176:179], v[208:211], v[62:65]
	v_mfma_f32_16x16x32_bf16 v[58:61], v[184:187], v[208:211], v[58:61]
	v_mfma_f32_16x16x32_bf16 v[46:49], v[176:179], v[216:219], v[46:49]
	v_mfma_f32_16x16x32_bf16 v[42:45], v[184:187], v[216:219], v[42:45]
	v_mfma_f32_16x16x32_bf16 v[30:33], v[176:179], v[224:227], v[30:33]
	v_mfma_f32_16x16x32_bf16 v[26:29], v[184:187], v[224:227], v[26:29]
	v_mfma_f32_16x16x32_bf16 v[14:17], v[176:179], v[232:235], v[14:17]
	v_mfma_f32_16x16x32_bf16 v[10:13], v[184:187], v[232:235], v[10:13]
	v_mfma_f32_16x16x32_bf16 v[54:57], v[188:191], v[204:207], 0
	v_mfma_f32_16x16x32_bf16 v[50:53], v[196:199], v[204:207], 0
	v_mfma_f32_16x16x32_bf16 v[38:41], v[188:191], v[212:215], 0
	v_mfma_f32_16x16x32_bf16 v[34:37], v[196:199], v[212:215], 0
	v_mfma_f32_16x16x32_bf16 v[22:25], v[188:191], v[220:223], 0
	v_mfma_f32_16x16x32_bf16 v[18:21], v[196:199], v[220:223], 0
	v_mfma_f32_16x16x32_bf16 v[6:9], v[188:191], v[228:231], 0
	v_mfma_f32_16x16x32_bf16 v[2:5], v[196:199], v[228:231], 0
	v_mfma_f32_16x16x32_bf16 v[54:57], v[192:195], v[208:211], v[54:57]
	v_mfma_f32_16x16x32_bf16 v[50:53], v[200:203], v[208:211], v[50:53]
	v_mfma_f32_16x16x32_bf16 v[38:41], v[192:195], v[216:219], v[38:41]
	v_mfma_f32_16x16x32_bf16 v[34:37], v[200:203], v[216:219], v[34:37]
	v_mfma_f32_16x16x32_bf16 v[22:25], v[192:195], v[224:227], v[22:25]
	v_mfma_f32_16x16x32_bf16 v[18:21], v[200:203], v[224:227], v[18:21]
	v_mfma_f32_16x16x32_bf16 v[6:9], v[192:195], v[232:235], v[6:9]
	v_mfma_f32_16x16x32_bf16 v[2:5], v[200:203], v[232:235], v[2:5]
	s_barrier
	v_add_u32_e32 v171, s60, v1
	ds_read_b128 v[172:175], v171
	ds_read_b128 v[176:179], v171 offset:1024
	ds_read_b128 v[180:183], v171 offset:2048
	ds_read_b128 v[184:187], v171 offset:3072
	v_add_u32_e32 v171, s61, v1
	ds_read_b128 v[188:191], v171
	ds_read_b128 v[192:195], v171 offset:1024
	ds_read_b128 v[196:199], v171 offset:2048
	ds_read_b128 v[200:203], v171 offset:3072
	s_add_u32 s36, s36, 0x80000
	s_addc_u32 s37, s37, 0
	s_mov_b32 m0, s44
	ds_read_b128 v[204:207], v170 offset:32768
	ds_read_b128 v[208:211], v170 offset:33792
	ds_read_b128 v[212:215], v170 offset:34816
	ds_read_b128 v[216:219], v170 offset:35840
	ds_read_b128 v[220:223], v170 offset:36864
	ds_read_b128 v[224:227], v170 offset:37888
	ds_read_b128 v[228:231], v170 offset:38912
	ds_read_b128 v[232:235], v170 offset:39936
	global_load_lds_dwordx4 v136, s[36:37]
	s_mov_b32 m0, s45
	s_nop 0
	global_load_lds_dwordx4 v132, s[36:37]
	s_waitcnt vmcnt(8) lgkmcnt(0)
	s_barrier
	v_mfma_f32_16x16x32_bf16 v[126:129], v[172:175], v[204:207], v[126:129]
	v_mfma_f32_16x16x32_bf16 v[122:125], v[180:183], v[204:207], v[122:125]
	v_mfma_f32_16x16x32_bf16 v[110:113], v[172:175], v[212:215], v[110:113]
	v_mfma_f32_16x16x32_bf16 v[106:109], v[180:183], v[212:215], v[106:109]
	v_mfma_f32_16x16x32_bf16 v[94:97], v[172:175], v[220:223], v[94:97]
	v_mfma_f32_16x16x32_bf16 v[90:93], v[180:183], v[220:223], v[90:93]
	v_mfma_f32_16x16x32_bf16 v[78:81], v[172:175], v[228:231], v[78:81]
	v_mfma_f32_16x16x32_bf16 v[74:77], v[180:183], v[228:231], v[74:77]
	v_mfma_f32_16x16x32_bf16 v[126:129], v[176:179], v[208:211], v[126:129]
	v_mfma_f32_16x16x32_bf16 v[122:125], v[184:187], v[208:211], v[122:125]
	v_mfma_f32_16x16x32_bf16 v[110:113], v[176:179], v[216:219], v[110:113]
	v_mfma_f32_16x16x32_bf16 v[106:109], v[184:187], v[216:219], v[106:109]
	v_mfma_f32_16x16x32_bf16 v[94:97], v[176:179], v[224:227], v[94:97]
	v_mfma_f32_16x16x32_bf16 v[90:93], v[184:187], v[224:227], v[90:93]
	v_mfma_f32_16x16x32_bf16 v[78:81], v[176:179], v[232:235], v[78:81]
	v_mfma_f32_16x16x32_bf16 v[74:77], v[184:187], v[232:235], v[74:77]
	v_mfma_f32_16x16x32_bf16 v[118:121], v[188:191], v[204:207], v[118:121]
	v_mfma_f32_16x16x32_bf16 v[114:117], v[196:199], v[204:207], v[114:117]
	v_mfma_f32_16x16x32_bf16 v[102:105], v[188:191], v[212:215], v[102:105]
	v_mfma_f32_16x16x32_bf16 v[98:101], v[196:199], v[212:215], v[98:101]
	v_mfma_f32_16x16x32_bf16 v[86:89], v[188:191], v[220:223], v[86:89]
	v_mfma_f32_16x16x32_bf16 v[82:85], v[196:199], v[220:223], v[82:85]
	v_mfma_f32_16x16x32_bf16 v[70:73], v[188:191], v[228:231], v[70:73]
	v_mfma_f32_16x16x32_bf16 v[66:69], v[196:199], v[228:231], v[66:69]
	v_mfma_f32_16x16x32_bf16 v[118:121], v[192:195], v[208:211], v[118:121]
	v_mfma_f32_16x16x32_bf16 v[114:117], v[200:203], v[208:211], v[114:117]
	v_mfma_f32_16x16x32_bf16 v[102:105], v[192:195], v[216:219], v[102:105]
	v_mfma_f32_16x16x32_bf16 v[98:101], v[200:203], v[216:219], v[98:101]
	v_mfma_f32_16x16x32_bf16 v[86:89], v[192:195], v[224:227], v[86:89]
	v_mfma_f32_16x16x32_bf16 v[82:85], v[200:203], v[224:227], v[82:85]
	v_mfma_f32_16x16x32_bf16 v[70:73], v[192:195], v[232:235], v[70:73]
	v_mfma_f32_16x16x32_bf16 v[66:69], v[200:203], v[232:235], v[66:69]
	s_barrier
; #define PG8_STAGE(bufoff, gbase, voff) do { _Pragma("unroll") for (int _i = 0; _i < 2; ++_i) \
;         __builtin_amdgcn_global_load_lds((const unsigned*)((const char*)(gbase) + (voff)[_i]), (LAS unsigned*)(lds + (bufoff) + ldsw + _i * 8192), 16, 0, 0); } while (0)
; #define PG8_LDA(dst, b, h) do { _Pragma("unroll") for (int m = 0; m < 4; ++m) _Pragma("unroll") for (int k = 0; k < 2; ++k) dst[m][k] = *(const LAS bf16x8*)(lds + PG8_SA(b, h) + aoff + m * 2048 + k * 1024); } while (0)
; #define PG8_LDB(dst, b, h) do { _Pragma("unroll") for (int n = 0; n < 2; ++n) _Pragma("unroll") for (int k = 0; k < 2; ++k) dst[n][k] = *(const LAS bf16x8*)(lds + PG8_SB(b, h) + boff + n * 2048 + k * 1024); } while (0)
; #define PG8_MMA(ai, bj, At, Bt) do { __builtin_amdgcn_s_setprio(1); _Pragma("unroll") for (int m = 0; m < 4; ++m) _Pragma("unroll") for (int n = 0; n < 2; ++n) _Pragma("unroll") for (int k = 0; k < 2; ++k) \
;         acc[ai][bj][m][n] = __builtin_amdgcn_mfma_f32_16x16x32_bf16(Bt[n][k], At[m][k], acc[ai][bj][m][n], 0, 0, 0); __builtin_amdgcn_s_setprio(0); } while (0)
; template <class Epi, class Sched, bool ABLK = false, bool ALIGN_EPI = true, bool SP2 = true, bool BBLK = true>
; __device__ __forceinline__ void gemm_phase(LAS unsigned char* lds, const Gemm g, const Sched& S, const Epi& E) {
;     ...
;         for (int t = 0; t < nt; t += 2) {
;     ...
;             PG8_LDB(B0, 0, 0); PG8_LDB(B1, 0, 1); PG8_SCHED; PG8_LDA(At, 0, 0); PG8_STAGE(PG8_SA(1, 1), a1 + hstepA, voffA);
;             PG8_WAIT_V(8); PG8_WAIT_L(0); PG8_BAR; PG8_MMA(0, 0, At, B0); PG8_MMA(0, 1, At, B1); PG8_BAR; PG8_SCHED;
;             PG8_LDA(At, 0, 1); PG8_STAGE(PG8_SB(0, 0), b2, voffB); PG8_STAGE(PG8_SB(0, 1), b2 + hstepB, voffB); PG8_STAGE(PG8_SA(0, 0), a2, voffA);
;             PG8_WAIT_V(8); PG8_WAIT_L(0); PG8_BAR; PG8_MMA(1, 0, At, B0); PG8_MMA(1, 1, At, B1); PG8_BAR; PG8_SCHED;
;             PG8_LDB(B0, 1, 0); PG8_LDB(B1, 1, 1); PG8_SCHED; PG8_LDA(At, 1, 0); PG8_STAGE(PG8_SA(0, 1), a2 + hstepA, voffA);
;             PG8_WAIT_V(8); PG8_WAIT_L(0); PG8_BAR; PG8_MMA(0, 0, At, B0); PG8_MMA(0, 1, At, B1); PG8_BAR; PG8_SCHED;
;             PG8_LDA(At, 1, 1); PG8_STAGE(PG8_SB(1, 0), b3, voffB); PG8_STAGE(PG8_SB(1, 1), b3 + hstepB, voffB); PG8_STAGE(PG8_SA(1, 0), a3, voffA);
;             PG8_WAIT_V(8); PG8_WAIT_L(0); PG8_BAR; PG8_MMA(1, 0, At, B0); PG8_MMA(1, 1, At, B1); PG8_BAR; PG8_SCHED;
	s_add_u32 s36, s34, 0x8000
	s_addc_u32 s37, s35, 0
	s_add_i32 s58, s60, s40
	s_mov_b32 m0, s58
	ds_read_b128 v[204:207], v170 offset:49152
	ds_read_b128 v[208:211], v170 offset:50176
	ds_read_b128 v[212:215], v170 offset:51200
	ds_read_b128 v[216:219], v170 offset:52224
	ds_read_b128 v[220:223], v170 offset:53248
	ds_read_b128 v[224:227], v170 offset:54272
	ds_read_b128 v[228:231], v170 offset:55296
	ds_read_b128 v[232:235], v170 offset:56320
	global_load_lds_dwordx4 v134, s[36:37]
	s_add_i32 m0, s58, 0x2000
	s_add_u32 s34, s34, 0xc000
	v_lshl_add_u64 v[236:237], s[36:37], 0, v[130:131]
	s_addc_u32 s35, s35, 0
	s_add_i32 s36, s61, s40
	global_load_lds_dwordx4 v[236:237], off
	s_mov_b32 m0, s36
	s_nop 0
	global_load_lds_dwordx4 v134, s[34:35]
	s_add_i32 m0, s36, 0x2000
	s_nop 0
	global_load_lds_dwordx4 v130, s[34:35]
	s_mov_b32 m0, s48
	s_nop 0
	global_load_lds_dwordx4 v136, s[30:31]
	s_mov_b32 m0, s49
	s_nop 0
	global_load_lds_dwordx4 v132, s[30:31]
	s_waitcnt vmcnt(8) lgkmcnt(0)
	s_barrier
	v_mfma_f32_16x16x32_bf16 v[62:65], v[172:175], v[204:207], v[62:65]
	v_mfma_f32_16x16x32_bf16 v[58:61], v[180:183], v[204:207], v[58:61]
	v_mfma_f32_16x16x32_bf16 v[46:49], v[172:175], v[212:215], v[46:49]
	v_mfma_f32_16x16x32_bf16 v[42:45], v[180:183], v[212:215], v[42:45]
	v_mfma_f32_16x16x32_bf16 v[30:33], v[172:175], v[220:223], v[30:33]
	v_mfma_f32_16x16x32_bf16 v[26:29], v[180:183], v[220:223], v[26:29]
	v_mfma_f32_16x16x32_bf16 v[14:17], v[172:175], v[228:231], v[14:17]
	v_mfma_f32_16x16x32_bf16 v[10:13], v[180:183], v[228:231], v[10:13]
	v_mfma_f32_16x16x32_bf16 v[62:65], v[176:179], v[208:211], v[62:65]
	v_mfma_f32_16x16x32_bf16 v[58:61], v[184:187], v[208:211], v[58:61]
	v_mfma_f32_16x16x32_bf16 v[46:49], v[176:179], v[216:219], v[46:49]
	v_mfma_f32_16x16x32_bf16 v[42:45], v[184:187], v[216:219], v[42:45]
	v_mfma_f32_16x16x32_bf16 v[30:33], v[176:179], v[224:227], v[30:33]
	v_mfma_f32_16x16x32_bf16 v[26:29], v[184:187], v[224:227], v[26:29]
	v_mfma_f32_16x16x32_bf16 v[14:17], v[176:179], v[232:235], v[14:17]
	v_mfma_f32_16x16x32_bf16 v[10:13], v[184:187], v[232:235], v[10:13]
	v_mfma_f32_16x16x32_bf16 v[54:57], v[188:191], v[204:207], v[54:57]
	v_mfma_f32_16x16x32_bf16 v[50:53], v[196:199], v[204:207], v[50:53]
	v_mfma_f32_16x16x32_bf16 v[38:41], v[188:191], v[212:215], v[38:41]
	v_mfma_f32_16x16x32_bf16 v[34:37], v[196:199], v[212:215], v[34:37]
	v_mfma_f32_16x16x32_bf16 v[22:25], v[188:191], v[220:223], v[22:25]
	v_mfma_f32_16x16x32_bf16 v[18:21], v[196:199], v[220:223], v[18:21]
	v_mfma_f32_16x16x32_bf16 v[6:9], v[188:191], v[228:231], v[6:9]
	v_mfma_f32_16x16x32_bf16 v[2:5], v[196:199], v[228:231], v[2:5]
	v_mfma_f32_16x16x32_bf16 v[54:57], v[192:195], v[208:211], v[54:57]
	v_mfma_f32_16x16x32_bf16 v[50:53], v[200:203], v[208:211], v[50:53]
	v_mfma_f32_16x16x32_bf16 v[38:41], v[192:195], v[216:219], v[38:41]
	v_mfma_f32_16x16x32_bf16 v[34:37], v[200:203], v[216:219], v[34:37]
	v_mfma_f32_16x16x32_bf16 v[22:25], v[192:195], v[224:227], v[22:25]
	v_mfma_f32_16x16x32_bf16 v[18:21], v[200:203], v[224:227], v[18:21]
	v_mfma_f32_16x16x32_bf16 v[6:9], v[192:195], v[232:235], v[6:9]
	v_mfma_f32_16x16x32_bf16 v[2:5], v[200:203], v[232:235], v[2:5]
	s_barrier
	s_add_i32 s57, s57, 2
	s_add_u32 s28, s28, 0x100
	s_addc_u32 s29, s29, 0
	s_add_u32 s55, s55, 0x10000
	s_addc_u32 s56, s56, 0
	s_cmp_gt_u32 s57, 29

; template <class Epi, class Sched, bool ABLK = false, bool ALIGN_EPI = true, bool SP2 = true, bool BBLK = true>
; __device__ __forceinline__ void gemm_phase(LAS unsigned char* lds, const Gemm g, const Sched& S, const Epi& E) {
;     ...
;     auto a_unit = [&](const Unit& u) -> const char* { return ABLK ? (const char*)g.A + (size_t)u.pm * ((size_t)g.lda / 64) * 32768 : (const char*)g.A + (size_t)u.pm * 2 * hstepA; };
;     auto a_tile = [&](const char* ub, int tau) -> const char* { return ub + (size_t)tau * (ABLK ? (size_t)32768 : kstep); };
;     ...
;     for (;;) {
;         const bool has_next = S.next(ui + 1, nxt);
;         const int nt = cur.nt;
;         const char* nuA = has_next ? a_unit(nxt) : uA; const int ntbA = has_next ? nxt.k0 / BK : tbA; const char* nB = has_next ? (const char*)g.Bt + (size_t)nxt.pn * tstepB + b_k0(nxt.k0) : cB;
;         for (int t = 0; t < nt; t += 2) {
;             const bool last = (t == nt - 2);
;             const char* a1 = a_tile(uA, tbA + t + 1);
;             const char* a2 = last ? a_tile(nuA, ntbA) : a_tile(uA, tbA + t + 2); const char* b2 = last ? nB : cB + (size_t)(t + 2) * kstepB;
;             const char* a3 = last ? a_tile(nuA, ntbA + 1) : a_tile(uA, tbA + t + 3); const char* b3 = b2 + kstepB;
;             if (last && has_next) S.a_ready(nxt);
;             if constexpr (SP2) {
;             PG8_LDB(B0, 0, 0); PG8_LDB(B1, 0, 1); PG8_SCHED; PG8_LDA(At, 0, 0); PG8_STAGE(PG8_SA(1, 1), a1 + hstepA, voffA);
;             PG8_WAIT_V(8); PG8_WAIT_L(0); PG8_BAR; PG8_MMA(0, 0, At, B0); PG8_MMA(0, 1, At, B1); PG8_BAR; PG8_SCHED;
;             PG8_LDA(At, 0, 1); PG8_STAGE(PG8_SB(0, 0), b2, voffB); PG8_STAGE(PG8_SB(0, 1), b2 + hstepB, voffB); PG8_STAGE(PG8_SA(0, 0), a2, voffA);
;             PG8_WAIT_V(8); PG8_WAIT_L(0); PG8_BAR; PG8_MMA(1, 0, At, B0); PG8_MMA(1, 1, At, B1); PG8_BAR; PG8_SCHED;
;             PG8_LDB(B0, 1, 0); PG8_LDB(B1, 1, 1); PG8_SCHED; PG8_LDA(At, 1, 0); PG8_STAGE(PG8_SA(0, 1), a2 + hstepA, voffA);
;             PG8_WAIT_V(8); PG8_WAIT_L(0); PG8_BAR; PG8_MMA(0, 0, At, B0); PG8_MMA(0, 1, At, B1); PG8_BAR; PG8_SCHED;
;             PG8_LDA(At, 1, 1); PG8_STAGE(PG8_SB(1, 0), b3, voffB); PG8_STAGE(PG8_SB(1, 1), b3 + hstepB, voffB); PG8_STAGE(PG8_SA(1, 0), a3, voffA);
;             PG8_WAIT_V(8); PG8_WAIT_L(0); PG8_BAR; PG8_MMA(1, 0, At, B0); PG8_MMA(1, 1, At, B1); PG8_BAR; PG8_SCHED;
.LBB0_2327:
	s_ashr_i32 s81, s80, 31
	s_andn2_b64 vcc, exec, s[4:5]
	s_lshl_b64 s[30:31], s[80:81], 22
	s_add_u32 s30, s1, s30
	s_addc_u32 s31, s33, s31
	s_and_b64 s[34:35], s[4:5], exec
	s_cselect_b32 s43, s31, s41
	s_cselect_b32 s57, s30, s40
	s_ashr_i32 s34, s0, 31
	s_lshr_b32 s34, s34, 26
	s_add_i32 s34, s0, s34
	s_ashr_i32 s34, s34, 6
	s_and_b64 s[36:37], s[4:5], exec
	s_cselect_b32 s44, s34, s42
	s_ashr_i32 s79, s78, 31
	s_lshl_b64 s[36:37], s[78:79], 22
	s_add_u32 s45, s46, s36
	s_addc_u32 s58, s47, s37
	s_ashr_i32 s35, s34, 31
	s_lshl_b64 s[36:37], s[34:35], 15
	s_add_u32 s36, s45, s36
	s_addc_u32 s37, s58, s37
	v_cndmask_b32_e64 v2, 0, 1, s[4:5]
	s_and_b64 s[4:5], s[4:5], exec
	s_cselect_b32 s4, s37, s39
	s_cselect_b32 s5, s36, s38
	s_ashr_i32 s45, s44, 31
	s_lshl_b64 s[44:45], s[44:45], 15
	s_add_u32 s35, s57, s44
	s_addc_u32 s57, s43, s45
	s_add_u32 s58, s35, 0x8000
	s_addc_u32 s59, s57, 0
	s_add_u32 s62, s38, 0x10000
	s_addc_u32 s63, s39, 0
	s_ashr_i32 s43, s42, 31
	v_cmp_ne_u32_e64 s[6:7], 1, v2
	s_lshl_b64 s[38:39], s[42:43], 15
	v_lshl_add_u64 v[2:3], s[40:41], 0, v[138:139]
	s_add_u32 s64, s40, s38
	v_lshl_add_u64 v[142:143], v[2:3], 0, s[38:39]
	v_lshl_add_u64 v[2:3], s[40:41], 0, v[140:141]
	s_addc_u32 s65, s41, s39
	v_lshl_add_u64 v[144:145], v[2:3], 0, s[38:39]
	s_lshl_b32 s38, s56, 15
	s_add_i32 s38, s38, 0xfff00000
	v_mov_b32_e32 v2, 0
	s_add_u32 s66, s38, 0xf0000
	s_mov_b32 s67, 0
	s_mov_b64 s[38:39], 0
	ds_read_b128 v[152:155], v148
	ds_read_b128 v[156:159], v148 offset:1024
	ds_read_b128 v[160:163], v148 offset:2048
	ds_read_b128 v[164:167], v148 offset:3072
	ds_read_b128 v[168:171], v149
	ds_read_b128 v[172:175], v149 offset:1024
	ds_read_b128 v[176:179], v149 offset:2048
	ds_read_b128 v[180:183], v149 offset:3072
	s_add_u32 s40, s64, s38
	s_addc_u32 s41, s65, s39
	s_add_u32 s44, s40, 0x10000
	s_addc_u32 s45, s41, 0
	s_add_i32 s67, s67, 2
	s_add_u32 s42, s62, s38
	s_addc_u32 s43, s63, s39
	s_add_u32 s40, s40, 0x18000
	s_addc_u32 s41, s41, 0
	s_cmp_eq_u32 s66, s38
	s_cselect_b32 s41, s59, s41
	s_cselect_b32 s40, s58, s40
	s_cselect_b32 s43, s4, s43
	s_cselect_b32 s42, s5, s42
	s_cselect_b32 s45, s57, s45
	s_cselect_b32 s44, s35, s44
	v_lshl_add_u64 v[216:217], v[142:143], 0, s[38:39]
	s_add_i32 m0, s49, 0xc000
	ds_read_b128 v[184:187], v150
	ds_read_b128 v[188:191], v150 offset:1024
	ds_read_b128 v[192:195], v150 offset:2048
	ds_read_b128 v[196:199], v150 offset:3072
	ds_read_b128 v[200:203], v150 offset:4096
	ds_read_b128 v[204:207], v150 offset:5120
	ds_read_b128 v[208:211], v150 offset:6144
	ds_read_b128 v[212:215], v150 offset:7168
	global_load_lds_dwordx4 v[216:217], off
	v_lshl_add_u64 v[216:217], v[144:145], 0, s[38:39]
	s_add_i32 m0, s49, 0xe000
	s_nop 0
	global_load_lds_dwordx4 v[216:217], off
	s_waitcnt vmcnt(8) lgkmcnt(0)
	s_barrier
	v_mfma_f32_16x16x32_bf16 v[126:129], v[152:155], v[184:187], 0
	v_mfma_f32_16x16x32_bf16 v[122:125], v[160:163], v[184:187], 0
	v_mfma_f32_16x16x32_bf16 v[110:113], v[152:155], v[192:195], 0
	v_mfma_f32_16x16x32_bf16 v[106:109], v[160:163], v[192:195], 0
	v_mfma_f32_16x16x32_bf16 v[94:97], v[152:155], v[200:203], 0
	v_mfma_f32_16x16x32_bf16 v[90:93], v[160:163], v[200:203], 0
	v_mfma_f32_16x16x32_bf16 v[78:81], v[152:155], v[208:211], 0
	v_mfma_f32_16x16x32_bf16 v[74:77], v[160:163], v[208:211], 0
	v_mfma_f32_16x16x32_bf16 v[126:129], v[156:159], v[188:191], v[126:129]
	v_mfma_f32_16x16x32_bf16 v[122:125], v[164:167], v[188:191], v[122:125]
	v_mfma_f32_16x16x32_bf16 v[110:113], v[156:159], v[196:199], v[110:113]
	v_mfma_f32_16x16x32_bf16 v[106:109], v[164:167], v[196:199], v[106:109]
	v_mfma_f32_16x16x32_bf16 v[94:97], v[156:159], v[204:207], v[94:97]
	v_mfma_f32_16x16x32_bf16 v[90:93], v[164:167], v[204:207], v[90:93]
	v_mfma_f32_16x16x32_bf16 v[78:81], v[156:159], v[212:215], v[78:81]
	v_mfma_f32_16x16x32_bf16 v[74:77], v[164:167], v[212:215], v[74:77]
	v_mfma_f32_16x16x32_bf16 v[118:121], v[168:171], v[184:187], 0
	v_mfma_f32_16x16x32_bf16 v[114:117], v[176:179], v[184:187], 0
	v_mfma_f32_16x16x32_bf16 v[102:105], v[168:171], v[192:195], 0
	v_mfma_f32_16x16x32_bf16 v[98:101], v[176:179], v[192:195], 0
	v_mfma_f32_16x16x32_bf16 v[86:89], v[168:171], v[200:203], 0
	v_mfma_f32_16x16x32_bf16 v[82:85], v[176:179], v[200:203], 0
	v_mfma_f32_16x16x32_bf16 v[70:73], v[168:171], v[208:211], 0
	v_mfma_f32_16x16x32_bf16 v[66:69], v[176:179], v[208:211], 0
	v_mfma_f32_16x16x32_bf16 v[118:121], v[172:175], v[188:191], v[118:121]
	v_mfma_f32_16x16x32_bf16 v[114:117], v[180:183], v[188:191], v[114:117]
	v_mfma_f32_16x16x32_bf16 v[102:105], v[172:175], v[196:199], v[102:105]
	v_mfma_f32_16x16x32_bf16 v[98:101], v[180:183], v[196:199], v[98:101]
	v_mfma_f32_16x16x32_bf16 v[86:89], v[172:175], v[204:207], v[86:89]
	v_mfma_f32_16x16x32_bf16 v[82:85], v[180:183], v[204:207], v[82:85]
	v_mfma_f32_16x16x32_bf16 v[70:73], v[172:175], v[212:215], v[70:73]
	v_mfma_f32_16x16x32_bf16 v[66:69], v[180:183], v[212:215], v[66:69]
	s_barrier
	s_add_i32 s70, s72, s48
	s_mov_b32 m0, s70
	ds_read_b128 v[184:187], v150 offset:16384
	ds_read_b128 v[188:191], v150 offset:17408
	ds_read_b128 v[192:195], v150 offset:18432
	ds_read_b128 v[196:199], v150 offset:19456
	ds_read_b128 v[200:203], v150 offset:20480
	ds_read_b128 v[204:207], v150 offset:21504
	ds_read_b128 v[208:211], v150 offset:22528
	ds_read_b128 v[212:215], v150 offset:23552
	global_load_lds_dwordx4 v130, s[42:43]
	s_add_i32 m0, s70, 0x2000
	s_add_u32 s76, s42, 0x4000
	s_addc_u32 s77, s43, 0
	s_add_i32 s70, s73, s48
	global_load_lds_dwordx4 v132, s[42:43]
	s_mov_b32 m0, s70
	s_nop 0
	global_load_lds_dwordx4 v130, s[76:77]
	s_add_i32 m0, s70, 0x2000
	s_nop 0
	global_load_lds_dwordx4 v132, s[76:77]
	s_mov_b32 m0, s49
	s_nop 0
	global_load_lds_dwordx4 v130, s[44:45]
	s_mov_b32 m0, s50
	s_nop 0
	global_load_lds_dwordx4 v132, s[44:45]
	s_waitcnt vmcnt(8) lgkmcnt(0)
	s_barrier
; #define PG8_STAGE(bufoff, gbase, voff) do { _Pragma("unroll") for (int _i = 0; _i < 2; ++_i) \
;         __builtin_amdgcn_global_load_lds((const unsigned*)((const char*)(gbase) + (voff)[_i]), (LAS unsigned*)(lds + (bufoff) + ldsw + _i * 8192), 16, 0, 0); } while (0)
; #define PG8_LDA(dst, b, h) do { _Pragma("unroll") for (int m = 0; m < 4; ++m) _Pragma("unroll") for (int k = 0; k < 2; ++k) dst[m][k] = *(const LAS bf16x8*)(lds + PG8_SA(b, h) + aoff + m * 2048 + k * 1024); } while (0)
; #define PG8_LDB(dst, b, h) do { _Pragma("unroll") for (int n = 0; n < 2; ++n) _Pragma("unroll") for (int k = 0; k < 2; ++k) dst[n][k] = *(const LAS bf16x8*)(lds + PG8_SB(b, h) + boff + n * 2048 + k * 1024); } while (0)
; #define PG8_MMA(ai, bj, At, Bt) do { __builtin_amdgcn_s_setprio(1); _Pragma("unroll") for (int m = 0; m < 4; ++m) _Pragma("unroll") for (int n = 0; n < 2; ++n) _Pragma("unroll") for (int k = 0; k < 2; ++k) \
;         acc[ai][bj][m][n] = __builtin_amdgcn_mfma_f32_16x16x32_bf16(Bt[n][k], At[m][k], acc[ai][bj][m][n], 0, 0, 0); __builtin_amdgcn_s_setprio(0); } while (0)
; #define PG8_BAR __builtin_amdgcn_s_barrier()
; template <class Epi, class Sched, bool ABLK = false, bool ALIGN_EPI = true, bool SP2 = true, bool BBLK = true>
; __device__ __forceinline__ void gemm_phase(LAS unsigned char* lds, const Gemm g, const Sched& S, const Epi& E) {
;     ...
;             PG8_LDB(B0, 0, 0); PG8_LDB(B1, 0, 1); PG8_SCHED; PG8_LDA(At, 0, 0); PG8_STAGE(PG8_SA(1, 1), a1 + hstepA, voffA);
;             PG8_WAIT_V(8); PG8_WAIT_L(0); PG8_BAR; PG8_MMA(0, 0, At, B0); PG8_MMA(0, 1, At, B1); PG8_BAR; PG8_SCHED;
;             PG8_LDA(At, 0, 1); PG8_STAGE(PG8_SB(0, 0), b2, voffB); PG8_STAGE(PG8_SB(0, 1), b2 + hstepB, voffB); PG8_STAGE(PG8_SA(0, 0), a2, voffA);
;             PG8_WAIT_V(8); PG8_WAIT_L(0); PG8_BAR; PG8_MMA(1, 0, At, B0); PG8_MMA(1, 1, At, B1); PG8_BAR; PG8_SCHED;
;             PG8_LDB(B0, 1, 0); PG8_LDB(B1, 1, 1); PG8_SCHED; PG8_LDA(At, 1, 0); PG8_STAGE(PG8_SA(0, 1), a2 + hstepA, voffA);
;             PG8_WAIT_V(8); PG8_WAIT_L(0); PG8_BAR; PG8_MMA(0, 0, At, B0); PG8_MMA(0, 1, At, B1); PG8_BAR; PG8_SCHED;
;             PG8_LDA(At, 1, 1); PG8_STAGE(PG8_SB(1, 0), b3, voffB); PG8_STAGE(PG8_SB(1, 1), b3 + hstepB, voffB); PG8_STAGE(PG8_SA(1, 0), a3, voffA);
;             PG8_WAIT_V(8); PG8_WAIT_L(0); PG8_BAR; PG8_MMA(1, 0, At, B0); PG8_MMA(1, 1, At, B1); PG8_BAR; PG8_SCHED;
	v_mfma_f32_16x16x32_bf16 v[62:65], v[152:155], v[184:187], 0
	v_mfma_f32_16x16x32_bf16 v[58:61], v[160:163], v[184:187], 0
	v_mfma_f32_16x16x32_bf16 v[46:49], v[152:155], v[192:195], 0
	v_mfma_f32_16x16x32_bf16 v[42:45], v[160:163], v[192:195], 0
	v_mfma_f32_16x16x32_bf16 v[30:33], v[152:155], v[200:203], 0
	v_mfma_f32_16x16x32_bf16 v[26:29], v[160:163], v[200:203], 0
	v_mfma_f32_16x16x32_bf16 v[14:17], v[152:155], v[208:211], 0
	v_mfma_f32_16x16x32_bf16 v[10:13], v[160:163], v[208:211], 0
	v_mfma_f32_16x16x32_bf16 v[62:65], v[156:159], v[188:191], v[62:65]
	v_mfma_f32_16x16x32_bf16 v[58:61], v[164:167], v[188:191], v[58:61]
	v_mfma_f32_16x16x32_bf16 v[46:49], v[156:159], v[196:199], v[46:49]
	v_mfma_f32_16x16x32_bf16 v[42:45], v[164:167], v[196:199], v[42:45]
	v_mfma_f32_16x16x32_bf16 v[30:33], v[156:159], v[204:207], v[30:33]
	v_mfma_f32_16x16x32_bf16 v[26:29], v[164:167], v[204:207], v[26:29]
	v_mfma_f32_16x16x32_bf16 v[14:17], v[156:159], v[212:215], v[14:17]
	v_mfma_f32_16x16x32_bf16 v[10:13], v[164:167], v[212:215], v[10:13]
	v_mfma_f32_16x16x32_bf16 v[54:57], v[168:171], v[184:187], 0
	v_mfma_f32_16x16x32_bf16 v[50:53], v[176:179], v[184:187], 0
	v_mfma_f32_16x16x32_bf16 v[38:41], v[168:171], v[192:195], 0
	v_mfma_f32_16x16x32_bf16 v[34:37], v[176:179], v[192:195], 0
	v_mfma_f32_16x16x32_bf16 v[22:25], v[168:171], v[200:203], 0
	v_mfma_f32_16x16x32_bf16 v[18:21], v[176:179], v[200:203], 0
	v_mfma_f32_16x16x32_bf16 v[6:9], v[168:171], v[208:211], 0
	v_mfma_f32_16x16x32_bf16 v[2:5], v[176:179], v[208:211], 0
	v_mfma_f32_16x16x32_bf16 v[54:57], v[172:175], v[188:191], v[54:57]
	v_mfma_f32_16x16x32_bf16 v[50:53], v[180:183], v[188:191], v[50:53]
	v_mfma_f32_16x16x32_bf16 v[38:41], v[172:175], v[196:199], v[38:41]
	v_mfma_f32_16x16x32_bf16 v[34:37], v[180:183], v[196:199], v[34:37]
	v_mfma_f32_16x16x32_bf16 v[22:25], v[172:175], v[204:207], v[22:25]
	v_mfma_f32_16x16x32_bf16 v[18:21], v[180:183], v[204:207], v[18:21]
	v_mfma_f32_16x16x32_bf16 v[6:9], v[172:175], v[212:215], v[6:9]
	v_mfma_f32_16x16x32_bf16 v[2:5], v[180:183], v[212:215], v[2:5]
	s_barrier
	v_add_u32_e32 v151, s60, v146
	ds_read_b128 v[152:155], v151
	ds_read_b128 v[156:159], v151 offset:1024
	ds_read_b128 v[160:163], v151 offset:2048
	ds_read_b128 v[164:167], v151 offset:3072
	v_add_u32_e32 v151, s61, v146
	ds_read_b128 v[168:171], v151
	ds_read_b128 v[172:175], v151 offset:1024
	ds_read_b128 v[176:179], v151 offset:2048
	ds_read_b128 v[180:183], v151 offset:3072
	s_add_u32 s44, s44, 0x4000
	s_addc_u32 s45, s45, 0
	s_mov_b32 m0, s51
	ds_read_b128 v[184:187], v150 offset:32768
	ds_read_b128 v[188:191], v150 offset:33792
	ds_read_b128 v[192:195], v150 offset:34816
	ds_read_b128 v[196:199], v150 offset:35840
	ds_read_b128 v[200:203], v150 offset:36864
	ds_read_b128 v[204:207], v150 offset:37888
	ds_read_b128 v[208:211], v150 offset:38912
	ds_read_b128 v[212:215], v150 offset:39936
	global_load_lds_dwordx4 v130, s[44:45]
	s_mov_b32 m0, s52
	s_nop 0
	global_load_lds_dwordx4 v132, s[44:45]
	s_waitcnt vmcnt(8) lgkmcnt(0)
	s_barrier
	v_mfma_f32_16x16x32_bf16 v[126:129], v[152:155], v[184:187], v[126:129]
	v_mfma_f32_16x16x32_bf16 v[122:125], v[160:163], v[184:187], v[122:125]
	v_mfma_f32_16x16x32_bf16 v[110:113], v[152:155], v[192:195], v[110:113]
	v_mfma_f32_16x16x32_bf16 v[106:109], v[160:163], v[192:195], v[106:109]
	v_mfma_f32_16x16x32_bf16 v[94:97], v[152:155], v[200:203], v[94:97]
	v_mfma_f32_16x16x32_bf16 v[90:93], v[160:163], v[200:203], v[90:93]
	v_mfma_f32_16x16x32_bf16 v[78:81], v[152:155], v[208:211], v[78:81]
	v_mfma_f32_16x16x32_bf16 v[74:77], v[160:163], v[208:211], v[74:77]
	v_mfma_f32_16x16x32_bf16 v[126:129], v[156:159], v[188:191], v[126:129]
	v_mfma_f32_16x16x32_bf16 v[122:125], v[164:167], v[188:191], v[122:125]
	v_mfma_f32_16x16x32_bf16 v[110:113], v[156:159], v[196:199], v[110:113]
	v_mfma_f32_16x16x32_bf16 v[106:109], v[164:167], v[196:199], v[106:109]
	v_mfma_f32_16x16x32_bf16 v[94:97], v[156:159], v[204:207], v[94:97]
	v_mfma_f32_16x16x32_bf16 v[90:93], v[164:167], v[204:207], v[90:93]
	v_mfma_f32_16x16x32_bf16 v[78:81], v[156:159], v[212:215], v[78:81]
	v_mfma_f32_16x16x32_bf16 v[74:77], v[164:167], v[212:215], v[74:77]
	v_mfma_f32_16x16x32_bf16 v[118:121], v[168:171], v[184:187], v[118:121]
	v_mfma_f32_16x16x32_bf16 v[114:117], v[176:179], v[184:187], v[114:117]
	v_mfma_f32_16x16x32_bf16 v[102:105], v[168:171], v[192:195], v[102:105]
	v_mfma_f32_16x16x32_bf16 v[98:101], v[176:179], v[192:195], v[98:101]
	v_mfma_f32_16x16x32_bf16 v[86:89], v[168:171], v[200:203], v[86:89]
	v_mfma_f32_16x16x32_bf16 v[82:85], v[176:179], v[200:203], v[82:85]
	v_mfma_f32_16x16x32_bf16 v[70:73], v[168:171], v[208:211], v[70:73]
	v_mfma_f32_16x16x32_bf16 v[66:69], v[176:179], v[208:211], v[66:69]
	v_mfma_f32_16x16x32_bf16 v[118:121], v[172:175], v[188:191], v[118:121]
	v_mfma_f32_16x16x32_bf16 v[114:117], v[180:183], v[188:191], v[114:117]
	v_mfma_f32_16x16x32_bf16 v[102:105], v[172:175], v[196:199], v[102:105]
	v_mfma_f32_16x16x32_bf16 v[98:101], v[180:183], v[196:199], v[98:101]
	v_mfma_f32_16x16x32_bf16 v[86:89], v[172:175], v[204:207], v[86:89]
	v_mfma_f32_16x16x32_bf16 v[82:85], v[180:183], v[204:207], v[82:85]
	v_mfma_f32_16x16x32_bf16 v[70:73], v[172:175], v[212:215], v[70:73]
	v_mfma_f32_16x16x32_bf16 v[66:69], v[180:183], v[212:215], v[66:69]
	s_barrier
; #define PG8_STAGE(bufoff, gbase, voff) do { _Pragma("unroll") for (int _i = 0; _i < 2; ++_i) \
;         __builtin_amdgcn_global_load_lds((const unsigned*)((const char*)(gbase) + (voff)[_i]), (LAS unsigned*)(lds + (bufoff) + ldsw + _i * 8192), 16, 0, 0); } while (0)
; #define PG8_LDA(dst, b, h) do { _Pragma("unroll") for (int m = 0; m < 4; ++m) _Pragma("unroll") for (int k = 0; k < 2; ++k) dst[m][k] = *(const LAS bf16x8*)(lds + PG8_SA(b, h) + aoff + m * 2048 + k * 1024); } while (0)
; #define PG8_LDB(dst, b, h) do { _Pragma("unroll") for (int n = 0; n < 2; ++n) _Pragma("unroll") for (int k = 0; k < 2; ++k) dst[n][k] = *(const LAS bf16x8*)(lds + PG8_SB(b, h) + boff + n * 2048 + k * 1024); } while (0)
; #define PG8_MMA(ai, bj, At, Bt) do { __builtin_amdgcn_s_setprio(1); _Pragma("unroll") for (int m = 0; m < 4; ++m) _Pragma("unroll") for (int n = 0; n < 2; ++n) _Pragma("unroll") for (int k = 0; k < 2; ++k) \
;         acc[ai][bj][m][n] = __builtin_amdgcn_mfma_f32_16x16x32_bf16(Bt[n][k], At[m][k], acc[ai][bj][m][n], 0, 0, 0); __builtin_amdgcn_s_setprio(0); } while (0)
; template <class Epi, class Sched, bool ABLK = false, bool ALIGN_EPI = true, bool SP2 = true, bool BBLK = true>
; __device__ __forceinline__ void gemm_phase(LAS unsigned char* lds, const Gemm g, const Sched& S, const Epi& E) {
;     ...
;         for (int t = 0; t < nt; t += 2) {
;     ...
;             PG8_LDB(B0, 0, 0); PG8_LDB(B1, 0, 1); PG8_SCHED; PG8_LDA(At, 0, 0); PG8_STAGE(PG8_SA(1, 1), a1 + hstepA, voffA);
;             PG8_WAIT_V(8); PG8_WAIT_L(0); PG8_BAR; PG8_MMA(0, 0, At, B0); PG8_MMA(0, 1, At, B1); PG8_BAR; PG8_SCHED;
;             PG8_LDA(At, 0, 1); PG8_STAGE(PG8_SB(0, 0), b2, voffB); PG8_STAGE(PG8_SB(0, 1), b2 + hstepB, voffB); PG8_STAGE(PG8_SA(0, 0), a2, voffA);
;             PG8_WAIT_V(8); PG8_WAIT_L(0); PG8_BAR; PG8_MMA(1, 0, At, B0); PG8_MMA(1, 1, At, B1); PG8_BAR; PG8_SCHED;
;             PG8_LDB(B0, 1, 0); PG8_LDB(B1, 1, 1); PG8_SCHED; PG8_LDA(At, 1, 0); PG8_STAGE(PG8_SA(0, 1), a2 + hstepA, voffA);
;             PG8_WAIT_V(8); PG8_WAIT_L(0); PG8_BAR; PG8_MMA(0, 0, At, B0); PG8_MMA(0, 1, At, B1); PG8_BAR; PG8_SCHED;
;             PG8_LDA(At, 1, 1); PG8_STAGE(PG8_SB(1, 0), b3, voffB); PG8_STAGE(PG8_SB(1, 1), b3 + hstepB, voffB); PG8_STAGE(PG8_SA(1, 0), a3, voffA);
;             PG8_WAIT_V(8); PG8_WAIT_L(0); PG8_BAR; PG8_MMA(1, 0, At, B0); PG8_MMA(1, 1, At, B1); PG8_BAR; PG8_SCHED;
	s_add_u32 s44, s42, 0x8000
	s_addc_u32 s45, s43, 0
	s_add_i32 s70, s60, s48
	s_mov_b32 m0, s70
	ds_read_b128 v[184:187], v150 offset:49152
	ds_read_b128 v[188:191], v150 offset:50176
	ds_read_b128 v[192:195], v150 offset:51200
	ds_read_b128 v[196:199], v150 offset:52224
	ds_read_b128 v[200:203], v150 offset:53248
	ds_read_b128 v[204:207], v150 offset:54272
	ds_read_b128 v[208:211], v150 offset:55296
	ds_read_b128 v[212:215], v150 offset:56320
	global_load_lds_dwordx4 v130, s[44:45]
	s_add_i32 m0, s70, 0x2000
	s_add_u32 s42, s42, 0xc000
	v_lshl_add_u64 v[216:217], s[44:45], 0, v[132:133]
	s_addc_u32 s43, s43, 0
	s_add_i32 s44, s61, s48
	global_load_lds_dwordx4 v[216:217], off
	s_mov_b32 m0, s44
	s_nop 0
	global_load_lds_dwordx4 v130, s[42:43]
	s_add_i32 m0, s44, 0x2000
	s_nop 0
	global_load_lds_dwordx4 v132, s[42:43]
	s_mov_b32 m0, s53
	s_nop 0
	global_load_lds_dwordx4 v130, s[40:41]
	s_mov_b32 m0, s54
	s_nop 0
	global_load_lds_dwordx4 v132, s[40:41]
	s_waitcnt vmcnt(8) lgkmcnt(0)
	s_barrier
	v_mfma_f32_16x16x32_bf16 v[62:65], v[152:155], v[184:187], v[62:65]
	v_mfma_f32_16x16x32_bf16 v[58:61], v[160:163], v[184:187], v[58:61]
	v_mfma_f32_16x16x32_bf16 v[46:49], v[152:155], v[192:195], v[46:49]
	v_mfma_f32_16x16x32_bf16 v[42:45], v[160:163], v[192:195], v[42:45]
	v_mfma_f32_16x16x32_bf16 v[30:33], v[152:155], v[200:203], v[30:33]
	v_mfma_f32_16x16x32_bf16 v[26:29], v[160:163], v[200:203], v[26:29]
	v_mfma_f32_16x16x32_bf16 v[14:17], v[152:155], v[208:211], v[14:17]
	v_mfma_f32_16x16x32_bf16 v[10:13], v[160:163], v[208:211], v[10:13]
	v_mfma_f32_16x16x32_bf16 v[62:65], v[156:159], v[188:191], v[62:65]
	v_mfma_f32_16x16x32_bf16 v[58:61], v[164:167], v[188:191], v[58:61]
	v_mfma_f32_16x16x32_bf16 v[46:49], v[156:159], v[196:199], v[46:49]
	v_mfma_f32_16x16x32_bf16 v[42:45], v[164:167], v[196:199], v[42:45]
	v_mfma_f32_16x16x32_bf16 v[30:33], v[156:159], v[204:207], v[30:33]
	v_mfma_f32_16x16x32_bf16 v[26:29], v[164:167], v[204:207], v[26:29]
	v_mfma_f32_16x16x32_bf16 v[14:17], v[156:159], v[212:215], v[14:17]
	v_mfma_f32_16x16x32_bf16 v[10:13], v[164:167], v[212:215], v[10:13]
	v_mfma_f32_16x16x32_bf16 v[54:57], v[168:171], v[184:187], v[54:57]
	v_mfma_f32_16x16x32_bf16 v[50:53], v[176:179], v[184:187], v[50:53]
	v_mfma_f32_16x16x32_bf16 v[38:41], v[168:171], v[192:195], v[38:41]
	v_mfma_f32_16x16x32_bf16 v[34:37], v[176:179], v[192:195], v[34:37]
	v_mfma_f32_16x16x32_bf16 v[22:25], v[168:171], v[200:203], v[22:25]
	v_mfma_f32_16x16x32_bf16 v[18:21], v[176:179], v[200:203], v[18:21]
	v_mfma_f32_16x16x32_bf16 v[6:9], v[168:171], v[208:211], v[6:9]
	v_mfma_f32_16x16x32_bf16 v[2:5], v[176:179], v[208:211], v[2:5]
	v_mfma_f32_16x16x32_bf16 v[54:57], v[172:175], v[188:191], v[54:57]
	v_mfma_f32_16x16x32_bf16 v[50:53], v[180:183], v[188:191], v[50:53]
	v_mfma_f32_16x16x32_bf16 v[38:41], v[172:175], v[196:199], v[38:41]
	v_mfma_f32_16x16x32_bf16 v[34:37], v[180:183], v[196:199], v[34:37]
	v_mfma_f32_16x16x32_bf16 v[22:25], v[172:175], v[204:207], v[22:25]
	v_mfma_f32_16x16x32_bf16 v[18:21], v[180:183], v[204:207], v[18:21]
	v_mfma_f32_16x16x32_bf16 v[6:9], v[172:175], v[212:215], v[6:9]
	v_mfma_f32_16x16x32_bf16 v[2:5], v[180:183], v[212:215], v[2:5]
	s_barrier
	s_add_u32 s38, s38, 0x10000
	s_addc_u32 s39, s39, 0
	s_cmp_ge_u32 s67, s56
